# removed all s_setprio flips; LDS-DMA loads in GEMM K-loops use saddr form (no v_lshl_add_u64); dropped redundant lgkmcnt(0) after barrier
# speedup vs baseline: 1.0118x; 1.0118x over previous
; #define PG8_STAGE(bufoff, gbase, voff) do { _Pragma("unroll") for (int _i = 0; _i < 2; ++_i) \
;         __builtin_amdgcn_global_load_lds((const unsigned*)((const char*)(gbase) + (voff)[_i]), (LAS unsigned*)(lds + (bufoff) + ldsw + _i * 8192), 16, 0, 0); } while (0)
; #define PG8_LDA(dst, b, h) do { _Pragma("unroll") for (int m = 0; m < 4; ++m) _Pragma("unroll") for (int k = 0; k < 2; ++k) dst[m][k] = *(const LAS bf16x8*)(lds + PG8_SA(b, h) + aoff + m * 2048 + k * 1024); } while (0)
; #define PG8_LDB(dst, b, h) do { _Pragma("unroll") for (int n = 0; n < 2; ++n) _Pragma("unroll") for (int k = 0; k < 2; ++k) dst[n][k] = *(const LAS bf16x8*)(lds + PG8_SB(b, h) + boff + n * 2048 + k * 1024); } while (0)
; #define PG8_MMA(ai, bj, At, Bt) do { __builtin_amdgcn_s_setprio(1); _Pragma("unroll") for (int m = 0; m < 4; ++m) _Pragma("unroll") for (int n = 0; n < 2; ++n) _Pragma("unroll") for (int k = 0; k < 2; ++k) \
;         acc[ai][bj][m][n] = __builtin_amdgcn_mfma_f32_16x16x32_bf16(Bt[n][k], At[m][k], acc[ai][bj][m][n], 0, 0, 0); __builtin_amdgcn_s_setprio(0); } while (0)
; #define PG8_WAIT_V(n) asm volatile("s_waitcnt vmcnt(" #n ")" ::: "memory")
; #define PG8_WAIT_L(n) asm volatile("s_waitcnt lgkmcnt(" #n ")" ::: "memory")
; #define PG8_BAR __builtin_amdgcn_s_barrier()
; #define PG8_SCHED __builtin_amdgcn_sched_barrier(0)
; template <class Epi, bool ALIGN_EPI>
; __device__ __forceinline__ void gemm_phase(LAS unsigned char* lds, const Gemm g, const StaticOrder& S, const Epi& E, const int tid) {
;     ...
;         for (int t = 0; t < nt; t += 2) {
;             const bool last = (t == nt - 2);
;             const char* a1 = cA + (size_t)(t + 1) * kstepA;
;             const char* a2 = last ? nA : cA + (size_t)(t + 2) * kstepA; const char* b2 = last ? nB : cB + (size_t)(t + 2) * kstepB;
;             const char* a3 = a2 + kstepA; const char* b3 = b2 + kstepB;
;             PG8_LDB(B0, 0, 0); PG8_LDB(B1, 0, 1); PG8_SCHED; PG8_LDA(At, 0, 0); PG8_STAGE(PG8_SA(1, 1), a1 + hstepA, voffA);
;             PG8_WAIT_V(8); PG8_WAIT_L(0); PG8_BAR; PG8_MMA(0, 0, At, B0); PG8_MMA(0, 1, At, B1); PG8_BAR; PG8_SCHED;
.LBB0_211:
	s_add_u32 s50, s48, 0x4000
	s_addc_u32 s51, s49, 0
	s_cmp_eq_u32 s89, 28
	s_cselect_b32 s54, s87, s50
	s_cselect_b32 s55, s43, s51
	s_cselect_b32 s52, vcc_lo, vcc_hi
	s_cselect_b32 s53, s35, s88
	s_add_u32 s50, s54, 0x8000
	s_addc_u32 s51, s55, 0
	s_add_i32 s90, 0, 0x10000
	v_add_u32_e32 v0, s90, v160
	s_add_i32 s92, 0, 0x14000
	ds_read_b128 v[132:135], v0
	ds_read_b128 v[136:139], v0 offset:1024
	ds_read_b128 v[152:155], v0 offset:2048
	ds_read_b128 v[156:159], v0 offset:3072
	v_add_u32_e32 v0, s92, v160
	ds_read_b128 v[162:165], v0
	ds_read_b128 v[166:169], v0 offset:1024
	ds_read_b128 v[170:173], v0 offset:2048
	ds_read_b128 v[174:177], v0 offset:3072
	s_add_i32 m0, s72, 0xc000
	ds_read_b128 v[178:181], v161
	ds_read_b128 v[182:185], v161 offset:1024
	ds_read_b128 v[186:189], v161 offset:2048
	ds_read_b128 v[190:193], v161 offset:3072
	ds_read_b128 v[194:197], v161 offset:4096
	ds_read_b128 v[198:201], v161 offset:5120
	ds_read_b128 v[214:217], v161 offset:6144
	ds_read_b128 v[218:221], v161 offset:7168
	global_load_lds_dwordx4 v148, s[48:49]
	s_add_i32 m0, s72, 0xe000
	s_nop 0
	global_load_lds_dwordx4 v150, s[48:49]
	s_waitcnt vmcnt(8)
	s_waitcnt lgkmcnt(0)
	s_barrier


; #define PG8_MMA(ai, bj, At, Bt) do { __builtin_amdgcn_s_setprio(1); _Pragma("unroll") for (int m = 0; m < 4; ++m) _Pragma("unroll") for (int n = 0; n < 2; ++n) _Pragma("unroll") for (int k = 0; k < 2; ++k) \
;         acc[ai][bj][m][n] = __builtin_amdgcn_mfma_f32_16x16x32_bf16(Bt[n][k], At[m][k], acc[ai][bj][m][n], 0, 0, 0); __builtin_amdgcn_s_setprio(0); } while (0)
; #define PG8_WAIT_V(n) asm volatile("s_waitcnt vmcnt(" #n ")" ::: "memory")
; #define PG8_WAIT_L(n) asm volatile("s_waitcnt lgkmcnt(" #n ")" ::: "memory")
; #define PG8_BAR __builtin_amdgcn_s_barrier()
; #define PG8_SCHED __builtin_amdgcn_sched_barrier(0)
; template <class Epi, bool ALIGN_EPI>
; __device__ __forceinline__ void gemm_phase(LAS unsigned char* lds, const Gemm g, const StaticOrder& S, const Epi& E, const int tid) {
;     ...
;             PG8_WAIT_V(8); PG8_WAIT_L(0); PG8_BAR; PG8_MMA(0, 0, At, B0); PG8_MMA(0, 1, At, B1); PG8_BAR; PG8_SCHED;
	v_mfma_f32_16x16x32_bf16 v[88:91], v[132:135], v[178:181], v[88:91]
	v_mfma_f32_16x16x32_bf16 v[124:127], v[152:155], v[178:181], v[124:127]
	v_mfma_f32_16x16x32_bf16 v[52:55], v[132:135], v[186:189], v[52:55]
	v_mfma_f32_16x16x32_bf16 v[120:123], v[152:155], v[186:189], v[120:123]
	v_mfma_f32_16x16x32_bf16 v[40:43], v[132:135], v[194:197], v[40:43]
	v_mfma_f32_16x16x32_bf16 v[116:119], v[152:155], v[194:197], v[116:119]
	v_mfma_f32_16x16x32_bf16 v[36:39], v[132:135], v[214:217], v[36:39]
	v_mfma_f32_16x16x32_bf16 v[112:115], v[152:155], v[214:217], v[112:115]
	v_mfma_f32_16x16x32_bf16 v[88:91], v[136:139], v[182:185], v[88:91]
	v_mfma_f32_16x16x32_bf16 v[124:127], v[156:159], v[182:185], v[124:127]
	v_mfma_f32_16x16x32_bf16 v[52:55], v[136:139], v[190:193], v[52:55]
	v_mfma_f32_16x16x32_bf16 v[120:123], v[156:159], v[190:193], v[120:123]
	v_mfma_f32_16x16x32_bf16 v[40:43], v[136:139], v[198:201], v[40:43]
	v_mfma_f32_16x16x32_bf16 v[116:119], v[156:159], v[198:201], v[116:119]
	v_mfma_f32_16x16x32_bf16 v[36:39], v[136:139], v[218:221], v[36:39]
	v_mfma_f32_16x16x32_bf16 v[112:115], v[156:159], v[218:221], v[112:115]


; #define PG8_MMA(ai, bj, At, Bt) do { __builtin_amdgcn_s_setprio(1); _Pragma("unroll") for (int m = 0; m < 4; ++m) _Pragma("unroll") for (int n = 0; n < 2; ++n) _Pragma("unroll") for (int k = 0; k < 2; ++k) \
;         acc[ai][bj][m][n] = __builtin_amdgcn_mfma_f32_16x16x32_bf16(Bt[n][k], At[m][k], acc[ai][bj][m][n], 0, 0, 0); __builtin_amdgcn_s_setprio(0); } while (0)
; #define PG8_WAIT_V(n) asm volatile("s_waitcnt vmcnt(" #n ")" ::: "memory")
; #define PG8_WAIT_L(n) asm volatile("s_waitcnt lgkmcnt(" #n ")" ::: "memory")
; #define PG8_BAR __builtin_amdgcn_s_barrier()
; #define PG8_SCHED __builtin_amdgcn_sched_barrier(0)
; template <class Epi, bool ALIGN_EPI>
; __device__ __forceinline__ void gemm_phase(LAS unsigned char* lds, const Gemm g, const StaticOrder& S, const Epi& E, const int tid) {
;     ...
;             PG8_WAIT_V(8); PG8_WAIT_L(0); PG8_BAR; PG8_MMA(0, 0, At, B0); PG8_MMA(0, 1, At, B1); PG8_BAR; PG8_SCHED;
	v_mfma_f32_16x16x32_bf16 v[80:83], v[162:165], v[178:181], v[80:83]
	v_mfma_f32_16x16x32_bf16 v[128:131], v[170:173], v[178:181], v[128:131]
	v_mfma_f32_16x16x32_bf16 v[68:71], v[162:165], v[186:189], v[68:71]
	v_mfma_f32_16x16x32_bf16 v[108:111], v[170:173], v[186:189], v[108:111]
	v_mfma_f32_16x16x32_bf16 v[60:63], v[162:165], v[194:197], v[60:63]
	v_mfma_f32_16x16x32_bf16 v[104:107], v[170:173], v[194:197], v[104:107]
	v_mfma_f32_16x16x32_bf16 v[48:51], v[162:165], v[214:217], v[48:51]
	v_mfma_f32_16x16x32_bf16 v[100:103], v[170:173], v[214:217], v[100:103]
	v_mfma_f32_16x16x32_bf16 v[80:83], v[166:169], v[182:185], v[80:83]
	v_mfma_f32_16x16x32_bf16 v[128:131], v[174:177], v[182:185], v[128:131]
	v_mfma_f32_16x16x32_bf16 v[68:71], v[166:169], v[190:193], v[68:71]
	v_mfma_f32_16x16x32_bf16 v[108:111], v[174:177], v[190:193], v[108:111]
	v_mfma_f32_16x16x32_bf16 v[60:63], v[166:169], v[198:201], v[60:63]
	v_mfma_f32_16x16x32_bf16 v[104:107], v[174:177], v[198:201], v[104:107]
	v_mfma_f32_16x16x32_bf16 v[48:51], v[166:169], v[218:221], v[48:51]
	v_mfma_f32_16x16x32_bf16 v[100:103], v[174:177], v[218:221], v[100:103]

; #define PG8_STAGE(bufoff, gbase, voff) do { _Pragma("unroll") for (int _i = 0; _i < 2; ++_i) \
;         __builtin_amdgcn_global_load_lds((const unsigned*)((const char*)(gbase) + (voff)[_i]), (LAS unsigned*)(lds + (bufoff) + ldsw + _i * 8192), 16, 0, 0); } while (0)
; #define PG8_LDA(dst, b, h) do { _Pragma("unroll") for (int m = 0; m < 4; ++m) _Pragma("unroll") for (int k = 0; k < 2; ++k) dst[m][k] = *(const LAS bf16x8*)(lds + PG8_SA(b, h) + aoff + m * 2048 + k * 1024); } while (0)
; #define PG8_MMA(ai, bj, At, Bt) do { __builtin_amdgcn_s_setprio(1); _Pragma("unroll") for (int m = 0; m < 4; ++m) _Pragma("unroll") for (int n = 0; n < 2; ++n) _Pragma("unroll") for (int k = 0; k < 2; ++k) \
;         acc[ai][bj][m][n] = __builtin_amdgcn_mfma_f32_16x16x32_bf16(Bt[n][k], At[m][k], acc[ai][bj][m][n], 0, 0, 0); __builtin_amdgcn_s_setprio(0); } while (0)
; #define PG8_WAIT_V(n) asm volatile("s_waitcnt vmcnt(" #n ")" ::: "memory")
; #define PG8_WAIT_L(n) asm volatile("s_waitcnt lgkmcnt(" #n ")" ::: "memory")
; #define PG8_BAR __builtin_amdgcn_s_barrier()
; #define PG8_SCHED __builtin_amdgcn_sched_barrier(0)
; template <class Epi, bool ALIGN_EPI>
; __device__ __forceinline__ void gemm_phase(LAS unsigned char* lds, const Gemm g, const StaticOrder& S, const Epi& E, const int tid) {
;     ...
;             PG8_WAIT_V(8); PG8_WAIT_L(0); PG8_BAR; PG8_MMA(0, 0, At, B0); PG8_MMA(0, 1, At, B1); PG8_BAR; PG8_SCHED;
;             PG8_LDA(At, 0, 1); PG8_STAGE(PG8_SB(0, 0), b2, voffB); PG8_STAGE(PG8_SB(0, 1), b2 + hstepB, voffB); PG8_STAGE(PG8_SA(0, 0), a2, voffA);
;             PG8_WAIT_V(8); PG8_WAIT_L(0); PG8_BAR; PG8_MMA(1, 0, At, B0); PG8_MMA(1, 1, At, B1); PG8_BAR; PG8_SCHED;
	s_barrier
	s_add_i32 s90, s90, s71
	s_mov_b32 m0, s90
	ds_read_b128 v[178:181], v161 offset:16384
	ds_read_b128 v[182:185], v161 offset:17408
	ds_read_b128 v[186:189], v161 offset:18432
	ds_read_b128 v[190:193], v161 offset:19456
	ds_read_b128 v[194:197], v161 offset:20480
	ds_read_b128 v[198:201], v161 offset:21504
	ds_read_b128 v[214:217], v161 offset:22528
	ds_read_b128 v[218:221], v161 offset:23552
	global_load_lds_dwordx4 v144, s[52:53]
	s_add_i32 m0, s90, 0x2000
	s_add_u32 s90, s52, 0x4000
	s_addc_u32 s91, s53, 0
	s_add_i32 s92, s92, s71
	global_load_lds_dwordx4 v140, s[52:53]
	s_mov_b32 m0, s92
	s_nop 0
	global_load_lds_dwordx4 v144, s[90:91]
	s_add_i32 m0, s92, 0x2000
	s_nop 0
	global_load_lds_dwordx4 v140, s[90:91]
	s_mov_b32 m0, s72
	s_nop 0
	global_load_lds_dwordx4 v146, s[54:55]
	s_mov_b32 m0, s73
	s_nop 0
	global_load_lds_dwordx4 v142, s[54:55]
	s_waitcnt vmcnt(8)
	s_waitcnt lgkmcnt(0)
	s_barrier


; #define PG8_MMA(ai, bj, At, Bt) do { __builtin_amdgcn_s_setprio(1); _Pragma("unroll") for (int m = 0; m < 4; ++m) _Pragma("unroll") for (int n = 0; n < 2; ++n) _Pragma("unroll") for (int k = 0; k < 2; ++k) \
;         acc[ai][bj][m][n] = __builtin_amdgcn_mfma_f32_16x16x32_bf16(Bt[n][k], At[m][k], acc[ai][bj][m][n], 0, 0, 0); __builtin_amdgcn_s_setprio(0); } while (0)
; #define PG8_WAIT_V(n) asm volatile("s_waitcnt vmcnt(" #n ")" ::: "memory")
; #define PG8_WAIT_L(n) asm volatile("s_waitcnt lgkmcnt(" #n ")" ::: "memory")
; #define PG8_BAR __builtin_amdgcn_s_barrier()
; #define PG8_SCHED __builtin_amdgcn_sched_barrier(0)
; template <class Epi, bool ALIGN_EPI>
; __device__ __forceinline__ void gemm_phase(LAS unsigned char* lds, const Gemm g, const StaticOrder& S, const Epi& E, const int tid) {
;     ...
;             PG8_WAIT_V(8); PG8_WAIT_L(0); PG8_BAR; PG8_MMA(1, 0, At, B0); PG8_MMA(1, 1, At, B1); PG8_BAR; PG8_SCHED;
	v_mfma_f32_16x16x32_bf16 v[24:27], v[132:135], v[178:181], v[24:27]
	v_mfma_f32_16x16x32_bf16 v[92:95], v[152:155], v[178:181], v[92:95]
	v_mfma_f32_16x16x32_bf16 v[16:19], v[132:135], v[186:189], v[16:19]
	v_mfma_f32_16x16x32_bf16 v[84:87], v[152:155], v[186:189], v[84:87]
	v_mfma_f32_16x16x32_bf16 v[8:11], v[132:135], v[194:197], v[8:11]
	v_mfma_f32_16x16x32_bf16 v[76:79], v[152:155], v[194:197], v[76:79]
	v_mfma_f32_16x16x32_bf16 v[2:5], v[132:135], v[214:217], v[4:7]
	v_mfma_f32_16x16x32_bf16 v[64:67], v[152:155], v[214:217], v[64:67]
	v_mfma_f32_16x16x32_bf16 v[24:27], v[136:139], v[182:185], v[24:27]
	v_mfma_f32_16x16x32_bf16 v[92:95], v[156:159], v[182:185], v[92:95]
	v_mfma_f32_16x16x32_bf16 v[16:19], v[136:139], v[190:193], v[16:19]
	v_mfma_f32_16x16x32_bf16 v[84:87], v[156:159], v[190:193], v[84:87]
	v_mfma_f32_16x16x32_bf16 v[8:11], v[136:139], v[198:201], v[8:11]
	v_mfma_f32_16x16x32_bf16 v[76:79], v[156:159], v[198:201], v[76:79]
	v_mfma_f32_16x16x32_bf16 v[2:5], v[136:139], v[218:221], v[2:5]
	v_mfma_f32_16x16x32_bf16 v[64:67], v[156:159], v[218:221], v[64:67]


; #define PG8_MMA(ai, bj, At, Bt) do { __builtin_amdgcn_s_setprio(1); _Pragma("unroll") for (int m = 0; m < 4; ++m) _Pragma("unroll") for (int n = 0; n < 2; ++n) _Pragma("unroll") for (int k = 0; k < 2; ++k) \
;         acc[ai][bj][m][n] = __builtin_amdgcn_mfma_f32_16x16x32_bf16(Bt[n][k], At[m][k], acc[ai][bj][m][n], 0, 0, 0); __builtin_amdgcn_s_setprio(0); } while (0)
; #define PG8_WAIT_V(n) asm volatile("s_waitcnt vmcnt(" #n ")" ::: "memory")
; #define PG8_WAIT_L(n) asm volatile("s_waitcnt lgkmcnt(" #n ")" ::: "memory")
; #define PG8_BAR __builtin_amdgcn_s_barrier()
; #define PG8_SCHED __builtin_amdgcn_sched_barrier(0)
; template <class Epi, bool ALIGN_EPI>
; __device__ __forceinline__ void gemm_phase(LAS unsigned char* lds, const Gemm g, const StaticOrder& S, const Epi& E, const int tid) {
;     ...
;             PG8_WAIT_V(8); PG8_WAIT_L(0); PG8_BAR; PG8_MMA(1, 0, At, B0); PG8_MMA(1, 1, At, B1); PG8_BAR; PG8_SCHED;
	v_mfma_f32_16x16x32_bf16 v[32:35], v[162:165], v[178:181], v[32:35]
	v_mfma_f32_16x16x32_bf16 v[72:75], v[170:173], v[178:181], v[72:75]
	v_mfma_f32_16x16x32_bf16 v[28:31], v[162:165], v[186:189], v[28:31]
	v_mfma_f32_16x16x32_bf16 v[96:99], v[170:173], v[186:189], v[96:99]
	v_mfma_f32_16x16x32_bf16 v[20:23], v[162:165], v[194:197], v[20:23]
	v_mfma_f32_16x16x32_bf16 v[56:59], v[170:173], v[194:197], v[56:59]
	v_mfma_f32_16x16x32_bf16 v[12:15], v[162:165], v[214:217], v[12:15]
	v_mfma_f32_16x16x32_bf16 v[44:47], v[170:173], v[214:217], v[44:47]
	v_mfma_f32_16x16x32_bf16 v[32:35], v[166:169], v[182:185], v[32:35]
	v_mfma_f32_16x16x32_bf16 v[72:75], v[174:177], v[182:185], v[72:75]
	v_mfma_f32_16x16x32_bf16 v[28:31], v[166:169], v[190:193], v[28:31]
	v_mfma_f32_16x16x32_bf16 v[96:99], v[174:177], v[190:193], v[96:99]
	v_mfma_f32_16x16x32_bf16 v[20:23], v[166:169], v[198:201], v[20:23]
	v_mfma_f32_16x16x32_bf16 v[56:59], v[174:177], v[198:201], v[56:59]
	v_mfma_f32_16x16x32_bf16 v[12:15], v[166:169], v[218:221], v[12:15]
	v_mfma_f32_16x16x32_bf16 v[44:47], v[174:177], v[218:221], v[44:47]

; #define PG8_STAGE(bufoff, gbase, voff) do { _Pragma("unroll") for (int _i = 0; _i < 2; ++_i) \
;         __builtin_amdgcn_global_load_lds((const unsigned*)((const char*)(gbase) + (voff)[_i]), (LAS unsigned*)(lds + (bufoff) + ldsw + _i * 8192), 16, 0, 0); } while (0)
; #define PG8_LDA(dst, b, h) do { _Pragma("unroll") for (int m = 0; m < 4; ++m) _Pragma("unroll") for (int k = 0; k < 2; ++k) dst[m][k] = *(const LAS bf16x8*)(lds + PG8_SA(b, h) + aoff + m * 2048 + k * 1024); } while (0)
; #define PG8_LDB(dst, b, h) do { _Pragma("unroll") for (int n = 0; n < 2; ++n) _Pragma("unroll") for (int k = 0; k < 2; ++k) dst[n][k] = *(const LAS bf16x8*)(lds + PG8_SB(b, h) + boff + n * 2048 + k * 1024); } while (0)
; #define PG8_MMA(ai, bj, At, Bt) do { __builtin_amdgcn_s_setprio(1); _Pragma("unroll") for (int m = 0; m < 4; ++m) _Pragma("unroll") for (int n = 0; n < 2; ++n) _Pragma("unroll") for (int k = 0; k < 2; ++k) \
;         acc[ai][bj][m][n] = __builtin_amdgcn_mfma_f32_16x16x32_bf16(Bt[n][k], At[m][k], acc[ai][bj][m][n], 0, 0, 0); __builtin_amdgcn_s_setprio(0); } while (0)
; #define PG8_WAIT_V(n) asm volatile("s_waitcnt vmcnt(" #n ")" ::: "memory")
; #define PG8_WAIT_L(n) asm volatile("s_waitcnt lgkmcnt(" #n ")" ::: "memory")
; #define PG8_BAR __builtin_amdgcn_s_barrier()
; #define PG8_SCHED __builtin_amdgcn_sched_barrier(0)
; template <class Epi, bool ALIGN_EPI>
; __device__ __forceinline__ void gemm_phase(LAS unsigned char* lds, const Gemm g, const StaticOrder& S, const Epi& E, const int tid) {
;     ...
;             PG8_WAIT_V(8); PG8_WAIT_L(0); PG8_BAR; PG8_MMA(1, 0, At, B0); PG8_MMA(1, 1, At, B1); PG8_BAR; PG8_SCHED;
;             PG8_LDB(B0, 1, 0); PG8_LDB(B1, 1, 1); PG8_SCHED; PG8_LDA(At, 1, 0); PG8_STAGE(PG8_SA(0, 1), a2 + hstepA, voffA);
;             PG8_WAIT_V(8); PG8_WAIT_L(0); PG8_BAR; PG8_MMA(0, 0, At, B0); PG8_MMA(0, 1, At, B1); PG8_BAR; PG8_SCHED;
	s_barrier
	s_add_i32 s90, 0, 0x18000
	v_add_u32_e32 v0, s90, v160
	s_add_i32 s91, 0, 0x1c000
	ds_read_b128 v[132:135], v0
	ds_read_b128 v[136:139], v0 offset:1024
	ds_read_b128 v[152:155], v0 offset:2048
	ds_read_b128 v[156:159], v0 offset:3072
	v_add_u32_e32 v0, s91, v160
	ds_read_b128 v[162:165], v0
	ds_read_b128 v[166:169], v0 offset:1024
	ds_read_b128 v[170:173], v0 offset:2048
	ds_read_b128 v[174:177], v0 offset:3072
	s_add_u32 s54, s54, 0x4000
	s_addc_u32 s55, s55, 0
	s_mov_b32 m0, s74
	ds_read_b128 v[178:181], v161 offset:32768
	ds_read_b128 v[182:185], v161 offset:33792
	ds_read_b128 v[186:189], v161 offset:34816
	ds_read_b128 v[190:193], v161 offset:35840
	ds_read_b128 v[194:197], v161 offset:36864
	ds_read_b128 v[198:201], v161 offset:37888
	ds_read_b128 v[214:217], v161 offset:38912
	ds_read_b128 v[218:221], v161 offset:39936
	global_load_lds_dwordx4 v146, s[54:55]
	s_mov_b32 m0, s75
	s_nop 0
	global_load_lds_dwordx4 v142, s[54:55]
	s_waitcnt vmcnt(8)
	s_waitcnt lgkmcnt(0)
	s_barrier


; #define PG8_MMA(ai, bj, At, Bt) do { __builtin_amdgcn_s_setprio(1); _Pragma("unroll") for (int m = 0; m < 4; ++m) _Pragma("unroll") for (int n = 0; n < 2; ++n) _Pragma("unroll") for (int k = 0; k < 2; ++k) \
;         acc[ai][bj][m][n] = __builtin_amdgcn_mfma_f32_16x16x32_bf16(Bt[n][k], At[m][k], acc[ai][bj][m][n], 0, 0, 0); __builtin_amdgcn_s_setprio(0); } while (0)
; #define PG8_WAIT_V(n) asm volatile("s_waitcnt vmcnt(" #n ")" ::: "memory")
; #define PG8_WAIT_L(n) asm volatile("s_waitcnt lgkmcnt(" #n ")" ::: "memory")
; #define PG8_BAR __builtin_amdgcn_s_barrier()
; #define PG8_SCHED __builtin_amdgcn_sched_barrier(0)
; template <class Epi, bool ALIGN_EPI>
; __device__ __forceinline__ void gemm_phase(LAS unsigned char* lds, const Gemm g, const StaticOrder& S, const Epi& E, const int tid) {
;     ...
;             PG8_WAIT_V(8); PG8_WAIT_L(0); PG8_BAR; PG8_MMA(0, 0, At, B0); PG8_MMA(0, 1, At, B1); PG8_BAR; PG8_SCHED;
	v_mfma_f32_16x16x32_bf16 v[88:91], v[132:135], v[178:181], v[88:91]
	v_mfma_f32_16x16x32_bf16 v[124:127], v[152:155], v[178:181], v[124:127]
	v_mfma_f32_16x16x32_bf16 v[52:55], v[132:135], v[186:189], v[52:55]
	v_mfma_f32_16x16x32_bf16 v[120:123], v[152:155], v[186:189], v[120:123]
	v_mfma_f32_16x16x32_bf16 v[40:43], v[132:135], v[194:197], v[40:43]
	v_mfma_f32_16x16x32_bf16 v[116:119], v[152:155], v[194:197], v[116:119]
	v_mfma_f32_16x16x32_bf16 v[36:39], v[132:135], v[214:217], v[36:39]
	v_mfma_f32_16x16x32_bf16 v[112:115], v[152:155], v[214:217], v[112:115]
	v_mfma_f32_16x16x32_bf16 v[88:91], v[136:139], v[182:185], v[88:91]
	v_mfma_f32_16x16x32_bf16 v[124:127], v[156:159], v[182:185], v[124:127]
	v_mfma_f32_16x16x32_bf16 v[52:55], v[136:139], v[190:193], v[52:55]
	v_mfma_f32_16x16x32_bf16 v[120:123], v[156:159], v[190:193], v[120:123]
	v_mfma_f32_16x16x32_bf16 v[40:43], v[136:139], v[198:201], v[40:43]
	v_mfma_f32_16x16x32_bf16 v[116:119], v[156:159], v[198:201], v[116:119]
	v_mfma_f32_16x16x32_bf16 v[36:39], v[136:139], v[218:221], v[36:39]
	v_mfma_f32_16x16x32_bf16 v[112:115], v[156:159], v[218:221], v[112:115]


; #define PG8_MMA(ai, bj, At, Bt) do { __builtin_amdgcn_s_setprio(1); _Pragma("unroll") for (int m = 0; m < 4; ++m) _Pragma("unroll") for (int n = 0; n < 2; ++n) _Pragma("unroll") for (int k = 0; k < 2; ++k) \
;         acc[ai][bj][m][n] = __builtin_amdgcn_mfma_f32_16x16x32_bf16(Bt[n][k], At[m][k], acc[ai][bj][m][n], 0, 0, 0); __builtin_amdgcn_s_setprio(0); } while (0)
; #define PG8_WAIT_V(n) asm volatile("s_waitcnt vmcnt(" #n ")" ::: "memory")
; #define PG8_WAIT_L(n) asm volatile("s_waitcnt lgkmcnt(" #n ")" ::: "memory")
; #define PG8_BAR __builtin_amdgcn_s_barrier()
; #define PG8_SCHED __builtin_amdgcn_sched_barrier(0)
; template <class Epi, bool ALIGN_EPI>
; __device__ __forceinline__ void gemm_phase(LAS unsigned char* lds, const Gemm g, const StaticOrder& S, const Epi& E, const int tid) {
;     ...
;             PG8_WAIT_V(8); PG8_WAIT_L(0); PG8_BAR; PG8_MMA(0, 0, At, B0); PG8_MMA(0, 1, At, B1); PG8_BAR; PG8_SCHED;
	v_mfma_f32_16x16x32_bf16 v[80:83], v[162:165], v[178:181], v[80:83]
	v_mfma_f32_16x16x32_bf16 v[128:131], v[170:173], v[178:181], v[128:131]
	v_mfma_f32_16x16x32_bf16 v[68:71], v[162:165], v[186:189], v[68:71]
	v_mfma_f32_16x16x32_bf16 v[108:111], v[170:173], v[186:189], v[108:111]
	v_mfma_f32_16x16x32_bf16 v[60:63], v[162:165], v[194:197], v[60:63]
	v_mfma_f32_16x16x32_bf16 v[104:107], v[170:173], v[194:197], v[104:107]
	v_mfma_f32_16x16x32_bf16 v[48:51], v[162:165], v[214:217], v[48:51]
	v_mfma_f32_16x16x32_bf16 v[100:103], v[170:173], v[214:217], v[100:103]
	v_mfma_f32_16x16x32_bf16 v[80:83], v[166:169], v[182:185], v[80:83]
	v_mfma_f32_16x16x32_bf16 v[128:131], v[174:177], v[182:185], v[128:131]
	v_mfma_f32_16x16x32_bf16 v[68:71], v[166:169], v[190:193], v[68:71]
	v_mfma_f32_16x16x32_bf16 v[108:111], v[174:177], v[190:193], v[108:111]
	v_mfma_f32_16x16x32_bf16 v[60:63], v[166:169], v[198:201], v[60:63]
	v_mfma_f32_16x16x32_bf16 v[104:107], v[174:177], v[198:201], v[104:107]
	v_mfma_f32_16x16x32_bf16 v[48:51], v[166:169], v[218:221], v[48:51]
	v_mfma_f32_16x16x32_bf16 v[100:103], v[174:177], v[218:221], v[100:103]

; #define PG8_STAGE(bufoff, gbase, voff) do { _Pragma("unroll") for (int _i = 0; _i < 2; ++_i) \
;         __builtin_amdgcn_global_load_lds((const unsigned*)((const char*)(gbase) + (voff)[_i]), (LAS unsigned*)(lds + (bufoff) + ldsw + _i * 8192), 16, 0, 0); } while (0)
; #define PG8_LDA(dst, b, h) do { _Pragma("unroll") for (int m = 0; m < 4; ++m) _Pragma("unroll") for (int k = 0; k < 2; ++k) dst[m][k] = *(const LAS bf16x8*)(lds + PG8_SA(b, h) + aoff + m * 2048 + k * 1024); } while (0)
; #define PG8_MMA(ai, bj, At, Bt) do { __builtin_amdgcn_s_setprio(1); _Pragma("unroll") for (int m = 0; m < 4; ++m) _Pragma("unroll") for (int n = 0; n < 2; ++n) _Pragma("unroll") for (int k = 0; k < 2; ++k) \
;         acc[ai][bj][m][n] = __builtin_amdgcn_mfma_f32_16x16x32_bf16(Bt[n][k], At[m][k], acc[ai][bj][m][n], 0, 0, 0); __builtin_amdgcn_s_setprio(0); } while (0)
; #define PG8_WAIT_V(n) asm volatile("s_waitcnt vmcnt(" #n ")" ::: "memory")
; #define PG8_WAIT_L(n) asm volatile("s_waitcnt lgkmcnt(" #n ")" ::: "memory")
; #define PG8_BAR __builtin_amdgcn_s_barrier()
; #define PG8_SCHED __builtin_amdgcn_sched_barrier(0)
; template <class Epi, bool ALIGN_EPI>
; __device__ __forceinline__ void gemm_phase(LAS unsigned char* lds, const Gemm g, const StaticOrder& S, const Epi& E, const int tid) {
;     ...
;             PG8_LDA(At, 1, 1); PG8_STAGE(PG8_SB(1, 0), b3, voffB); PG8_STAGE(PG8_SB(1, 1), b3 + hstepB, voffB); PG8_STAGE(PG8_SA(1, 0), a3, voffA);
;             PG8_WAIT_V(8); PG8_WAIT_L(0); PG8_BAR; PG8_MMA(1, 0, At, B0); PG8_MMA(1, 1, At, B1); PG8_BAR; PG8_SCHED;
	s_barrier
	s_add_u32 s54, s52, 0x8000
	s_addc_u32 s55, s53, 0
	s_add_i32 s90, s90, s71
	s_mov_b32 m0, s90
	ds_read_b128 v[178:181], v161 offset:49152
	ds_read_b128 v[182:185], v161 offset:50176
	ds_read_b128 v[186:189], v161 offset:51200
	ds_read_b128 v[190:193], v161 offset:52224
	ds_read_b128 v[194:197], v161 offset:53248
	ds_read_b128 v[198:201], v161 offset:54272
	ds_read_b128 v[214:217], v161 offset:55296
	ds_read_b128 v[218:221], v161 offset:56320
	global_load_lds_dwordx4 v144, s[54:55]
	s_add_i32 m0, s90, 0x2000
	s_add_u32 s52, s52, 0xc000
	s_addc_u32 s53, s53, 0
	global_load_lds_dwordx4 v140, s[54:55]
	s_add_i32 s54, s91, s71
	s_mov_b32 m0, s54
	s_nop 0
	global_load_lds_dwordx4 v144, s[52:53]
	s_add_i32 m0, s54, 0x2000
	s_nop 0
	global_load_lds_dwordx4 v140, s[52:53]
	s_mov_b32 m0, s79
	s_nop 0
	global_load_lds_dwordx4 v146, s[50:51]
	s_mov_b32 m0, s80
	s_nop 0
	global_load_lds_dwordx4 v142, s[50:51]
	s_waitcnt vmcnt(8)
	s_waitcnt lgkmcnt(0)
	s_barrier


; #define PG8_MMA(ai, bj, At, Bt) do { __builtin_amdgcn_s_setprio(1); _Pragma("unroll") for (int m = 0; m < 4; ++m) _Pragma("unroll") for (int n = 0; n < 2; ++n) _Pragma("unroll") for (int k = 0; k < 2; ++k) \
;         acc[ai][bj][m][n] = __builtin_amdgcn_mfma_f32_16x16x32_bf16(Bt[n][k], At[m][k], acc[ai][bj][m][n], 0, 0, 0); __builtin_amdgcn_s_setprio(0); } while (0)
; #define PG8_WAIT_V(n) asm volatile("s_waitcnt vmcnt(" #n ")" ::: "memory")
; #define PG8_WAIT_L(n) asm volatile("s_waitcnt lgkmcnt(" #n ")" ::: "memory")
; #define PG8_BAR __builtin_amdgcn_s_barrier()
; #define PG8_SCHED __builtin_amdgcn_sched_barrier(0)
; template <class Epi, bool ALIGN_EPI>
; __device__ __forceinline__ void gemm_phase(LAS unsigned char* lds, const Gemm g, const StaticOrder& S, const Epi& E, const int tid) {
;     ...
;             PG8_WAIT_V(8); PG8_WAIT_L(0); PG8_BAR; PG8_MMA(1, 0, At, B0); PG8_MMA(1, 1, At, B1); PG8_BAR; PG8_SCHED;
	v_mfma_f32_16x16x32_bf16 v[24:27], v[132:135], v[178:181], v[24:27]
	v_mfma_f32_16x16x32_bf16 v[92:95], v[152:155], v[178:181], v[92:95]
	v_mfma_f32_16x16x32_bf16 v[16:19], v[132:135], v[186:189], v[16:19]
	v_mfma_f32_16x16x32_bf16 v[84:87], v[152:155], v[186:189], v[84:87]
	v_mfma_f32_16x16x32_bf16 v[6:9], v[132:135], v[194:197], v[8:11]
	v_mfma_f32_16x16x32_bf16 v[76:79], v[152:155], v[194:197], v[76:79]
	v_mfma_f32_16x16x32_bf16 v[2:5], v[132:135], v[214:217], v[2:5]
	v_mfma_f32_16x16x32_bf16 v[64:67], v[152:155], v[214:217], v[64:67]
	v_mfma_f32_16x16x32_bf16 v[24:27], v[136:139], v[182:185], v[24:27]
	v_mfma_f32_16x16x32_bf16 v[92:95], v[156:159], v[182:185], v[92:95]
	v_mfma_f32_16x16x32_bf16 v[16:19], v[136:139], v[190:193], v[16:19]
	v_mfma_f32_16x16x32_bf16 v[84:87], v[156:159], v[190:193], v[84:87]
	v_mfma_f32_16x16x32_bf16 v[8:11], v[136:139], v[198:201], v[6:9]
	v_mfma_f32_16x16x32_bf16 v[76:79], v[156:159], v[198:201], v[76:79]
	v_mfma_f32_16x16x32_bf16 v[4:7], v[136:139], v[218:221], v[2:5]
	v_mfma_f32_16x16x32_bf16 v[64:67], v[156:159], v[218:221], v[64:67]


; #define PG8_MMA(ai, bj, At, Bt) do { __builtin_amdgcn_s_setprio(1); _Pragma("unroll") for (int m = 0; m < 4; ++m) _Pragma("unroll") for (int n = 0; n < 2; ++n) _Pragma("unroll") for (int k = 0; k < 2; ++k) \
;         acc[ai][bj][m][n] = __builtin_amdgcn_mfma_f32_16x16x32_bf16(Bt[n][k], At[m][k], acc[ai][bj][m][n], 0, 0, 0); __builtin_amdgcn_s_setprio(0); } while (0)
; #define PG8_WAIT_V(n) asm volatile("s_waitcnt vmcnt(" #n ")" ::: "memory")
; #define PG8_WAIT_L(n) asm volatile("s_waitcnt lgkmcnt(" #n ")" ::: "memory")
; #define PG8_BAR __builtin_amdgcn_s_barrier()
; #define PG8_SCHED __builtin_amdgcn_sched_barrier(0)
; template <class Epi, bool ALIGN_EPI>
; __device__ __forceinline__ void gemm_phase(LAS unsigned char* lds, const Gemm g, const StaticOrder& S, const Epi& E, const int tid) {
;     ...
;             PG8_WAIT_V(8); PG8_WAIT_L(0); PG8_BAR; PG8_MMA(1, 0, At, B0); PG8_MMA(1, 1, At, B1); PG8_BAR; PG8_SCHED;
	v_mfma_f32_16x16x32_bf16 v[32:35], v[162:165], v[178:181], v[32:35]
	v_mfma_f32_16x16x32_bf16 v[72:75], v[170:173], v[178:181], v[72:75]
	v_mfma_f32_16x16x32_bf16 v[28:31], v[162:165], v[186:189], v[28:31]
	v_mfma_f32_16x16x32_bf16 v[96:99], v[170:173], v[186:189], v[96:99]
	v_mfma_f32_16x16x32_bf16 v[20:23], v[162:165], v[194:197], v[20:23]
	v_mfma_f32_16x16x32_bf16 v[56:59], v[170:173], v[194:197], v[56:59]
	v_mfma_f32_16x16x32_bf16 v[12:15], v[162:165], v[214:217], v[12:15]
	v_mfma_f32_16x16x32_bf16 v[44:47], v[170:173], v[214:217], v[44:47]
	v_mfma_f32_16x16x32_bf16 v[32:35], v[166:169], v[182:185], v[32:35]
	v_mfma_f32_16x16x32_bf16 v[72:75], v[174:177], v[182:185], v[72:75]
	v_mfma_f32_16x16x32_bf16 v[28:31], v[166:169], v[190:193], v[28:31]
	v_mfma_f32_16x16x32_bf16 v[96:99], v[174:177], v[190:193], v[96:99]
	v_mfma_f32_16x16x32_bf16 v[20:23], v[166:169], v[198:201], v[20:23]
	v_mfma_f32_16x16x32_bf16 v[56:59], v[174:177], v[198:201], v[56:59]
	v_mfma_f32_16x16x32_bf16 v[12:15], v[166:169], v[218:221], v[12:15]
	v_mfma_f32_16x16x32_bf16 v[44:47], v[174:177], v[218:221], v[44:47]

; #define PG8_MMA(ai, bj, At, Bt) do { __builtin_amdgcn_s_setprio(1); _Pragma("unroll") for (int m = 0; m < 4; ++m) _Pragma("unroll") for (int n = 0; n < 2; ++n) _Pragma("unroll") for (int k = 0; k < 2; ++k) \
;         acc[ai][bj][m][n] = __builtin_amdgcn_mfma_f32_16x16x32_bf16(Bt[n][k], At[m][k], acc[ai][bj][m][n], 0, 0, 0); __builtin_amdgcn_s_setprio(0); } while (0)
; #define PG8_WAIT_V(n) asm volatile("s_waitcnt vmcnt(" #n ")" ::: "memory")
; #define PG8_WAIT_L(n) asm volatile("s_waitcnt lgkmcnt(" #n ")" ::: "memory")
; #define PG8_BAR __builtin_amdgcn_s_barrier()
; #define PG8_SCHED __builtin_amdgcn_sched_barrier(0)
; template <class Epi, bool ALIGN_EPI>
; __device__ __forceinline__ void gemm_phase(LAS unsigned char* lds, const Gemm g, const StaticOrder& S, const Epi& E, const int tid) {
;     ...
;             PG8_WAIT_V(8); PG8_WAIT_L(0); PG8_BAR; PG8_MMA(1, 0, At, B0); PG8_MMA(1, 1, At, B1); PG8_BAR; PG8_SCHED;
;         }
;         if constexpr (ALIGN_EPI) { if (wr == 0) PG8_BAR; }
	s_barrier
	s_add_i32 s89, s89, 2
	s_add_u32 s48, s48, 0x10000
	s_addc_u32 s49, s49, 0
	s_add_u32 vcc_hi, vcc_hi, 0x10000
	s_addc_u32 s88, s88, 0
	s_cmp_gt_u32 s89, 29
	s_cbranch_scc0 .LBB0_211
	s_and_b64 vcc, exec, s[22:23]
	s_cbranch_vccz .LBB0_214
	s_barrier

; #define PG8_STAGE(bufoff, gbase, voff) do { _Pragma("unroll") for (int _i = 0; _i < 2; ++_i) \
;         __builtin_amdgcn_global_load_lds((const unsigned*)((const char*)(gbase) + (voff)[_i]), (LAS unsigned*)(lds + (bufoff) + ldsw + _i * 8192), 16, 0, 0); } while (0)
; #define PG8_LDA(dst, b, h) do { _Pragma("unroll") for (int m = 0; m < 4; ++m) _Pragma("unroll") for (int k = 0; k < 2; ++k) dst[m][k] = *(const LAS bf16x8*)(lds + PG8_SA(b, h) + aoff + m * 2048 + k * 1024); } while (0)
; #define PG8_LDB(dst, b, h) do { _Pragma("unroll") for (int n = 0; n < 2; ++n) _Pragma("unroll") for (int k = 0; k < 2; ++k) dst[n][k] = *(const LAS bf16x8*)(lds + PG8_SB(b, h) + boff + n * 2048 + k * 1024); } while (0)
; #define PG8_MMA(ai, bj, At, Bt) do { __builtin_amdgcn_s_setprio(1); _Pragma("unroll") for (int m = 0; m < 4; ++m) _Pragma("unroll") for (int n = 0; n < 2; ++n) _Pragma("unroll") for (int k = 0; k < 2; ++k) \
;         acc[ai][bj][m][n] = __builtin_amdgcn_mfma_f32_16x16x32_bf16(Bt[n][k], At[m][k], acc[ai][bj][m][n], 0, 0, 0); __builtin_amdgcn_s_setprio(0); } while (0)
; #define PG8_WAIT_V(n) asm volatile("s_waitcnt vmcnt(" #n ")" ::: "memory")
; #define PG8_WAIT_L(n) asm volatile("s_waitcnt lgkmcnt(" #n ")" ::: "memory")
; #define PG8_BAR __builtin_amdgcn_s_barrier()
; #define PG8_SCHED __builtin_amdgcn_sched_barrier(0)
; template <class Epi, bool ALIGN_EPI>
; __device__ __forceinline__ void gemm_phase(LAS unsigned char* lds, const Gemm g, const StaticOrder& S, const Epi& E, const int tid) {
;     ...
;         for (int t = 0; t < nt; t += 2) {
;             const bool last = (t == nt - 2);
;             const char* a1 = cA + (size_t)(t + 1) * kstepA;
;             const char* a2 = last ? nA : cA + (size_t)(t + 2) * kstepA; const char* b2 = last ? nB : cB + (size_t)(t + 2) * kstepB;
;             const char* a3 = a2 + kstepA; const char* b3 = b2 + kstepB;
;             PG8_LDB(B0, 0, 0); PG8_LDB(B1, 0, 1); PG8_SCHED; PG8_LDA(At, 0, 0); PG8_STAGE(PG8_SA(1, 1), a1 + hstepA, voffA);
;             PG8_WAIT_V(8); PG8_WAIT_L(0); PG8_BAR; PG8_MMA(0, 0, At, B0); PG8_MMA(0, 1, At, B1); PG8_BAR; PG8_SCHED;
.LBB0_294:
	s_add_u32 s22, s10, 0x4000
	s_addc_u32 s23, s11, 0
	s_cmpk_eq_i32 s86, 0x54
	s_cselect_b32 s42, s48, s22
	s_cselect_b32 s43, s49, s23
	s_cselect_b32 s34, s50, s84
	s_cselect_b32 s35, s51, s85
	s_add_u32 s22, s42, 0x8000
	s_addc_u32 s23, s43, 0
	s_add_i32 s87, 0, 0x10000
	v_add_u32_e32 v0, s87, v154
	s_add_i32 s90, 0, 0x14000
	s_waitcnt lgkmcnt(0)
	ds_read_b128 v[132:135], v0
	ds_read_b128 v[148:151], v0 offset:1024
	ds_read_b128 v[156:159], v0 offset:2048
	ds_read_b128 v[160:163], v0 offset:3072
	v_add_u32_e32 v0, s90, v154
	ds_read_b128 v[164:167], v0
	ds_read_b128 v[168:171], v0 offset:1024
	ds_read_b128 v[172:175], v0 offset:2048
	ds_read_b128 v[176:179], v0 offset:3072
	s_add_i32 m0, s57, 0xc000
	ds_read_b128 v[180:183], v155
	ds_read_b128 v[184:187], v155 offset:1024
	ds_read_b128 v[188:191], v155 offset:2048
	ds_read_b128 v[192:195], v155 offset:3072
	ds_read_b128 v[196:199], v155 offset:4096
	ds_read_b128 v[214:217], v155 offset:5120
	ds_read_b128 v[218:221], v155 offset:6144
	ds_read_b128 v[222:225], v155 offset:7168
	global_load_lds_dwordx4 v144, s[10:11]
	s_add_i32 m0, s57, 0xe000
	s_nop 0
	global_load_lds_dwordx4 v146, s[10:11]
	s_waitcnt vmcnt(8)
	s_waitcnt lgkmcnt(0)
	s_barrier


; #define PG8_MMA(ai, bj, At, Bt) do { __builtin_amdgcn_s_setprio(1); _Pragma("unroll") for (int m = 0; m < 4; ++m) _Pragma("unroll") for (int n = 0; n < 2; ++n) _Pragma("unroll") for (int k = 0; k < 2; ++k) \
;         acc[ai][bj][m][n] = __builtin_amdgcn_mfma_f32_16x16x32_bf16(Bt[n][k], At[m][k], acc[ai][bj][m][n], 0, 0, 0); __builtin_amdgcn_s_setprio(0); } while (0)
; #define PG8_WAIT_V(n) asm volatile("s_waitcnt vmcnt(" #n ")" ::: "memory")
; #define PG8_WAIT_L(n) asm volatile("s_waitcnt lgkmcnt(" #n ")" ::: "memory")
; #define PG8_BAR __builtin_amdgcn_s_barrier()
; #define PG8_SCHED __builtin_amdgcn_sched_barrier(0)
; template <class Epi, bool ALIGN_EPI>
; __device__ __forceinline__ void gemm_phase(LAS unsigned char* lds, const Gemm g, const StaticOrder& S, const Epi& E, const int tid) {
;     ...
;             PG8_WAIT_V(8); PG8_WAIT_L(0); PG8_BAR; PG8_MMA(0, 0, At, B0); PG8_MMA(0, 1, At, B1); PG8_BAR; PG8_SCHED;
	v_mfma_f32_16x16x32_bf16 v[8:11], v[132:135], v[180:183], v[8:11]
	v_mfma_f32_16x16x32_bf16 v[56:59], v[156:159], v[180:183], v[56:59]
	v_mfma_f32_16x16x32_bf16 v[52:55], v[132:135], v[188:191], v[52:55]
	v_mfma_f32_16x16x32_bf16 v[48:51], v[156:159], v[188:191], v[48:51]
	v_mfma_f32_16x16x32_bf16 v[44:47], v[132:135], v[196:199], v[44:47]
	v_mfma_f32_16x16x32_bf16 v[40:43], v[156:159], v[196:199], v[40:43]
	v_mfma_f32_16x16x32_bf16 v[36:39], v[132:135], v[218:221], v[36:39]
	v_mfma_f32_16x16x32_bf16 v[32:35], v[156:159], v[218:221], v[32:35]
	v_mfma_f32_16x16x32_bf16 v[8:11], v[148:151], v[184:187], v[8:11]
	v_mfma_f32_16x16x32_bf16 v[56:59], v[160:163], v[184:187], v[56:59]
	v_mfma_f32_16x16x32_bf16 v[52:55], v[148:151], v[192:195], v[52:55]
	v_mfma_f32_16x16x32_bf16 v[48:51], v[160:163], v[192:195], v[48:51]
	v_mfma_f32_16x16x32_bf16 v[44:47], v[148:151], v[214:217], v[44:47]
	v_mfma_f32_16x16x32_bf16 v[40:43], v[160:163], v[214:217], v[40:43]
	v_mfma_f32_16x16x32_bf16 v[36:39], v[148:151], v[222:225], v[36:39]
	v_mfma_f32_16x16x32_bf16 v[32:35], v[160:163], v[222:225], v[32:35]


; #define PG8_MMA(ai, bj, At, Bt) do { __builtin_amdgcn_s_setprio(1); _Pragma("unroll") for (int m = 0; m < 4; ++m) _Pragma("unroll") for (int n = 0; n < 2; ++n) _Pragma("unroll") for (int k = 0; k < 2; ++k) \
;         acc[ai][bj][m][n] = __builtin_amdgcn_mfma_f32_16x16x32_bf16(Bt[n][k], At[m][k], acc[ai][bj][m][n], 0, 0, 0); __builtin_amdgcn_s_setprio(0); } while (0)
; #define PG8_WAIT_V(n) asm volatile("s_waitcnt vmcnt(" #n ")" ::: "memory")
; #define PG8_WAIT_L(n) asm volatile("s_waitcnt lgkmcnt(" #n ")" ::: "memory")
; #define PG8_BAR __builtin_amdgcn_s_barrier()
; #define PG8_SCHED __builtin_amdgcn_sched_barrier(0)
; template <class Epi, bool ALIGN_EPI>
; __device__ __forceinline__ void gemm_phase(LAS unsigned char* lds, const Gemm g, const StaticOrder& S, const Epi& E, const int tid) {
;     ...
;             PG8_WAIT_V(8); PG8_WAIT_L(0); PG8_BAR; PG8_MMA(0, 0, At, B0); PG8_MMA(0, 1, At, B1); PG8_BAR; PG8_SCHED;
	v_mfma_f32_16x16x32_bf16 v[2:5], v[164:167], v[180:183], v[4:7]
	v_mfma_f32_16x16x32_bf16 v[28:31], v[172:175], v[180:183], v[28:31]
	v_mfma_f32_16x16x32_bf16 v[96:99], v[164:167], v[188:191], v[96:99]
	v_mfma_f32_16x16x32_bf16 v[92:95], v[172:175], v[188:191], v[92:95]
	v_mfma_f32_16x16x32_bf16 v[88:91], v[164:167], v[196:199], v[88:91]
	v_mfma_f32_16x16x32_bf16 v[84:87], v[172:175], v[196:199], v[84:87]
	v_mfma_f32_16x16x32_bf16 v[80:83], v[164:167], v[218:221], v[80:83]
	v_mfma_f32_16x16x32_bf16 v[76:79], v[172:175], v[218:221], v[76:79]
	v_mfma_f32_16x16x32_bf16 v[2:5], v[168:171], v[184:187], v[2:5]
	v_mfma_f32_16x16x32_bf16 v[28:31], v[176:179], v[184:187], v[28:31]
	v_mfma_f32_16x16x32_bf16 v[96:99], v[168:171], v[192:195], v[96:99]
	v_mfma_f32_16x16x32_bf16 v[92:95], v[176:179], v[192:195], v[92:95]
	v_mfma_f32_16x16x32_bf16 v[88:91], v[168:171], v[214:217], v[88:91]
	v_mfma_f32_16x16x32_bf16 v[84:87], v[176:179], v[214:217], v[84:87]
	v_mfma_f32_16x16x32_bf16 v[80:83], v[168:171], v[222:225], v[80:83]
	v_mfma_f32_16x16x32_bf16 v[76:79], v[176:179], v[222:225], v[76:79]

; #define PG8_STAGE(bufoff, gbase, voff) do { _Pragma("unroll") for (int _i = 0; _i < 2; ++_i) \
;         __builtin_amdgcn_global_load_lds((const unsigned*)((const char*)(gbase) + (voff)[_i]), (LAS unsigned*)(lds + (bufoff) + ldsw + _i * 8192), 16, 0, 0); } while (0)
; #define PG8_LDA(dst, b, h) do { _Pragma("unroll") for (int m = 0; m < 4; ++m) _Pragma("unroll") for (int k = 0; k < 2; ++k) dst[m][k] = *(const LAS bf16x8*)(lds + PG8_SA(b, h) + aoff + m * 2048 + k * 1024); } while (0)
; #define PG8_MMA(ai, bj, At, Bt) do { __builtin_amdgcn_s_setprio(1); _Pragma("unroll") for (int m = 0; m < 4; ++m) _Pragma("unroll") for (int n = 0; n < 2; ++n) _Pragma("unroll") for (int k = 0; k < 2; ++k) \
;         acc[ai][bj][m][n] = __builtin_amdgcn_mfma_f32_16x16x32_bf16(Bt[n][k], At[m][k], acc[ai][bj][m][n], 0, 0, 0); __builtin_amdgcn_s_setprio(0); } while (0)
; #define PG8_WAIT_V(n) asm volatile("s_waitcnt vmcnt(" #n ")" ::: "memory")
; #define PG8_WAIT_L(n) asm volatile("s_waitcnt lgkmcnt(" #n ")" ::: "memory")
; #define PG8_BAR __builtin_amdgcn_s_barrier()
; #define PG8_SCHED __builtin_amdgcn_sched_barrier(0)
; template <class Epi, bool ALIGN_EPI>
; __device__ __forceinline__ void gemm_phase(LAS unsigned char* lds, const Gemm g, const StaticOrder& S, const Epi& E, const int tid) {
;     ...
;             PG8_WAIT_V(8); PG8_WAIT_L(0); PG8_BAR; PG8_MMA(0, 0, At, B0); PG8_MMA(0, 1, At, B1); PG8_BAR; PG8_SCHED;
;             PG8_LDA(At, 0, 1); PG8_STAGE(PG8_SB(0, 0), b2, voffB); PG8_STAGE(PG8_SB(0, 1), b2 + hstepB, voffB); PG8_STAGE(PG8_SA(0, 0), a2, voffA);
;             PG8_WAIT_V(8); PG8_WAIT_L(0); PG8_BAR; PG8_MMA(1, 0, At, B0); PG8_MMA(1, 1, At, B1); PG8_BAR; PG8_SCHED;
	s_barrier
	s_add_i32 s87, s87, s56
	s_mov_b32 m0, s87
	ds_read_b128 v[180:183], v155 offset:16384
	ds_read_b128 v[184:187], v155 offset:17408
	ds_read_b128 v[188:191], v155 offset:18432
	ds_read_b128 v[192:195], v155 offset:19456
	ds_read_b128 v[196:199], v155 offset:20480
	ds_read_b128 v[214:217], v155 offset:21504
	ds_read_b128 v[218:221], v155 offset:22528
	ds_read_b128 v[222:225], v155 offset:23552
	global_load_lds_dwordx4 v140, s[34:35]
	s_add_i32 m0, s87, 0x2000
	s_add_u32 s88, s34, 0x4000
	s_addc_u32 s89, s35, 0
	s_add_i32 s87, s90, s56
	global_load_lds_dwordx4 v136, s[34:35]
	s_mov_b32 m0, s87
	s_nop 0
	global_load_lds_dwordx4 v140, s[88:89]
	s_add_i32 m0, s87, 0x2000
	s_nop 0
	global_load_lds_dwordx4 v136, s[88:89]
	s_mov_b32 m0, s57
	s_nop 0
	global_load_lds_dwordx4 v142, s[42:43]
	s_mov_b32 m0, s60
	s_nop 0
	global_load_lds_dwordx4 v138, s[42:43]
	s_waitcnt vmcnt(8)
	s_waitcnt lgkmcnt(0)
	s_barrier


; #define PG8_MMA(ai, bj, At, Bt) do { __builtin_amdgcn_s_setprio(1); _Pragma("unroll") for (int m = 0; m < 4; ++m) _Pragma("unroll") for (int n = 0; n < 2; ++n) _Pragma("unroll") for (int k = 0; k < 2; ++k) \
;         acc[ai][bj][m][n] = __builtin_amdgcn_mfma_f32_16x16x32_bf16(Bt[n][k], At[m][k], acc[ai][bj][m][n], 0, 0, 0); __builtin_amdgcn_s_setprio(0); } while (0)
; #define PG8_WAIT_V(n) asm volatile("s_waitcnt vmcnt(" #n ")" ::: "memory")
; #define PG8_WAIT_L(n) asm volatile("s_waitcnt lgkmcnt(" #n ")" ::: "memory")
; #define PG8_BAR __builtin_amdgcn_s_barrier()
; #define PG8_SCHED __builtin_amdgcn_sched_barrier(0)
; template <class Epi, bool ALIGN_EPI>
; __device__ __forceinline__ void gemm_phase(LAS unsigned char* lds, const Gemm g, const StaticOrder& S, const Epi& E, const int tid) {
;     ...
;             PG8_WAIT_V(8); PG8_WAIT_L(0); PG8_BAR; PG8_MMA(1, 0, At, B0); PG8_MMA(1, 1, At, B1); PG8_BAR; PG8_SCHED;
	v_mfma_f32_16x16x32_bf16 v[24:27], v[132:135], v[180:183], v[24:27]
	v_mfma_f32_16x16x32_bf16 v[20:23], v[156:159], v[180:183], v[20:23]
	v_mfma_f32_16x16x32_bf16 v[64:67], v[132:135], v[188:191], v[64:67]
	v_mfma_f32_16x16x32_bf16 v[72:75], v[156:159], v[188:191], v[72:75]
	v_mfma_f32_16x16x32_bf16 v[16:19], v[132:135], v[196:199], v[16:19]
	v_mfma_f32_16x16x32_bf16 v[12:15], v[156:159], v[196:199], v[12:15]
	v_mfma_f32_16x16x32_bf16 v[60:63], v[132:135], v[218:221], v[60:63]
	v_mfma_f32_16x16x32_bf16 v[68:71], v[156:159], v[218:221], v[68:71]
	v_mfma_f32_16x16x32_bf16 v[24:27], v[148:151], v[184:187], v[24:27]
	v_mfma_f32_16x16x32_bf16 v[20:23], v[160:163], v[184:187], v[20:23]
	v_mfma_f32_16x16x32_bf16 v[64:67], v[148:151], v[192:195], v[64:67]
	v_mfma_f32_16x16x32_bf16 v[72:75], v[160:163], v[192:195], v[72:75]
	v_mfma_f32_16x16x32_bf16 v[16:19], v[148:151], v[214:217], v[16:19]
	v_mfma_f32_16x16x32_bf16 v[12:15], v[160:163], v[214:217], v[12:15]
	v_mfma_f32_16x16x32_bf16 v[60:63], v[148:151], v[222:225], v[60:63]
	v_mfma_f32_16x16x32_bf16 v[68:71], v[160:163], v[222:225], v[68:71]


; #define PG8_MMA(ai, bj, At, Bt) do { __builtin_amdgcn_s_setprio(1); _Pragma("unroll") for (int m = 0; m < 4; ++m) _Pragma("unroll") for (int n = 0; n < 2; ++n) _Pragma("unroll") for (int k = 0; k < 2; ++k) \
;         acc[ai][bj][m][n] = __builtin_amdgcn_mfma_f32_16x16x32_bf16(Bt[n][k], At[m][k], acc[ai][bj][m][n], 0, 0, 0); __builtin_amdgcn_s_setprio(0); } while (0)
; #define PG8_WAIT_V(n) asm volatile("s_waitcnt vmcnt(" #n ")" ::: "memory")
; #define PG8_WAIT_L(n) asm volatile("s_waitcnt lgkmcnt(" #n ")" ::: "memory")
; #define PG8_BAR __builtin_amdgcn_s_barrier()
; #define PG8_SCHED __builtin_amdgcn_sched_barrier(0)
; template <class Epi, bool ALIGN_EPI>
; __device__ __forceinline__ void gemm_phase(LAS unsigned char* lds, const Gemm g, const StaticOrder& S, const Epi& E, const int tid) {
;     ...
;             PG8_WAIT_V(8); PG8_WAIT_L(0); PG8_BAR; PG8_MMA(1, 0, At, B0); PG8_MMA(1, 1, At, B1); PG8_BAR; PG8_SCHED;
	v_mfma_f32_16x16x32_bf16 v[128:131], v[164:167], v[180:183], v[128:131]
	v_mfma_f32_16x16x32_bf16 v[124:127], v[172:175], v[180:183], v[124:127]
	v_mfma_f32_16x16x32_bf16 v[120:123], v[164:167], v[188:191], v[120:123]
	v_mfma_f32_16x16x32_bf16 v[116:119], v[172:175], v[188:191], v[116:119]
	v_mfma_f32_16x16x32_bf16 v[112:115], v[164:167], v[196:199], v[112:115]
	v_mfma_f32_16x16x32_bf16 v[108:111], v[172:175], v[196:199], v[108:111]
	v_mfma_f32_16x16x32_bf16 v[104:107], v[164:167], v[218:221], v[104:107]
	v_mfma_f32_16x16x32_bf16 v[100:103], v[172:175], v[218:221], v[100:103]
	v_mfma_f32_16x16x32_bf16 v[128:131], v[168:171], v[184:187], v[128:131]
	v_mfma_f32_16x16x32_bf16 v[124:127], v[176:179], v[184:187], v[124:127]
	v_mfma_f32_16x16x32_bf16 v[120:123], v[168:171], v[192:195], v[120:123]
	v_mfma_f32_16x16x32_bf16 v[116:119], v[176:179], v[192:195], v[116:119]
	v_mfma_f32_16x16x32_bf16 v[112:115], v[168:171], v[214:217], v[112:115]
	v_mfma_f32_16x16x32_bf16 v[108:111], v[176:179], v[214:217], v[108:111]
	v_mfma_f32_16x16x32_bf16 v[104:107], v[168:171], v[222:225], v[104:107]
	v_mfma_f32_16x16x32_bf16 v[100:103], v[176:179], v[222:225], v[100:103]

; #define PG8_STAGE(bufoff, gbase, voff) do { _Pragma("unroll") for (int _i = 0; _i < 2; ++_i) \
;         __builtin_amdgcn_global_load_lds((const unsigned*)((const char*)(gbase) + (voff)[_i]), (LAS unsigned*)(lds + (bufoff) + ldsw + _i * 8192), 16, 0, 0); } while (0)
; #define PG8_LDA(dst, b, h) do { _Pragma("unroll") for (int m = 0; m < 4; ++m) _Pragma("unroll") for (int k = 0; k < 2; ++k) dst[m][k] = *(const LAS bf16x8*)(lds + PG8_SA(b, h) + aoff + m * 2048 + k * 1024); } while (0)
; #define PG8_LDB(dst, b, h) do { _Pragma("unroll") for (int n = 0; n < 2; ++n) _Pragma("unroll") for (int k = 0; k < 2; ++k) dst[n][k] = *(const LAS bf16x8*)(lds + PG8_SB(b, h) + boff + n * 2048 + k * 1024); } while (0)
; #define PG8_MMA(ai, bj, At, Bt) do { __builtin_amdgcn_s_setprio(1); _Pragma("unroll") for (int m = 0; m < 4; ++m) _Pragma("unroll") for (int n = 0; n < 2; ++n) _Pragma("unroll") for (int k = 0; k < 2; ++k) \
;         acc[ai][bj][m][n] = __builtin_amdgcn_mfma_f32_16x16x32_bf16(Bt[n][k], At[m][k], acc[ai][bj][m][n], 0, 0, 0); __builtin_amdgcn_s_setprio(0); } while (0)
; #define PG8_WAIT_V(n) asm volatile("s_waitcnt vmcnt(" #n ")" ::: "memory")
; #define PG8_WAIT_L(n) asm volatile("s_waitcnt lgkmcnt(" #n ")" ::: "memory")
; #define PG8_BAR __builtin_amdgcn_s_barrier()
; #define PG8_SCHED __builtin_amdgcn_sched_barrier(0)
; template <class Epi, bool ALIGN_EPI>
; __device__ __forceinline__ void gemm_phase(LAS unsigned char* lds, const Gemm g, const StaticOrder& S, const Epi& E, const int tid) {
;     ...
;             PG8_WAIT_V(8); PG8_WAIT_L(0); PG8_BAR; PG8_MMA(1, 0, At, B0); PG8_MMA(1, 1, At, B1); PG8_BAR; PG8_SCHED;
;             PG8_LDB(B0, 1, 0); PG8_LDB(B1, 1, 1); PG8_SCHED; PG8_LDA(At, 1, 0); PG8_STAGE(PG8_SA(0, 1), a2 + hstepA, voffA);
;             PG8_WAIT_V(8); PG8_WAIT_L(0); PG8_BAR; PG8_MMA(0, 0, At, B0); PG8_MMA(0, 1, At, B1); PG8_BAR; PG8_SCHED;
	s_barrier
	s_add_i32 s87, 0, 0x18000
	v_add_u32_e32 v0, s87, v154
	s_add_i32 s88, 0, 0x1c000
	ds_read_b128 v[132:135], v0
	ds_read_b128 v[148:151], v0 offset:1024
	ds_read_b128 v[156:159], v0 offset:2048
	ds_read_b128 v[160:163], v0 offset:3072
	v_add_u32_e32 v0, s88, v154
	ds_read_b128 v[164:167], v0
	ds_read_b128 v[168:171], v0 offset:1024
	ds_read_b128 v[172:175], v0 offset:2048
	ds_read_b128 v[176:179], v0 offset:3072
	s_add_u32 s42, s42, 0x4000
	s_addc_u32 s43, s43, 0
	s_mov_b32 m0, s61
	ds_read_b128 v[180:183], v155 offset:32768
	ds_read_b128 v[184:187], v155 offset:33792
	ds_read_b128 v[188:191], v155 offset:34816
	ds_read_b128 v[192:195], v155 offset:35840
	ds_read_b128 v[196:199], v155 offset:36864
	ds_read_b128 v[214:217], v155 offset:37888
	ds_read_b128 v[218:221], v155 offset:38912
	ds_read_b128 v[222:225], v155 offset:39936
	global_load_lds_dwordx4 v142, s[42:43]
	s_mov_b32 m0, s71
	s_nop 0
	global_load_lds_dwordx4 v138, s[42:43]
	s_waitcnt vmcnt(8)
	s_waitcnt lgkmcnt(0)
	s_barrier


; #define PG8_MMA(ai, bj, At, Bt) do { __builtin_amdgcn_s_setprio(1); _Pragma("unroll") for (int m = 0; m < 4; ++m) _Pragma("unroll") for (int n = 0; n < 2; ++n) _Pragma("unroll") for (int k = 0; k < 2; ++k) \
;         acc[ai][bj][m][n] = __builtin_amdgcn_mfma_f32_16x16x32_bf16(Bt[n][k], At[m][k], acc[ai][bj][m][n], 0, 0, 0); __builtin_amdgcn_s_setprio(0); } while (0)
; #define PG8_WAIT_V(n) asm volatile("s_waitcnt vmcnt(" #n ")" ::: "memory")
; #define PG8_WAIT_L(n) asm volatile("s_waitcnt lgkmcnt(" #n ")" ::: "memory")
; #define PG8_BAR __builtin_amdgcn_s_barrier()
; #define PG8_SCHED __builtin_amdgcn_sched_barrier(0)
; template <class Epi, bool ALIGN_EPI>
; __device__ __forceinline__ void gemm_phase(LAS unsigned char* lds, const Gemm g, const StaticOrder& S, const Epi& E, const int tid) {
;     ...
;             PG8_WAIT_V(8); PG8_WAIT_L(0); PG8_BAR; PG8_MMA(0, 0, At, B0); PG8_MMA(0, 1, At, B1); PG8_BAR; PG8_SCHED;
	v_mfma_f32_16x16x32_bf16 v[6:9], v[132:135], v[180:183], v[8:11]
	v_mfma_f32_16x16x32_bf16 v[56:59], v[156:159], v[180:183], v[56:59]
	v_mfma_f32_16x16x32_bf16 v[52:55], v[132:135], v[188:191], v[52:55]
	v_mfma_f32_16x16x32_bf16 v[48:51], v[156:159], v[188:191], v[48:51]
	v_mfma_f32_16x16x32_bf16 v[44:47], v[132:135], v[196:199], v[44:47]
	v_mfma_f32_16x16x32_bf16 v[40:43], v[156:159], v[196:199], v[40:43]
	v_mfma_f32_16x16x32_bf16 v[36:39], v[132:135], v[218:221], v[36:39]
	v_mfma_f32_16x16x32_bf16 v[32:35], v[156:159], v[218:221], v[32:35]
	v_mfma_f32_16x16x32_bf16 v[8:11], v[148:151], v[184:187], v[6:9]
	v_mfma_f32_16x16x32_bf16 v[56:59], v[160:163], v[184:187], v[56:59]
	v_mfma_f32_16x16x32_bf16 v[52:55], v[148:151], v[192:195], v[52:55]
	v_mfma_f32_16x16x32_bf16 v[48:51], v[160:163], v[192:195], v[48:51]
	v_mfma_f32_16x16x32_bf16 v[44:47], v[148:151], v[214:217], v[44:47]
	v_mfma_f32_16x16x32_bf16 v[40:43], v[160:163], v[214:217], v[40:43]
	v_mfma_f32_16x16x32_bf16 v[36:39], v[148:151], v[222:225], v[36:39]
	v_mfma_f32_16x16x32_bf16 v[32:35], v[160:163], v[222:225], v[32:35]


; #define PG8_MMA(ai, bj, At, Bt) do { __builtin_amdgcn_s_setprio(1); _Pragma("unroll") for (int m = 0; m < 4; ++m) _Pragma("unroll") for (int n = 0; n < 2; ++n) _Pragma("unroll") for (int k = 0; k < 2; ++k) \
;         acc[ai][bj][m][n] = __builtin_amdgcn_mfma_f32_16x16x32_bf16(Bt[n][k], At[m][k], acc[ai][bj][m][n], 0, 0, 0); __builtin_amdgcn_s_setprio(0); } while (0)
; #define PG8_WAIT_V(n) asm volatile("s_waitcnt vmcnt(" #n ")" ::: "memory")
; #define PG8_WAIT_L(n) asm volatile("s_waitcnt lgkmcnt(" #n ")" ::: "memory")
; #define PG8_BAR __builtin_amdgcn_s_barrier()
; #define PG8_SCHED __builtin_amdgcn_sched_barrier(0)
; template <class Epi, bool ALIGN_EPI>
; __device__ __forceinline__ void gemm_phase(LAS unsigned char* lds, const Gemm g, const StaticOrder& S, const Epi& E, const int tid) {
;     ...
;             PG8_WAIT_V(8); PG8_WAIT_L(0); PG8_BAR; PG8_MMA(0, 0, At, B0); PG8_MMA(0, 1, At, B1); PG8_BAR; PG8_SCHED;
	v_mfma_f32_16x16x32_bf16 v[2:5], v[164:167], v[180:183], v[2:5]
	v_mfma_f32_16x16x32_bf16 v[28:31], v[172:175], v[180:183], v[28:31]
	v_mfma_f32_16x16x32_bf16 v[96:99], v[164:167], v[188:191], v[96:99]
	v_mfma_f32_16x16x32_bf16 v[92:95], v[172:175], v[188:191], v[92:95]
	v_mfma_f32_16x16x32_bf16 v[88:91], v[164:167], v[196:199], v[88:91]
	v_mfma_f32_16x16x32_bf16 v[84:87], v[172:175], v[196:199], v[84:87]
	v_mfma_f32_16x16x32_bf16 v[80:83], v[164:167], v[218:221], v[80:83]
	v_mfma_f32_16x16x32_bf16 v[76:79], v[172:175], v[218:221], v[76:79]
	v_mfma_f32_16x16x32_bf16 v[4:7], v[168:171], v[184:187], v[2:5]
	v_mfma_f32_16x16x32_bf16 v[28:31], v[176:179], v[184:187], v[28:31]
	v_mfma_f32_16x16x32_bf16 v[96:99], v[168:171], v[192:195], v[96:99]
	v_mfma_f32_16x16x32_bf16 v[92:95], v[176:179], v[192:195], v[92:95]
	v_mfma_f32_16x16x32_bf16 v[88:91], v[168:171], v[214:217], v[88:91]
	v_mfma_f32_16x16x32_bf16 v[84:87], v[176:179], v[214:217], v[84:87]
	v_mfma_f32_16x16x32_bf16 v[80:83], v[168:171], v[222:225], v[80:83]
	v_mfma_f32_16x16x32_bf16 v[76:79], v[176:179], v[222:225], v[76:79]

; #define PG8_STAGE(bufoff, gbase, voff) do { _Pragma("unroll") for (int _i = 0; _i < 2; ++_i) \
;         __builtin_amdgcn_global_load_lds((const unsigned*)((const char*)(gbase) + (voff)[_i]), (LAS unsigned*)(lds + (bufoff) + ldsw + _i * 8192), 16, 0, 0); } while (0)
; #define PG8_LDA(dst, b, h) do { _Pragma("unroll") for (int m = 0; m < 4; ++m) _Pragma("unroll") for (int k = 0; k < 2; ++k) dst[m][k] = *(const LAS bf16x8*)(lds + PG8_SA(b, h) + aoff + m * 2048 + k * 1024); } while (0)
; #define PG8_MMA(ai, bj, At, Bt) do { __builtin_amdgcn_s_setprio(1); _Pragma("unroll") for (int m = 0; m < 4; ++m) _Pragma("unroll") for (int n = 0; n < 2; ++n) _Pragma("unroll") for (int k = 0; k < 2; ++k) \
;         acc[ai][bj][m][n] = __builtin_amdgcn_mfma_f32_16x16x32_bf16(Bt[n][k], At[m][k], acc[ai][bj][m][n], 0, 0, 0); __builtin_amdgcn_s_setprio(0); } while (0)
; #define PG8_WAIT_V(n) asm volatile("s_waitcnt vmcnt(" #n ")" ::: "memory")
; #define PG8_WAIT_L(n) asm volatile("s_waitcnt lgkmcnt(" #n ")" ::: "memory")
; #define PG8_BAR __builtin_amdgcn_s_barrier()
; #define PG8_SCHED __builtin_amdgcn_sched_barrier(0)
; template <class Epi, bool ALIGN_EPI>
; __device__ __forceinline__ void gemm_phase(LAS unsigned char* lds, const Gemm g, const StaticOrder& S, const Epi& E, const int tid) {
;     ...
;             PG8_LDA(At, 1, 1); PG8_STAGE(PG8_SB(1, 0), b3, voffB); PG8_STAGE(PG8_SB(1, 1), b3 + hstepB, voffB); PG8_STAGE(PG8_SA(1, 0), a3, voffA);
;             PG8_WAIT_V(8); PG8_WAIT_L(0); PG8_BAR; PG8_MMA(1, 0, At, B0); PG8_MMA(1, 1, At, B1); PG8_BAR; PG8_SCHED;
	s_barrier
	s_add_u32 s42, s34, 0x8000
	s_addc_u32 s43, s35, 0
	s_add_i32 s87, s87, s56
	s_mov_b32 m0, s87
	ds_read_b128 v[180:183], v155 offset:49152
	ds_read_b128 v[184:187], v155 offset:50176
	ds_read_b128 v[188:191], v155 offset:51200
	ds_read_b128 v[192:195], v155 offset:52224
	ds_read_b128 v[196:199], v155 offset:53248
	ds_read_b128 v[214:217], v155 offset:54272
	ds_read_b128 v[218:221], v155 offset:55296
	ds_read_b128 v[222:225], v155 offset:56320
	global_load_lds_dwordx4 v140, s[42:43]
	s_add_i32 m0, s87, 0x2000
	s_add_u32 s34, s34, 0xc000
	s_addc_u32 s35, s35, 0
	global_load_lds_dwordx4 v136, s[42:43]
	s_add_i32 s42, s88, s56
	s_mov_b32 m0, s42
	s_nop 0
	global_load_lds_dwordx4 v140, s[34:35]
	s_add_i32 m0, s42, 0x2000
	s_nop 0
	global_load_lds_dwordx4 v136, s[34:35]
	s_mov_b32 m0, s76
	s_nop 0
	global_load_lds_dwordx4 v142, s[22:23]
	s_mov_b32 m0, s77
	s_nop 0
	global_load_lds_dwordx4 v138, s[22:23]
	s_waitcnt vmcnt(8)
	s_waitcnt lgkmcnt(0)
	s_barrier


; #define PG8_MMA(ai, bj, At, Bt) do { __builtin_amdgcn_s_setprio(1); _Pragma("unroll") for (int m = 0; m < 4; ++m) _Pragma("unroll") for (int n = 0; n < 2; ++n) _Pragma("unroll") for (int k = 0; k < 2; ++k) \
;         acc[ai][bj][m][n] = __builtin_amdgcn_mfma_f32_16x16x32_bf16(Bt[n][k], At[m][k], acc[ai][bj][m][n], 0, 0, 0); __builtin_amdgcn_s_setprio(0); } while (0)
; #define PG8_WAIT_V(n) asm volatile("s_waitcnt vmcnt(" #n ")" ::: "memory")
; #define PG8_WAIT_L(n) asm volatile("s_waitcnt lgkmcnt(" #n ")" ::: "memory")
; #define PG8_BAR __builtin_amdgcn_s_barrier()
; #define PG8_SCHED __builtin_amdgcn_sched_barrier(0)
; template <class Epi, bool ALIGN_EPI>
; __device__ __forceinline__ void gemm_phase(LAS unsigned char* lds, const Gemm g, const StaticOrder& S, const Epi& E, const int tid) {
;     ...
;             PG8_WAIT_V(8); PG8_WAIT_L(0); PG8_BAR; PG8_MMA(1, 0, At, B0); PG8_MMA(1, 1, At, B1); PG8_BAR; PG8_SCHED;
	v_mfma_f32_16x16x32_bf16 v[24:27], v[132:135], v[180:183], v[24:27]
	v_mfma_f32_16x16x32_bf16 v[20:23], v[156:159], v[180:183], v[20:23]
	v_mfma_f32_16x16x32_bf16 v[64:67], v[132:135], v[188:191], v[64:67]
	v_mfma_f32_16x16x32_bf16 v[72:75], v[156:159], v[188:191], v[72:75]
	v_mfma_f32_16x16x32_bf16 v[16:19], v[132:135], v[196:199], v[16:19]
	v_mfma_f32_16x16x32_bf16 v[12:15], v[156:159], v[196:199], v[12:15]
	v_mfma_f32_16x16x32_bf16 v[60:63], v[132:135], v[218:221], v[60:63]
	v_mfma_f32_16x16x32_bf16 v[68:71], v[156:159], v[218:221], v[68:71]
	v_mfma_f32_16x16x32_bf16 v[24:27], v[148:151], v[184:187], v[24:27]
	v_mfma_f32_16x16x32_bf16 v[20:23], v[160:163], v[184:187], v[20:23]
	v_mfma_f32_16x16x32_bf16 v[64:67], v[148:151], v[192:195], v[64:67]
	v_mfma_f32_16x16x32_bf16 v[72:75], v[160:163], v[192:195], v[72:75]
	v_mfma_f32_16x16x32_bf16 v[16:19], v[148:151], v[214:217], v[16:19]
	v_mfma_f32_16x16x32_bf16 v[12:15], v[160:163], v[214:217], v[12:15]
	v_mfma_f32_16x16x32_bf16 v[60:63], v[148:151], v[222:225], v[60:63]
	v_mfma_f32_16x16x32_bf16 v[68:71], v[160:163], v[222:225], v[68:71]


; #define PG8_MMA(ai, bj, At, Bt) do { __builtin_amdgcn_s_setprio(1); _Pragma("unroll") for (int m = 0; m < 4; ++m) _Pragma("unroll") for (int n = 0; n < 2; ++n) _Pragma("unroll") for (int k = 0; k < 2; ++k) \
;         acc[ai][bj][m][n] = __builtin_amdgcn_mfma_f32_16x16x32_bf16(Bt[n][k], At[m][k], acc[ai][bj][m][n], 0, 0, 0); __builtin_amdgcn_s_setprio(0); } while (0)
; #define PG8_WAIT_V(n) asm volatile("s_waitcnt vmcnt(" #n ")" ::: "memory")
; #define PG8_WAIT_L(n) asm volatile("s_waitcnt lgkmcnt(" #n ")" ::: "memory")
; #define PG8_BAR __builtin_amdgcn_s_barrier()
; #define PG8_SCHED __builtin_amdgcn_sched_barrier(0)
; template <class Epi, bool ALIGN_EPI>
; __device__ __forceinline__ void gemm_phase(LAS unsigned char* lds, const Gemm g, const StaticOrder& S, const Epi& E, const int tid) {
;     ...
;             PG8_WAIT_V(8); PG8_WAIT_L(0); PG8_BAR; PG8_MMA(1, 0, At, B0); PG8_MMA(1, 1, At, B1); PG8_BAR; PG8_SCHED;
	v_mfma_f32_16x16x32_bf16 v[128:131], v[164:167], v[180:183], v[128:131]
	v_mfma_f32_16x16x32_bf16 v[124:127], v[172:175], v[180:183], v[124:127]
	v_mfma_f32_16x16x32_bf16 v[120:123], v[164:167], v[188:191], v[120:123]
	v_mfma_f32_16x16x32_bf16 v[116:119], v[172:175], v[188:191], v[116:119]
	v_mfma_f32_16x16x32_bf16 v[112:115], v[164:167], v[196:199], v[112:115]
	v_mfma_f32_16x16x32_bf16 v[108:111], v[172:175], v[196:199], v[108:111]
	v_mfma_f32_16x16x32_bf16 v[104:107], v[164:167], v[218:221], v[104:107]
	v_mfma_f32_16x16x32_bf16 v[100:103], v[172:175], v[218:221], v[100:103]
	v_mfma_f32_16x16x32_bf16 v[128:131], v[168:171], v[184:187], v[128:131]
	v_mfma_f32_16x16x32_bf16 v[124:127], v[176:179], v[184:187], v[124:127]
	v_mfma_f32_16x16x32_bf16 v[120:123], v[168:171], v[192:195], v[120:123]
	v_mfma_f32_16x16x32_bf16 v[116:119], v[176:179], v[192:195], v[116:119]
	v_mfma_f32_16x16x32_bf16 v[112:115], v[168:171], v[214:217], v[112:115]
	v_mfma_f32_16x16x32_bf16 v[108:111], v[176:179], v[214:217], v[108:111]
	v_mfma_f32_16x16x32_bf16 v[104:107], v[168:171], v[222:225], v[104:107]
	v_mfma_f32_16x16x32_bf16 v[100:103], v[176:179], v[222:225], v[100:103]

; #define PG8_MMA(ai, bj, At, Bt) do { __builtin_amdgcn_s_setprio(1); _Pragma("unroll") for (int m = 0; m < 4; ++m) _Pragma("unroll") for (int n = 0; n < 2; ++n) _Pragma("unroll") for (int k = 0; k < 2; ++k) \
;         acc[ai][bj][m][n] = __builtin_amdgcn_mfma_f32_16x16x32_bf16(Bt[n][k], At[m][k], acc[ai][bj][m][n], 0, 0, 0); __builtin_amdgcn_s_setprio(0); } while (0)
; #define PG8_WAIT_V(n) asm volatile("s_waitcnt vmcnt(" #n ")" ::: "memory")
; #define PG8_WAIT_L(n) asm volatile("s_waitcnt lgkmcnt(" #n ")" ::: "memory")
; #define PG8_BAR __builtin_amdgcn_s_barrier()
; #define PG8_SCHED __builtin_amdgcn_sched_barrier(0)
; template <class Epi, bool ALIGN_EPI>
; __device__ __forceinline__ void gemm_phase(LAS unsigned char* lds, const Gemm g, const StaticOrder& S, const Epi& E, const int tid) {
;     ...
;             PG8_WAIT_V(8); PG8_WAIT_L(0); PG8_BAR; PG8_MMA(1, 0, At, B0); PG8_MMA(1, 1, At, B1); PG8_BAR; PG8_SCHED;
;         }
;         if constexpr (ALIGN_EPI) { if (wr == 0) PG8_BAR; }
	s_barrier
	s_add_i32 s86, s86, 2
	s_add_u32 s84, s84, 0x10000
	s_addc_u32 s85, s85, 0
	s_add_u32 s10, s10, 0x10000
	s_addc_u32 s11, s11, 0
	s_cmpk_gt_u32 s86, 0x55
	s_cbranch_scc0 .LBB0_294
	s_and_b64 vcc, exec, s[46:47]
	s_cbranch_vccz .LBB0_297
	s_barrier

; #define PG8_STAGE(bufoff, gbase, voff) do { _Pragma("unroll") for (int _i = 0; _i < 2; ++_i) \
;         __builtin_amdgcn_global_load_lds((const unsigned*)((const char*)(gbase) + (voff)[_i]), (LAS unsigned*)(lds + (bufoff) + ldsw + _i * 8192), 16, 0, 0); } while (0)
; #define PG8_LDA(dst, b, h) do { _Pragma("unroll") for (int m = 0; m < 4; ++m) _Pragma("unroll") for (int k = 0; k < 2; ++k) dst[m][k] = *(const LAS bf16x8*)(lds + PG8_SA(b, h) + aoff + m * 2048 + k * 1024); } while (0)
; #define PG8_LDB(dst, b, h) do { _Pragma("unroll") for (int n = 0; n < 2; ++n) _Pragma("unroll") for (int k = 0; k < 2; ++k) dst[n][k] = *(const LAS bf16x8*)(lds + PG8_SB(b, h) + boff + n * 2048 + k * 1024); } while (0)
; #define PG8_MMA(ai, bj, At, Bt) do { __builtin_amdgcn_s_setprio(1); _Pragma("unroll") for (int m = 0; m < 4; ++m) _Pragma("unroll") for (int n = 0; n < 2; ++n) _Pragma("unroll") for (int k = 0; k < 2; ++k) \
;         acc[ai][bj][m][n] = __builtin_amdgcn_mfma_f32_16x16x32_bf16(Bt[n][k], At[m][k], acc[ai][bj][m][n], 0, 0, 0); __builtin_amdgcn_s_setprio(0); } while (0)
; #define PG8_WAIT_V(n) asm volatile("s_waitcnt vmcnt(" #n ")" ::: "memory")
; #define PG8_WAIT_L(n) asm volatile("s_waitcnt lgkmcnt(" #n ")" ::: "memory")
; #define PG8_BAR __builtin_amdgcn_s_barrier()
; #define PG8_SCHED __builtin_amdgcn_sched_barrier(0)
; template <class Epi, bool ALIGN_EPI>
; __device__ __forceinline__ void gemm_phase(LAS unsigned char* lds, const Gemm g, const StaticOrder& S, const Epi& E, const int tid) {
;     ...
;         for (int t = 0; t < nt; t += 2) {
;             const bool last = (t == nt - 2);
;             const char* a1 = cA + (size_t)(t + 1) * kstepA;
;             const char* a2 = last ? nA : cA + (size_t)(t + 2) * kstepA; const char* b2 = last ? nB : cB + (size_t)(t + 2) * kstepB;
;             const char* a3 = a2 + kstepA; const char* b3 = b2 + kstepB;
;             PG8_LDB(B0, 0, 0); PG8_LDB(B1, 0, 1); PG8_SCHED; PG8_LDA(At, 0, 0); PG8_STAGE(PG8_SA(1, 1), a1 + hstepA, voffA);
;             PG8_WAIT_V(8); PG8_WAIT_L(0); PG8_BAR; PG8_MMA(0, 0, At, B0); PG8_MMA(0, 1, At, B1); PG8_BAR; PG8_SCHED;
.LBB0_385:
	s_add_u32 s50, s48, 0x4000
	s_addc_u32 s51, s49, 0
	s_cmp_eq_u32 s88, 28
	s_cselect_b32 s54, s84, s50
	s_cselect_b32 s55, s43, s51
	s_cselect_b32 s52, s85, s86
	s_cselect_b32 s53, s41, s87
	s_add_u32 s50, s54, 0x8000
	s_addc_u32 s51, s55, 0
	s_add_i32 s89, 0, 0x10000
	v_add_u32_e32 v0, s89, v167
	s_add_i32 s92, 0, 0x14000
	ds_read_b128 v[132:135], v0
	ds_read_b128 v[136:139], v0 offset:1024
	ds_read_b128 v[152:155], v0 offset:2048
	ds_read_b128 v[156:159], v0 offset:3072
	v_add_u32_e32 v0, s92, v167
	ds_read_b128 v[160:163], v0
	ds_read_b128 v[172:175], v0 offset:1024
	ds_read_b128 v[176:179], v0 offset:2048
	ds_read_b128 v[180:183], v0 offset:3072
	s_add_i32 m0, s71, 0xc000
	ds_read_b128 v[184:187], v171
	ds_read_b128 v[188:191], v171 offset:1024
	ds_read_b128 v[192:195], v171 offset:2048
	ds_read_b128 v[196:199], v171 offset:3072
	ds_read_b128 v[214:217], v171 offset:4096
	ds_read_b128 v[218:221], v171 offset:5120
	ds_read_b128 v[222:225], v171 offset:6144
	ds_read_b128 v[226:229], v171 offset:7168
	global_load_lds_dwordx4 v148, s[48:49]
	s_add_i32 m0, s71, 0xe000
	s_nop 0
	global_load_lds_dwordx4 v150, s[48:49]
	s_waitcnt vmcnt(8)
	s_waitcnt lgkmcnt(0)
	s_barrier


; #define PG8_MMA(ai, bj, At, Bt) do { __builtin_amdgcn_s_setprio(1); _Pragma("unroll") for (int m = 0; m < 4; ++m) _Pragma("unroll") for (int n = 0; n < 2; ++n) _Pragma("unroll") for (int k = 0; k < 2; ++k) \
;         acc[ai][bj][m][n] = __builtin_amdgcn_mfma_f32_16x16x32_bf16(Bt[n][k], At[m][k], acc[ai][bj][m][n], 0, 0, 0); __builtin_amdgcn_s_setprio(0); } while (0)
; #define PG8_WAIT_V(n) asm volatile("s_waitcnt vmcnt(" #n ")" ::: "memory")
; #define PG8_WAIT_L(n) asm volatile("s_waitcnt lgkmcnt(" #n ")" ::: "memory")
; #define PG8_BAR __builtin_amdgcn_s_barrier()
; #define PG8_SCHED __builtin_amdgcn_sched_barrier(0)
; template <class Epi, bool ALIGN_EPI>
; __device__ __forceinline__ void gemm_phase(LAS unsigned char* lds, const Gemm g, const StaticOrder& S, const Epi& E, const int tid) {
;     ...
;             PG8_WAIT_V(8); PG8_WAIT_L(0); PG8_BAR; PG8_MMA(0, 0, At, B0); PG8_MMA(0, 1, At, B1); PG8_BAR; PG8_SCHED;
	v_mfma_f32_16x16x32_bf16 v[128:131], v[132:135], v[184:187], v[128:131]
	v_mfma_f32_16x16x32_bf16 v[116:119], v[152:155], v[184:187], v[116:119]
	v_mfma_f32_16x16x32_bf16 v[124:127], v[132:135], v[192:195], v[124:127]
	v_mfma_f32_16x16x32_bf16 v[108:111], v[152:155], v[192:195], v[108:111]
	v_mfma_f32_16x16x32_bf16 v[120:123], v[132:135], v[214:217], v[120:123]
	v_mfma_f32_16x16x32_bf16 v[100:103], v[152:155], v[214:217], v[100:103]
	v_mfma_f32_16x16x32_bf16 v[112:115], v[132:135], v[222:225], v[112:115]
	v_mfma_f32_16x16x32_bf16 v[92:95], v[152:155], v[222:225], v[92:95]
	v_mfma_f32_16x16x32_bf16 v[128:131], v[136:139], v[188:191], v[128:131]
	v_mfma_f32_16x16x32_bf16 v[116:119], v[156:159], v[188:191], v[116:119]
	v_mfma_f32_16x16x32_bf16 v[124:127], v[136:139], v[196:199], v[124:127]
	v_mfma_f32_16x16x32_bf16 v[108:111], v[156:159], v[196:199], v[108:111]
	v_mfma_f32_16x16x32_bf16 v[120:123], v[136:139], v[218:221], v[120:123]
	v_mfma_f32_16x16x32_bf16 v[100:103], v[156:159], v[218:221], v[100:103]
	v_mfma_f32_16x16x32_bf16 v[112:115], v[136:139], v[226:229], v[112:115]
	v_mfma_f32_16x16x32_bf16 v[92:95], v[156:159], v[226:229], v[92:95]


; #define PG8_MMA(ai, bj, At, Bt) do { __builtin_amdgcn_s_setprio(1); _Pragma("unroll") for (int m = 0; m < 4; ++m) _Pragma("unroll") for (int n = 0; n < 2; ++n) _Pragma("unroll") for (int k = 0; k < 2; ++k) \
;         acc[ai][bj][m][n] = __builtin_amdgcn_mfma_f32_16x16x32_bf16(Bt[n][k], At[m][k], acc[ai][bj][m][n], 0, 0, 0); __builtin_amdgcn_s_setprio(0); } while (0)
; #define PG8_WAIT_V(n) asm volatile("s_waitcnt vmcnt(" #n ")" ::: "memory")
; #define PG8_WAIT_L(n) asm volatile("s_waitcnt lgkmcnt(" #n ")" ::: "memory")
; #define PG8_BAR __builtin_amdgcn_s_barrier()
; #define PG8_SCHED __builtin_amdgcn_sched_barrier(0)
; template <class Epi, bool ALIGN_EPI>
; __device__ __forceinline__ void gemm_phase(LAS unsigned char* lds, const Gemm g, const StaticOrder& S, const Epi& E, const int tid) {
;     ...
;             PG8_WAIT_V(8); PG8_WAIT_L(0); PG8_BAR; PG8_MMA(0, 0, At, B0); PG8_MMA(0, 1, At, B1); PG8_BAR; PG8_SCHED;
	v_mfma_f32_16x16x32_bf16 v[104:107], v[160:163], v[184:187], v[104:107]
	v_mfma_f32_16x16x32_bf16 v[80:83], v[176:179], v[184:187], v[80:83]
	v_mfma_f32_16x16x32_bf16 v[96:99], v[160:163], v[192:195], v[96:99]
	v_mfma_f32_16x16x32_bf16 v[68:71], v[176:179], v[192:195], v[68:71]
	v_mfma_f32_16x16x32_bf16 v[88:91], v[160:163], v[214:217], v[88:91]
	v_mfma_f32_16x16x32_bf16 v[60:63], v[176:179], v[214:217], v[60:63]
	v_mfma_f32_16x16x32_bf16 v[76:79], v[160:163], v[222:225], v[76:79]
	v_mfma_f32_16x16x32_bf16 v[48:51], v[176:179], v[222:225], v[48:51]
	v_mfma_f32_16x16x32_bf16 v[104:107], v[172:175], v[188:191], v[104:107]
	v_mfma_f32_16x16x32_bf16 v[80:83], v[180:183], v[188:191], v[80:83]
	v_mfma_f32_16x16x32_bf16 v[96:99], v[172:175], v[196:199], v[96:99]
	v_mfma_f32_16x16x32_bf16 v[68:71], v[180:183], v[196:199], v[68:71]
	v_mfma_f32_16x16x32_bf16 v[88:91], v[172:175], v[218:221], v[88:91]
	v_mfma_f32_16x16x32_bf16 v[60:63], v[180:183], v[218:221], v[60:63]
	v_mfma_f32_16x16x32_bf16 v[76:79], v[172:175], v[226:229], v[76:79]
	v_mfma_f32_16x16x32_bf16 v[48:51], v[180:183], v[226:229], v[48:51]

; #define PG8_STAGE(bufoff, gbase, voff) do { _Pragma("unroll") for (int _i = 0; _i < 2; ++_i) \
;         __builtin_amdgcn_global_load_lds((const unsigned*)((const char*)(gbase) + (voff)[_i]), (LAS unsigned*)(lds + (bufoff) + ldsw + _i * 8192), 16, 0, 0); } while (0)
; #define PG8_LDA(dst, b, h) do { _Pragma("unroll") for (int m = 0; m < 4; ++m) _Pragma("unroll") for (int k = 0; k < 2; ++k) dst[m][k] = *(const LAS bf16x8*)(lds + PG8_SA(b, h) + aoff + m * 2048 + k * 1024); } while (0)
; #define PG8_MMA(ai, bj, At, Bt) do { __builtin_amdgcn_s_setprio(1); _Pragma("unroll") for (int m = 0; m < 4; ++m) _Pragma("unroll") for (int n = 0; n < 2; ++n) _Pragma("unroll") for (int k = 0; k < 2; ++k) \
;         acc[ai][bj][m][n] = __builtin_amdgcn_mfma_f32_16x16x32_bf16(Bt[n][k], At[m][k], acc[ai][bj][m][n], 0, 0, 0); __builtin_amdgcn_s_setprio(0); } while (0)
; #define PG8_WAIT_V(n) asm volatile("s_waitcnt vmcnt(" #n ")" ::: "memory")
; #define PG8_WAIT_L(n) asm volatile("s_waitcnt lgkmcnt(" #n ")" ::: "memory")
; #define PG8_BAR __builtin_amdgcn_s_barrier()
; #define PG8_SCHED __builtin_amdgcn_sched_barrier(0)
; template <class Epi, bool ALIGN_EPI>
; __device__ __forceinline__ void gemm_phase(LAS unsigned char* lds, const Gemm g, const StaticOrder& S, const Epi& E, const int tid) {
;     ...
;             PG8_WAIT_V(8); PG8_WAIT_L(0); PG8_BAR; PG8_MMA(0, 0, At, B0); PG8_MMA(0, 1, At, B1); PG8_BAR; PG8_SCHED;
;             PG8_LDA(At, 0, 1); PG8_STAGE(PG8_SB(0, 0), b2, voffB); PG8_STAGE(PG8_SB(0, 1), b2 + hstepB, voffB); PG8_STAGE(PG8_SA(0, 0), a2, voffA);
;             PG8_WAIT_V(8); PG8_WAIT_L(0); PG8_BAR; PG8_MMA(1, 0, At, B0); PG8_MMA(1, 1, At, B1); PG8_BAR; PG8_SCHED;
	s_barrier
	s_add_i32 s89, s89, s61
	s_mov_b32 m0, s89
	ds_read_b128 v[184:187], v171 offset:16384
	ds_read_b128 v[188:191], v171 offset:17408
	ds_read_b128 v[192:195], v171 offset:18432
	ds_read_b128 v[196:199], v171 offset:19456
	ds_read_b128 v[214:217], v171 offset:20480
	ds_read_b128 v[218:221], v171 offset:21504
	ds_read_b128 v[222:225], v171 offset:22528
	ds_read_b128 v[226:229], v171 offset:23552
	global_load_lds_dwordx4 v144, s[52:53]
	s_add_i32 m0, s89, 0x2000
	s_add_u32 s90, s52, 0x4000
	s_addc_u32 s91, s53, 0
	s_add_i32 s89, s92, s61
	global_load_lds_dwordx4 v140, s[52:53]
	s_mov_b32 m0, s89
	s_nop 0
	global_load_lds_dwordx4 v144, s[90:91]
	s_add_i32 m0, s89, 0x2000
	s_nop 0
	global_load_lds_dwordx4 v140, s[90:91]
	s_mov_b32 m0, s71
	s_nop 0
	global_load_lds_dwordx4 v146, s[54:55]
	s_mov_b32 m0, s72
	s_nop 0
	global_load_lds_dwordx4 v142, s[54:55]
	s_waitcnt vmcnt(8)
	s_waitcnt lgkmcnt(0)
	s_barrier


; #define PG8_MMA(ai, bj, At, Bt) do { __builtin_amdgcn_s_setprio(1); _Pragma("unroll") for (int m = 0; m < 4; ++m) _Pragma("unroll") for (int n = 0; n < 2; ++n) _Pragma("unroll") for (int k = 0; k < 2; ++k) \
;         acc[ai][bj][m][n] = __builtin_amdgcn_mfma_f32_16x16x32_bf16(Bt[n][k], At[m][k], acc[ai][bj][m][n], 0, 0, 0); __builtin_amdgcn_s_setprio(0); } while (0)
; #define PG8_WAIT_V(n) asm volatile("s_waitcnt vmcnt(" #n ")" ::: "memory")
; #define PG8_WAIT_L(n) asm volatile("s_waitcnt lgkmcnt(" #n ")" ::: "memory")
; #define PG8_BAR __builtin_amdgcn_s_barrier()
; #define PG8_SCHED __builtin_amdgcn_sched_barrier(0)
; template <class Epi, bool ALIGN_EPI>
; __device__ __forceinline__ void gemm_phase(LAS unsigned char* lds, const Gemm g, const StaticOrder& S, const Epi& E, const int tid) {
;     ...
;             PG8_WAIT_V(8); PG8_WAIT_L(0); PG8_BAR; PG8_MMA(1, 0, At, B0); PG8_MMA(1, 1, At, B1); PG8_BAR; PG8_SCHED;
	v_mfma_f32_16x16x32_bf16 v[84:87], v[132:135], v[184:187], v[84:87]
	v_mfma_f32_16x16x32_bf16 v[56:59], v[152:155], v[184:187], v[56:59]
	v_mfma_f32_16x16x32_bf16 v[72:75], v[132:135], v[192:195], v[72:75]
	v_mfma_f32_16x16x32_bf16 v[44:47], v[152:155], v[192:195], v[44:47]
	v_mfma_f32_16x16x32_bf16 v[64:67], v[132:135], v[214:217], v[64:67]
	v_mfma_f32_16x16x32_bf16 v[36:39], v[152:155], v[214:217], v[36:39]
	v_mfma_f32_16x16x32_bf16 v[52:55], v[132:135], v[222:225], v[52:55]
	v_mfma_f32_16x16x32_bf16 v[28:31], v[152:155], v[222:225], v[28:31]
	v_mfma_f32_16x16x32_bf16 v[84:87], v[136:139], v[188:191], v[84:87]
	v_mfma_f32_16x16x32_bf16 v[56:59], v[156:159], v[188:191], v[56:59]
	v_mfma_f32_16x16x32_bf16 v[72:75], v[136:139], v[196:199], v[72:75]
	v_mfma_f32_16x16x32_bf16 v[44:47], v[156:159], v[196:199], v[44:47]
	v_mfma_f32_16x16x32_bf16 v[64:67], v[136:139], v[218:221], v[64:67]
	v_mfma_f32_16x16x32_bf16 v[36:39], v[156:159], v[218:221], v[36:39]
	v_mfma_f32_16x16x32_bf16 v[52:55], v[136:139], v[226:229], v[52:55]
	v_mfma_f32_16x16x32_bf16 v[28:31], v[156:159], v[226:229], v[28:31]


; #define PG8_MMA(ai, bj, At, Bt) do { __builtin_amdgcn_s_setprio(1); _Pragma("unroll") for (int m = 0; m < 4; ++m) _Pragma("unroll") for (int n = 0; n < 2; ++n) _Pragma("unroll") for (int k = 0; k < 2; ++k) \
;         acc[ai][bj][m][n] = __builtin_amdgcn_mfma_f32_16x16x32_bf16(Bt[n][k], At[m][k], acc[ai][bj][m][n], 0, 0, 0); __builtin_amdgcn_s_setprio(0); } while (0)
; #define PG8_WAIT_V(n) asm volatile("s_waitcnt vmcnt(" #n ")" ::: "memory")
; #define PG8_WAIT_L(n) asm volatile("s_waitcnt lgkmcnt(" #n ")" ::: "memory")
; #define PG8_BAR __builtin_amdgcn_s_barrier()
; #define PG8_SCHED __builtin_amdgcn_sched_barrier(0)
; template <class Epi, bool ALIGN_EPI>
; __device__ __forceinline__ void gemm_phase(LAS unsigned char* lds, const Gemm g, const StaticOrder& S, const Epi& E, const int tid) {
;     ...
;             PG8_WAIT_V(8); PG8_WAIT_L(0); PG8_BAR; PG8_MMA(1, 0, At, B0); PG8_MMA(1, 1, At, B1); PG8_BAR; PG8_SCHED;
	v_mfma_f32_16x16x32_bf16 v[40:43], v[160:163], v[184:187], v[40:43]
	v_mfma_f32_16x16x32_bf16 v[20:23], v[176:179], v[184:187], v[20:23]
	v_mfma_f32_16x16x32_bf16 v[32:35], v[160:163], v[192:195], v[32:35]
	v_mfma_f32_16x16x32_bf16 v[12:15], v[176:179], v[192:195], v[12:15]
	v_mfma_f32_16x16x32_bf16 v[24:27], v[160:163], v[214:217], v[24:27]
	v_mfma_f32_16x16x32_bf16 v[8:11], v[176:179], v[214:217], v[8:11]
	v_mfma_f32_16x16x32_bf16 v[16:19], v[160:163], v[222:225], v[16:19]
	v_mfma_f32_16x16x32_bf16 v[2:5], v[176:179], v[222:225], v[4:7]
	v_mfma_f32_16x16x32_bf16 v[40:43], v[172:175], v[188:191], v[40:43]
	v_mfma_f32_16x16x32_bf16 v[20:23], v[180:183], v[188:191], v[20:23]
	v_mfma_f32_16x16x32_bf16 v[32:35], v[172:175], v[196:199], v[32:35]
	v_mfma_f32_16x16x32_bf16 v[12:15], v[180:183], v[196:199], v[12:15]
	v_mfma_f32_16x16x32_bf16 v[24:27], v[172:175], v[218:221], v[24:27]
	v_mfma_f32_16x16x32_bf16 v[8:11], v[180:183], v[218:221], v[8:11]
	v_mfma_f32_16x16x32_bf16 v[16:19], v[172:175], v[226:229], v[16:19]
	v_mfma_f32_16x16x32_bf16 v[2:5], v[180:183], v[226:229], v[2:5]

; #define PG8_STAGE(bufoff, gbase, voff) do { _Pragma("unroll") for (int _i = 0; _i < 2; ++_i) \
;         __builtin_amdgcn_global_load_lds((const unsigned*)((const char*)(gbase) + (voff)[_i]), (LAS unsigned*)(lds + (bufoff) + ldsw + _i * 8192), 16, 0, 0); } while (0)
; #define PG8_LDA(dst, b, h) do { _Pragma("unroll") for (int m = 0; m < 4; ++m) _Pragma("unroll") for (int k = 0; k < 2; ++k) dst[m][k] = *(const LAS bf16x8*)(lds + PG8_SA(b, h) + aoff + m * 2048 + k * 1024); } while (0)
; #define PG8_LDB(dst, b, h) do { _Pragma("unroll") for (int n = 0; n < 2; ++n) _Pragma("unroll") for (int k = 0; k < 2; ++k) dst[n][k] = *(const LAS bf16x8*)(lds + PG8_SB(b, h) + boff + n * 2048 + k * 1024); } while (0)
; #define PG8_MMA(ai, bj, At, Bt) do { __builtin_amdgcn_s_setprio(1); _Pragma("unroll") for (int m = 0; m < 4; ++m) _Pragma("unroll") for (int n = 0; n < 2; ++n) _Pragma("unroll") for (int k = 0; k < 2; ++k) \
;         acc[ai][bj][m][n] = __builtin_amdgcn_mfma_f32_16x16x32_bf16(Bt[n][k], At[m][k], acc[ai][bj][m][n], 0, 0, 0); __builtin_amdgcn_s_setprio(0); } while (0)
; #define PG8_WAIT_V(n) asm volatile("s_waitcnt vmcnt(" #n ")" ::: "memory")
; #define PG8_WAIT_L(n) asm volatile("s_waitcnt lgkmcnt(" #n ")" ::: "memory")
; #define PG8_BAR __builtin_amdgcn_s_barrier()
; #define PG8_SCHED __builtin_amdgcn_sched_barrier(0)
; template <class Epi, bool ALIGN_EPI>
; __device__ __forceinline__ void gemm_phase(LAS unsigned char* lds, const Gemm g, const StaticOrder& S, const Epi& E, const int tid) {
;     ...
;             PG8_WAIT_V(8); PG8_WAIT_L(0); PG8_BAR; PG8_MMA(1, 0, At, B0); PG8_MMA(1, 1, At, B1); PG8_BAR; PG8_SCHED;
;             PG8_LDB(B0, 1, 0); PG8_LDB(B1, 1, 1); PG8_SCHED; PG8_LDA(At, 1, 0); PG8_STAGE(PG8_SA(0, 1), a2 + hstepA, voffA);
;             PG8_WAIT_V(8); PG8_WAIT_L(0); PG8_BAR; PG8_MMA(0, 0, At, B0); PG8_MMA(0, 1, At, B1); PG8_BAR; PG8_SCHED;
	s_barrier
	s_add_i32 s89, 0, 0x18000
	v_add_u32_e32 v0, s89, v167
	s_add_i32 s90, 0, 0x1c000
	ds_read_b128 v[132:135], v0
	ds_read_b128 v[136:139], v0 offset:1024
	ds_read_b128 v[152:155], v0 offset:2048
	ds_read_b128 v[156:159], v0 offset:3072
	v_add_u32_e32 v0, s90, v167
	ds_read_b128 v[160:163], v0
	ds_read_b128 v[172:175], v0 offset:1024
	ds_read_b128 v[176:179], v0 offset:2048
	ds_read_b128 v[180:183], v0 offset:3072
	s_add_u32 s54, s54, 0x4000
	s_addc_u32 s55, s55, 0
	s_mov_b32 m0, s73
	ds_read_b128 v[184:187], v171 offset:32768
	ds_read_b128 v[188:191], v171 offset:33792
	ds_read_b128 v[192:195], v171 offset:34816
	ds_read_b128 v[196:199], v171 offset:35840
	ds_read_b128 v[214:217], v171 offset:36864
	ds_read_b128 v[218:221], v171 offset:37888
	ds_read_b128 v[222:225], v171 offset:38912
	ds_read_b128 v[226:229], v171 offset:39936
	global_load_lds_dwordx4 v146, s[54:55]
	s_mov_b32 m0, s74
	s_nop 0
	global_load_lds_dwordx4 v142, s[54:55]
	s_waitcnt vmcnt(8)
	s_waitcnt lgkmcnt(0)
	s_barrier


; #define PG8_MMA(ai, bj, At, Bt) do { __builtin_amdgcn_s_setprio(1); _Pragma("unroll") for (int m = 0; m < 4; ++m) _Pragma("unroll") for (int n = 0; n < 2; ++n) _Pragma("unroll") for (int k = 0; k < 2; ++k) \
;         acc[ai][bj][m][n] = __builtin_amdgcn_mfma_f32_16x16x32_bf16(Bt[n][k], At[m][k], acc[ai][bj][m][n], 0, 0, 0); __builtin_amdgcn_s_setprio(0); } while (0)
; #define PG8_WAIT_V(n) asm volatile("s_waitcnt vmcnt(" #n ")" ::: "memory")
; #define PG8_WAIT_L(n) asm volatile("s_waitcnt lgkmcnt(" #n ")" ::: "memory")
; #define PG8_BAR __builtin_amdgcn_s_barrier()
; #define PG8_SCHED __builtin_amdgcn_sched_barrier(0)
; template <class Epi, bool ALIGN_EPI>
; __device__ __forceinline__ void gemm_phase(LAS unsigned char* lds, const Gemm g, const StaticOrder& S, const Epi& E, const int tid) {
;     ...
;             PG8_WAIT_V(8); PG8_WAIT_L(0); PG8_BAR; PG8_MMA(0, 0, At, B0); PG8_MMA(0, 1, At, B1); PG8_BAR; PG8_SCHED;
	v_mfma_f32_16x16x32_bf16 v[128:131], v[132:135], v[184:187], v[128:131]
	v_mfma_f32_16x16x32_bf16 v[116:119], v[152:155], v[184:187], v[116:119]
	v_mfma_f32_16x16x32_bf16 v[124:127], v[132:135], v[192:195], v[124:127]
	v_mfma_f32_16x16x32_bf16 v[108:111], v[152:155], v[192:195], v[108:111]
	v_mfma_f32_16x16x32_bf16 v[120:123], v[132:135], v[214:217], v[120:123]
	v_mfma_f32_16x16x32_bf16 v[100:103], v[152:155], v[214:217], v[100:103]
	v_mfma_f32_16x16x32_bf16 v[112:115], v[132:135], v[222:225], v[112:115]
	v_mfma_f32_16x16x32_bf16 v[92:95], v[152:155], v[222:225], v[92:95]
	v_mfma_f32_16x16x32_bf16 v[128:131], v[136:139], v[188:191], v[128:131]
	v_mfma_f32_16x16x32_bf16 v[116:119], v[156:159], v[188:191], v[116:119]
	v_mfma_f32_16x16x32_bf16 v[124:127], v[136:139], v[196:199], v[124:127]
	v_mfma_f32_16x16x32_bf16 v[108:111], v[156:159], v[196:199], v[108:111]
	v_mfma_f32_16x16x32_bf16 v[120:123], v[136:139], v[218:221], v[120:123]
	v_mfma_f32_16x16x32_bf16 v[100:103], v[156:159], v[218:221], v[100:103]
	v_mfma_f32_16x16x32_bf16 v[112:115], v[136:139], v[226:229], v[112:115]
	v_mfma_f32_16x16x32_bf16 v[92:95], v[156:159], v[226:229], v[92:95]


; #define PG8_MMA(ai, bj, At, Bt) do { __builtin_amdgcn_s_setprio(1); _Pragma("unroll") for (int m = 0; m < 4; ++m) _Pragma("unroll") for (int n = 0; n < 2; ++n) _Pragma("unroll") for (int k = 0; k < 2; ++k) \
;         acc[ai][bj][m][n] = __builtin_amdgcn_mfma_f32_16x16x32_bf16(Bt[n][k], At[m][k], acc[ai][bj][m][n], 0, 0, 0); __builtin_amdgcn_s_setprio(0); } while (0)
; #define PG8_WAIT_V(n) asm volatile("s_waitcnt vmcnt(" #n ")" ::: "memory")
; #define PG8_WAIT_L(n) asm volatile("s_waitcnt lgkmcnt(" #n ")" ::: "memory")
; #define PG8_BAR __builtin_amdgcn_s_barrier()
; #define PG8_SCHED __builtin_amdgcn_sched_barrier(0)
; template <class Epi, bool ALIGN_EPI>
; __device__ __forceinline__ void gemm_phase(LAS unsigned char* lds, const Gemm g, const StaticOrder& S, const Epi& E, const int tid) {
;     ...
;             PG8_WAIT_V(8); PG8_WAIT_L(0); PG8_BAR; PG8_MMA(0, 0, At, B0); PG8_MMA(0, 1, At, B1); PG8_BAR; PG8_SCHED;
	v_mfma_f32_16x16x32_bf16 v[104:107], v[160:163], v[184:187], v[104:107]
	v_mfma_f32_16x16x32_bf16 v[80:83], v[176:179], v[184:187], v[80:83]
	v_mfma_f32_16x16x32_bf16 v[96:99], v[160:163], v[192:195], v[96:99]
	v_mfma_f32_16x16x32_bf16 v[68:71], v[176:179], v[192:195], v[68:71]
	v_mfma_f32_16x16x32_bf16 v[88:91], v[160:163], v[214:217], v[88:91]
	v_mfma_f32_16x16x32_bf16 v[60:63], v[176:179], v[214:217], v[60:63]
	v_mfma_f32_16x16x32_bf16 v[76:79], v[160:163], v[222:225], v[76:79]
	v_mfma_f32_16x16x32_bf16 v[48:51], v[176:179], v[222:225], v[48:51]
	v_mfma_f32_16x16x32_bf16 v[104:107], v[172:175], v[188:191], v[104:107]
	v_mfma_f32_16x16x32_bf16 v[80:83], v[180:183], v[188:191], v[80:83]
	v_mfma_f32_16x16x32_bf16 v[96:99], v[172:175], v[196:199], v[96:99]
	v_mfma_f32_16x16x32_bf16 v[68:71], v[180:183], v[196:199], v[68:71]
	v_mfma_f32_16x16x32_bf16 v[88:91], v[172:175], v[218:221], v[88:91]
	v_mfma_f32_16x16x32_bf16 v[60:63], v[180:183], v[218:221], v[60:63]
	v_mfma_f32_16x16x32_bf16 v[76:79], v[172:175], v[226:229], v[76:79]
	v_mfma_f32_16x16x32_bf16 v[48:51], v[180:183], v[226:229], v[48:51]

; #define PG8_STAGE(bufoff, gbase, voff) do { _Pragma("unroll") for (int _i = 0; _i < 2; ++_i) \
;         __builtin_amdgcn_global_load_lds((const unsigned*)((const char*)(gbase) + (voff)[_i]), (LAS unsigned*)(lds + (bufoff) + ldsw + _i * 8192), 16, 0, 0); } while (0)
; #define PG8_LDA(dst, b, h) do { _Pragma("unroll") for (int m = 0; m < 4; ++m) _Pragma("unroll") for (int k = 0; k < 2; ++k) dst[m][k] = *(const LAS bf16x8*)(lds + PG8_SA(b, h) + aoff + m * 2048 + k * 1024); } while (0)
; #define PG8_MMA(ai, bj, At, Bt) do { __builtin_amdgcn_s_setprio(1); _Pragma("unroll") for (int m = 0; m < 4; ++m) _Pragma("unroll") for (int n = 0; n < 2; ++n) _Pragma("unroll") for (int k = 0; k < 2; ++k) \
;         acc[ai][bj][m][n] = __builtin_amdgcn_mfma_f32_16x16x32_bf16(Bt[n][k], At[m][k], acc[ai][bj][m][n], 0, 0, 0); __builtin_amdgcn_s_setprio(0); } while (0)
; #define PG8_WAIT_V(n) asm volatile("s_waitcnt vmcnt(" #n ")" ::: "memory")
; #define PG8_WAIT_L(n) asm volatile("s_waitcnt lgkmcnt(" #n ")" ::: "memory")
; #define PG8_BAR __builtin_amdgcn_s_barrier()
; #define PG8_SCHED __builtin_amdgcn_sched_barrier(0)
; template <class Epi, bool ALIGN_EPI>
; __device__ __forceinline__ void gemm_phase(LAS unsigned char* lds, const Gemm g, const StaticOrder& S, const Epi& E, const int tid) {
;     ...
;             PG8_LDA(At, 1, 1); PG8_STAGE(PG8_SB(1, 0), b3, voffB); PG8_STAGE(PG8_SB(1, 1), b3 + hstepB, voffB); PG8_STAGE(PG8_SA(1, 0), a3, voffA);
;             PG8_WAIT_V(8); PG8_WAIT_L(0); PG8_BAR; PG8_MMA(1, 0, At, B0); PG8_MMA(1, 1, At, B1); PG8_BAR; PG8_SCHED;
	s_barrier
	s_add_u32 s54, s52, 0x8000
	s_addc_u32 s55, s53, 0
	s_add_i32 s89, s89, s61
	s_mov_b32 m0, s89
	ds_read_b128 v[184:187], v171 offset:49152
	ds_read_b128 v[188:191], v171 offset:50176
	ds_read_b128 v[192:195], v171 offset:51200
	ds_read_b128 v[196:199], v171 offset:52224
	ds_read_b128 v[214:217], v171 offset:53248
	ds_read_b128 v[218:221], v171 offset:54272
	ds_read_b128 v[222:225], v171 offset:55296
	ds_read_b128 v[226:229], v171 offset:56320
	global_load_lds_dwordx4 v144, s[54:55]
	s_add_i32 m0, s89, 0x2000
	s_add_u32 s52, s52, 0xc000
	s_addc_u32 s53, s53, 0
	global_load_lds_dwordx4 v140, s[54:55]
	s_add_i32 s54, s90, s61
	s_mov_b32 m0, s54
	s_nop 0
	global_load_lds_dwordx4 v144, s[52:53]
	s_add_i32 m0, s54, 0x2000
	s_nop 0
	global_load_lds_dwordx4 v140, s[52:53]
	s_mov_b32 m0, s77
	s_nop 0
	global_load_lds_dwordx4 v146, s[50:51]
	s_mov_b32 m0, s78
	s_nop 0
	global_load_lds_dwordx4 v142, s[50:51]
	s_waitcnt vmcnt(8)
	s_waitcnt lgkmcnt(0)
	s_barrier


; #define PG8_MMA(ai, bj, At, Bt) do { __builtin_amdgcn_s_setprio(1); _Pragma("unroll") for (int m = 0; m < 4; ++m) _Pragma("unroll") for (int n = 0; n < 2; ++n) _Pragma("unroll") for (int k = 0; k < 2; ++k) \
;         acc[ai][bj][m][n] = __builtin_amdgcn_mfma_f32_16x16x32_bf16(Bt[n][k], At[m][k], acc[ai][bj][m][n], 0, 0, 0); __builtin_amdgcn_s_setprio(0); } while (0)
; #define PG8_WAIT_V(n) asm volatile("s_waitcnt vmcnt(" #n ")" ::: "memory")
; #define PG8_WAIT_L(n) asm volatile("s_waitcnt lgkmcnt(" #n ")" ::: "memory")
; #define PG8_BAR __builtin_amdgcn_s_barrier()
; #define PG8_SCHED __builtin_amdgcn_sched_barrier(0)
; template <class Epi, bool ALIGN_EPI>
; __device__ __forceinline__ void gemm_phase(LAS unsigned char* lds, const Gemm g, const StaticOrder& S, const Epi& E, const int tid) {
;     ...
;             PG8_WAIT_V(8); PG8_WAIT_L(0); PG8_BAR; PG8_MMA(1, 0, At, B0); PG8_MMA(1, 1, At, B1); PG8_BAR; PG8_SCHED;
	v_mfma_f32_16x16x32_bf16 v[84:87], v[132:135], v[184:187], v[84:87]
	v_mfma_f32_16x16x32_bf16 v[56:59], v[152:155], v[184:187], v[56:59]
	v_mfma_f32_16x16x32_bf16 v[72:75], v[132:135], v[192:195], v[72:75]
	v_mfma_f32_16x16x32_bf16 v[44:47], v[152:155], v[192:195], v[44:47]
	v_mfma_f32_16x16x32_bf16 v[64:67], v[132:135], v[214:217], v[64:67]
	v_mfma_f32_16x16x32_bf16 v[36:39], v[152:155], v[214:217], v[36:39]
	v_mfma_f32_16x16x32_bf16 v[52:55], v[132:135], v[222:225], v[52:55]
	v_mfma_f32_16x16x32_bf16 v[28:31], v[152:155], v[222:225], v[28:31]
	v_mfma_f32_16x16x32_bf16 v[84:87], v[136:139], v[188:191], v[84:87]
	v_mfma_f32_16x16x32_bf16 v[56:59], v[156:159], v[188:191], v[56:59]
	v_mfma_f32_16x16x32_bf16 v[72:75], v[136:139], v[196:199], v[72:75]
	v_mfma_f32_16x16x32_bf16 v[44:47], v[156:159], v[196:199], v[44:47]
	v_mfma_f32_16x16x32_bf16 v[64:67], v[136:139], v[218:221], v[64:67]
	v_mfma_f32_16x16x32_bf16 v[36:39], v[156:159], v[218:221], v[36:39]
	v_mfma_f32_16x16x32_bf16 v[52:55], v[136:139], v[226:229], v[52:55]
	v_mfma_f32_16x16x32_bf16 v[28:31], v[156:159], v[226:229], v[28:31]


; #define PG8_MMA(ai, bj, At, Bt) do { __builtin_amdgcn_s_setprio(1); _Pragma("unroll") for (int m = 0; m < 4; ++m) _Pragma("unroll") for (int n = 0; n < 2; ++n) _Pragma("unroll") for (int k = 0; k < 2; ++k) \
;         acc[ai][bj][m][n] = __builtin_amdgcn_mfma_f32_16x16x32_bf16(Bt[n][k], At[m][k], acc[ai][bj][m][n], 0, 0, 0); __builtin_amdgcn_s_setprio(0); } while (0)
; #define PG8_WAIT_V(n) asm volatile("s_waitcnt vmcnt(" #n ")" ::: "memory")
; #define PG8_WAIT_L(n) asm volatile("s_waitcnt lgkmcnt(" #n ")" ::: "memory")
; #define PG8_BAR __builtin_amdgcn_s_barrier()
; #define PG8_SCHED __builtin_amdgcn_sched_barrier(0)
; template <class Epi, bool ALIGN_EPI>
; __device__ __forceinline__ void gemm_phase(LAS unsigned char* lds, const Gemm g, const StaticOrder& S, const Epi& E, const int tid) {
;     ...
;             PG8_WAIT_V(8); PG8_WAIT_L(0); PG8_BAR; PG8_MMA(1, 0, At, B0); PG8_MMA(1, 1, At, B1); PG8_BAR; PG8_SCHED;
	v_mfma_f32_16x16x32_bf16 v[40:43], v[160:163], v[184:187], v[40:43]
	v_mfma_f32_16x16x32_bf16 v[20:23], v[176:179], v[184:187], v[20:23]
	v_mfma_f32_16x16x32_bf16 v[32:35], v[160:163], v[192:195], v[32:35]
	v_mfma_f32_16x16x32_bf16 v[12:15], v[176:179], v[192:195], v[12:15]
	v_mfma_f32_16x16x32_bf16 v[24:27], v[160:163], v[214:217], v[24:27]
	v_mfma_f32_16x16x32_bf16 v[6:9], v[176:179], v[214:217], v[8:11]
	v_mfma_f32_16x16x32_bf16 v[16:19], v[160:163], v[222:225], v[16:19]
	v_mfma_f32_16x16x32_bf16 v[2:5], v[176:179], v[222:225], v[2:5]
	v_mfma_f32_16x16x32_bf16 v[40:43], v[172:175], v[188:191], v[40:43]
	v_mfma_f32_16x16x32_bf16 v[20:23], v[180:183], v[188:191], v[20:23]
	v_mfma_f32_16x16x32_bf16 v[32:35], v[172:175], v[196:199], v[32:35]
	v_mfma_f32_16x16x32_bf16 v[12:15], v[180:183], v[196:199], v[12:15]
	v_mfma_f32_16x16x32_bf16 v[24:27], v[172:175], v[218:221], v[24:27]
	v_mfma_f32_16x16x32_bf16 v[8:11], v[180:183], v[218:221], v[6:9]
	v_mfma_f32_16x16x32_bf16 v[16:19], v[172:175], v[226:229], v[16:19]
	v_mfma_f32_16x16x32_bf16 v[4:7], v[180:183], v[226:229], v[2:5]

; #define PG8_MMA(ai, bj, At, Bt) do { __builtin_amdgcn_s_setprio(1); _Pragma("unroll") for (int m = 0; m < 4; ++m) _Pragma("unroll") for (int n = 0; n < 2; ++n) _Pragma("unroll") for (int k = 0; k < 2; ++k) \
;         acc[ai][bj][m][n] = __builtin_amdgcn_mfma_f32_16x16x32_bf16(Bt[n][k], At[m][k], acc[ai][bj][m][n], 0, 0, 0); __builtin_amdgcn_s_setprio(0); } while (0)
; #define PG8_WAIT_V(n) asm volatile("s_waitcnt vmcnt(" #n ")" ::: "memory")
; #define PG8_WAIT_L(n) asm volatile("s_waitcnt lgkmcnt(" #n ")" ::: "memory")
; #define PG8_BAR __builtin_amdgcn_s_barrier()
; #define PG8_SCHED __builtin_amdgcn_sched_barrier(0)
; template <class Epi, bool ALIGN_EPI>
; __device__ __forceinline__ void gemm_phase(LAS unsigned char* lds, const Gemm g, const StaticOrder& S, const Epi& E, const int tid) {
;     ...
;             PG8_WAIT_V(8); PG8_WAIT_L(0); PG8_BAR; PG8_MMA(1, 0, At, B0); PG8_MMA(1, 1, At, B1); PG8_BAR; PG8_SCHED;
;         }
;         if constexpr (ALIGN_EPI) { if (wr == 0) PG8_BAR; }
	s_barrier
	s_add_i32 s88, s88, 2
	s_add_u32 s48, s48, 0x10000
	s_addc_u32 s49, s49, 0
	s_add_u32 s86, s86, 0x10000
	s_addc_u32 s87, s87, 0
	s_cmp_gt_u32 s88, 29
	s_cbranch_scc0 .LBB0_385
	s_and_b64 vcc, exec, s[34:35]
	s_cbranch_vccz .LBB0_388
	s_barrier

; #define PG8_STAGE(bufoff, gbase, voff) do { _Pragma("unroll") for (int _i = 0; _i < 2; ++_i) \
;         __builtin_amdgcn_global_load_lds((const unsigned*)((const char*)(gbase) + (voff)[_i]), (LAS unsigned*)(lds + (bufoff) + ldsw + _i * 8192), 16, 0, 0); } while (0)
; #define PG8_LDA(dst, b, h) do { _Pragma("unroll") for (int m = 0; m < 4; ++m) _Pragma("unroll") for (int k = 0; k < 2; ++k) dst[m][k] = *(const LAS bf16x8*)(lds + PG8_SA(b, h) + aoff + m * 2048 + k * 1024); } while (0)
; #define PG8_LDB(dst, b, h) do { _Pragma("unroll") for (int n = 0; n < 2; ++n) _Pragma("unroll") for (int k = 0; k < 2; ++k) dst[n][k] = *(const LAS bf16x8*)(lds + PG8_SB(b, h) + boff + n * 2048 + k * 1024); } while (0)
; #define PG8_MMA(ai, bj, At, Bt) do { __builtin_amdgcn_s_setprio(1); _Pragma("unroll") for (int m = 0; m < 4; ++m) _Pragma("unroll") for (int n = 0; n < 2; ++n) _Pragma("unroll") for (int k = 0; k < 2; ++k) \
;         acc[ai][bj][m][n] = __builtin_amdgcn_mfma_f32_16x16x32_bf16(Bt[n][k], At[m][k], acc[ai][bj][m][n], 0, 0, 0); __builtin_amdgcn_s_setprio(0); } while (0)
; #define PG8_WAIT_V(n) asm volatile("s_waitcnt vmcnt(" #n ")" ::: "memory")
; #define PG8_WAIT_L(n) asm volatile("s_waitcnt lgkmcnt(" #n ")" ::: "memory")
; #define PG8_BAR __builtin_amdgcn_s_barrier()
; #define PG8_SCHED __builtin_amdgcn_sched_barrier(0)
; template <class Epi, bool ALIGN_EPI>
; __device__ __forceinline__ void gemm_phase(LAS unsigned char* lds, const Gemm g, const StaticOrder& S, const Epi& E, const int tid) {
;     ...
;         const bool has_next = S.next(ui + 1, nxt);
;         const char* nA = has_next ? (const char*)g.A + (size_t)nxt.pm * tstepA + (size_t)nxt.pn * g.acs : cA; const char* nB = has_next ? (const char*)g.Bt + (size_t)nxt.pn * tstepB : cB;
;         for (int t = 0; t < nt; t += 2) {
;             const bool last = (t == nt - 2);
;             const char* a1 = cA + (size_t)(t + 1) * kstepA;
;             const char* a2 = last ? nA : cA + (size_t)(t + 2) * kstepA; const char* b2 = last ? nB : cB + (size_t)(t + 2) * kstepB;
;             const char* a3 = a2 + kstepA; const char* b3 = b2 + kstepB;
;             PG8_LDB(B0, 0, 0); PG8_LDB(B1, 0, 1); PG8_SCHED; PG8_LDA(At, 0, 0); PG8_STAGE(PG8_SA(1, 1), a1 + hstepA, voffA);
;             PG8_WAIT_V(8); PG8_WAIT_L(0); PG8_BAR; PG8_MMA(0, 0, At, B0); PG8_MMA(0, 1, At, B1); PG8_BAR; PG8_SCHED;
.LBB0_717:
	s_ashr_i32 s45, s44, 31
	s_lshl_b64 s[46:47], s[44:45], 19
	s_add_u32 s45, s30, s46
	s_addc_u32 s48, s60, s47
	s_ashr_i32 s43, s42, 31
	s_lshl_b64 s[46:47], s[42:43], 9
	s_add_u32 s46, s45, s46
	s_addc_u32 s47, s48, s47
	s_and_b64 s[48:49], s[38:39], exec
	s_cselect_b32 s57, s47, s51
	s_cselect_b32 s56, s46, s50
	s_lshl_b64 s[48:49], s[42:43], 17
	s_add_u32 s48, s61, s48
	s_addc_u32 s49, s71, s49
	s_and_b64 s[54:55], s[38:39], exec
	s_cselect_b32 s55, s49, s53
	s_cselect_b32 s54, s48, s52
	s_add_i32 s45, 0, 0x10000
	s_add_i32 s83, 0, 0x14000
	v_add_u32_e32 v222, s45, v170
	v_add_u32_e32 v223, s83, v170
	ds_read_b128 v[130:133], v222
	ds_read_b128 v[134:137], v222 offset:1024
	ds_read_b128 v[138:141], v222 offset:2048
	ds_read_b128 v[142:145], v222 offset:3072
	ds_read_b128 v[146:149], v223
	ds_read_b128 v[150:153], v223 offset:1024
	ds_read_b128 v[154:157], v223 offset:2048
	ds_read_b128 v[164:167], v223 offset:3072
	s_add_u32 s84, s50, 0x40080
	s_addc_u32 s85, s51, 0
	s_add_i32 s87, s73, 0xc000
	v_lshl_add_u64 v[168:169], s[84:85], 0, v[162:163]
	s_mov_b32 m0, s87
	s_add_i32 s43, s73, 0xe000
	ds_read_b128 v[172:175], v171
	ds_read_b128 v[176:179], v171 offset:1024
	ds_read_b128 v[180:183], v171 offset:2048
	ds_read_b128 v[184:187], v171 offset:3072
	ds_read_b128 v[188:191], v171 offset:4096
	ds_read_b128 v[192:195], v171 offset:5120
	ds_read_b128 v[196:199], v171 offset:6144
	ds_read_b128 v[214:217], v171 offset:7168
	global_load_lds_dwordx4 v[168:169], off
	v_lshl_add_u64 v[168:169], s[84:85], 0, v[160:161]
	s_mov_b32 m0, s43
	s_nop 0
	global_load_lds_dwordx4 v[168:169], off
	s_waitcnt vmcnt(8)
	s_waitcnt lgkmcnt(0)
	s_barrier

; #define PG8_MMA(ai, bj, At, Bt) do { __builtin_amdgcn_s_setprio(1); _Pragma("unroll") for (int m = 0; m < 4; ++m) _Pragma("unroll") for (int n = 0; n < 2; ++n) _Pragma("unroll") for (int k = 0; k < 2; ++k) \
;         acc[ai][bj][m][n] = __builtin_amdgcn_mfma_f32_16x16x32_bf16(Bt[n][k], At[m][k], acc[ai][bj][m][n], 0, 0, 0); __builtin_amdgcn_s_setprio(0); } while (0)
; #define PG8_WAIT_V(n) asm volatile("s_waitcnt vmcnt(" #n ")" ::: "memory")
; #define PG8_WAIT_L(n) asm volatile("s_waitcnt lgkmcnt(" #n ")" ::: "memory")
; #define PG8_BAR __builtin_amdgcn_s_barrier()
; #define PG8_SCHED __builtin_amdgcn_sched_barrier(0)
; template <class Epi, bool ALIGN_EPI>
; __device__ __forceinline__ void gemm_phase(LAS unsigned char* lds, const Gemm g, const StaticOrder& S, const Epi& E, const int tid) {
;     ...
;             PG8_WAIT_V(8); PG8_WAIT_L(0); PG8_BAR; PG8_MMA(0, 0, At, B0); PG8_MMA(0, 1, At, B1); PG8_BAR; PG8_SCHED;
	s_waitcnt lgkmcnt(0)
	v_mfma_f32_16x16x32_bf16 v[30:33], v[130:133], v[180:183], v[30:33]
	v_mfma_f32_16x16x32_bf16 v[26:29], v[138:141], v[180:183], v[26:29]
	v_mfma_f32_16x16x32_bf16 v[42:45], v[130:133], v[188:191], v[42:45]
	v_mfma_f32_16x16x32_bf16 v[34:37], v[138:141], v[188:191], v[34:37]
	v_mfma_f32_16x16x32_bf16 v[70:73], v[130:133], v[196:199], v[70:73]
	v_mfma_f32_16x16x32_bf16 v[78:81], v[138:141], v[196:199], v[78:81]
	v_mfma_f32_16x16x32_bf16 v[14:17], v[130:133], v[172:175], v[14:17]
	v_mfma_f32_16x16x32_bf16 v[10:13], v[138:141], v[172:175], v[10:13]
	v_mfma_f32_16x16x32_bf16 v[30:33], v[134:137], v[184:187], v[30:33]
	v_mfma_f32_16x16x32_bf16 v[26:29], v[142:145], v[184:187], v[26:29]
	v_mfma_f32_16x16x32_bf16 v[42:45], v[134:137], v[192:195], v[42:45]
	v_mfma_f32_16x16x32_bf16 v[34:37], v[142:145], v[192:195], v[34:37]
	v_mfma_f32_16x16x32_bf16 v[70:73], v[134:137], v[214:217], v[70:73]
	v_mfma_f32_16x16x32_bf16 v[78:81], v[142:145], v[214:217], v[78:81]
	v_mfma_f32_16x16x32_bf16 v[14:17], v[134:137], v[176:179], v[14:17]
	v_mfma_f32_16x16x32_bf16 v[10:13], v[142:145], v[176:179], v[10:13]


; #define PG8_MMA(ai, bj, At, Bt) do { __builtin_amdgcn_s_setprio(1); _Pragma("unroll") for (int m = 0; m < 4; ++m) _Pragma("unroll") for (int n = 0; n < 2; ++n) _Pragma("unroll") for (int k = 0; k < 2; ++k) \
;         acc[ai][bj][m][n] = __builtin_amdgcn_mfma_f32_16x16x32_bf16(Bt[n][k], At[m][k], acc[ai][bj][m][n], 0, 0, 0); __builtin_amdgcn_s_setprio(0); } while (0)
; #define PG8_WAIT_V(n) asm volatile("s_waitcnt vmcnt(" #n ")" ::: "memory")
; #define PG8_WAIT_L(n) asm volatile("s_waitcnt lgkmcnt(" #n ")" ::: "memory")
; #define PG8_BAR __builtin_amdgcn_s_barrier()
; #define PG8_SCHED __builtin_amdgcn_sched_barrier(0)
; template <class Epi, bool ALIGN_EPI>
; __device__ __forceinline__ void gemm_phase(LAS unsigned char* lds, const Gemm g, const StaticOrder& S, const Epi& E, const int tid) {
;     ...
;             PG8_WAIT_V(8); PG8_WAIT_L(0); PG8_BAR; PG8_MMA(0, 0, At, B0); PG8_MMA(0, 1, At, B1); PG8_BAR; PG8_SCHED;
	v_mfma_f32_16x16x32_bf16 v[6:9], v[146:149], v[172:175], v[6:9]
	v_mfma_f32_16x16x32_bf16 v[2:5], v[154:157], v[172:175], v[2:5]
	v_mfma_f32_16x16x32_bf16 v[22:25], v[146:149], v[180:183], v[22:25]
	v_mfma_f32_16x16x32_bf16 v[18:21], v[154:157], v[180:183], v[18:21]
	v_mfma_f32_16x16x32_bf16 v[38:41], v[146:149], v[188:191], v[38:41]
	v_mfma_f32_16x16x32_bf16 v[46:49], v[154:157], v[188:191], v[46:49]
	v_mfma_f32_16x16x32_bf16 v[62:65], v[146:149], v[196:199], v[62:65]
	v_mfma_f32_16x16x32_bf16 v[74:77], v[154:157], v[196:199], v[74:77]
	v_mfma_f32_16x16x32_bf16 v[6:9], v[150:153], v[176:179], v[6:9]
	v_mfma_f32_16x16x32_bf16 v[2:5], v[164:167], v[176:179], v[2:5]
	v_mfma_f32_16x16x32_bf16 v[22:25], v[150:153], v[184:187], v[22:25]
	v_mfma_f32_16x16x32_bf16 v[18:21], v[164:167], v[184:187], v[18:21]
	v_mfma_f32_16x16x32_bf16 v[38:41], v[150:153], v[192:195], v[38:41]
	v_mfma_f32_16x16x32_bf16 v[46:49], v[164:167], v[192:195], v[46:49]
	v_mfma_f32_16x16x32_bf16 v[62:65], v[150:153], v[214:217], v[62:65]
	v_mfma_f32_16x16x32_bf16 v[74:77], v[164:167], v[214:217], v[74:77]

; #define PG8_STAGE(bufoff, gbase, voff) do { _Pragma("unroll") for (int _i = 0; _i < 2; ++_i) \
;         __builtin_amdgcn_global_load_lds((const unsigned*)((const char*)(gbase) + (voff)[_i]), (LAS unsigned*)(lds + (bufoff) + ldsw + _i * 8192), 16, 0, 0); } while (0)
; #define PG8_LDA(dst, b, h) do { _Pragma("unroll") for (int m = 0; m < 4; ++m) _Pragma("unroll") for (int k = 0; k < 2; ++k) dst[m][k] = *(const LAS bf16x8*)(lds + PG8_SA(b, h) + aoff + m * 2048 + k * 1024); } while (0)
; #define PG8_MMA(ai, bj, At, Bt) do { __builtin_amdgcn_s_setprio(1); _Pragma("unroll") for (int m = 0; m < 4; ++m) _Pragma("unroll") for (int n = 0; n < 2; ++n) _Pragma("unroll") for (int k = 0; k < 2; ++k) \
;         acc[ai][bj][m][n] = __builtin_amdgcn_mfma_f32_16x16x32_bf16(Bt[n][k], At[m][k], acc[ai][bj][m][n], 0, 0, 0); __builtin_amdgcn_s_setprio(0); } while (0)
; #define PG8_WAIT_V(n) asm volatile("s_waitcnt vmcnt(" #n ")" ::: "memory")
; #define PG8_WAIT_L(n) asm volatile("s_waitcnt lgkmcnt(" #n ")" ::: "memory")
; #define PG8_BAR __builtin_amdgcn_s_barrier()
; #define PG8_SCHED __builtin_amdgcn_sched_barrier(0)
; template <class Epi, bool ALIGN_EPI>
; __device__ __forceinline__ void gemm_phase(LAS unsigned char* lds, const Gemm g, const StaticOrder& S, const Epi& E, const int tid) {
;     ...
;             PG8_WAIT_V(8); PG8_WAIT_L(0); PG8_BAR; PG8_MMA(0, 0, At, B0); PG8_MMA(0, 1, At, B1); PG8_BAR; PG8_SCHED;
;             PG8_LDA(At, 0, 1); PG8_STAGE(PG8_SB(0, 0), b2, voffB); PG8_STAGE(PG8_SB(0, 1), b2 + hstepB, voffB); PG8_STAGE(PG8_SA(0, 0), a2, voffA);
;             PG8_WAIT_V(8); PG8_WAIT_L(0); PG8_BAR; PG8_MMA(1, 0, At, B0); PG8_MMA(1, 1, At, B1); PG8_BAR; PG8_SCHED;
	s_barrier
	v_lshl_add_u64 v[168:169], s[52:53], 0, v[0:1]
	s_mov_b64 s[90:91], 0x100
	s_add_i32 s85, s45, s72
	v_lshl_add_u64 v[200:201], v[168:169], 0, s[90:91]
	s_mov_b32 m0, s85
	s_add_i32 s45, s85, 0x2000
	ds_read_b128 v[172:175], v171 offset:16384
	ds_read_b128 v[176:179], v171 offset:17408
	ds_read_b128 v[180:183], v171 offset:18432
	ds_read_b128 v[184:187], v171 offset:19456
	ds_read_b128 v[188:191], v171 offset:20480
	ds_read_b128 v[192:195], v171 offset:21504
	ds_read_b128 v[196:199], v171 offset:22528
	ds_read_b128 v[214:217], v171 offset:23552
	global_load_lds_dwordx4 v[200:201], off
	v_lshl_add_u64 v[200:201], s[52:53], 0, v[158:159]
	s_add_u32 s88, s52, 0x10100
	v_lshl_add_u64 v[210:211], v[200:201], 0, s[90:91]
	s_mov_b32 m0, s45
	s_addc_u32 s89, s53, 0
	s_add_i32 s83, s83, s72
	global_load_lds_dwordx4 v[210:211], off
	v_lshl_add_u64 v[210:211], s[88:89], 0, v[0:1]
	s_mov_b32 m0, s83
	s_add_i32 s84, s83, 0x2000
	global_load_lds_dwordx4 v[210:211], off
	v_lshl_add_u64 v[210:211], s[88:89], 0, v[158:159]
	s_mov_b32 m0, s84
	s_nop 0
	global_load_lds_dwordx4 v[210:211], off
	v_lshl_add_u64 v[210:211], s[50:51], 0, v[162:163]
	v_lshl_add_u64 v[218:219], v[210:211], 0, s[90:91]
	s_mov_b32 m0, s73
	s_nop 0
	global_load_lds_dwordx4 v[218:219], off
	v_lshl_add_u64 v[218:219], s[50:51], 0, v[160:161]
	v_lshl_add_u64 v[220:221], v[218:219], 0, s[90:91]
	s_mov_b32 m0, s74
	s_nop 0
	global_load_lds_dwordx4 v[220:221], off
	s_waitcnt vmcnt(8)
	s_waitcnt lgkmcnt(0)
	s_barrier

; #define PG8_MMA(ai, bj, At, Bt) do { __builtin_amdgcn_s_setprio(1); _Pragma("unroll") for (int m = 0; m < 4; ++m) _Pragma("unroll") for (int n = 0; n < 2; ++n) _Pragma("unroll") for (int k = 0; k < 2; ++k) \
;         acc[ai][bj][m][n] = __builtin_amdgcn_mfma_f32_16x16x32_bf16(Bt[n][k], At[m][k], acc[ai][bj][m][n], 0, 0, 0); __builtin_amdgcn_s_setprio(0); } while (0)
; #define PG8_WAIT_V(n) asm volatile("s_waitcnt vmcnt(" #n ")" ::: "memory")
; #define PG8_WAIT_L(n) asm volatile("s_waitcnt lgkmcnt(" #n ")" ::: "memory")
; #define PG8_BAR __builtin_amdgcn_s_barrier()
; #define PG8_SCHED __builtin_amdgcn_sched_barrier(0)
; template <class Epi, bool ALIGN_EPI>
; __device__ __forceinline__ void gemm_phase(LAS unsigned char* lds, const Gemm g, const StaticOrder& S, const Epi& E, const int tid) {
;     ...
;             PG8_WAIT_V(8); PG8_WAIT_L(0); PG8_BAR; PG8_MMA(1, 0, At, B0); PG8_MMA(1, 1, At, B1); PG8_BAR; PG8_SCHED;
	s_waitcnt lgkmcnt(0)
	v_mfma_f32_16x16x32_bf16 v[50:53], v[130:133], v[172:175], v[50:53]
	v_mfma_f32_16x16x32_bf16 v[58:61], v[138:141], v[172:175], v[58:61]
	v_mfma_f32_16x16x32_bf16 v[82:85], v[130:133], v[180:183], v[82:85]
	v_mfma_f32_16x16x32_bf16 v[90:93], v[138:141], v[180:183], v[90:93]
	v_mfma_f32_16x16x32_bf16 v[98:101], v[130:133], v[188:191], v[98:101]
	v_mfma_f32_16x16x32_bf16 v[106:109], v[138:141], v[188:191], v[106:109]
	v_mfma_f32_16x16x32_bf16 v[118:121], v[130:133], v[196:199], v[118:121]
	v_mfma_f32_16x16x32_bf16 v[126:129], v[138:141], v[196:199], v[126:129]
	v_mfma_f32_16x16x32_bf16 v[50:53], v[134:137], v[176:179], v[50:53]
	v_mfma_f32_16x16x32_bf16 v[58:61], v[142:145], v[176:179], v[58:61]
	v_mfma_f32_16x16x32_bf16 v[82:85], v[134:137], v[184:187], v[82:85]
	v_mfma_f32_16x16x32_bf16 v[90:93], v[142:145], v[184:187], v[90:93]
	v_mfma_f32_16x16x32_bf16 v[98:101], v[134:137], v[192:195], v[98:101]
	v_mfma_f32_16x16x32_bf16 v[106:109], v[142:145], v[192:195], v[106:109]
	v_mfma_f32_16x16x32_bf16 v[118:121], v[134:137], v[214:217], v[118:121]
	v_mfma_f32_16x16x32_bf16 v[126:129], v[142:145], v[214:217], v[126:129]


; #define PG8_MMA(ai, bj, At, Bt) do { __builtin_amdgcn_s_setprio(1); _Pragma("unroll") for (int m = 0; m < 4; ++m) _Pragma("unroll") for (int n = 0; n < 2; ++n) _Pragma("unroll") for (int k = 0; k < 2; ++k) \
;         acc[ai][bj][m][n] = __builtin_amdgcn_mfma_f32_16x16x32_bf16(Bt[n][k], At[m][k], acc[ai][bj][m][n], 0, 0, 0); __builtin_amdgcn_s_setprio(0); } while (0)
; #define PG8_WAIT_V(n) asm volatile("s_waitcnt vmcnt(" #n ")" ::: "memory")
; #define PG8_WAIT_L(n) asm volatile("s_waitcnt lgkmcnt(" #n ")" ::: "memory")
; #define PG8_BAR __builtin_amdgcn_s_barrier()
; #define PG8_SCHED __builtin_amdgcn_sched_barrier(0)
; template <class Epi, bool ALIGN_EPI>
; __device__ __forceinline__ void gemm_phase(LAS unsigned char* lds, const Gemm g, const StaticOrder& S, const Epi& E, const int tid) {
;     ...
;             PG8_WAIT_V(8); PG8_WAIT_L(0); PG8_BAR; PG8_MMA(1, 0, At, B0); PG8_MMA(1, 1, At, B1); PG8_BAR; PG8_SCHED;
	v_mfma_f32_16x16x32_bf16 v[54:57], v[146:149], v[172:175], v[54:57]
	v_mfma_f32_16x16x32_bf16 v[66:69], v[154:157], v[172:175], v[66:69]
	v_mfma_f32_16x16x32_bf16 v[86:89], v[146:149], v[180:183], v[86:89]
	v_mfma_f32_16x16x32_bf16 v[94:97], v[154:157], v[180:183], v[94:97]
	v_mfma_f32_16x16x32_bf16 v[102:105], v[146:149], v[188:191], v[102:105]
	v_mfma_f32_16x16x32_bf16 v[110:113], v[154:157], v[188:191], v[110:113]
	v_mfma_f32_16x16x32_bf16 v[122:125], v[146:149], v[196:199], v[122:125]
	v_mfma_f32_16x16x32_bf16 v[114:117], v[154:157], v[196:199], v[114:117]
	v_mfma_f32_16x16x32_bf16 v[54:57], v[150:153], v[176:179], v[54:57]
	v_mfma_f32_16x16x32_bf16 v[66:69], v[164:167], v[176:179], v[66:69]
	v_mfma_f32_16x16x32_bf16 v[86:89], v[150:153], v[184:187], v[86:89]
	v_mfma_f32_16x16x32_bf16 v[94:97], v[164:167], v[184:187], v[94:97]
	v_mfma_f32_16x16x32_bf16 v[102:105], v[150:153], v[192:195], v[102:105]
	v_mfma_f32_16x16x32_bf16 v[110:113], v[164:167], v[192:195], v[110:113]
	v_mfma_f32_16x16x32_bf16 v[122:125], v[150:153], v[214:217], v[122:125]
	v_mfma_f32_16x16x32_bf16 v[114:117], v[164:167], v[214:217], v[114:117]

; #define PG8_STAGE(bufoff, gbase, voff) do { _Pragma("unroll") for (int _i = 0; _i < 2; ++_i) \
;         __builtin_amdgcn_global_load_lds((const unsigned*)((const char*)(gbase) + (voff)[_i]), (LAS unsigned*)(lds + (bufoff) + ldsw + _i * 8192), 16, 0, 0); } while (0)
; #define PG8_LDA(dst, b, h) do { _Pragma("unroll") for (int m = 0; m < 4; ++m) _Pragma("unroll") for (int k = 0; k < 2; ++k) dst[m][k] = *(const LAS bf16x8*)(lds + PG8_SA(b, h) + aoff + m * 2048 + k * 1024); } while (0)
; #define PG8_LDB(dst, b, h) do { _Pragma("unroll") for (int n = 0; n < 2; ++n) _Pragma("unroll") for (int k = 0; k < 2; ++k) dst[n][k] = *(const LAS bf16x8*)(lds + PG8_SB(b, h) + boff + n * 2048 + k * 1024); } while (0)
; #define PG8_MMA(ai, bj, At, Bt) do { __builtin_amdgcn_s_setprio(1); _Pragma("unroll") for (int m = 0; m < 4; ++m) _Pragma("unroll") for (int n = 0; n < 2; ++n) _Pragma("unroll") for (int k = 0; k < 2; ++k) \
;         acc[ai][bj][m][n] = __builtin_amdgcn_mfma_f32_16x16x32_bf16(Bt[n][k], At[m][k], acc[ai][bj][m][n], 0, 0, 0); __builtin_amdgcn_s_setprio(0); } while (0)
; #define PG8_WAIT_V(n) asm volatile("s_waitcnt vmcnt(" #n ")" ::: "memory")
; #define PG8_WAIT_L(n) asm volatile("s_waitcnt lgkmcnt(" #n ")" ::: "memory")
; #define PG8_BAR __builtin_amdgcn_s_barrier()
; #define PG8_SCHED __builtin_amdgcn_sched_barrier(0)
; template <class Epi, bool ALIGN_EPI>
; __device__ __forceinline__ void gemm_phase(LAS unsigned char* lds, const Gemm g, const StaticOrder& S, const Epi& E, const int tid) {
;     ...
;             PG8_WAIT_V(8); PG8_WAIT_L(0); PG8_BAR; PG8_MMA(1, 0, At, B0); PG8_MMA(1, 1, At, B1); PG8_BAR; PG8_SCHED;
;             PG8_LDB(B0, 1, 0); PG8_LDB(B1, 1, 1); PG8_SCHED; PG8_LDA(At, 1, 0); PG8_STAGE(PG8_SA(0, 1), a2 + hstepA, voffA);
;             PG8_WAIT_V(8); PG8_WAIT_L(0); PG8_BAR; PG8_MMA(0, 0, At, B0); PG8_MMA(0, 1, At, B1); PG8_BAR; PG8_SCHED;
	s_barrier
	s_add_i32 s86, 0, 0x18000
	s_add_i32 s92, 0, 0x1c000
	v_add_u32_e32 v224, s86, v170
	v_add_u32_e32 v225, s92, v170
	ds_read_b128 v[130:133], v224
	ds_read_b128 v[134:137], v224 offset:1024
	ds_read_b128 v[138:141], v224 offset:2048
	ds_read_b128 v[142:145], v224 offset:3072
	ds_read_b128 v[146:149], v225
	ds_read_b128 v[150:153], v225 offset:1024
	ds_read_b128 v[154:157], v225 offset:2048
	ds_read_b128 v[164:167], v225 offset:3072
	s_add_u32 s88, s50, 0x40100
	s_addc_u32 s89, s51, 0
	s_mov_b32 m0, s75
	v_lshl_add_u64 v[220:221], s[88:89], 0, v[162:163]
	ds_read_b128 v[172:175], v171 offset:32768
	ds_read_b128 v[176:179], v171 offset:33792
	ds_read_b128 v[180:183], v171 offset:34816
	ds_read_b128 v[184:187], v171 offset:35840
	ds_read_b128 v[188:191], v171 offset:36864
	ds_read_b128 v[192:195], v171 offset:37888
	ds_read_b128 v[196:199], v171 offset:38912
	ds_read_b128 v[214:217], v171 offset:39936
	global_load_lds_dwordx4 v[220:221], off
	v_lshl_add_u64 v[220:221], s[88:89], 0, v[160:161]
	s_mov_b32 m0, s76
	s_nop 0
	global_load_lds_dwordx4 v[220:221], off
	s_waitcnt vmcnt(8)
	s_waitcnt lgkmcnt(0)
	s_barrier

; #define PG8_MMA(ai, bj, At, Bt) do { __builtin_amdgcn_s_setprio(1); _Pragma("unroll") for (int m = 0; m < 4; ++m) _Pragma("unroll") for (int n = 0; n < 2; ++n) _Pragma("unroll") for (int k = 0; k < 2; ++k) \
;         acc[ai][bj][m][n] = __builtin_amdgcn_mfma_f32_16x16x32_bf16(Bt[n][k], At[m][k], acc[ai][bj][m][n], 0, 0, 0); __builtin_amdgcn_s_setprio(0); } while (0)
; #define PG8_WAIT_V(n) asm volatile("s_waitcnt vmcnt(" #n ")" ::: "memory")
; #define PG8_WAIT_L(n) asm volatile("s_waitcnt lgkmcnt(" #n ")" ::: "memory")
; #define PG8_BAR __builtin_amdgcn_s_barrier()
; #define PG8_SCHED __builtin_amdgcn_sched_barrier(0)
; template <class Epi, bool ALIGN_EPI>
; __device__ __forceinline__ void gemm_phase(LAS unsigned char* lds, const Gemm g, const StaticOrder& S, const Epi& E, const int tid) {
;     ...
;             PG8_WAIT_V(8); PG8_WAIT_L(0); PG8_BAR; PG8_MMA(0, 0, At, B0); PG8_MMA(0, 1, At, B1); PG8_BAR; PG8_SCHED;
	s_waitcnt lgkmcnt(0)
	v_mfma_f32_16x16x32_bf16 v[30:33], v[130:133], v[180:183], v[30:33]
	v_mfma_f32_16x16x32_bf16 v[26:29], v[138:141], v[180:183], v[26:29]
	v_mfma_f32_16x16x32_bf16 v[42:45], v[130:133], v[188:191], v[42:45]
	v_mfma_f32_16x16x32_bf16 v[34:37], v[138:141], v[188:191], v[34:37]
	v_mfma_f32_16x16x32_bf16 v[70:73], v[130:133], v[196:199], v[70:73]
	v_mfma_f32_16x16x32_bf16 v[78:81], v[138:141], v[196:199], v[78:81]
	v_mfma_f32_16x16x32_bf16 v[14:17], v[130:133], v[172:175], v[14:17]
	v_mfma_f32_16x16x32_bf16 v[10:13], v[138:141], v[172:175], v[10:13]
	v_mfma_f32_16x16x32_bf16 v[30:33], v[134:137], v[184:187], v[30:33]
	v_mfma_f32_16x16x32_bf16 v[26:29], v[142:145], v[184:187], v[26:29]
	v_mfma_f32_16x16x32_bf16 v[42:45], v[134:137], v[192:195], v[42:45]
	v_mfma_f32_16x16x32_bf16 v[34:37], v[142:145], v[192:195], v[34:37]
	v_mfma_f32_16x16x32_bf16 v[70:73], v[134:137], v[214:217], v[70:73]
	v_mfma_f32_16x16x32_bf16 v[78:81], v[142:145], v[214:217], v[78:81]
	v_mfma_f32_16x16x32_bf16 v[14:17], v[134:137], v[176:179], v[14:17]
	v_mfma_f32_16x16x32_bf16 v[10:13], v[142:145], v[176:179], v[10:13]


; #define PG8_MMA(ai, bj, At, Bt) do { __builtin_amdgcn_s_setprio(1); _Pragma("unroll") for (int m = 0; m < 4; ++m) _Pragma("unroll") for (int n = 0; n < 2; ++n) _Pragma("unroll") for (int k = 0; k < 2; ++k) \
;         acc[ai][bj][m][n] = __builtin_amdgcn_mfma_f32_16x16x32_bf16(Bt[n][k], At[m][k], acc[ai][bj][m][n], 0, 0, 0); __builtin_amdgcn_s_setprio(0); } while (0)
; #define PG8_WAIT_V(n) asm volatile("s_waitcnt vmcnt(" #n ")" ::: "memory")
; #define PG8_WAIT_L(n) asm volatile("s_waitcnt lgkmcnt(" #n ")" ::: "memory")
; #define PG8_BAR __builtin_amdgcn_s_barrier()
; #define PG8_SCHED __builtin_amdgcn_sched_barrier(0)
; template <class Epi, bool ALIGN_EPI>
; __device__ __forceinline__ void gemm_phase(LAS unsigned char* lds, const Gemm g, const StaticOrder& S, const Epi& E, const int tid) {
;     ...
;             PG8_WAIT_V(8); PG8_WAIT_L(0); PG8_BAR; PG8_MMA(0, 0, At, B0); PG8_MMA(0, 1, At, B1); PG8_BAR; PG8_SCHED;
	v_mfma_f32_16x16x32_bf16 v[6:9], v[146:149], v[172:175], v[6:9]
	v_mfma_f32_16x16x32_bf16 v[2:5], v[154:157], v[172:175], v[2:5]
	v_mfma_f32_16x16x32_bf16 v[22:25], v[146:149], v[180:183], v[22:25]
	v_mfma_f32_16x16x32_bf16 v[18:21], v[154:157], v[180:183], v[18:21]
	v_mfma_f32_16x16x32_bf16 v[38:41], v[146:149], v[188:191], v[38:41]
	v_mfma_f32_16x16x32_bf16 v[46:49], v[154:157], v[188:191], v[46:49]
	v_mfma_f32_16x16x32_bf16 v[62:65], v[146:149], v[196:199], v[62:65]
	v_mfma_f32_16x16x32_bf16 v[74:77], v[154:157], v[196:199], v[74:77]
	v_mfma_f32_16x16x32_bf16 v[6:9], v[150:153], v[176:179], v[6:9]
	v_mfma_f32_16x16x32_bf16 v[2:5], v[164:167], v[176:179], v[2:5]
	v_mfma_f32_16x16x32_bf16 v[22:25], v[150:153], v[184:187], v[22:25]
	v_mfma_f32_16x16x32_bf16 v[18:21], v[164:167], v[184:187], v[18:21]
	v_mfma_f32_16x16x32_bf16 v[38:41], v[150:153], v[192:195], v[38:41]
	v_mfma_f32_16x16x32_bf16 v[46:49], v[164:167], v[192:195], v[46:49]
	v_mfma_f32_16x16x32_bf16 v[62:65], v[150:153], v[214:217], v[62:65]
	v_mfma_f32_16x16x32_bf16 v[74:77], v[164:167], v[214:217], v[74:77]

; #define PG8_STAGE(bufoff, gbase, voff) do { _Pragma("unroll") for (int _i = 0; _i < 2; ++_i) \
;         __builtin_amdgcn_global_load_lds((const unsigned*)((const char*)(gbase) + (voff)[_i]), (LAS unsigned*)(lds + (bufoff) + ldsw + _i * 8192), 16, 0, 0); } while (0)
; #define PG8_LDA(dst, b, h) do { _Pragma("unroll") for (int m = 0; m < 4; ++m) _Pragma("unroll") for (int k = 0; k < 2; ++k) dst[m][k] = *(const LAS bf16x8*)(lds + PG8_SA(b, h) + aoff + m * 2048 + k * 1024); } while (0)
; #define PG8_MMA(ai, bj, At, Bt) do { __builtin_amdgcn_s_setprio(1); _Pragma("unroll") for (int m = 0; m < 4; ++m) _Pragma("unroll") for (int n = 0; n < 2; ++n) _Pragma("unroll") for (int k = 0; k < 2; ++k) \
;         acc[ai][bj][m][n] = __builtin_amdgcn_mfma_f32_16x16x32_bf16(Bt[n][k], At[m][k], acc[ai][bj][m][n], 0, 0, 0); __builtin_amdgcn_s_setprio(0); } while (0)
; #define PG8_WAIT_V(n) asm volatile("s_waitcnt vmcnt(" #n ")" ::: "memory")
; #define PG8_WAIT_L(n) asm volatile("s_waitcnt lgkmcnt(" #n ")" ::: "memory")
; #define PG8_BAR __builtin_amdgcn_s_barrier()
; #define PG8_SCHED __builtin_amdgcn_sched_barrier(0)
; template <class Epi, bool ALIGN_EPI>
; __device__ __forceinline__ void gemm_phase(LAS unsigned char* lds, const Gemm g, const StaticOrder& S, const Epi& E, const int tid) {
;     ...
;             PG8_WAIT_V(8); PG8_WAIT_L(0); PG8_BAR; PG8_MMA(0, 0, At, B0); PG8_MMA(0, 1, At, B1); PG8_BAR; PG8_SCHED;
;             PG8_LDA(At, 1, 1); PG8_STAGE(PG8_SB(1, 0), b3, voffB); PG8_STAGE(PG8_SB(1, 1), b3 + hstepB, voffB); PG8_STAGE(PG8_SA(1, 0), a3, voffA);
;             PG8_WAIT_V(8); PG8_WAIT_L(0); PG8_BAR; PG8_MMA(1, 0, At, B0); PG8_MMA(1, 1, At, B1); PG8_BAR; PG8_SCHED;
	s_barrier
	s_add_i32 s88, s86, s72
	s_mov_b64 vcc, 0x180
	s_add_i32 s86, s88, 0x2000
	v_lshl_add_u64 v[168:169], v[168:169], 0, vcc
	s_mov_b32 m0, s88
	s_add_u32 s90, s52, 0x10180
	ds_read_b128 v[172:175], v171 offset:49152
	ds_read_b128 v[176:179], v171 offset:50176
	ds_read_b128 v[180:183], v171 offset:51200
	ds_read_b128 v[184:187], v171 offset:52224
	ds_read_b128 v[188:191], v171 offset:53248
	ds_read_b128 v[192:195], v171 offset:54272
	ds_read_b128 v[196:199], v171 offset:55296
	ds_read_b128 v[214:217], v171 offset:56320
	global_load_lds_dwordx4 v[168:169], off
	v_lshl_add_u64 v[168:169], v[200:201], 0, vcc
	s_mov_b32 m0, s86
	s_addc_u32 s91, s53, 0
	s_add_i32 s52, s92, s72
	global_load_lds_dwordx4 v[168:169], off
	v_lshl_add_u64 v[168:169], s[90:91], 0, v[0:1]
	s_mov_b32 m0, s52
	s_add_i32 s53, s52, 0x2000
	global_load_lds_dwordx4 v[168:169], off
	v_lshl_add_u64 v[168:169], s[90:91], 0, v[158:159]
	s_mov_b32 m0, s53
	s_nop 0
	global_load_lds_dwordx4 v[168:169], off
	v_lshl_add_u64 v[168:169], v[210:211], 0, vcc
	s_mov_b32 m0, s79
	s_nop 0
	global_load_lds_dwordx4 v[168:169], off
	v_lshl_add_u64 v[168:169], v[218:219], 0, vcc
	s_mov_b32 m0, s80
	s_nop 0
	global_load_lds_dwordx4 v[168:169], off
	s_waitcnt vmcnt(8)
	s_waitcnt lgkmcnt(0)
	s_barrier

; #define PG8_MMA(ai, bj, At, Bt) do { __builtin_amdgcn_s_setprio(1); _Pragma("unroll") for (int m = 0; m < 4; ++m) _Pragma("unroll") for (int n = 0; n < 2; ++n) _Pragma("unroll") for (int k = 0; k < 2; ++k) \
;         acc[ai][bj][m][n] = __builtin_amdgcn_mfma_f32_16x16x32_bf16(Bt[n][k], At[m][k], acc[ai][bj][m][n], 0, 0, 0); __builtin_amdgcn_s_setprio(0); } while (0)
; #define PG8_WAIT_V(n) asm volatile("s_waitcnt vmcnt(" #n ")" ::: "memory")
; #define PG8_WAIT_L(n) asm volatile("s_waitcnt lgkmcnt(" #n ")" ::: "memory")
; #define PG8_BAR __builtin_amdgcn_s_barrier()
; #define PG8_SCHED __builtin_amdgcn_sched_barrier(0)
; template <class Epi, bool ALIGN_EPI>
; __device__ __forceinline__ void gemm_phase(LAS unsigned char* lds, const Gemm g, const StaticOrder& S, const Epi& E, const int tid) {
;     ...
;             PG8_WAIT_V(8); PG8_WAIT_L(0); PG8_BAR; PG8_MMA(1, 0, At, B0); PG8_MMA(1, 1, At, B1); PG8_BAR; PG8_SCHED;
	s_waitcnt lgkmcnt(0)
	v_mfma_f32_16x16x32_bf16 v[50:53], v[130:133], v[172:175], v[50:53]
	v_mfma_f32_16x16x32_bf16 v[58:61], v[138:141], v[172:175], v[58:61]
	v_mfma_f32_16x16x32_bf16 v[82:85], v[130:133], v[180:183], v[82:85]
	v_mfma_f32_16x16x32_bf16 v[90:93], v[138:141], v[180:183], v[90:93]
	v_mfma_f32_16x16x32_bf16 v[98:101], v[130:133], v[188:191], v[98:101]
	v_mfma_f32_16x16x32_bf16 v[106:109], v[138:141], v[188:191], v[106:109]
	v_mfma_f32_16x16x32_bf16 v[118:121], v[130:133], v[196:199], v[118:121]
	v_mfma_f32_16x16x32_bf16 v[126:129], v[138:141], v[196:199], v[126:129]
	v_mfma_f32_16x16x32_bf16 v[50:53], v[134:137], v[176:179], v[50:53]
	v_mfma_f32_16x16x32_bf16 v[58:61], v[142:145], v[176:179], v[58:61]
	v_mfma_f32_16x16x32_bf16 v[82:85], v[134:137], v[184:187], v[82:85]
	v_mfma_f32_16x16x32_bf16 v[90:93], v[142:145], v[184:187], v[90:93]
	v_mfma_f32_16x16x32_bf16 v[98:101], v[134:137], v[192:195], v[98:101]
	v_mfma_f32_16x16x32_bf16 v[106:109], v[142:145], v[192:195], v[106:109]
	v_mfma_f32_16x16x32_bf16 v[118:121], v[134:137], v[214:217], v[118:121]
	v_mfma_f32_16x16x32_bf16 v[126:129], v[142:145], v[214:217], v[126:129]


; #define PG8_MMA(ai, bj, At, Bt) do { __builtin_amdgcn_s_setprio(1); _Pragma("unroll") for (int m = 0; m < 4; ++m) _Pragma("unroll") for (int n = 0; n < 2; ++n) _Pragma("unroll") for (int k = 0; k < 2; ++k) \
;         acc[ai][bj][m][n] = __builtin_amdgcn_mfma_f32_16x16x32_bf16(Bt[n][k], At[m][k], acc[ai][bj][m][n], 0, 0, 0); __builtin_amdgcn_s_setprio(0); } while (0)
; #define PG8_WAIT_V(n) asm volatile("s_waitcnt vmcnt(" #n ")" ::: "memory")
; #define PG8_WAIT_L(n) asm volatile("s_waitcnt lgkmcnt(" #n ")" ::: "memory")
; #define PG8_BAR __builtin_amdgcn_s_barrier()
; #define PG8_SCHED __builtin_amdgcn_sched_barrier(0)
; template <class Epi, bool ALIGN_EPI>
; __device__ __forceinline__ void gemm_phase(LAS unsigned char* lds, const Gemm g, const StaticOrder& S, const Epi& E, const int tid) {
;     ...
;             PG8_WAIT_V(8); PG8_WAIT_L(0); PG8_BAR; PG8_MMA(1, 0, At, B0); PG8_MMA(1, 1, At, B1); PG8_BAR; PG8_SCHED;
	v_mfma_f32_16x16x32_bf16 v[54:57], v[146:149], v[172:175], v[54:57]
	v_mfma_f32_16x16x32_bf16 v[66:69], v[154:157], v[172:175], v[66:69]
	v_mfma_f32_16x16x32_bf16 v[86:89], v[146:149], v[180:183], v[86:89]
	v_mfma_f32_16x16x32_bf16 v[94:97], v[154:157], v[180:183], v[94:97]
	v_mfma_f32_16x16x32_bf16 v[102:105], v[146:149], v[188:191], v[102:105]
	v_mfma_f32_16x16x32_bf16 v[110:113], v[154:157], v[188:191], v[110:113]
	v_mfma_f32_16x16x32_bf16 v[122:125], v[146:149], v[196:199], v[122:125]
	v_mfma_f32_16x16x32_bf16 v[114:117], v[154:157], v[196:199], v[114:117]
	v_mfma_f32_16x16x32_bf16 v[54:57], v[150:153], v[176:179], v[54:57]
	v_mfma_f32_16x16x32_bf16 v[66:69], v[164:167], v[176:179], v[66:69]
	v_mfma_f32_16x16x32_bf16 v[86:89], v[150:153], v[184:187], v[86:89]
	v_mfma_f32_16x16x32_bf16 v[94:97], v[164:167], v[184:187], v[94:97]
	v_mfma_f32_16x16x32_bf16 v[102:105], v[150:153], v[192:195], v[102:105]
	v_mfma_f32_16x16x32_bf16 v[110:113], v[164:167], v[192:195], v[110:113]
	v_mfma_f32_16x16x32_bf16 v[122:125], v[150:153], v[214:217], v[122:125]
	v_mfma_f32_16x16x32_bf16 v[114:117], v[164:167], v[214:217], v[114:117]

; #define PG8_STAGE(bufoff, gbase, voff) do { _Pragma("unroll") for (int _i = 0; _i < 2; ++_i) \
;         __builtin_amdgcn_global_load_lds((const unsigned*)((const char*)(gbase) + (voff)[_i]), (LAS unsigned*)(lds + (bufoff) + ldsw + _i * 8192), 16, 0, 0); } while (0)
; #define PG8_LDA(dst, b, h) do { _Pragma("unroll") for (int m = 0; m < 4; ++m) _Pragma("unroll") for (int k = 0; k < 2; ++k) dst[m][k] = *(const LAS bf16x8*)(lds + PG8_SA(b, h) + aoff + m * 2048 + k * 1024); } while (0)
; #define PG8_LDB(dst, b, h) do { _Pragma("unroll") for (int n = 0; n < 2; ++n) _Pragma("unroll") for (int k = 0; k < 2; ++k) dst[n][k] = *(const LAS bf16x8*)(lds + PG8_SB(b, h) + boff + n * 2048 + k * 1024); } while (0)
; #define PG8_MMA(ai, bj, At, Bt) do { __builtin_amdgcn_s_setprio(1); _Pragma("unroll") for (int m = 0; m < 4; ++m) _Pragma("unroll") for (int n = 0; n < 2; ++n) _Pragma("unroll") for (int k = 0; k < 2; ++k) \
;         acc[ai][bj][m][n] = __builtin_amdgcn_mfma_f32_16x16x32_bf16(Bt[n][k], At[m][k], acc[ai][bj][m][n], 0, 0, 0); __builtin_amdgcn_s_setprio(0); } while (0)
; #define PG8_WAIT_V(n) asm volatile("s_waitcnt vmcnt(" #n ")" ::: "memory")
; #define PG8_WAIT_L(n) asm volatile("s_waitcnt lgkmcnt(" #n ")" ::: "memory")
; #define PG8_BAR __builtin_amdgcn_s_barrier()
; #define PG8_SCHED __builtin_amdgcn_sched_barrier(0)
; template <class Epi, bool ALIGN_EPI>
; __device__ __forceinline__ void gemm_phase(LAS unsigned char* lds, const Gemm g, const StaticOrder& S, const Epi& E, const int tid) {
;     ...
;             const char* a1 = cA + (size_t)(t + 1) * kstepA;
;             const char* a2 = last ? nA : cA + (size_t)(t + 2) * kstepA; const char* b2 = last ? nB : cB + (size_t)(t + 2) * kstepB;
;             const char* a3 = a2 + kstepA; const char* b3 = b2 + kstepB;
;             PG8_LDB(B0, 0, 0); PG8_LDB(B1, 0, 1); PG8_SCHED; PG8_LDA(At, 0, 0); PG8_STAGE(PG8_SA(1, 1), a1 + hstepA, voffA);
;             PG8_WAIT_V(8); PG8_WAIT_L(0); PG8_BAR; PG8_MMA(0, 0, At, B0); PG8_MMA(0, 1, At, B1); PG8_BAR; PG8_SCHED;
	s_barrier
	ds_read_b128 v[130:133], v222
	ds_read_b128 v[134:137], v222 offset:1024
	ds_read_b128 v[138:141], v222 offset:2048
	ds_read_b128 v[142:145], v222 offset:3072
	ds_read_b128 v[146:149], v223
	ds_read_b128 v[150:153], v223 offset:1024
	ds_read_b128 v[154:157], v223 offset:2048
	ds_read_b128 v[164:167], v223 offset:3072
	s_add_u32 s50, s50, 0x40180
	s_addc_u32 s51, s51, 0
	s_mov_b32 m0, s87
	v_lshl_add_u64 v[168:169], s[50:51], 0, v[162:163]
	ds_read_b128 v[172:175], v171
	ds_read_b128 v[176:179], v171 offset:1024
	ds_read_b128 v[180:183], v171 offset:2048
	ds_read_b128 v[184:187], v171 offset:3072
	ds_read_b128 v[188:191], v171 offset:4096
	ds_read_b128 v[192:195], v171 offset:5120
	ds_read_b128 v[196:199], v171 offset:6144
	ds_read_b128 v[214:217], v171 offset:7168
	global_load_lds_dwordx4 v[168:169], off
	v_lshl_add_u64 v[168:169], s[50:51], 0, v[160:161]
	s_mov_b32 m0, s43
	s_nop 0
	global_load_lds_dwordx4 v[168:169], off
	s_waitcnt vmcnt(8)
	s_waitcnt lgkmcnt(0)
	s_barrier

; #define PG8_MMA(ai, bj, At, Bt) do { __builtin_amdgcn_s_setprio(1); _Pragma("unroll") for (int m = 0; m < 4; ++m) _Pragma("unroll") for (int n = 0; n < 2; ++n) _Pragma("unroll") for (int k = 0; k < 2; ++k) \
;         acc[ai][bj][m][n] = __builtin_amdgcn_mfma_f32_16x16x32_bf16(Bt[n][k], At[m][k], acc[ai][bj][m][n], 0, 0, 0); __builtin_amdgcn_s_setprio(0); } while (0)
; #define PG8_WAIT_V(n) asm volatile("s_waitcnt vmcnt(" #n ")" ::: "memory")
; #define PG8_WAIT_L(n) asm volatile("s_waitcnt lgkmcnt(" #n ")" ::: "memory")
; #define PG8_BAR __builtin_amdgcn_s_barrier()
; #define PG8_SCHED __builtin_amdgcn_sched_barrier(0)
; template <class Epi, bool ALIGN_EPI>
; __device__ __forceinline__ void gemm_phase(LAS unsigned char* lds, const Gemm g, const StaticOrder& S, const Epi& E, const int tid) {
;     ...
;             PG8_WAIT_V(8); PG8_WAIT_L(0); PG8_BAR; PG8_MMA(0, 0, At, B0); PG8_MMA(0, 1, At, B1); PG8_BAR; PG8_SCHED;
	s_waitcnt lgkmcnt(0)
	v_mfma_f32_16x16x32_bf16 v[30:33], v[130:133], v[180:183], v[30:33]
	v_mfma_f32_16x16x32_bf16 v[26:29], v[138:141], v[180:183], v[26:29]
	v_mfma_f32_16x16x32_bf16 v[42:45], v[130:133], v[188:191], v[42:45]
	v_mfma_f32_16x16x32_bf16 v[34:37], v[138:141], v[188:191], v[34:37]
	v_mfma_f32_16x16x32_bf16 v[70:73], v[130:133], v[196:199], v[70:73]
	v_mfma_f32_16x16x32_bf16 v[78:81], v[138:141], v[196:199], v[78:81]
	v_mfma_f32_16x16x32_bf16 v[14:17], v[130:133], v[172:175], v[14:17]
	v_mfma_f32_16x16x32_bf16 v[10:13], v[138:141], v[172:175], v[10:13]
	v_mfma_f32_16x16x32_bf16 v[30:33], v[134:137], v[184:187], v[30:33]
	v_mfma_f32_16x16x32_bf16 v[26:29], v[142:145], v[184:187], v[26:29]
	v_mfma_f32_16x16x32_bf16 v[42:45], v[134:137], v[192:195], v[42:45]
	v_mfma_f32_16x16x32_bf16 v[34:37], v[142:145], v[192:195], v[34:37]
	v_mfma_f32_16x16x32_bf16 v[70:73], v[134:137], v[214:217], v[70:73]
	v_mfma_f32_16x16x32_bf16 v[78:81], v[142:145], v[214:217], v[78:81]
	v_mfma_f32_16x16x32_bf16 v[14:17], v[134:137], v[176:179], v[14:17]
	v_mfma_f32_16x16x32_bf16 v[10:13], v[142:145], v[176:179], v[10:13]


; #define PG8_MMA(ai, bj, At, Bt) do { __builtin_amdgcn_s_setprio(1); _Pragma("unroll") for (int m = 0; m < 4; ++m) _Pragma("unroll") for (int n = 0; n < 2; ++n) _Pragma("unroll") for (int k = 0; k < 2; ++k) \
;         acc[ai][bj][m][n] = __builtin_amdgcn_mfma_f32_16x16x32_bf16(Bt[n][k], At[m][k], acc[ai][bj][m][n], 0, 0, 0); __builtin_amdgcn_s_setprio(0); } while (0)
; #define PG8_WAIT_V(n) asm volatile("s_waitcnt vmcnt(" #n ")" ::: "memory")
; #define PG8_WAIT_L(n) asm volatile("s_waitcnt lgkmcnt(" #n ")" ::: "memory")
; #define PG8_BAR __builtin_amdgcn_s_barrier()
; #define PG8_SCHED __builtin_amdgcn_sched_barrier(0)
; template <class Epi, bool ALIGN_EPI>
; __device__ __forceinline__ void gemm_phase(LAS unsigned char* lds, const Gemm g, const StaticOrder& S, const Epi& E, const int tid) {
;     ...
;             PG8_WAIT_V(8); PG8_WAIT_L(0); PG8_BAR; PG8_MMA(0, 0, At, B0); PG8_MMA(0, 1, At, B1); PG8_BAR; PG8_SCHED;
	v_mfma_f32_16x16x32_bf16 v[2:5], v[154:157], v[172:175], v[2:5]
	v_mfma_f32_16x16x32_bf16 v[6:9], v[146:149], v[172:175], v[6:9]
	v_mfma_f32_16x16x32_bf16 v[172:175], v[164:167], v[176:179], v[2:5]
	v_mfma_f32_16x16x32_bf16 v[2:5], v[146:149], v[180:183], v[22:25]
	v_mfma_f32_16x16x32_bf16 v[218:221], v[150:153], v[176:179], v[6:9]
	v_mfma_f32_16x16x32_bf16 v[176:179], v[150:153], v[184:187], v[2:5]
	v_mfma_f32_16x16x32_bf16 v[2:5], v[154:157], v[180:183], v[18:21]
	v_mfma_f32_16x16x32_bf16 v[180:183], v[164:167], v[184:187], v[2:5]
	v_mfma_f32_16x16x32_bf16 v[2:5], v[146:149], v[188:191], v[38:41]
	v_mfma_f32_16x16x32_bf16 v[38:41], v[150:153], v[192:195], v[2:5]
	v_mfma_f32_16x16x32_bf16 v[2:5], v[154:157], v[188:191], v[46:49]
	v_mfma_f32_16x16x32_bf16 v[46:49], v[164:167], v[192:195], v[2:5]
	v_mfma_f32_16x16x32_bf16 v[2:5], v[146:149], v[196:199], v[62:65]
	v_mfma_f32_16x16x32_bf16 v[62:65], v[150:153], v[214:217], v[2:5]
	v_mfma_f32_16x16x32_bf16 v[2:5], v[154:157], v[196:199], v[74:77]
	v_mfma_f32_16x16x32_bf16 v[74:77], v[164:167], v[214:217], v[2:5]

; #define PG8_STAGE(bufoff, gbase, voff) do { _Pragma("unroll") for (int _i = 0; _i < 2; ++_i) \
;         __builtin_amdgcn_global_load_lds((const unsigned*)((const char*)(gbase) + (voff)[_i]), (LAS unsigned*)(lds + (bufoff) + ldsw + _i * 8192), 16, 0, 0); } while (0)
; #define PG8_LDA(dst, b, h) do { _Pragma("unroll") for (int m = 0; m < 4; ++m) _Pragma("unroll") for (int k = 0; k < 2; ++k) dst[m][k] = *(const LAS bf16x8*)(lds + PG8_SA(b, h) + aoff + m * 2048 + k * 1024); } while (0)
; #define PG8_MMA(ai, bj, At, Bt) do { __builtin_amdgcn_s_setprio(1); _Pragma("unroll") for (int m = 0; m < 4; ++m) _Pragma("unroll") for (int n = 0; n < 2; ++n) _Pragma("unroll") for (int k = 0; k < 2; ++k) \
;         acc[ai][bj][m][n] = __builtin_amdgcn_mfma_f32_16x16x32_bf16(Bt[n][k], At[m][k], acc[ai][bj][m][n], 0, 0, 0); __builtin_amdgcn_s_setprio(0); } while (0)
; #define PG8_WAIT_V(n) asm volatile("s_waitcnt vmcnt(" #n ")" ::: "memory")
; #define PG8_WAIT_L(n) asm volatile("s_waitcnt lgkmcnt(" #n ")" ::: "memory")
; #define PG8_BAR __builtin_amdgcn_s_barrier()
; #define PG8_SCHED __builtin_amdgcn_sched_barrier(0)
; template <class Epi, bool ALIGN_EPI>
; __device__ __forceinline__ void gemm_phase(LAS unsigned char* lds, const Gemm g, const StaticOrder& S, const Epi& E, const int tid) {
;     ...
;             PG8_WAIT_V(8); PG8_WAIT_L(0); PG8_BAR; PG8_MMA(0, 0, At, B0); PG8_MMA(0, 1, At, B1); PG8_BAR; PG8_SCHED;
;             PG8_LDA(At, 0, 1); PG8_STAGE(PG8_SB(0, 0), b2, voffB); PG8_STAGE(PG8_SB(0, 1), b2 + hstepB, voffB); PG8_STAGE(PG8_SA(0, 0), a2, voffA);
;             PG8_WAIT_V(8); PG8_WAIT_L(0); PG8_BAR; PG8_MMA(1, 0, At, B0); PG8_MMA(1, 1, At, B1); PG8_BAR; PG8_SCHED;
	s_barrier
	s_mov_b32 m0, s85
	v_lshl_add_u64 v[168:169], s[54:55], 0, v[0:1]
	s_add_u32 s50, s54, 0x10000
	s_nop 1
	ds_read_b128 v[2:5], v171 offset:16384
	ds_read_b128 v[6:9], v171 offset:17408
	ds_read_b128 v[18:21], v171 offset:18432
	ds_read_b128 v[22:25], v171 offset:19456
	ds_read_b128 v[184:187], v171 offset:20480
	ds_read_b128 v[188:191], v171 offset:21504
	ds_read_b128 v[192:195], v171 offset:22528
	ds_read_b128 v[196:199], v171 offset:23552
	global_load_lds_dwordx4 v[168:169], off
	v_lshl_add_u64 v[200:201], s[54:55], 0, v[158:159]
	s_mov_b32 m0, s45
	s_addc_u32 s51, s55, 0
	global_load_lds_dwordx4 v[200:201], off
	v_lshl_add_u64 v[210:211], s[50:51], 0, v[0:1]
	s_mov_b32 m0, s83
	v_lshl_add_u64 v[234:235], s[56:57], 0, v[160:161]
	global_load_lds_dwordx4 v[210:211], off
	v_lshl_add_u64 v[210:211], s[50:51], 0, v[158:159]
	s_mov_b32 m0, s84
	s_nop 0
	global_load_lds_dwordx4 v[210:211], off
	v_lshl_add_u64 v[210:211], s[56:57], 0, v[162:163]
	s_mov_b32 m0, s73
	s_nop 0
	global_load_lds_dwordx4 v[210:211], off
	s_mov_b32 m0, s74
	s_nop 0
	global_load_lds_dwordx4 v[234:235], off
	s_waitcnt vmcnt(8)
	s_waitcnt lgkmcnt(0)
	s_barrier

; #define PG8_MMA(ai, bj, At, Bt) do { __builtin_amdgcn_s_setprio(1); _Pragma("unroll") for (int m = 0; m < 4; ++m) _Pragma("unroll") for (int n = 0; n < 2; ++n) _Pragma("unroll") for (int k = 0; k < 2; ++k) \
;         acc[ai][bj][m][n] = __builtin_amdgcn_mfma_f32_16x16x32_bf16(Bt[n][k], At[m][k], acc[ai][bj][m][n], 0, 0, 0); __builtin_amdgcn_s_setprio(0); } while (0)
; #define PG8_WAIT_V(n) asm volatile("s_waitcnt vmcnt(" #n ")" ::: "memory")
; #define PG8_WAIT_L(n) asm volatile("s_waitcnt lgkmcnt(" #n ")" ::: "memory")
; #define PG8_BAR __builtin_amdgcn_s_barrier()
; #define PG8_SCHED __builtin_amdgcn_sched_barrier(0)
; template <class Epi, bool ALIGN_EPI>
; __device__ __forceinline__ void gemm_phase(LAS unsigned char* lds, const Gemm g, const StaticOrder& S, const Epi& E, const int tid) {
;     ...
;             PG8_WAIT_V(8); PG8_WAIT_L(0); PG8_BAR; PG8_MMA(1, 0, At, B0); PG8_MMA(1, 1, At, B1); PG8_BAR; PG8_SCHED;
	s_waitcnt lgkmcnt(0)
	v_mfma_f32_16x16x32_bf16 v[50:53], v[130:133], v[2:5], v[50:53]
	v_mfma_f32_16x16x32_bf16 v[58:61], v[138:141], v[2:5], v[58:61]
	v_mfma_f32_16x16x32_bf16 v[82:85], v[130:133], v[18:21], v[82:85]
	v_mfma_f32_16x16x32_bf16 v[90:93], v[138:141], v[18:21], v[90:93]
	v_mfma_f32_16x16x32_bf16 v[98:101], v[130:133], v[184:187], v[98:101]
	v_mfma_f32_16x16x32_bf16 v[106:109], v[138:141], v[184:187], v[106:109]
	v_mfma_f32_16x16x32_bf16 v[118:121], v[130:133], v[192:195], v[118:121]
	v_mfma_f32_16x16x32_bf16 v[126:129], v[138:141], v[192:195], v[126:129]
	v_mfma_f32_16x16x32_bf16 v[50:53], v[134:137], v[6:9], v[50:53]
	v_mfma_f32_16x16x32_bf16 v[58:61], v[142:145], v[6:9], v[58:61]
	v_mfma_f32_16x16x32_bf16 v[82:85], v[134:137], v[22:25], v[82:85]
	v_mfma_f32_16x16x32_bf16 v[90:93], v[142:145], v[22:25], v[90:93]
	v_mfma_f32_16x16x32_bf16 v[98:101], v[134:137], v[188:191], v[98:101]
	v_mfma_f32_16x16x32_bf16 v[106:109], v[142:145], v[188:191], v[106:109]
	v_mfma_f32_16x16x32_bf16 v[118:121], v[134:137], v[196:199], v[118:121]
	v_mfma_f32_16x16x32_bf16 v[126:129], v[142:145], v[196:199], v[126:129]


; #define PG8_MMA(ai, bj, At, Bt) do { __builtin_amdgcn_s_setprio(1); _Pragma("unroll") for (int m = 0; m < 4; ++m) _Pragma("unroll") for (int n = 0; n < 2; ++n) _Pragma("unroll") for (int k = 0; k < 2; ++k) \
;         acc[ai][bj][m][n] = __builtin_amdgcn_mfma_f32_16x16x32_bf16(Bt[n][k], At[m][k], acc[ai][bj][m][n], 0, 0, 0); __builtin_amdgcn_s_setprio(0); } while (0)
; #define PG8_WAIT_V(n) asm volatile("s_waitcnt vmcnt(" #n ")" ::: "memory")
; #define PG8_WAIT_L(n) asm volatile("s_waitcnt lgkmcnt(" #n ")" ::: "memory")
; #define PG8_BAR __builtin_amdgcn_s_barrier()
; #define PG8_SCHED __builtin_amdgcn_sched_barrier(0)
; template <class Epi, bool ALIGN_EPI>
; __device__ __forceinline__ void gemm_phase(LAS unsigned char* lds, const Gemm g, const StaticOrder& S, const Epi& E, const int tid) {
;     ...
;             PG8_WAIT_V(8); PG8_WAIT_L(0); PG8_BAR; PG8_MMA(1, 0, At, B0); PG8_MMA(1, 1, At, B1); PG8_BAR; PG8_SCHED;
	v_mfma_f32_16x16x32_bf16 v[54:57], v[146:149], v[2:5], v[54:57]
	v_mfma_f32_16x16x32_bf16 v[2:5], v[154:157], v[2:5], v[66:69]
	v_mfma_f32_16x16x32_bf16 v[66:69], v[164:167], v[6:9], v[2:5]
	v_mfma_f32_16x16x32_bf16 v[2:5], v[146:149], v[18:21], v[86:89]
	v_mfma_f32_16x16x32_bf16 v[86:89], v[150:153], v[22:25], v[2:5]
	v_mfma_f32_16x16x32_bf16 v[2:5], v[154:157], v[18:21], v[94:97]
	v_mfma_f32_16x16x32_bf16 v[94:97], v[164:167], v[22:25], v[2:5]
	v_mfma_f32_16x16x32_bf16 v[2:5], v[146:149], v[184:187], v[102:105]
	v_mfma_f32_16x16x32_bf16 v[102:105], v[150:153], v[188:191], v[2:5]
	v_mfma_f32_16x16x32_bf16 v[2:5], v[154:157], v[184:187], v[110:113]
	v_mfma_f32_16x16x32_bf16 v[110:113], v[164:167], v[188:191], v[2:5]
	v_mfma_f32_16x16x32_bf16 v[2:5], v[146:149], v[192:195], v[122:125]
	v_mfma_f32_16x16x32_bf16 v[54:57], v[150:153], v[6:9], v[54:57]
	v_mfma_f32_16x16x32_bf16 v[122:125], v[150:153], v[196:199], v[2:5]
	v_mfma_f32_16x16x32_bf16 v[2:5], v[154:157], v[192:195], v[114:117]
	v_mfma_f32_16x16x32_bf16 v[130:133], v[164:167], v[196:199], v[2:5]

; #define PG8_STAGE(bufoff, gbase, voff) do { _Pragma("unroll") for (int _i = 0; _i < 2; ++_i) \
;         __builtin_amdgcn_global_load_lds((const unsigned*)((const char*)(gbase) + (voff)[_i]), (LAS unsigned*)(lds + (bufoff) + ldsw + _i * 8192), 16, 0, 0); } while (0)
; #define PG8_LDA(dst, b, h) do { _Pragma("unroll") for (int m = 0; m < 4; ++m) _Pragma("unroll") for (int k = 0; k < 2; ++k) dst[m][k] = *(const LAS bf16x8*)(lds + PG8_SA(b, h) + aoff + m * 2048 + k * 1024); } while (0)
; #define PG8_LDB(dst, b, h) do { _Pragma("unroll") for (int n = 0; n < 2; ++n) _Pragma("unroll") for (int k = 0; k < 2; ++k) dst[n][k] = *(const LAS bf16x8*)(lds + PG8_SB(b, h) + boff + n * 2048 + k * 1024); } while (0)
; #define PG8_MMA(ai, bj, At, Bt) do { __builtin_amdgcn_s_setprio(1); _Pragma("unroll") for (int m = 0; m < 4; ++m) _Pragma("unroll") for (int n = 0; n < 2; ++n) _Pragma("unroll") for (int k = 0; k < 2; ++k) \
;         acc[ai][bj][m][n] = __builtin_amdgcn_mfma_f32_16x16x32_bf16(Bt[n][k], At[m][k], acc[ai][bj][m][n], 0, 0, 0); __builtin_amdgcn_s_setprio(0); } while (0)
; #define PG8_WAIT_V(n) asm volatile("s_waitcnt vmcnt(" #n ")" ::: "memory")
; #define PG8_WAIT_L(n) asm volatile("s_waitcnt lgkmcnt(" #n ")" ::: "memory")
; #define PG8_BAR __builtin_amdgcn_s_barrier()
; #define PG8_SCHED __builtin_amdgcn_sched_barrier(0)
; template <class Epi, bool ALIGN_EPI>
; __device__ __forceinline__ void gemm_phase(LAS unsigned char* lds, const Gemm g, const StaticOrder& S, const Epi& E, const int tid) {
;     ...
;             PG8_WAIT_V(8); PG8_WAIT_L(0); PG8_BAR; PG8_MMA(1, 0, At, B0); PG8_MMA(1, 1, At, B1); PG8_BAR; PG8_SCHED;
;             PG8_LDB(B0, 1, 0); PG8_LDB(B1, 1, 1); PG8_SCHED; PG8_LDA(At, 1, 0); PG8_STAGE(PG8_SA(0, 1), a2 + hstepA, voffA);
;             PG8_WAIT_V(8); PG8_WAIT_L(0); PG8_BAR; PG8_MMA(0, 0, At, B0); PG8_MMA(0, 1, At, B1); PG8_BAR; PG8_SCHED;
	s_barrier
	ds_read_b128 v[114:117], v224
	ds_read_b128 v[134:137], v224 offset:1024
	ds_read_b128 v[138:141], v224 offset:2048
	ds_read_b128 v[142:145], v224 offset:3072
	ds_read_b128 v[146:149], v225
	ds_read_b128 v[164:167], v225 offset:1024
	ds_read_b128 v[184:187], v225 offset:2048
	ds_read_b128 v[188:191], v225 offset:3072
	s_add_u32 s50, s56, 0x40000
	s_addc_u32 s51, s57, 0
	s_mov_b32 m0, s75
	v_lshl_add_u64 v[2:3], s[50:51], 0, v[162:163]
	ds_read_b128 v[150:153], v171 offset:32768
	ds_read_b128 v[154:157], v171 offset:33792
	ds_read_b128 v[192:195], v171 offset:34816
	ds_read_b128 v[196:199], v171 offset:35840
	ds_read_b128 v[214:217], v171 offset:36864
	ds_read_b128 v[222:225], v171 offset:37888
	ds_read_b128 v[226:229], v171 offset:38912
	ds_read_b128 v[230:233], v171 offset:39936
	global_load_lds_dwordx4 v[2:3], off
	v_lshl_add_u64 v[2:3], s[50:51], 0, v[160:161]
	s_mov_b32 m0, s76
	s_nop 0
	global_load_lds_dwordx4 v[2:3], off
	s_waitcnt vmcnt(8)
	s_waitcnt lgkmcnt(0)
	s_barrier

; #define PG8_MMA(ai, bj, At, Bt) do { __builtin_amdgcn_s_setprio(1); _Pragma("unroll") for (int m = 0; m < 4; ++m) _Pragma("unroll") for (int n = 0; n < 2; ++n) _Pragma("unroll") for (int k = 0; k < 2; ++k) \
;         acc[ai][bj][m][n] = __builtin_amdgcn_mfma_f32_16x16x32_bf16(Bt[n][k], At[m][k], acc[ai][bj][m][n], 0, 0, 0); __builtin_amdgcn_s_setprio(0); } while (0)
; #define PG8_WAIT_V(n) asm volatile("s_waitcnt vmcnt(" #n ")" ::: "memory")
; #define PG8_WAIT_L(n) asm volatile("s_waitcnt lgkmcnt(" #n ")" ::: "memory")
; #define PG8_BAR __builtin_amdgcn_s_barrier()
; #define PG8_SCHED __builtin_amdgcn_sched_barrier(0)
; template <class Epi, bool ALIGN_EPI>
; __device__ __forceinline__ void gemm_phase(LAS unsigned char* lds, const Gemm g, const StaticOrder& S, const Epi& E, const int tid) {
;     ...
;             PG8_WAIT_V(8); PG8_WAIT_L(0); PG8_BAR; PG8_MMA(0, 0, At, B0); PG8_MMA(0, 1, At, B1); PG8_BAR; PG8_SCHED;
	s_waitcnt lgkmcnt(0)
	v_mfma_f32_16x16x32_bf16 v[6:9], v[138:141], v[150:153], v[10:13]
	v_mfma_f32_16x16x32_bf16 v[10:13], v[114:117], v[192:195], v[30:33]
	v_mfma_f32_16x16x32_bf16 v[18:21], v[134:137], v[196:199], v[10:13]
	v_mfma_f32_16x16x32_bf16 v[10:13], v[138:141], v[192:195], v[26:29]
	v_mfma_f32_16x16x32_bf16 v[22:25], v[142:145], v[196:199], v[10:13]
	v_mfma_f32_16x16x32_bf16 v[10:13], v[114:117], v[214:217], v[42:45]
	v_mfma_f32_16x16x32_bf16 v[42:45], v[134:137], v[222:225], v[10:13]
	v_mfma_f32_16x16x32_bf16 v[10:13], v[138:141], v[214:217], v[34:37]
	v_mfma_f32_16x16x32_bf16 v[34:37], v[142:145], v[222:225], v[10:13]
	v_mfma_f32_16x16x32_bf16 v[10:13], v[114:117], v[226:229], v[70:73]
	v_mfma_f32_16x16x32_bf16 v[2:5], v[114:117], v[150:153], v[14:17]
	v_mfma_f32_16x16x32_bf16 v[70:73], v[134:137], v[230:233], v[10:13]
	v_mfma_f32_16x16x32_bf16 v[10:13], v[138:141], v[226:229], v[78:81]
	v_mfma_f32_16x16x32_bf16 v[2:5], v[134:137], v[154:157], v[2:5]
	v_mfma_f32_16x16x32_bf16 v[6:9], v[142:145], v[154:157], v[6:9]
	v_mfma_f32_16x16x32_bf16 v[78:81], v[142:145], v[230:233], v[10:13]


; #define PG8_MMA(ai, bj, At, Bt) do { __builtin_amdgcn_s_setprio(1); _Pragma("unroll") for (int m = 0; m < 4; ++m) _Pragma("unroll") for (int n = 0; n < 2; ++n) _Pragma("unroll") for (int k = 0; k < 2; ++k) \
;         acc[ai][bj][m][n] = __builtin_amdgcn_mfma_f32_16x16x32_bf16(Bt[n][k], At[m][k], acc[ai][bj][m][n], 0, 0, 0); __builtin_amdgcn_s_setprio(0); } while (0)
; #define PG8_WAIT_V(n) asm volatile("s_waitcnt vmcnt(" #n ")" ::: "memory")
; #define PG8_WAIT_L(n) asm volatile("s_waitcnt lgkmcnt(" #n ")" ::: "memory")
; #define PG8_BAR __builtin_amdgcn_s_barrier()
; #define PG8_SCHED __builtin_amdgcn_sched_barrier(0)
; template <class Epi, bool ALIGN_EPI>
; __device__ __forceinline__ void gemm_phase(LAS unsigned char* lds, const Gemm g, const StaticOrder& S, const Epi& E, const int tid) {
;     ...
;             PG8_WAIT_V(8); PG8_WAIT_L(0); PG8_BAR; PG8_MMA(1, 0, At, B0); PG8_MMA(1, 1, At, B1); PG8_BAR; PG8_SCHED;
	v_mfma_f32_16x16x32_bf16 v[10:13], v[146:149], v[150:153], v[218:221]
	v_mfma_f32_16x16x32_bf16 v[26:29], v[164:167], v[154:157], v[10:13]
	v_mfma_f32_16x16x32_bf16 v[10:13], v[184:187], v[150:153], v[172:175]
	v_mfma_f32_16x16x32_bf16 v[30:33], v[188:191], v[154:157], v[10:13]
	v_mfma_f32_16x16x32_bf16 v[10:13], v[146:149], v[192:195], v[176:179]
	v_mfma_f32_16x16x32_bf16 v[150:153], v[164:167], v[196:199], v[10:13]
	v_mfma_f32_16x16x32_bf16 v[10:13], v[184:187], v[192:195], v[180:183]
	v_mfma_f32_16x16x32_bf16 v[154:157], v[188:191], v[196:199], v[10:13]
	v_mfma_f32_16x16x32_bf16 v[10:13], v[146:149], v[214:217], v[38:41]
	v_mfma_f32_16x16x32_bf16 v[38:41], v[164:167], v[222:225], v[10:13]
	v_mfma_f32_16x16x32_bf16 v[10:13], v[184:187], v[214:217], v[46:49]
	v_mfma_f32_16x16x32_bf16 v[46:49], v[188:191], v[222:225], v[10:13]
	v_mfma_f32_16x16x32_bf16 v[10:13], v[146:149], v[226:229], v[62:65]
	v_mfma_f32_16x16x32_bf16 v[62:65], v[164:167], v[230:233], v[10:13]
	v_mfma_f32_16x16x32_bf16 v[10:13], v[184:187], v[226:229], v[74:77]
	v_mfma_f32_16x16x32_bf16 v[74:77], v[188:191], v[230:233], v[10:13]

; #define PG8_STAGE(bufoff, gbase, voff) do { _Pragma("unroll") for (int _i = 0; _i < 2; ++_i) \
;         __builtin_amdgcn_global_load_lds((const unsigned*)((const char*)(gbase) + (voff)[_i]), (LAS unsigned*)(lds + (bufoff) + ldsw + _i * 8192), 16, 0, 0); } while (0)
; #define PG8_LDA(dst, b, h) do { _Pragma("unroll") for (int m = 0; m < 4; ++m) _Pragma("unroll") for (int k = 0; k < 2; ++k) dst[m][k] = *(const LAS bf16x8*)(lds + PG8_SA(b, h) + aoff + m * 2048 + k * 1024); } while (0)
; #define PG8_MMA(ai, bj, At, Bt) do { __builtin_amdgcn_s_setprio(1); _Pragma("unroll") for (int m = 0; m < 4; ++m) _Pragma("unroll") for (int n = 0; n < 2; ++n) _Pragma("unroll") for (int k = 0; k < 2; ++k) \
;         acc[ai][bj][m][n] = __builtin_amdgcn_mfma_f32_16x16x32_bf16(Bt[n][k], At[m][k], acc[ai][bj][m][n], 0, 0, 0); __builtin_amdgcn_s_setprio(0); } while (0)
; #define PG8_WAIT_V(n) asm volatile("s_waitcnt vmcnt(" #n ")" ::: "memory")
; #define PG8_WAIT_L(n) asm volatile("s_waitcnt lgkmcnt(" #n ")" ::: "memory")
; #define PG8_BAR __builtin_amdgcn_s_barrier()
; #define PG8_SCHED __builtin_amdgcn_sched_barrier(0)
; template <class Epi, bool ALIGN_EPI>
; __device__ __forceinline__ void gemm_phase(LAS unsigned char* lds, const Gemm g, const StaticOrder& S, const Epi& E, const int tid) {
;     ...
;             PG8_LDA(At, 1, 1); PG8_STAGE(PG8_SB(1, 0), b3, voffB); PG8_STAGE(PG8_SB(1, 1), b3 + hstepB, voffB); PG8_STAGE(PG8_SA(1, 0), a3, voffA);
;             PG8_WAIT_V(8); PG8_WAIT_L(0); PG8_BAR; PG8_MMA(1, 0, At, B0); PG8_MMA(1, 1, At, B1); PG8_BAR; PG8_SCHED;
	s_barrier
	s_mov_b32 m0, s88
	v_lshl_add_u64 v[168:169], v[168:169], 0, s[6:7]
	s_add_u32 s50, s54, 0x10080
	s_nop 1
	ds_read_b128 v[10:13], v171 offset:49152
	ds_read_b128 v[14:17], v171 offset:50176
	ds_read_b128 v[172:175], v171 offset:51200
	ds_read_b128 v[176:179], v171 offset:52224
	ds_read_b128 v[180:183], v171 offset:53248
	ds_read_b128 v[192:195], v171 offset:54272
	ds_read_b128 v[196:199], v171 offset:55296
	ds_read_b128 v[214:217], v171 offset:56320
	global_load_lds_dwordx4 v[168:169], off
	v_lshl_add_u64 v[168:169], v[200:201], 0, s[6:7]
	s_mov_b32 m0, s86
	s_addc_u32 s51, s55, 0
	global_load_lds_dwordx4 v[168:169], off
	v_lshl_add_u64 v[168:169], s[50:51], 0, v[0:1]
	s_mov_b32 m0, s52
	s_nop 0
	global_load_lds_dwordx4 v[168:169], off
	v_lshl_add_u64 v[168:169], s[50:51], 0, v[158:159]
	s_mov_b32 m0, s53
	s_nop 0
	global_load_lds_dwordx4 v[168:169], off
	v_lshl_add_u64 v[168:169], v[210:211], 0, s[6:7]
	s_mov_b32 m0, s79
	s_nop 0
	global_load_lds_dwordx4 v[168:169], off
	v_lshl_add_u64 v[168:169], v[234:235], 0, s[6:7]
	s_mov_b32 m0, s80
	s_nop 0
	global_load_lds_dwordx4 v[168:169], off
	s_waitcnt vmcnt(8)
	s_waitcnt lgkmcnt(0)
	s_barrier

; #define PG8_MMA(ai, bj, At, Bt) do { __builtin_amdgcn_s_setprio(1); _Pragma("unroll") for (int m = 0; m < 4; ++m) _Pragma("unroll") for (int n = 0; n < 2; ++n) _Pragma("unroll") for (int k = 0; k < 2; ++k) \
;         acc[ai][bj][m][n] = __builtin_amdgcn_mfma_f32_16x16x32_bf16(Bt[n][k], At[m][k], acc[ai][bj][m][n], 0, 0, 0); __builtin_amdgcn_s_setprio(0); } while (0)
; #define PG8_WAIT_V(n) asm volatile("s_waitcnt vmcnt(" #n ")" ::: "memory")
; #define PG8_WAIT_L(n) asm volatile("s_waitcnt lgkmcnt(" #n ")" ::: "memory")
; #define PG8_BAR __builtin_amdgcn_s_barrier()
; #define PG8_SCHED __builtin_amdgcn_sched_barrier(0)
; template <class Epi, bool ALIGN_EPI>
; __device__ __forceinline__ void gemm_phase(LAS unsigned char* lds, const Gemm g, const StaticOrder& S, const Epi& E, const int tid) {
;     ...
;             PG8_WAIT_V(8); PG8_WAIT_L(0); PG8_BAR; PG8_MMA(1, 0, At, B0); PG8_MMA(1, 1, At, B1); PG8_BAR; PG8_SCHED;
	s_waitcnt lgkmcnt(0)
	v_mfma_f32_16x16x32_bf16 v[50:53], v[114:117], v[10:13], v[50:53]
	v_mfma_f32_16x16x32_bf16 v[82:85], v[114:117], v[172:175], v[82:85]
	v_mfma_f32_16x16x32_bf16 v[98:101], v[114:117], v[180:183], v[98:101]
	v_mfma_f32_16x16x32_bf16 v[114:117], v[114:117], v[196:199], v[118:121]
	v_mfma_f32_16x16x32_bf16 v[58:61], v[138:141], v[10:13], v[58:61]
	v_mfma_f32_16x16x32_bf16 v[90:93], v[138:141], v[172:175], v[90:93]
	v_mfma_f32_16x16x32_bf16 v[106:109], v[138:141], v[180:183], v[106:109]
	v_mfma_f32_16x16x32_bf16 v[118:121], v[134:137], v[214:217], v[114:117]
	v_mfma_f32_16x16x32_bf16 v[114:117], v[138:141], v[196:199], v[126:129]
	v_mfma_f32_16x16x32_bf16 v[50:53], v[134:137], v[14:17], v[50:53]
	v_mfma_f32_16x16x32_bf16 v[58:61], v[142:145], v[14:17], v[58:61]
	v_mfma_f32_16x16x32_bf16 v[82:85], v[134:137], v[176:179], v[82:85]
	v_mfma_f32_16x16x32_bf16 v[90:93], v[142:145], v[176:179], v[90:93]
	v_mfma_f32_16x16x32_bf16 v[98:101], v[134:137], v[192:195], v[98:101]
	v_mfma_f32_16x16x32_bf16 v[106:109], v[142:145], v[192:195], v[106:109]
	v_mfma_f32_16x16x32_bf16 v[126:129], v[142:145], v[214:217], v[114:117]


; #define PG8_MMA(ai, bj, At, Bt) do { __builtin_amdgcn_s_setprio(1); _Pragma("unroll") for (int m = 0; m < 4; ++m) _Pragma("unroll") for (int n = 0; n < 2; ++n) _Pragma("unroll") for (int k = 0; k < 2; ++k) \
;         acc[ai][bj][m][n] = __builtin_amdgcn_mfma_f32_16x16x32_bf16(Bt[n][k], At[m][k], acc[ai][bj][m][n], 0, 0, 0); __builtin_amdgcn_s_setprio(0); } while (0)
; #define PG8_WAIT_V(n) asm volatile("s_waitcnt vmcnt(" #n ")" ::: "memory")
; #define PG8_WAIT_L(n) asm volatile("s_waitcnt lgkmcnt(" #n ")" ::: "memory")
; #define PG8_BAR __builtin_amdgcn_s_barrier()
; #define PG8_SCHED __builtin_amdgcn_sched_barrier(0)
; template <class Epi, bool ALIGN_EPI>
; __device__ __forceinline__ void gemm_phase(LAS unsigned char* lds, const Gemm g, const StaticOrder& S, const Epi& E, const int tid) {
;     ...
;             PG8_WAIT_V(8); PG8_WAIT_L(0); PG8_BAR; PG8_MMA(1, 0, At, B0); PG8_MMA(1, 1, At, B1); PG8_BAR; PG8_SCHED;
	v_mfma_f32_16x16x32_bf16 v[54:57], v[146:149], v[10:13], v[54:57]
	v_mfma_f32_16x16x32_bf16 v[10:13], v[184:187], v[10:13], v[66:69]
	v_mfma_f32_16x16x32_bf16 v[66:69], v[188:191], v[14:17], v[10:13]
	v_mfma_f32_16x16x32_bf16 v[10:13], v[146:149], v[172:175], v[86:89]
	v_mfma_f32_16x16x32_bf16 v[86:89], v[164:167], v[176:179], v[10:13]
	v_mfma_f32_16x16x32_bf16 v[10:13], v[184:187], v[172:175], v[94:97]
	v_mfma_f32_16x16x32_bf16 v[94:97], v[188:191], v[176:179], v[10:13]
	v_mfma_f32_16x16x32_bf16 v[10:13], v[146:149], v[180:183], v[102:105]
	v_mfma_f32_16x16x32_bf16 v[102:105], v[164:167], v[192:195], v[10:13]
	v_mfma_f32_16x16x32_bf16 v[10:13], v[184:187], v[180:183], v[110:113]
	v_mfma_f32_16x16x32_bf16 v[110:113], v[188:191], v[192:195], v[10:13]
	v_mfma_f32_16x16x32_bf16 v[10:13], v[146:149], v[196:199], v[122:125]
	v_mfma_f32_16x16x32_bf16 v[114:117], v[164:167], v[214:217], v[10:13]
	v_mfma_f32_16x16x32_bf16 v[10:13], v[184:187], v[196:199], v[130:133]
	v_mfma_f32_16x16x32_bf16 v[54:57], v[164:167], v[14:17], v[54:57]
	v_mfma_f32_16x16x32_bf16 v[122:125], v[188:191], v[214:217], v[10:13]

; #define PG8_MMA(ai, bj, At, Bt) do { __builtin_amdgcn_s_setprio(1); _Pragma("unroll") for (int m = 0; m < 4; ++m) _Pragma("unroll") for (int n = 0; n < 2; ++n) _Pragma("unroll") for (int k = 0; k < 2; ++k) \
;         acc[ai][bj][m][n] = __builtin_amdgcn_mfma_f32_16x16x32_bf16(Bt[n][k], At[m][k], acc[ai][bj][m][n], 0, 0, 0); __builtin_amdgcn_s_setprio(0); } while (0)
; #define PG8_WAIT_V(n) asm volatile("s_waitcnt vmcnt(" #n ")" ::: "memory")
; #define PG8_WAIT_L(n) asm volatile("s_waitcnt lgkmcnt(" #n ")" ::: "memory")
; #define PG8_BAR __builtin_amdgcn_s_barrier()
; #define PG8_SCHED __builtin_amdgcn_sched_barrier(0)
; template <class Epi, bool ALIGN_EPI>
; __device__ __forceinline__ void gemm_phase(LAS unsigned char* lds, const Gemm g, const StaticOrder& S, const Epi& E, const int tid) {
;     ...
;             PG8_WAIT_V(8); PG8_WAIT_L(0); PG8_BAR; PG8_MMA(1, 0, At, B0); PG8_MMA(1, 1, At, B1); PG8_BAR; PG8_SCHED;
;         }
;         if constexpr (ALIGN_EPI) { if (wr == 0) PG8_BAR; }
	s_barrier
	s_andn2_b64 vcc, exec, s[34:35]
	s_cbranch_vccnz .LBB0_719
	s_barrier

; #define LAS __attribute__((address_space(3)))
; #define CONV_LOADA(e_, k_) do { const int xh_ = min(32 * (e_) + xa, L - 8); rh[k_] = *(const u32x4a4*)(Rc + xh_); asm volatile("" ::: "memory"); rl[k_] = *(const unsigned*)(Rc + xh_ - 2); } while (0)
; template <bool PROMPT, int HALF>
; __device__ __forceinline__ void conv_item(unsigned char* ws, KArgs ka, int ib, int oct, int g, LAS unsigned char* lds, int tid, int lane, int wave) {
;     ...
;     { const bf16* Vg = (const bf16*)(ws + WS_VVT) + (size_t)c * T + (PROMPT ? 0 : TP + 4 * g * LS);
;       __syncthreads();
; #pragma unroll 4
;       for (int it = 0; it < 16; ++it) { const int s_ = (it * 64 + lane) * 8; *(LAS u32x4*)(vl + (s_ >> 8) * 528 + (s_ & 255) * 2) = *(const u32x4*)(Vg + s_); }
;       unsigned zz_ = 0u; asm volatile("" : "+v"(zz_));
;       if (lane < 33) *(LAS u32x4*)(vl + 32 * 528 + lane * 16) = (u32x4){zz_, zz_, zz_, zz_}; }
;     constexpr int NB = PROMPT ? 32 : 8, GS = PROMPT ? 16 : 4;
;     const int nbv = PROMPT ? nn : (nn >> 2);
;     LAS unsigned char* vcol = vl + 16 * kq + (PROMPT ? 0 : 8 * (nn & 3)) * 528;
;     const int zrow = PROMPT ? 32 : 32 - 8 * (nn & 3);
;     constexpr int W = (HALF == 2) ? 8 : 4, MO = (HALF == 1) ? 4 : 0;
;     f32x4 acc[2][W][2];
; #pragma unroll
;     for (int r = 0; r < 2; ++r)
; #pragma unroll
;         for (int q = 0; q < W; ++q)
; #pragma unroll
;             for (int gg = 0; gg < 2; ++gg) acc[r][q][gg] = (f32x4){0.f, 0.f, 0.f, 0.f};
;     constexpr int E0 = PROMPT ? -255 : -63, E1 = PROMPT ? -135 : -39, E2 = PROMPT ? 129 : 33, E3 = PROMPT ? 257 : 65;
;     static_assert((E1 - E0) % 8 == 0 && (E2 - E1) % 8 == 0 && (E3 - E2) % 8 == 0, "segments are whole 8-step blocks");
;     constexpr int DA = (HALF == 2) ? 2 : 4;
;     u32x4 rh[DA]; unsigned rl[DA];
;     u32x4 F0[W], F1[W];
;     ...
; #pragma unroll
;     for (int k = 0; k < DA; ++k) CONV_LOADA(E0 + k, k);
;     { unsigned zz_ = 0u; asm volatile("" : "+v"(zz_));
; #pragma unroll
;       for (int k = 0; k < W; ++k) F1[k] = (u32x4){zz_, zz_, zz_, zz_}; }
.LBB0_728:
	v_add_u32_e32 v4, s23, v7
	v_ashrrev_i32_e32 v5, 31, v4
	v_lshl_add_u64 v[8:9], v[4:5], 1, s[10:11]
	global_load_dwordx4 v[8:11], v[8:9], off
	v_lshrrev_b32_e32 v3, 8, v4
	v_add_u32_e32 v12, 0x200, v4
	v_mad_i32_i24 v3, v3, s58, v2
	v_ashrrev_i32_e32 v13, 31, v12
	s_addk_i32 s23, 0x800
	s_cmpk_eq_i32 s23, 0x2000
	s_waitcnt vmcnt(0)
	ds_write_b128 v3, v[8:11]
	v_lshl_add_u64 v[8:9], v[12:13], 1, s[10:11]
	global_load_dwordx4 v[8:11], v[8:9], off
	v_lshrrev_b32_e32 v3, 8, v12
	v_add_u32_e32 v12, 0x400, v4
	v_mad_i32_i24 v3, v3, s58, v2
	v_ashrrev_i32_e32 v13, 31, v12
	v_add_u32_e32 v4, 0x600, v4
	v_ashrrev_i32_e32 v5, 31, v4
	s_waitcnt vmcnt(0)
	ds_write_b128 v3, v[8:11]
	v_lshl_add_u64 v[8:9], v[12:13], 1, s[10:11]
	global_load_dwordx4 v[8:11], v[8:9], off
	v_lshrrev_b32_e32 v3, 8, v12
	v_mad_i32_i24 v3, v3, s58, v2
	s_waitcnt vmcnt(0)
	ds_write_b128 v3, v[8:11]
	v_lshl_add_u64 v[8:9], v[4:5], 1, s[10:11]
	global_load_dwordx4 v[8:11], v[8:9], off
	v_lshrrev_b32_e32 v3, 8, v4
	v_mad_i32_i24 v3, v3, s58, v2
	s_waitcnt vmcnt(0)
	ds_write_b128 v3, v[8:11]
	s_cbranch_scc0 .LBB0_728
	v_mov_b32_e32 v2, v1
	v_cmp_gt_i32_e32 vcc, 33, v0
	s_and_saveexec_b64 s[10:11], vcc
	v_mov_b32_e32 v3, v2
	v_mov_b32_e32 v4, v2
	v_mov_b32_e32 v5, v2
	v_add_u32_e32 v6, s37, v6
	ds_write_b128 v6, v[2:5] offset:16896
	s_or_b64 exec, exec, s[10:11]
	v_lshrrev_b32_e32 v2, 1, v0
	v_and_b32_e32 v3, 15, v0
	v_lshlrev_b32_e32 v3, 1, v3
	v_and_b32_e32 v2, 56, v2
	v_sub_u32_e32 v215, v2, v3
	v_add_u32_e32 v2, 0xfffff820, v215
	s_add_u32 s10, s19, 0x53a01000
	v_min_i32_e32 v2, 0x7f8, v2
	s_addc_u32 s11, s22, 0
	v_ashrrev_i32_e32 v3, 31, v2
	v_add_u32_e32 v6, 0xfffff840, v215
	v_lshl_add_u64 v[8:9], v[2:3], 1, s[10:11]
	v_min_i32_e32 v10, 0x7f8, v6
	global_load_dwordx4 v[2:5], v[8:9], off
	v_ashrrev_i32_e32 v11, 31, v10
	v_lshl_add_u64 v[14:15], v[10:11], 1, s[10:11]
	global_load_dword v16, v[8:9], off offset:-4
	global_load_dwordx4 v[10:13], v[14:15], off
	v_add_u32_e32 v8, 0xfffff860, v215
	v_min_i32_e32 v8, 0x7f8, v8
	v_ashrrev_i32_e32 v9, 31, v8
	v_mov_b32_e32 v6, v1
	v_lshl_add_u64 v[8:9], v[8:9], 1, s[10:11]
	global_load_dword v20, v[14:15], off offset:-4
	global_load_dwordx4 v[22:25], v[8:9], off
	global_load_dword v46, v[8:9], off offset:-4
	v_and_b32_e32 v7, 24, v7
	v_and_b32_e32 v8, 0x70, v0
	v_bfe_u32 v216, v0, 2, 2
	v_mul_u32_u24_e32 v0, 0x210, v7
	v_sub_u32_e32 v214, 32, v7
	v_or_b32_e32 v217, 4, v216
	v_add3_u32 v0, s37, v8, v0
	v_mov_b32_e32 v7, v6
	v_mov_b32_e32 v8, v6
	v_mov_b32_e32 v9, v6
	s_waitcnt vmcnt(5)
	v_perm_b32 v15, v2, v3, s67
	v_perm_b32 v17, v4, v5, s67
	s_waitcnt vmcnt(4)
	v_perm_b32 v14, v16, v2, s67
	v_perm_b32 v16, v3, v4, s67

	v_add_u32_e32 v18, -3, v216
	v_cmp_gt_u32_e32 vcc, 8, v18
	v_mfma_f32_16x16x32_bf16 v[26:29], v[14:17], v[6:9], 0
	s_nop 0
	v_cndmask_b32_e32 v14, v214, v18, vcc
	v_mad_i32_i24 v102, v14, s58, v0
	ds_read_b128 v[14:17], v102 offset:64
	v_mfma_f32_16x16x32_bf16 v[2:5], v[2:5], v[6:9], 0

	v_add_u32_e32 v18, 0xfffff880, v215
	v_min_i32_e32 v18, 0x7f8, v18
	v_ashrrev_i32_e32 v19, 31, v18
	v_lshl_add_u64 v[18:19], v[18:19], 1, s[10:11]
	global_load_dwordx4 v[30:33], v[18:19], off
	global_load_dword v58, v[18:19], off offset:-4
	s_waitcnt vmcnt(4)
	v_perm_b32 v34, v20, v10, s67
	v_perm_b32 v35, v10, v11, s67
	v_perm_b32 v36, v11, v12, s67
	v_perm_b32 v37, v12, v13, s67

	ds_read_b128 v[18:21], v102 offset:128
	v_mfma_f32_16x16x32_bf16 v[38:41], v[34:37], v[6:9], v[26:29]
	v_mfma_f32_16x16x32_bf16 v[42:45], v[10:13], v[6:9], v[2:5]
	s_waitcnt lgkmcnt(1)
	v_mfma_f32_16x16x32_bf16 v[2:5], v[10:13], v[14:17], v[2:5]
	v_mfma_f32_16x16x32_bf16 v[10:13], v[34:37], v[14:17], v[26:29]

	s_nop 1
	v_add_u32_e32 v26, 0xfffff8a0, v215
	v_min_i32_e32 v26, 0x7f8, v26
	v_ashrrev_i32_e32 v27, 31, v26
	v_lshl_add_u64 v[26:27], v[26:27], 1, s[10:11]
	global_load_dwordx4 v[34:37], v[26:27], off
	global_load_dword v70, v[26:27], off offset:-4
	s_waitcnt vmcnt(4)
	v_perm_b32 v26, v46, v22, s67
	v_perm_b32 v27, v22, v23, s67
	v_perm_b32 v28, v23, v24, s67
	v_perm_b32 v29, v24, v25, s67

	v_mfma_f32_16x16x32_bf16 v[50:53], v[22:25], v[6:9], v[42:45]
	v_mfma_f32_16x16x32_bf16 v[42:45], v[22:25], v[14:17], v[42:45]
	s_waitcnt lgkmcnt(0)
	v_mfma_f32_16x16x32_bf16 v[2:5], v[22:25], v[18:21], v[2:5]
	ds_read_b128 v[22:25], v102 offset:192
	v_mfma_f32_16x16x32_bf16 v[46:49], v[26:29], v[6:9], v[38:41]
	v_mfma_f32_16x16x32_bf16 v[38:41], v[26:29], v[14:17], v[38:41]
	v_mfma_f32_16x16x32_bf16 v[10:13], v[26:29], v[18:21], v[10:13]

	v_add_u32_e32 v26, 0xfffff8c0, v215
	v_min_i32_e32 v26, 0x7f8, v26
	v_ashrrev_i32_e32 v27, 31, v26
	v_lshl_add_u64 v[26:27], v[26:27], 1, s[10:11]
	global_load_dwordx4 v[54:57], v[26:27], off
	global_load_dword v82, v[26:27], off offset:-4
	s_waitcnt vmcnt(4)
	v_perm_b32 v58, v58, v30, s67
	v_perm_b32 v59, v30, v31, s67
	v_perm_b32 v60, v31, v32, s67
	v_perm_b32 v61, v32, v33, s67

	ds_read_b128 v[26:29], v102 offset:256
	v_mfma_f32_16x16x32_bf16 v[62:65], v[58:61], v[6:9], v[46:49]
	v_mfma_f32_16x16x32_bf16 v[66:69], v[30:33], v[6:9], v[50:53]
	v_mfma_f32_16x16x32_bf16 v[50:53], v[30:33], v[14:17], v[50:53]
	v_mfma_f32_16x16x32_bf16 v[46:49], v[58:61], v[14:17], v[46:49]
	v_mfma_f32_16x16x32_bf16 v[42:45], v[30:33], v[18:21], v[42:45]
	v_mfma_f32_16x16x32_bf16 v[38:41], v[58:61], v[18:21], v[38:41]
	s_waitcnt lgkmcnt(1)
	v_mfma_f32_16x16x32_bf16 v[2:5], v[30:33], v[22:25], v[2:5]
	v_mfma_f32_16x16x32_bf16 v[10:13], v[58:61], v[22:25], v[10:13]

	v_add_u32_e32 v30, 0xfffff8e0, v215
	v_min_i32_e32 v30, 0x7f8, v30
	v_ashrrev_i32_e32 v31, 31, v30
	v_lshl_add_u64 v[30:31], v[30:31], 1, s[10:11]
	global_load_dwordx4 v[58:61], v[30:31], off
	global_load_dword v94, v[30:31], off offset:-4
	s_waitcnt vmcnt(4)
	v_perm_b32 v30, v70, v34, s67
	v_perm_b32 v31, v34, v35, s67
	v_perm_b32 v32, v35, v36, s67
	v_perm_b32 v33, v36, v37, s67

	v_mfma_f32_16x16x32_bf16 v[74:77], v[34:37], v[6:9], v[66:69]
	v_mfma_f32_16x16x32_bf16 v[66:69], v[34:37], v[14:17], v[66:69]
	v_mfma_f32_16x16x32_bf16 v[50:53], v[34:37], v[18:21], v[50:53]
	v_mfma_f32_16x16x32_bf16 v[42:45], v[34:37], v[22:25], v[42:45]
	s_waitcnt lgkmcnt(0)
	v_mfma_f32_16x16x32_bf16 v[2:5], v[34:37], v[26:29], v[2:5]
	ds_read_b128 v[34:37], v102 offset:320
	v_mfma_f32_16x16x32_bf16 v[70:73], v[30:33], v[6:9], v[62:65]
	v_mfma_f32_16x16x32_bf16 v[62:65], v[30:33], v[14:17], v[62:65]
	v_mfma_f32_16x16x32_bf16 v[46:49], v[30:33], v[18:21], v[46:49]
	v_mfma_f32_16x16x32_bf16 v[38:41], v[30:33], v[22:25], v[38:41]
	v_mfma_f32_16x16x32_bf16 v[10:13], v[30:33], v[26:29], v[10:13]

	v_add_u32_e32 v30, 0xfffff900, v215
	v_min_i32_e32 v30, 0x7f8, v30
	v_ashrrev_i32_e32 v31, 31, v30
	v_lshl_add_u64 v[30:31], v[30:31], 1, s[10:11]
	global_load_dwordx4 v[78:81], v[30:31], off
	global_load_dword v104, v[30:31], off offset:-4
	s_waitcnt vmcnt(4)
	v_perm_b32 v82, v82, v54, s67
	v_perm_b32 v83, v54, v55, s67
	v_perm_b32 v84, v55, v56, s67
	v_perm_b32 v85, v56, v57, s67

	ds_read_b128 v[30:33], v102 offset:384
	v_mfma_f32_16x16x32_bf16 v[86:89], v[82:85], v[6:9], v[70:73]
	v_mfma_f32_16x16x32_bf16 v[90:93], v[54:57], v[6:9], v[74:77]
	v_mfma_f32_16x16x32_bf16 v[74:77], v[54:57], v[14:17], v[74:77]
	v_mfma_f32_16x16x32_bf16 v[70:73], v[82:85], v[14:17], v[70:73]
	v_mfma_f32_16x16x32_bf16 v[66:69], v[54:57], v[18:21], v[66:69]
	v_mfma_f32_16x16x32_bf16 v[62:65], v[82:85], v[18:21], v[62:65]
	v_mfma_f32_16x16x32_bf16 v[50:53], v[54:57], v[22:25], v[50:53]
	v_mfma_f32_16x16x32_bf16 v[46:49], v[82:85], v[22:25], v[46:49]
	v_mfma_f32_16x16x32_bf16 v[42:45], v[54:57], v[26:29], v[42:45]
	v_mfma_f32_16x16x32_bf16 v[38:41], v[82:85], v[26:29], v[38:41]
	s_waitcnt lgkmcnt(1)
	v_mfma_f32_16x16x32_bf16 v[2:5], v[54:57], v[34:37], v[2:5]
	v_mfma_f32_16x16x32_bf16 v[10:13], v[82:85], v[34:37], v[10:13]

	v_add_u32_e32 v54, 0xfffff920, v215
	v_min_i32_e32 v54, 0x7f8, v54
	v_ashrrev_i32_e32 v55, 31, v54
	v_lshl_add_u64 v[82:83], v[54:55], 1, s[10:11]
	global_load_dwordx4 v[54:57], v[82:83], off
	global_load_dword v118, v[82:83], off offset:-4
	s_waitcnt vmcnt(4)
	v_perm_b32 v82, v94, v58, s67
	v_perm_b32 v83, v58, v59, s67
	v_perm_b32 v84, v59, v60, s67
	v_perm_b32 v85, v60, v61, s67

	v_mfma_f32_16x16x32_bf16 v[98:101], v[58:61], v[6:9], v[90:93]
	v_mfma_f32_16x16x32_bf16 v[90:93], v[58:61], v[14:17], v[90:93]
	v_mfma_f32_16x16x32_bf16 v[74:77], v[58:61], v[18:21], v[74:77]
	v_mfma_f32_16x16x32_bf16 v[66:69], v[58:61], v[22:25], v[66:69]
	v_mfma_f32_16x16x32_bf16 v[50:53], v[58:61], v[26:29], v[50:53]
	v_mfma_f32_16x16x32_bf16 v[42:45], v[58:61], v[34:37], v[42:45]
	s_waitcnt lgkmcnt(0)
	v_mfma_f32_16x16x32_bf16 v[58:61], v[58:61], v[30:33], v[2:5]
	s_nop 2
	ds_read_b128 v[2:5], v102 offset:448
	v_mfma_f32_16x16x32_bf16 v[94:97], v[82:85], v[6:9], v[86:89]
	v_mfma_f32_16x16x32_bf16 v[86:89], v[82:85], v[14:17], v[86:89]
	v_mfma_f32_16x16x32_bf16 v[70:73], v[82:85], v[18:21], v[70:73]
	v_mfma_f32_16x16x32_bf16 v[62:65], v[82:85], v[22:25], v[62:65]
	v_mfma_f32_16x16x32_bf16 v[46:49], v[82:85], v[26:29], v[46:49]
	v_mfma_f32_16x16x32_bf16 v[38:41], v[82:85], v[34:37], v[38:41]
	v_mfma_f32_16x16x32_bf16 v[10:13], v[82:85], v[30:33], v[10:13]

	v_add_u32_e32 v82, 0xfffff940, v215
	v_min_i32_e32 v82, 0x7f8, v82
	v_ashrrev_i32_e32 v83, 31, v82
	v_lshl_add_u64 v[102:103], v[82:83], 1, s[10:11]
	global_load_dwordx4 v[82:85], v[102:103], off
	global_load_dword v120, v[102:103], off offset:-4
	s_waitcnt vmcnt(4)
	v_perm_b32 v102, v104, v78, s67
	v_perm_b32 v103, v78, v79, s67
	v_perm_b32 v104, v79, v80, s67
	v_perm_b32 v105, v80, v81, s67

	s_nop 0
	v_mfma_f32_16x16x32_bf16 v[114:117], v[102:105], v[30:33], v[38:41]
	s_nop 2
	v_add_u32_e32 v38, -2, v216
	v_cmp_gt_u32_e32 vcc, 8, v38
	v_mfma_f32_16x16x32_bf16 v[106:109], v[102:105], v[6:9], v[94:97]
	s_nop 0
	v_cndmask_b32_e32 v38, v214, v38, vcc
	v_mad_i32_i24 v122, v38, s58, v0
	ds_read_b128 v[38:41], v122
	v_mfma_f32_16x16x32_bf16 v[110:113], v[78:81], v[14:17], v[98:101]
	v_mfma_f32_16x16x32_bf16 v[94:97], v[102:105], v[14:17], v[94:97]
	v_mfma_f32_16x16x32_bf16 v[90:93], v[78:81], v[18:21], v[90:93]
	v_mfma_f32_16x16x32_bf16 v[86:89], v[102:105], v[18:21], v[86:89]
	v_mfma_f32_16x16x32_bf16 v[74:77], v[78:81], v[22:25], v[74:77]
	v_mfma_f32_16x16x32_bf16 v[70:73], v[102:105], v[22:25], v[70:73]
	v_mfma_f32_16x16x32_bf16 v[66:69], v[78:81], v[26:29], v[66:69]
	v_mfma_f32_16x16x32_bf16 v[62:65], v[102:105], v[26:29], v[62:65]
	v_mfma_f32_16x16x32_bf16 v[50:53], v[78:81], v[34:37], v[50:53]
	v_mfma_f32_16x16x32_bf16 v[46:49], v[102:105], v[34:37], v[46:49]
	v_mfma_f32_16x16x32_bf16 v[42:45], v[78:81], v[30:33], v[42:45]
	s_waitcnt lgkmcnt(1)
	v_mfma_f32_16x16x32_bf16 v[58:61], v[78:81], v[2:5], v[58:61]
	v_mfma_f32_16x16x32_bf16 v[10:13], v[102:105], v[2:5], v[10:13]
	v_mfma_f32_16x16x32_bf16 v[78:81], v[78:81], v[6:9], v[98:101]

	v_add_u32_e32 v6, 0xfffff960, v215
	v_min_i32_e32 v6, 0x7f8, v6
	v_ashrrev_i32_e32 v7, 31, v6
	v_lshl_add_u64 v[6:7], v[6:7], 1, s[10:11]
	global_load_dwordx4 v[98:101], v[6:7], off
	global_load_dword v123, v[6:7], off offset:-4
	s_waitcnt vmcnt(4)
	v_perm_b32 v102, v118, v54, s67
	v_perm_b32 v103, v54, v55, s67
	v_perm_b32 v104, v55, v56, s67
	v_perm_b32 v105, v56, v57, s67

	ds_read_b128 v[6:9], v122 offset:64
	v_mfma_f32_16x16x32_bf16 v[106:109], v[102:105], v[14:17], v[106:109]
	v_mfma_f32_16x16x32_bf16 v[110:113], v[54:57], v[18:21], v[110:113]
	v_mfma_f32_16x16x32_bf16 v[94:97], v[102:105], v[18:21], v[94:97]
	v_mfma_f32_16x16x32_bf16 v[90:93], v[54:57], v[22:25], v[90:93]
	v_mfma_f32_16x16x32_bf16 v[86:89], v[102:105], v[22:25], v[86:89]
	v_mfma_f32_16x16x32_bf16 v[74:77], v[54:57], v[26:29], v[74:77]
	v_mfma_f32_16x16x32_bf16 v[70:73], v[102:105], v[26:29], v[70:73]
	v_mfma_f32_16x16x32_bf16 v[66:69], v[54:57], v[34:37], v[66:69]
	v_mfma_f32_16x16x32_bf16 v[62:65], v[102:105], v[34:37], v[62:65]
	v_mfma_f32_16x16x32_bf16 v[50:53], v[54:57], v[30:33], v[50:53]
	v_mfma_f32_16x16x32_bf16 v[46:49], v[102:105], v[30:33], v[46:49]
	v_mfma_f32_16x16x32_bf16 v[42:45], v[54:57], v[2:5], v[42:45]
	v_mfma_f32_16x16x32_bf16 v[114:117], v[102:105], v[2:5], v[114:117]
	s_waitcnt lgkmcnt(1)
	v_mfma_f32_16x16x32_bf16 v[58:61], v[54:57], v[38:41], v[58:61]
	v_mfma_f32_16x16x32_bf16 v[10:13], v[102:105], v[38:41], v[10:13]

	v_add_u32_e32 v102, 0xfffff980, v215
	v_min_i32_e32 v102, 0x7f8, v102
	v_ashrrev_i32_e32 v103, 31, v102
	v_lshl_add_u64 v[118:119], v[102:103], 1, s[10:11]
	global_load_dwordx4 v[102:105], v[118:119], off
	global_load_dword v124, v[118:119], off offset:-4
	s_waitcnt vmcnt(4)
	v_perm_b32 v118, v120, v82, s67
	v_perm_b32 v119, v82, v83, s67
	v_perm_b32 v120, v83, v84, s67
	v_perm_b32 v121, v84, v85, s67

	s_nop 0
	v_mfma_f32_16x16x32_bf16 v[106:109], v[118:121], v[18:21], v[106:109]
	v_mfma_f32_16x16x32_bf16 v[94:97], v[118:121], v[22:25], v[94:97]
	v_mfma_f32_16x16x32_bf16 v[86:89], v[118:121], v[26:29], v[86:89]
	v_mfma_f32_16x16x32_bf16 v[70:73], v[118:121], v[34:37], v[70:73]
	v_mfma_f32_16x16x32_bf16 v[62:65], v[118:121], v[30:33], v[62:65]
	v_mfma_f32_16x16x32_bf16 v[46:49], v[118:121], v[2:5], v[46:49]
	v_mfma_f32_16x16x32_bf16 v[114:117], v[118:121], v[38:41], v[114:117]
	s_waitcnt lgkmcnt(0)
	v_mfma_f32_16x16x32_bf16 v[118:121], v[118:121], v[6:9], v[10:13]
	s_nop 2
	ds_read_b128 v[10:13], v122 offset:128
	v_mfma_f32_16x16x32_bf16 v[110:113], v[82:85], v[22:25], v[110:113]
	v_mfma_f32_16x16x32_bf16 v[90:93], v[82:85], v[26:29], v[90:93]
	v_mfma_f32_16x16x32_bf16 v[74:77], v[82:85], v[34:37], v[74:77]
	v_mfma_f32_16x16x32_bf16 v[66:69], v[82:85], v[30:33], v[66:69]
	v_mfma_f32_16x16x32_bf16 v[50:53], v[82:85], v[2:5], v[50:53]
	v_mfma_f32_16x16x32_bf16 v[42:45], v[82:85], v[38:41], v[42:45]
	v_mfma_f32_16x16x32_bf16 v[58:61], v[82:85], v[6:9], v[58:61]
	v_mfma_f32_16x16x32_bf16 v[54:57], v[54:57], v[14:17], v[78:81]

	v_add_u32_e32 v14, 0xfffff9a0, v215
	v_min_i32_e32 v14, 0x7f8, v14
	v_ashrrev_i32_e32 v15, 31, v14
	v_lshl_add_u64 v[14:15], v[14:15], 1, s[10:11]
	global_load_dwordx4 v[78:81], v[14:15], off
	global_load_dword v125, v[14:15], off offset:-4
	s_waitcnt vmcnt(4)
	v_perm_b32 v14, v123, v98, s67
	v_perm_b32 v15, v98, v99, s67
	v_perm_b32 v16, v99, v100, s67
	v_perm_b32 v17, v100, v101, s67

	s_nop 0
	v_mfma_f32_16x16x32_bf16 v[106:109], v[14:17], v[22:25], v[106:109]
	v_mfma_f32_16x16x32_bf16 v[94:97], v[14:17], v[26:29], v[94:97]
	v_mfma_f32_16x16x32_bf16 v[86:89], v[14:17], v[34:37], v[86:89]
	v_mfma_f32_16x16x32_bf16 v[70:73], v[14:17], v[30:33], v[70:73]
	v_mfma_f32_16x16x32_bf16 v[62:65], v[14:17], v[2:5], v[62:65]
	v_mfma_f32_16x16x32_bf16 v[46:49], v[14:17], v[38:41], v[46:49]
	v_mfma_f32_16x16x32_bf16 v[114:117], v[14:17], v[6:9], v[114:117]
	s_waitcnt lgkmcnt(0)
	v_mfma_f32_16x16x32_bf16 v[118:121], v[14:17], v[10:13], v[118:121]
	ds_read_b128 v[14:17], v122 offset:192
	v_mfma_f32_16x16x32_bf16 v[110:113], v[98:101], v[26:29], v[110:113]
	v_mfma_f32_16x16x32_bf16 v[90:93], v[98:101], v[34:37], v[90:93]
	v_mfma_f32_16x16x32_bf16 v[74:77], v[98:101], v[30:33], v[74:77]
	v_mfma_f32_16x16x32_bf16 v[66:69], v[98:101], v[2:5], v[66:69]
	v_mfma_f32_16x16x32_bf16 v[50:53], v[98:101], v[38:41], v[50:53]
	v_mfma_f32_16x16x32_bf16 v[42:45], v[98:101], v[6:9], v[42:45]
	v_mfma_f32_16x16x32_bf16 v[58:61], v[98:101], v[10:13], v[58:61]
	v_mfma_f32_16x16x32_bf16 v[54:57], v[82:85], v[18:21], v[54:57]

	v_add_u32_e32 v18, 0xfffff9c0, v215
	v_min_i32_e32 v18, 0x7f8, v18
	v_ashrrev_i32_e32 v19, 31, v18
	v_lshl_add_u64 v[18:19], v[18:19], 1, s[10:11]
	global_load_dwordx4 v[82:85], v[18:19], off
	global_load_dword v123, v[18:19], off offset:-4
	s_waitcnt vmcnt(4)
	v_perm_b32 v18, v124, v102, s67
	v_perm_b32 v19, v102, v103, s67
	v_perm_b32 v20, v103, v104, s67
	v_perm_b32 v21, v104, v105, s67

	s_nop 0
	v_mfma_f32_16x16x32_bf16 v[106:109], v[18:21], v[26:29], v[106:109]
	v_mfma_f32_16x16x32_bf16 v[94:97], v[18:21], v[34:37], v[94:97]
	v_mfma_f32_16x16x32_bf16 v[86:89], v[18:21], v[30:33], v[86:89]
	v_mfma_f32_16x16x32_bf16 v[70:73], v[18:21], v[2:5], v[70:73]
	v_mfma_f32_16x16x32_bf16 v[62:65], v[18:21], v[38:41], v[62:65]
	v_mfma_f32_16x16x32_bf16 v[46:49], v[18:21], v[6:9], v[46:49]
	v_mfma_f32_16x16x32_bf16 v[114:117], v[18:21], v[10:13], v[114:117]
	s_waitcnt lgkmcnt(0)
	v_mfma_f32_16x16x32_bf16 v[118:121], v[18:21], v[14:17], v[118:121]
	ds_read_b128 v[18:21], v122 offset:256
	v_mfma_f32_16x16x32_bf16 v[110:113], v[102:105], v[34:37], v[110:113]
	v_mfma_f32_16x16x32_bf16 v[90:93], v[102:105], v[30:33], v[90:93]
	v_mfma_f32_16x16x32_bf16 v[74:77], v[102:105], v[2:5], v[74:77]
	v_mfma_f32_16x16x32_bf16 v[66:69], v[102:105], v[38:41], v[66:69]
	v_mfma_f32_16x16x32_bf16 v[50:53], v[102:105], v[6:9], v[50:53]
	v_mfma_f32_16x16x32_bf16 v[42:45], v[102:105], v[10:13], v[42:45]
	v_mfma_f32_16x16x32_bf16 v[58:61], v[102:105], v[14:17], v[58:61]
	v_mfma_f32_16x16x32_bf16 v[54:57], v[98:101], v[22:25], v[54:57]

	v_add_u32_e32 v22, 0xfffff9e0, v215
	v_min_i32_e32 v22, 0x7f8, v22
	v_ashrrev_i32_e32 v23, 31, v22
	v_lshl_add_u64 v[22:23], v[22:23], 1, s[10:11]
	global_load_dwordx4 v[98:101], v[22:23], off
	global_load_dword v124, v[22:23], off offset:-4
	s_waitcnt vmcnt(4)
	v_perm_b32 v22, v125, v78, s67
	v_perm_b32 v23, v78, v79, s67
	v_perm_b32 v24, v79, v80, s67
	v_perm_b32 v25, v80, v81, s67

	s_nop 0
	v_mfma_f32_16x16x32_bf16 v[106:109], v[22:25], v[34:37], v[106:109]
	v_mfma_f32_16x16x32_bf16 v[94:97], v[22:25], v[30:33], v[94:97]
	v_mfma_f32_16x16x32_bf16 v[86:89], v[22:25], v[2:5], v[86:89]
	v_mfma_f32_16x16x32_bf16 v[70:73], v[22:25], v[38:41], v[70:73]
	v_mfma_f32_16x16x32_bf16 v[62:65], v[22:25], v[6:9], v[62:65]
	v_mfma_f32_16x16x32_bf16 v[46:49], v[22:25], v[10:13], v[46:49]
	v_mfma_f32_16x16x32_bf16 v[114:117], v[22:25], v[14:17], v[114:117]
	s_waitcnt lgkmcnt(0)
	v_mfma_f32_16x16x32_bf16 v[118:121], v[22:25], v[18:21], v[118:121]
	ds_read_b128 v[22:25], v122 offset:320
	v_mfma_f32_16x16x32_bf16 v[110:113], v[78:81], v[30:33], v[110:113]
	v_mfma_f32_16x16x32_bf16 v[90:93], v[78:81], v[2:5], v[90:93]
	v_mfma_f32_16x16x32_bf16 v[74:77], v[78:81], v[38:41], v[74:77]
	v_mfma_f32_16x16x32_bf16 v[66:69], v[78:81], v[6:9], v[66:69]
	v_mfma_f32_16x16x32_bf16 v[50:53], v[78:81], v[10:13], v[50:53]
	v_mfma_f32_16x16x32_bf16 v[42:45], v[78:81], v[14:17], v[42:45]
	v_mfma_f32_16x16x32_bf16 v[58:61], v[78:81], v[18:21], v[58:61]
	v_mfma_f32_16x16x32_bf16 v[54:57], v[102:105], v[26:29], v[54:57]

	v_add_u32_e32 v26, 0xfffffa00, v215
	v_min_i32_e32 v26, 0x7f8, v26
	v_ashrrev_i32_e32 v27, 31, v26
	v_lshl_add_u64 v[26:27], v[26:27], 1, s[10:11]
	global_load_dwordx4 v[102:105], v[26:27], off
	global_load_dword v125, v[26:27], off offset:-4
	s_waitcnt vmcnt(4)
	v_perm_b32 v26, v123, v82, s67
	v_perm_b32 v27, v82, v83, s67
	v_perm_b32 v28, v83, v84, s67
	v_perm_b32 v29, v84, v85, s67

	s_nop 0
	v_mfma_f32_16x16x32_bf16 v[106:109], v[26:29], v[30:33], v[106:109]
	v_mfma_f32_16x16x32_bf16 v[94:97], v[26:29], v[2:5], v[94:97]
	v_mfma_f32_16x16x32_bf16 v[86:89], v[26:29], v[38:41], v[86:89]
	v_mfma_f32_16x16x32_bf16 v[70:73], v[26:29], v[6:9], v[70:73]
	v_mfma_f32_16x16x32_bf16 v[62:65], v[26:29], v[10:13], v[62:65]
	v_mfma_f32_16x16x32_bf16 v[46:49], v[26:29], v[14:17], v[46:49]
	v_mfma_f32_16x16x32_bf16 v[114:117], v[26:29], v[18:21], v[114:117]
	s_waitcnt lgkmcnt(0)
	v_mfma_f32_16x16x32_bf16 v[118:121], v[26:29], v[22:25], v[118:121]
	ds_read_b128 v[26:29], v122 offset:384
	v_mfma_f32_16x16x32_bf16 v[110:113], v[82:85], v[2:5], v[110:113]
	v_mfma_f32_16x16x32_bf16 v[90:93], v[82:85], v[38:41], v[90:93]
	v_mfma_f32_16x16x32_bf16 v[74:77], v[82:85], v[6:9], v[74:77]
	v_mfma_f32_16x16x32_bf16 v[66:69], v[82:85], v[10:13], v[66:69]
	v_mfma_f32_16x16x32_bf16 v[50:53], v[82:85], v[14:17], v[50:53]
	v_mfma_f32_16x16x32_bf16 v[42:45], v[82:85], v[18:21], v[42:45]
	v_mfma_f32_16x16x32_bf16 v[58:61], v[82:85], v[22:25], v[58:61]
	v_mfma_f32_16x16x32_bf16 v[54:57], v[78:81], v[34:37], v[54:57]

	v_add_u32_e32 v34, 0xfffffa20, v215
	v_min_i32_e32 v34, 0x7f8, v34
	v_ashrrev_i32_e32 v35, 31, v34
	v_lshl_add_u64 v[34:35], v[34:35], 1, s[10:11]
	global_load_dwordx4 v[78:81], v[34:35], off
	global_load_dword v126, v[34:35], off offset:-4
	s_waitcnt vmcnt(4)
	v_perm_b32 v34, v124, v98, s67
	v_perm_b32 v35, v98, v99, s67
	v_perm_b32 v36, v99, v100, s67
	v_perm_b32 v37, v100, v101, s67

	s_nop 0
	v_mfma_f32_16x16x32_bf16 v[106:109], v[34:37], v[2:5], v[106:109]
	v_mfma_f32_16x16x32_bf16 v[94:97], v[34:37], v[38:41], v[94:97]
	v_mfma_f32_16x16x32_bf16 v[86:89], v[34:37], v[6:9], v[86:89]
	v_mfma_f32_16x16x32_bf16 v[70:73], v[34:37], v[10:13], v[70:73]
	v_mfma_f32_16x16x32_bf16 v[62:65], v[34:37], v[14:17], v[62:65]
	v_mfma_f32_16x16x32_bf16 v[46:49], v[34:37], v[18:21], v[46:49]
	v_mfma_f32_16x16x32_bf16 v[114:117], v[34:37], v[22:25], v[114:117]
	s_waitcnt lgkmcnt(0)
	v_mfma_f32_16x16x32_bf16 v[118:121], v[34:37], v[26:29], v[118:121]
	ds_read_b128 v[34:37], v122 offset:448
	v_mfma_f32_16x16x32_bf16 v[110:113], v[98:101], v[38:41], v[110:113]
	v_mfma_f32_16x16x32_bf16 v[90:93], v[98:101], v[6:9], v[90:93]
	v_mfma_f32_16x16x32_bf16 v[74:77], v[98:101], v[10:13], v[74:77]
	v_mfma_f32_16x16x32_bf16 v[66:69], v[98:101], v[14:17], v[66:69]
	v_mfma_f32_16x16x32_bf16 v[50:53], v[98:101], v[18:21], v[50:53]
	v_mfma_f32_16x16x32_bf16 v[42:45], v[98:101], v[22:25], v[42:45]
	v_mfma_f32_16x16x32_bf16 v[58:61], v[98:101], v[26:29], v[58:61]
	v_mfma_f32_16x16x32_bf16 v[30:33], v[82:85], v[30:33], v[54:57]

	s_nop 1
	v_add_u32_e32 v54, 0xfffffa40, v215
	v_min_i32_e32 v54, 0x7f8, v54
	v_ashrrev_i32_e32 v55, 31, v54
	v_lshl_add_u64 v[82:83], v[54:55], 1, s[10:11]
	global_load_dwordx4 v[54:57], v[82:83], off
	global_load_dword v127, v[82:83], off offset:-4
	s_waitcnt vmcnt(4)
	v_perm_b32 v82, v125, v102, s67
	v_perm_b32 v83, v102, v103, s67
	v_perm_b32 v84, v103, v104, s67
	v_perm_b32 v85, v104, v105, s67

	v_mfma_f32_16x16x32_bf16 v[122:125], v[102:105], v[26:29], v[42:45]
	s_nop 2
	v_add_u32_e32 v42, -1, v216
	v_mfma_f32_16x16x32_bf16 v[2:5], v[98:101], v[2:5], v[30:33]
	v_cmp_gt_u32_e32 vcc, 8, v42
	s_nop 1
	v_cndmask_b32_e32 v30, v214, v42, vcc
	v_mad_i32_i24 v130, v30, s58, v0
	ds_read_b128 v[42:45], v130
	v_mfma_f32_16x16x32_bf16 v[106:109], v[82:85], v[38:41], v[106:109]
	v_mfma_f32_16x16x32_bf16 v[110:113], v[102:105], v[6:9], v[110:113]
	v_mfma_f32_16x16x32_bf16 v[94:97], v[82:85], v[6:9], v[94:97]
	v_mfma_f32_16x16x32_bf16 v[90:93], v[102:105], v[10:13], v[90:93]
	v_mfma_f32_16x16x32_bf16 v[86:89], v[82:85], v[10:13], v[86:89]
	v_mfma_f32_16x16x32_bf16 v[74:77], v[102:105], v[14:17], v[74:77]
	v_mfma_f32_16x16x32_bf16 v[70:73], v[82:85], v[14:17], v[70:73]
	v_mfma_f32_16x16x32_bf16 v[66:69], v[102:105], v[18:21], v[66:69]
	v_mfma_f32_16x16x32_bf16 v[62:65], v[82:85], v[18:21], v[62:65]
	v_mfma_f32_16x16x32_bf16 v[50:53], v[102:105], v[22:25], v[50:53]
	v_mfma_f32_16x16x32_bf16 v[46:49], v[82:85], v[22:25], v[46:49]
	v_mfma_f32_16x16x32_bf16 v[114:117], v[82:85], v[26:29], v[114:117]
	s_waitcnt lgkmcnt(1)
	v_mfma_f32_16x16x32_bf16 v[58:61], v[102:105], v[34:37], v[58:61]
	v_mfma_f32_16x16x32_bf16 v[82:85], v[82:85], v[34:37], v[118:121]
	v_mfma_f32_16x16x32_bf16 v[2:5], v[102:105], v[38:41], v[2:5]

	v_add_u32_e32 v30, 0xfffffa60, v215
	v_min_i32_e32 v30, 0x7f8, v30
	v_ashrrev_i32_e32 v31, 31, v30
	v_lshl_add_u64 v[38:39], v[30:31], 1, s[10:11]
	global_load_dwordx4 v[30:33], v[38:39], off
	global_load_dword v128, v[38:39], off offset:-4
	s_waitcnt vmcnt(4)
	v_perm_b32 v38, v126, v78, s67
	v_perm_b32 v39, v78, v79, s67
	v_perm_b32 v40, v79, v80, s67
	v_perm_b32 v41, v80, v81, s67

	s_nop 0
	v_mfma_f32_16x16x32_bf16 v[98:101], v[38:41], v[6:9], v[106:109]
	v_mfma_f32_16x16x32_bf16 v[106:109], v[78:81], v[18:21], v[74:77]
	s_nop 2
	ds_read_b128 v[74:77], v130 offset:64
	v_mfma_f32_16x16x32_bf16 v[102:105], v[78:81], v[10:13], v[110:113]
	v_mfma_f32_16x16x32_bf16 v[94:97], v[38:41], v[10:13], v[94:97]
	v_mfma_f32_16x16x32_bf16 v[90:93], v[78:81], v[14:17], v[90:93]
	v_mfma_f32_16x16x32_bf16 v[86:89], v[38:41], v[14:17], v[86:89]
	v_mfma_f32_16x16x32_bf16 v[70:73], v[38:41], v[18:21], v[70:73]
	v_mfma_f32_16x16x32_bf16 v[66:69], v[78:81], v[22:25], v[66:69]
	v_mfma_f32_16x16x32_bf16 v[62:65], v[38:41], v[22:25], v[62:65]
	v_mfma_f32_16x16x32_bf16 v[50:53], v[78:81], v[26:29], v[50:53]
	v_mfma_f32_16x16x32_bf16 v[46:49], v[38:41], v[26:29], v[46:49]
	v_mfma_f32_16x16x32_bf16 v[110:113], v[78:81], v[34:37], v[122:125]
	v_mfma_f32_16x16x32_bf16 v[114:117], v[38:41], v[34:37], v[114:117]
	s_waitcnt lgkmcnt(1)
	v_mfma_f32_16x16x32_bf16 v[58:61], v[78:81], v[42:45], v[58:61]
	v_mfma_f32_16x16x32_bf16 v[38:41], v[38:41], v[42:45], v[82:85]

	s_nop 1
	v_add_u32_e32 v82, 0xfffffa80, v215
	v_min_i32_e32 v82, 0x7f8, v82
	v_ashrrev_i32_e32 v83, 31, v82
	v_lshl_add_u64 v[82:83], v[82:83], 1, s[10:11]
	global_load_dwordx4 v[118:121], v[82:83], off
	global_load_dword v126, v[82:83], off offset:-4
	s_waitcnt vmcnt(4)
	v_perm_b32 v82, v127, v54, s67
	v_perm_b32 v83, v54, v55, s67
	v_perm_b32 v84, v55, v56, s67
	v_perm_b32 v85, v56, v57, s67

	s_nop 0
	v_mfma_f32_16x16x32_bf16 v[98:101], v[82:85], v[10:13], v[98:101]
	v_mfma_f32_16x16x32_bf16 v[94:97], v[82:85], v[14:17], v[94:97]
	v_mfma_f32_16x16x32_bf16 v[86:89], v[82:85], v[18:21], v[86:89]
	v_mfma_f32_16x16x32_bf16 v[70:73], v[82:85], v[22:25], v[70:73]
	v_mfma_f32_16x16x32_bf16 v[62:65], v[82:85], v[26:29], v[62:65]
	v_mfma_f32_16x16x32_bf16 v[46:49], v[82:85], v[34:37], v[46:49]
	v_mfma_f32_16x16x32_bf16 v[114:117], v[82:85], v[42:45], v[114:117]
	s_waitcnt lgkmcnt(0)
	v_mfma_f32_16x16x32_bf16 v[38:41], v[82:85], v[74:77], v[38:41]
	ds_read_b128 v[82:85], v130 offset:128
	v_mfma_f32_16x16x32_bf16 v[102:105], v[54:57], v[14:17], v[102:105]
	v_mfma_f32_16x16x32_bf16 v[90:93], v[54:57], v[18:21], v[90:93]
	v_mfma_f32_16x16x32_bf16 v[106:109], v[54:57], v[22:25], v[106:109]
	v_mfma_f32_16x16x32_bf16 v[66:69], v[54:57], v[26:29], v[66:69]
	v_mfma_f32_16x16x32_bf16 v[50:53], v[54:57], v[34:37], v[50:53]
	v_mfma_f32_16x16x32_bf16 v[110:113], v[54:57], v[42:45], v[110:113]
	v_mfma_f32_16x16x32_bf16 v[58:61], v[54:57], v[74:77], v[58:61]
	v_mfma_f32_16x16x32_bf16 v[2:5], v[78:81], v[6:9], v[2:5]

	v_add_u32_e32 v6, 0xfffffaa0, v215
	v_min_i32_e32 v6, 0x7f8, v6
	v_ashrrev_i32_e32 v7, 31, v6
	v_lshl_add_u64 v[78:79], v[6:7], 1, s[10:11]
	global_load_dwordx4 v[6:9], v[78:79], off
	global_load_dword v127, v[78:79], off offset:-4
	s_waitcnt vmcnt(4)
	v_perm_b32 v78, v128, v30, s67
	v_perm_b32 v79, v30, v31, s67
	v_perm_b32 v80, v31, v32, s67
	v_perm_b32 v81, v32, v33, s67

	v_mfma_f32_16x16x32_bf16 v[122:125], v[30:33], v[22:25], v[90:93]
	s_nop 2
	ds_read_b128 v[90:93], v130 offset:192
	v_mfma_f32_16x16x32_bf16 v[98:101], v[78:81], v[14:17], v[98:101]
	v_mfma_f32_16x16x32_bf16 v[102:105], v[30:33], v[18:21], v[102:105]
	v_mfma_f32_16x16x32_bf16 v[94:97], v[78:81], v[18:21], v[94:97]
	v_mfma_f32_16x16x32_bf16 v[86:89], v[78:81], v[22:25], v[86:89]
	v_mfma_f32_16x16x32_bf16 v[106:109], v[30:33], v[26:29], v[106:109]
	v_mfma_f32_16x16x32_bf16 v[70:73], v[78:81], v[26:29], v[70:73]
	v_mfma_f32_16x16x32_bf16 v[66:69], v[30:33], v[34:37], v[66:69]
	v_mfma_f32_16x16x32_bf16 v[62:65], v[78:81], v[34:37], v[62:65]
	v_mfma_f32_16x16x32_bf16 v[50:53], v[30:33], v[42:45], v[50:53]
	v_mfma_f32_16x16x32_bf16 v[46:49], v[78:81], v[42:45], v[46:49]
	v_mfma_f32_16x16x32_bf16 v[110:113], v[30:33], v[74:77], v[110:113]
	v_mfma_f32_16x16x32_bf16 v[114:117], v[78:81], v[74:77], v[114:117]
	s_waitcnt lgkmcnt(1)
	v_mfma_f32_16x16x32_bf16 v[58:61], v[30:33], v[82:85], v[58:61]
	v_mfma_f32_16x16x32_bf16 v[38:41], v[78:81], v[82:85], v[38:41]
	v_mfma_f32_16x16x32_bf16 v[2:5], v[54:57], v[10:13], v[2:5]

	v_add_u32_e32 v10, 0xfffffac0, v215
	v_min_i32_e32 v10, 0x7f8, v10
	v_ashrrev_i32_e32 v11, 31, v10
	v_lshl_add_u64 v[54:55], v[10:11], 1, s[10:11]
	global_load_dwordx4 v[10:13], v[54:55], off
	global_load_dword v131, v[54:55], off offset:-4
	s_waitcnt vmcnt(4)
	v_perm_b32 v54, v126, v118, s67
	v_perm_b32 v55, v118, v119, s67
	v_perm_b32 v56, v119, v120, s67
	v_perm_b32 v57, v120, v121, s67

	s_nop 0
	v_mfma_f32_16x16x32_bf16 v[78:81], v[54:57], v[18:21], v[98:101]
	v_mfma_f32_16x16x32_bf16 v[98:101], v[118:121], v[22:25], v[102:105]
	s_nop 2
	ds_read_b128 v[102:105], v130 offset:256
	v_mfma_f32_16x16x32_bf16 v[94:97], v[54:57], v[22:25], v[94:97]
	v_mfma_f32_16x16x32_bf16 v[122:125], v[118:121], v[26:29], v[122:125]
	v_mfma_f32_16x16x32_bf16 v[86:89], v[54:57], v[26:29], v[86:89]
	v_mfma_f32_16x16x32_bf16 v[106:109], v[118:121], v[34:37], v[106:109]
	v_mfma_f32_16x16x32_bf16 v[70:73], v[54:57], v[34:37], v[70:73]
	v_mfma_f32_16x16x32_bf16 v[66:69], v[118:121], v[42:45], v[66:69]
	v_mfma_f32_16x16x32_bf16 v[62:65], v[54:57], v[42:45], v[62:65]
	v_mfma_f32_16x16x32_bf16 v[50:53], v[118:121], v[74:77], v[50:53]
	v_mfma_f32_16x16x32_bf16 v[46:49], v[54:57], v[74:77], v[46:49]
	v_mfma_f32_16x16x32_bf16 v[110:113], v[118:121], v[82:85], v[110:113]
	v_mfma_f32_16x16x32_bf16 v[114:117], v[54:57], v[82:85], v[114:117]
	s_waitcnt lgkmcnt(1)
	v_mfma_f32_16x16x32_bf16 v[58:61], v[118:121], v[90:93], v[58:61]
	v_mfma_f32_16x16x32_bf16 v[38:41], v[54:57], v[90:93], v[38:41]
	v_mfma_f32_16x16x32_bf16 v[2:5], v[30:33], v[14:17], v[2:5]

	v_add_u32_e32 v14, 0xfffffae0, v215
	v_min_i32_e32 v14, 0x7f8, v14
	v_ashrrev_i32_e32 v15, 31, v14
	v_lshl_add_u64 v[14:15], v[14:15], 1, s[10:11]
	global_load_dwordx4 v[54:57], v[14:15], off
	global_load_dword v132, v[14:15], off offset:-4
	s_waitcnt vmcnt(4)
	v_perm_b32 v14, v127, v6, s67
	v_perm_b32 v15, v6, v7, s67
	v_perm_b32 v16, v7, v8, s67
	v_perm_b32 v17, v8, v9, s67

	ds_read_b128 v[126:129], v130 offset:320
	v_mfma_f32_16x16x32_bf16 v[30:33], v[14:17], v[22:25], v[78:81]
	v_mfma_f32_16x16x32_bf16 v[78:81], v[6:9], v[26:29], v[98:101]
	v_mfma_f32_16x16x32_bf16 v[94:97], v[14:17], v[26:29], v[94:97]
	v_mfma_f32_16x16x32_bf16 v[98:101], v[6:9], v[34:37], v[122:125]
	v_mfma_f32_16x16x32_bf16 v[86:89], v[14:17], v[34:37], v[86:89]
	v_mfma_f32_16x16x32_bf16 v[106:109], v[6:9], v[42:45], v[106:109]
	v_mfma_f32_16x16x32_bf16 v[70:73], v[14:17], v[42:45], v[70:73]
	v_mfma_f32_16x16x32_bf16 v[66:69], v[6:9], v[74:77], v[66:69]
	v_mfma_f32_16x16x32_bf16 v[62:65], v[14:17], v[74:77], v[62:65]
	v_mfma_f32_16x16x32_bf16 v[50:53], v[6:9], v[82:85], v[50:53]
	v_mfma_f32_16x16x32_bf16 v[46:49], v[14:17], v[82:85], v[46:49]
	v_mfma_f32_16x16x32_bf16 v[110:113], v[6:9], v[90:93], v[110:113]
	v_mfma_f32_16x16x32_bf16 v[114:117], v[14:17], v[90:93], v[114:117]
	s_waitcnt lgkmcnt(1)
	v_mfma_f32_16x16x32_bf16 v[58:61], v[6:9], v[102:105], v[58:61]
	v_mfma_f32_16x16x32_bf16 v[14:17], v[14:17], v[102:105], v[38:41]
	v_mfma_f32_16x16x32_bf16 v[2:5], v[118:121], v[18:21], v[2:5]

	v_add_u32_e32 v18, 0xfffffb00, v215
	v_min_i32_e32 v18, 0x7f8, v18
	v_ashrrev_i32_e32 v19, 31, v18
	v_lshl_add_u64 v[18:19], v[18:19], 1, s[10:11]
	global_load_dwordx4 v[38:41], v[18:19], off
	global_load_dword v118, v[18:19], off offset:-4
	s_waitcnt vmcnt(4)
	v_perm_b32 v18, v131, v10, s67
	v_perm_b32 v19, v10, v11, s67
	v_perm_b32 v20, v11, v12, s67
	v_perm_b32 v21, v12, v13, s67

	ds_read_b128 v[142:145], v130 offset:384
	v_mfma_f32_16x16x32_bf16 v[30:33], v[18:21], v[26:29], v[30:33]
	v_mfma_f32_16x16x32_bf16 v[78:81], v[10:13], v[34:37], v[78:81]
	v_mfma_f32_16x16x32_bf16 v[94:97], v[18:21], v[34:37], v[94:97]
	v_mfma_f32_16x16x32_bf16 v[98:101], v[10:13], v[42:45], v[98:101]
	v_mfma_f32_16x16x32_bf16 v[86:89], v[18:21], v[42:45], v[86:89]
	v_mfma_f32_16x16x32_bf16 v[106:109], v[10:13], v[74:77], v[106:109]
	v_mfma_f32_16x16x32_bf16 v[70:73], v[18:21], v[74:77], v[70:73]
	v_mfma_f32_16x16x32_bf16 v[66:69], v[10:13], v[82:85], v[66:69]
	v_mfma_f32_16x16x32_bf16 v[62:65], v[18:21], v[82:85], v[62:65]
	v_mfma_f32_16x16x32_bf16 v[50:53], v[10:13], v[90:93], v[50:53]
	v_mfma_f32_16x16x32_bf16 v[46:49], v[18:21], v[90:93], v[46:49]
	v_mfma_f32_16x16x32_bf16 v[110:113], v[10:13], v[102:105], v[110:113]
	v_mfma_f32_16x16x32_bf16 v[114:117], v[18:21], v[102:105], v[114:117]
	s_waitcnt lgkmcnt(1)
	v_mfma_f32_16x16x32_bf16 v[58:61], v[10:13], v[126:129], v[58:61]
	v_mfma_f32_16x16x32_bf16 v[14:17], v[18:21], v[126:129], v[14:17]
	v_mfma_f32_16x16x32_bf16 v[2:5], v[6:9], v[22:25], v[2:5]

	v_add_u32_e32 v6, 0xfffffb20, v215
	v_min_i32_e32 v6, 0x7f8, v6
	v_ashrrev_i32_e32 v7, 31, v6
	v_lshl_add_u64 v[6:7], v[6:7], 1, s[10:11]
	global_load_dwordx4 v[162:165], v[6:7], off
	global_load_dword v219, v[6:7], off offset:-4
	s_waitcnt vmcnt(4)
	v_perm_b32 v6, v132, v54, s67
	v_perm_b32 v7, v54, v55, s67
	v_perm_b32 v8, v55, v56, s67
	v_perm_b32 v9, v56, v57, s67

	ds_read_b128 v[150:153], v130 offset:448
	v_mfma_f32_16x16x32_bf16 v[18:21], v[6:9], v[34:37], v[30:33]
	v_mfma_f32_16x16x32_bf16 v[22:25], v[54:57], v[42:45], v[78:81]
	v_mfma_f32_16x16x32_bf16 v[30:33], v[6:9], v[42:45], v[94:97]
	v_mfma_f32_16x16x32_bf16 v[78:81], v[54:57], v[74:77], v[98:101]
	v_mfma_f32_16x16x32_bf16 v[86:89], v[6:9], v[74:77], v[86:89]
	v_mfma_f32_16x16x32_bf16 v[94:97], v[54:57], v[82:85], v[106:109]
	v_mfma_f32_16x16x32_bf16 v[70:73], v[6:9], v[82:85], v[70:73]
	v_mfma_f32_16x16x32_bf16 v[66:69], v[54:57], v[90:93], v[66:69]
	v_mfma_f32_16x16x32_bf16 v[62:65], v[6:9], v[90:93], v[62:65]
	v_mfma_f32_16x16x32_bf16 v[50:53], v[54:57], v[102:105], v[50:53]
	v_mfma_f32_16x16x32_bf16 v[46:49], v[6:9], v[102:105], v[46:49]
	v_mfma_f32_16x16x32_bf16 v[110:113], v[54:57], v[126:129], v[110:113]
	v_mfma_f32_16x16x32_bf16 v[134:137], v[6:9], v[126:129], v[114:117]
	s_waitcnt lgkmcnt(1)
	v_mfma_f32_16x16x32_bf16 v[58:61], v[54:57], v[142:145], v[58:61]
	v_mfma_f32_16x16x32_bf16 v[138:141], v[6:9], v[142:145], v[14:17]
	v_mfma_f32_16x16x32_bf16 v[146:149], v[10:13], v[26:29], v[2:5]

	s_nop 1
	v_add_u32_e32 v2, 0xfffffb40, v215
	v_min_i32_e32 v2, 0x7f8, v2
	v_ashrrev_i32_e32 v3, 31, v2
	v_lshl_add_u64 v[2:3], v[2:3], 1, s[10:11]
	global_load_dwordx4 v[166:169], v[2:3], off
	global_load_dword v220, v[2:3], off offset:-4
	s_waitcnt vmcnt(4)
	v_perm_b32 v2, v118, v38, s67
	v_perm_b32 v3, v38, v39, s67
	v_perm_b32 v4, v39, v40, s67
	v_perm_b32 v5, v40, v41, s67

	v_mfma_f32_16x16x32_bf16 v[34:37], v[54:57], v[34:37], v[146:149]
	v_mfma_f32_16x16x32_bf16 v[130:133], v[2:5], v[42:45], v[18:21]
	v_mfma_f32_16x16x32_bf16 v[18:21], v[2:5], v[126:129], v[46:49]
	s_nop 2
	v_mad_u32_u24 v46, v216, s58, v0
	ds_read_b128 v[158:161], v46
	v_mfma_f32_16x16x32_bf16 v[122:125], v[38:41], v[74:77], v[22:25]
	v_mfma_f32_16x16x32_bf16 v[118:121], v[2:5], v[74:77], v[30:33]
	v_mfma_f32_16x16x32_bf16 v[114:117], v[38:41], v[82:85], v[78:81]
	v_mfma_f32_16x16x32_bf16 v[106:109], v[2:5], v[82:85], v[86:89]
	v_mfma_f32_16x16x32_bf16 v[98:101], v[38:41], v[90:93], v[94:97]
	v_mfma_f32_16x16x32_bf16 v[94:97], v[2:5], v[90:93], v[70:73]
	v_mfma_f32_16x16x32_bf16 v[30:33], v[38:41], v[102:105], v[66:69]
	v_mfma_f32_16x16x32_bf16 v[26:29], v[2:5], v[102:105], v[62:65]
	v_mfma_f32_16x16x32_bf16 v[22:25], v[38:41], v[126:129], v[50:53]
	v_mfma_f32_16x16x32_bf16 v[14:17], v[38:41], v[142:145], v[110:113]
	v_mfma_f32_16x16x32_bf16 v[10:13], v[2:5], v[142:145], v[134:137]
	s_waitcnt lgkmcnt(1)
	v_mfma_f32_16x16x32_bf16 v[6:9], v[38:41], v[150:153], v[58:61]
	v_mfma_f32_16x16x32_bf16 v[2:5], v[2:5], v[150:153], v[138:141]
	v_mfma_f32_16x16x32_bf16 v[138:141], v[38:41], v[42:45], v[34:37]

; #define CONV_BLOCK(DO0, DO1) do { CONV_STEP(0, DO0, DO1); CONV_STEP(1, DO0, DO1); CONV_STEP(2, DO0, DO1); CONV_STEP(3, DO0, DO1); CONV_STEP(4, DO0, DO1); CONV_STEP(5, DO0, DO1); CONV_STEP(6, DO0, DO1); CONV_STEP(7, DO0, DO1); } while (0)
; template <bool PROMPT, int HALF>
; __device__ __forceinline__ void conv_item(unsigned char* ws, KArgs ka, int ib, int oct, int g, LAS unsigned char* lds, int tid, int lane, int wave) {
;     ...
;     { unsigned zz_ = 0u; asm volatile("" : "+v"(zz_));
; #pragma unroll
;       for (int k = 0; k < W; ++k) F0[k] = (u32x4){zz_, zz_, zz_, zz_}; }
;     for (int e = E1; e < E2; e += 8) CONV_BLOCK(true, true);
	v_mov_b32_e32 v66, v1
	s_nop 0
	v_mov_b32_e32 v34, 0
	v_add_u32_e32 v218, 0xfffffb60, v215
	s_movk_i32 s19, 0xffd1
	s_movk_i32 s22, 0xf640
	v_mov_b32_e32 v35, v34
	v_mov_b32_e32 v36, v34
	v_mov_b32_e32 v37, v34
	v_mov_b32_e32 v38, v34
	v_mov_b32_e32 v39, v34
	v_mov_b32_e32 v40, v34
	v_mov_b32_e32 v41, v34
	v_mov_b32_e32 v46, v34
	v_mov_b32_e32 v47, v34
	v_mov_b32_e32 v48, v34
	v_mov_b32_e32 v49, v34
	v_mov_b32_e32 v54, v34
	v_mov_b32_e32 v55, v34
	v_mov_b32_e32 v56, v34
	v_mov_b32_e32 v57, v34
	v_mov_b32_e32 v170, v34
	v_mov_b32_e32 v171, v34
	v_mov_b32_e32 v172, v34
	v_mov_b32_e32 v173, v34
	v_mov_b32_e32 v174, v34
	v_mov_b32_e32 v175, v34
	v_mov_b32_e32 v176, v34
	v_mov_b32_e32 v177, v34
	v_mov_b32_e32 v182, v34
	v_mov_b32_e32 v183, v34
	v_mov_b32_e32 v184, v34
	v_mov_b32_e32 v185, v34
	v_mov_b32_e32 v190, v34
	v_mov_b32_e32 v191, v34
	v_mov_b32_e32 v192, v34
	v_mov_b32_e32 v193, v34
	v_mov_b32_e32 v42, v34
	v_mov_b32_e32 v43, v34
	v_mov_b32_e32 v44, v34
	v_mov_b32_e32 v45, v34
	v_mov_b32_e32 v50, v34
	v_mov_b32_e32 v51, v34
	v_mov_b32_e32 v52, v34
	v_mov_b32_e32 v53, v34
	v_mov_b32_e32 v58, v34
	v_mov_b32_e32 v59, v34
	v_mov_b32_e32 v60, v34
	v_mov_b32_e32 v61, v34
	v_mov_b32_e32 v62, v34
	v_mov_b32_e32 v63, v34
	v_mov_b32_e32 v64, v34
	v_mov_b32_e32 v65, v34
	v_mov_b32_e32 v178, v34
	v_mov_b32_e32 v179, v34
	v_mov_b32_e32 v180, v34
	v_mov_b32_e32 v181, v34
	v_mov_b32_e32 v186, v34
	v_mov_b32_e32 v187, v34
	v_mov_b32_e32 v188, v34
	v_mov_b32_e32 v189, v34
	v_mov_b32_e32 v198, v34
	v_mov_b32_e32 v199, v34
	v_mov_b32_e32 v200, v34
	v_mov_b32_e32 v201, v34
	v_mov_b32_e32 v194, v34
	v_mov_b32_e32 v195, v34
	v_mov_b32_e32 v196, v34
	v_mov_b32_e32 v197, v34
	v_mov_b32_e32 v67, v66
	v_mov_b32_e32 v68, v66
	v_mov_b32_e32 v69, v66
	v_mov_b32_e32 v70, v66
	v_mov_b32_e32 v71, v66
	v_mov_b32_e32 v72, v66
	v_mov_b32_e32 v73, v66
	v_mov_b32_e32 v78, v66
	v_mov_b32_e32 v79, v66
	v_mov_b32_e32 v80, v66
	v_mov_b32_e32 v81, v66
	v_mov_b32_e32 v86, v66
	v_mov_b32_e32 v87, v66
	v_mov_b32_e32 v88, v66
	v_mov_b32_e32 v89, v66
	v_mov_b32_e32 v110, v66
	v_mov_b32_e32 v111, v66
	v_mov_b32_e32 v112, v66
	v_mov_b32_e32 v113, v66
	v_mov_b32_e32 v134, v66
	v_mov_b32_e32 v135, v66
	v_mov_b32_e32 v136, v66
	v_mov_b32_e32 v137, v66
	v_mov_b32_e32 v146, v66
	v_mov_b32_e32 v147, v66
	v_mov_b32_e32 v148, v66
	v_mov_b32_e32 v149, v66
	v_mov_b32_e32 v154, v66
	v_mov_b32_e32 v155, v66
	v_mov_b32_e32 v156, v66
	v_mov_b32_e32 v157, v66
.LBB0_732:
	v_min_i32_e32 v210, 0x7f8, v218
	v_ashrrev_i32_e32 v211, 31, v210
	v_lshl_add_u64 v[210:211], v[210:211], 1, s[10:11]
	global_load_dwordx4 v[222:225], v[210:211], off
	global_load_dword v221, v[210:211], off offset:-4
	s_waitcnt vmcnt(4)
	v_perm_b32 v226, v219, v162, s67
	v_perm_b32 v227, v162, v163, s67
	v_perm_b32 v228, v163, v164, s67
	v_perm_b32 v229, v164, v165, s67

	s_add_i32 s23, s19, 16
	s_ashr_i32 s23, s23, 3
	v_mfma_f32_16x16x32_bf16 v[138:141], v[162:165], v[74:77], v[138:141]
	s_and_b32 s30, s22, 0x1c0
	v_mfma_f32_16x16x32_bf16 v[130:133], v[226:229], v[74:77], v[130:133]
	v_add_u32_e32 v74, s23, v216
	v_add_u32_e32 v75, s23, v217
	v_cmp_gt_u32_e32 vcc, 8, v74
	v_mfma_f32_16x16x32_bf16 v[194:197], v[162:165], v[154:157], v[194:197]
	s_nop 0
	v_cndmask_b32_e32 v74, v214, v74, vcc
	v_cmp_gt_u32_e32 vcc, 8, v75
	v_mul_lo_u32 v74, v74, s58
	v_add3_u32 v74, v0, v74, s30
	v_cndmask_b32_e32 v75, v214, v75, vcc
	v_mul_lo_u32 v75, v75, s58
	v_add3_u32 v75, v0, v75, s30
	v_mfma_f32_16x16x32_bf16 v[190:193], v[226:229], v[154:157], v[190:193]
	ds_read_b128 v[154:157], v74
	ds_read_b128 v[74:77], v75
	v_mfma_f32_16x16x32_bf16 v[198:201], v[162:165], v[146:149], v[198:201]
	v_mfma_f32_16x16x32_bf16 v[182:185], v[226:229], v[146:149], v[182:185]
	v_mfma_f32_16x16x32_bf16 v[122:125], v[162:165], v[82:85], v[122:125]
	v_mfma_f32_16x16x32_bf16 v[118:121], v[226:229], v[82:85], v[118:121]
	v_mfma_f32_16x16x32_bf16 v[186:189], v[162:165], v[134:137], v[186:189]
	v_mfma_f32_16x16x32_bf16 v[174:177], v[226:229], v[134:137], v[174:177]
	v_mfma_f32_16x16x32_bf16 v[114:117], v[162:165], v[90:93], v[114:117]
	v_mfma_f32_16x16x32_bf16 v[106:109], v[226:229], v[90:93], v[106:109]
	v_mfma_f32_16x16x32_bf16 v[178:181], v[162:165], v[110:113], v[178:181]
	v_mfma_f32_16x16x32_bf16 v[170:173], v[226:229], v[110:113], v[170:173]
	v_mfma_f32_16x16x32_bf16 v[98:101], v[162:165], v[102:105], v[98:101]
	v_mfma_f32_16x16x32_bf16 v[94:97], v[226:229], v[102:105], v[94:97]
	v_mfma_f32_16x16x32_bf16 v[62:65], v[162:165], v[86:89], v[62:65]
	v_mfma_f32_16x16x32_bf16 v[54:57], v[226:229], v[86:89], v[54:57]
	v_mfma_f32_16x16x32_bf16 v[30:33], v[162:165], v[126:129], v[30:33]
	v_mfma_f32_16x16x32_bf16 v[26:29], v[226:229], v[126:129], v[26:29]
	v_mfma_f32_16x16x32_bf16 v[58:61], v[162:165], v[78:81], v[58:61]
	v_mfma_f32_16x16x32_bf16 v[46:49], v[226:229], v[78:81], v[46:49]
	v_mfma_f32_16x16x32_bf16 v[22:25], v[162:165], v[142:145], v[22:25]
	v_mfma_f32_16x16x32_bf16 v[18:21], v[226:229], v[142:145], v[18:21]
	v_mfma_f32_16x16x32_bf16 v[50:53], v[162:165], v[70:73], v[50:53]
	v_mfma_f32_16x16x32_bf16 v[38:41], v[226:229], v[70:73], v[38:41]
	v_mfma_f32_16x16x32_bf16 v[14:17], v[162:165], v[150:153], v[14:17]
	v_mfma_f32_16x16x32_bf16 v[10:13], v[226:229], v[150:153], v[10:13]
	s_waitcnt lgkmcnt(3)
	v_mfma_f32_16x16x32_bf16 v[42:45], v[162:165], v[66:69], v[42:45]
	v_mfma_f32_16x16x32_bf16 v[34:37], v[226:229], v[66:69], v[34:37]
	s_waitcnt lgkmcnt(2)
	v_mfma_f32_16x16x32_bf16 v[6:9], v[162:165], v[158:161], v[6:9]
	v_mfma_f32_16x16x32_bf16 v[2:5], v[226:229], v[158:161], v[2:5]

	v_add_u32_e32 v162, 32, v218
	v_min_i32_e32 v162, 0x7f8, v162
	v_ashrrev_i32_e32 v163, 31, v162
	v_lshl_add_u64 v[210:211], v[162:163], 1, s[10:11]
	global_load_dwordx4 v[162:165], v[210:211], off
	global_load_dword v219, v[210:211], off offset:-4
	s_waitcnt vmcnt(4)
	v_perm_b32 v226, v220, v166, s67
	v_perm_b32 v227, v166, v167, s67
	v_perm_b32 v228, v167, v168, s67
	v_perm_b32 v229, v168, v169, s67

	s_add_i32 s23, s19, 17
	s_ashr_i32 s23, s23, 3
	v_mfma_f32_16x16x32_bf16 v[138:141], v[166:169], v[82:85], v[138:141]
	s_add_i32 s30, s22, 0x240
	s_and_b32 s30, s30, 0x1c0
	v_mfma_f32_16x16x32_bf16 v[130:133], v[226:229], v[82:85], v[130:133]
	v_add_u32_e32 v82, s23, v216
	v_add_u32_e32 v83, s23, v217
	v_cmp_gt_u32_e32 vcc, 8, v82
	v_mfma_f32_16x16x32_bf16 v[194:197], v[166:169], v[146:149], v[194:197]
	s_nop 0
	v_cndmask_b32_e32 v82, v214, v82, vcc
	v_cmp_gt_u32_e32 vcc, 8, v83
	v_mul_lo_u32 v82, v82, s58
	v_add3_u32 v82, v0, v82, s30
	v_cndmask_b32_e32 v83, v214, v83, vcc
	v_mul_lo_u32 v83, v83, s58
	v_add3_u32 v83, v0, v83, s30
	v_mfma_f32_16x16x32_bf16 v[190:193], v[226:229], v[146:149], v[190:193]
	ds_read_b128 v[146:149], v82
	ds_read_b128 v[82:85], v83
	v_mfma_f32_16x16x32_bf16 v[198:201], v[166:169], v[134:137], v[198:201]
	v_mfma_f32_16x16x32_bf16 v[182:185], v[226:229], v[134:137], v[182:185]
	v_mfma_f32_16x16x32_bf16 v[122:125], v[166:169], v[90:93], v[122:125]
	v_mfma_f32_16x16x32_bf16 v[118:121], v[226:229], v[90:93], v[118:121]
	v_mfma_f32_16x16x32_bf16 v[186:189], v[166:169], v[110:113], v[186:189]
	v_mfma_f32_16x16x32_bf16 v[174:177], v[226:229], v[110:113], v[174:177]
	v_mfma_f32_16x16x32_bf16 v[114:117], v[166:169], v[102:105], v[114:117]
	v_mfma_f32_16x16x32_bf16 v[106:109], v[226:229], v[102:105], v[106:109]
	v_mfma_f32_16x16x32_bf16 v[178:181], v[166:169], v[86:89], v[178:181]
	v_mfma_f32_16x16x32_bf16 v[170:173], v[226:229], v[86:89], v[170:173]
	v_mfma_f32_16x16x32_bf16 v[98:101], v[166:169], v[126:129], v[98:101]
	v_mfma_f32_16x16x32_bf16 v[94:97], v[226:229], v[126:129], v[94:97]
	v_mfma_f32_16x16x32_bf16 v[62:65], v[166:169], v[78:81], v[62:65]
	v_mfma_f32_16x16x32_bf16 v[54:57], v[226:229], v[78:81], v[54:57]
	v_mfma_f32_16x16x32_bf16 v[30:33], v[166:169], v[142:145], v[30:33]
	v_mfma_f32_16x16x32_bf16 v[26:29], v[226:229], v[142:145], v[26:29]
	v_mfma_f32_16x16x32_bf16 v[58:61], v[166:169], v[70:73], v[58:61]
	v_mfma_f32_16x16x32_bf16 v[46:49], v[226:229], v[70:73], v[46:49]
	v_mfma_f32_16x16x32_bf16 v[22:25], v[166:169], v[150:153], v[22:25]
	v_mfma_f32_16x16x32_bf16 v[18:21], v[226:229], v[150:153], v[18:21]
	v_mfma_f32_16x16x32_bf16 v[50:53], v[166:169], v[66:69], v[50:53]
	v_mfma_f32_16x16x32_bf16 v[38:41], v[226:229], v[66:69], v[38:41]
	v_mfma_f32_16x16x32_bf16 v[14:17], v[166:169], v[158:161], v[14:17]
	v_mfma_f32_16x16x32_bf16 v[10:13], v[226:229], v[158:161], v[10:13]
	s_waitcnt lgkmcnt(3)
	v_mfma_f32_16x16x32_bf16 v[42:45], v[166:169], v[154:157], v[42:45]
	v_mfma_f32_16x16x32_bf16 v[34:37], v[226:229], v[154:157], v[34:37]
	s_waitcnt lgkmcnt(2)
	v_mfma_f32_16x16x32_bf16 v[6:9], v[166:169], v[74:77], v[6:9]
	v_mfma_f32_16x16x32_bf16 v[2:5], v[226:229], v[74:77], v[2:5]

	v_add_u32_e32 v166, 64, v218
	v_min_i32_e32 v166, 0x7f8, v166
	v_ashrrev_i32_e32 v167, 31, v166
	v_lshl_add_u64 v[210:211], v[166:167], 1, s[10:11]
	global_load_dwordx4 v[166:169], v[210:211], off
	global_load_dword v230, v[210:211], off offset:-4
	s_waitcnt vmcnt(4)
	v_perm_b32 v226, v221, v222, s67
	v_perm_b32 v227, v222, v223, s67
	v_perm_b32 v228, v223, v224, s67
	v_perm_b32 v229, v224, v225, s67

	s_add_i32 s23, s19, 18
	s_ashr_i32 s23, s23, 3
	v_mfma_f32_16x16x32_bf16 v[138:141], v[222:225], v[90:93], v[138:141]
	s_add_i32 s30, s22, 0x280
	s_and_b32 s30, s30, 0x1c0
	v_mfma_f32_16x16x32_bf16 v[130:133], v[226:229], v[90:93], v[130:133]
	v_add_u32_e32 v90, s23, v216
	v_add_u32_e32 v91, s23, v217
	v_cmp_gt_u32_e32 vcc, 8, v90
	v_mfma_f32_16x16x32_bf16 v[194:197], v[222:225], v[134:137], v[194:197]
	s_nop 0
	v_cndmask_b32_e32 v90, v214, v90, vcc
	v_cmp_gt_u32_e32 vcc, 8, v91
	v_mul_lo_u32 v90, v90, s58
	v_add3_u32 v90, v0, v90, s30
	v_cndmask_b32_e32 v91, v214, v91, vcc
	v_mul_lo_u32 v91, v91, s58
	v_add3_u32 v91, v0, v91, s30
	v_mfma_f32_16x16x32_bf16 v[190:193], v[226:229], v[134:137], v[190:193]
	ds_read_b128 v[134:137], v90
	ds_read_b128 v[90:93], v91
	v_mfma_f32_16x16x32_bf16 v[198:201], v[222:225], v[110:113], v[198:201]
	v_mfma_f32_16x16x32_bf16 v[182:185], v[226:229], v[110:113], v[182:185]
	v_mfma_f32_16x16x32_bf16 v[122:125], v[222:225], v[102:105], v[122:125]
	v_mfma_f32_16x16x32_bf16 v[118:121], v[226:229], v[102:105], v[118:121]
	v_mfma_f32_16x16x32_bf16 v[186:189], v[222:225], v[86:89], v[186:189]
	v_mfma_f32_16x16x32_bf16 v[174:177], v[226:229], v[86:89], v[174:177]
	v_mfma_f32_16x16x32_bf16 v[114:117], v[222:225], v[126:129], v[114:117]
	v_mfma_f32_16x16x32_bf16 v[106:109], v[226:229], v[126:129], v[106:109]
	v_mfma_f32_16x16x32_bf16 v[178:181], v[222:225], v[78:81], v[178:181]
	v_mfma_f32_16x16x32_bf16 v[170:173], v[226:229], v[78:81], v[170:173]
	v_mfma_f32_16x16x32_bf16 v[98:101], v[222:225], v[142:145], v[98:101]
	v_mfma_f32_16x16x32_bf16 v[94:97], v[226:229], v[142:145], v[94:97]
	v_mfma_f32_16x16x32_bf16 v[62:65], v[222:225], v[70:73], v[62:65]
	v_mfma_f32_16x16x32_bf16 v[54:57], v[226:229], v[70:73], v[54:57]
	v_mfma_f32_16x16x32_bf16 v[30:33], v[222:225], v[150:153], v[30:33]
	v_mfma_f32_16x16x32_bf16 v[26:29], v[226:229], v[150:153], v[26:29]
	v_mfma_f32_16x16x32_bf16 v[58:61], v[222:225], v[66:69], v[58:61]
	v_mfma_f32_16x16x32_bf16 v[46:49], v[226:229], v[66:69], v[46:49]
	v_mfma_f32_16x16x32_bf16 v[22:25], v[222:225], v[158:161], v[22:25]
	v_mfma_f32_16x16x32_bf16 v[18:21], v[226:229], v[158:161], v[18:21]
	v_mfma_f32_16x16x32_bf16 v[50:53], v[222:225], v[154:157], v[50:53]
	v_mfma_f32_16x16x32_bf16 v[38:41], v[226:229], v[154:157], v[38:41]
	v_mfma_f32_16x16x32_bf16 v[14:17], v[222:225], v[74:77], v[14:17]
	v_mfma_f32_16x16x32_bf16 v[10:13], v[226:229], v[74:77], v[10:13]
	s_waitcnt lgkmcnt(3)
	v_mfma_f32_16x16x32_bf16 v[42:45], v[222:225], v[146:149], v[42:45]
	v_mfma_f32_16x16x32_bf16 v[34:37], v[226:229], v[146:149], v[34:37]
	s_waitcnt lgkmcnt(2)
	v_mfma_f32_16x16x32_bf16 v[6:9], v[222:225], v[82:85], v[6:9]
	v_mfma_f32_16x16x32_bf16 v[2:5], v[226:229], v[82:85], v[2:5]

	v_add_u32_e32 v210, 0x60, v218
	v_min_i32_e32 v210, 0x7f8, v210
	v_ashrrev_i32_e32 v211, 31, v210
	v_lshl_add_u64 v[210:211], v[210:211], 1, s[10:11]
	global_load_dwordx4 v[220:223], v[210:211], off
	global_load_dword v210, v[210:211], off offset:-4
	s_waitcnt vmcnt(4)
	v_perm_b32 v224, v219, v162, s67
	v_perm_b32 v225, v162, v163, s67
	v_perm_b32 v226, v163, v164, s67
	v_perm_b32 v227, v164, v165, s67

	s_add_i32 s23, s19, 19
	s_ashr_i32 s23, s23, 3
	v_mfma_f32_16x16x32_bf16 v[138:141], v[162:165], v[102:105], v[138:141]
	s_add_i32 s30, s22, 0x2c0
	s_and_b32 s30, s30, 0x1c0
	v_mfma_f32_16x16x32_bf16 v[130:133], v[224:227], v[102:105], v[130:133]
	v_add_u32_e32 v102, s23, v216
	v_add_u32_e32 v103, s23, v217
	v_cmp_gt_u32_e32 vcc, 8, v102
	v_mfma_f32_16x16x32_bf16 v[194:197], v[162:165], v[110:113], v[194:197]
	s_nop 0
	v_cndmask_b32_e32 v102, v214, v102, vcc
	v_cmp_gt_u32_e32 vcc, 8, v103
	v_mul_lo_u32 v102, v102, s58
	v_add3_u32 v102, v0, v102, s30
	v_cndmask_b32_e32 v103, v214, v103, vcc
	v_mul_lo_u32 v103, v103, s58
	v_add3_u32 v103, v0, v103, s30
	v_mfma_f32_16x16x32_bf16 v[190:193], v[224:227], v[110:113], v[190:193]
	ds_read_b128 v[110:113], v102
	ds_read_b128 v[102:105], v103
	v_mfma_f32_16x16x32_bf16 v[198:201], v[162:165], v[86:89], v[198:201]
	v_mfma_f32_16x16x32_bf16 v[182:185], v[224:227], v[86:89], v[182:185]
	v_mfma_f32_16x16x32_bf16 v[122:125], v[162:165], v[126:129], v[122:125]
	v_mfma_f32_16x16x32_bf16 v[118:121], v[224:227], v[126:129], v[118:121]
	v_mfma_f32_16x16x32_bf16 v[186:189], v[162:165], v[78:81], v[186:189]
	v_mfma_f32_16x16x32_bf16 v[174:177], v[224:227], v[78:81], v[174:177]
	v_mfma_f32_16x16x32_bf16 v[114:117], v[162:165], v[142:145], v[114:117]
	v_mfma_f32_16x16x32_bf16 v[106:109], v[224:227], v[142:145], v[106:109]
	v_mfma_f32_16x16x32_bf16 v[178:181], v[162:165], v[70:73], v[178:181]
	v_mfma_f32_16x16x32_bf16 v[170:173], v[224:227], v[70:73], v[170:173]
	v_mfma_f32_16x16x32_bf16 v[98:101], v[162:165], v[150:153], v[98:101]
	v_mfma_f32_16x16x32_bf16 v[94:97], v[224:227], v[150:153], v[94:97]
	v_mfma_f32_16x16x32_bf16 v[62:65], v[162:165], v[66:69], v[62:65]
	v_mfma_f32_16x16x32_bf16 v[54:57], v[224:227], v[66:69], v[54:57]
	v_mfma_f32_16x16x32_bf16 v[30:33], v[162:165], v[158:161], v[30:33]
	v_mfma_f32_16x16x32_bf16 v[26:29], v[224:227], v[158:161], v[26:29]
	v_mfma_f32_16x16x32_bf16 v[58:61], v[162:165], v[154:157], v[58:61]
	v_mfma_f32_16x16x32_bf16 v[46:49], v[224:227], v[154:157], v[46:49]
	v_mfma_f32_16x16x32_bf16 v[22:25], v[162:165], v[74:77], v[22:25]
	v_mfma_f32_16x16x32_bf16 v[18:21], v[224:227], v[74:77], v[18:21]
	v_mfma_f32_16x16x32_bf16 v[50:53], v[162:165], v[146:149], v[50:53]
	v_mfma_f32_16x16x32_bf16 v[38:41], v[224:227], v[146:149], v[38:41]
	v_mfma_f32_16x16x32_bf16 v[14:17], v[162:165], v[82:85], v[14:17]
	v_mfma_f32_16x16x32_bf16 v[10:13], v[224:227], v[82:85], v[10:13]
	s_waitcnt lgkmcnt(3)
	v_mfma_f32_16x16x32_bf16 v[42:45], v[162:165], v[134:137], v[42:45]
	v_mfma_f32_16x16x32_bf16 v[34:37], v[224:227], v[134:137], v[34:37]
	s_waitcnt lgkmcnt(2)
	v_mfma_f32_16x16x32_bf16 v[6:9], v[162:165], v[90:93], v[6:9]
	v_mfma_f32_16x16x32_bf16 v[2:5], v[224:227], v[90:93], v[2:5]

	v_add_u32_e32 v162, 0x80, v218
	v_min_i32_e32 v162, 0x7f8, v162
	v_ashrrev_i32_e32 v163, 31, v162
	v_lshl_add_u64 v[162:163], v[162:163], 1, s[10:11]
	global_load_dwordx4 v[224:227], v[162:163], off
	global_load_dword v211, v[162:163], off offset:-4
	s_waitcnt vmcnt(4)
	v_perm_b32 v162, v230, v166, s67
	v_perm_b32 v163, v166, v167, s67
	v_perm_b32 v164, v167, v168, s67
	v_perm_b32 v165, v168, v169, s67

	s_add_i32 s23, s19, 20
	s_ashr_i32 s23, s23, 3
	v_mfma_f32_16x16x32_bf16 v[194:197], v[166:169], v[86:89], v[194:197]
	s_add_i32 s30, s22, 0x300
	s_and_b32 s30, s30, 0x1c0
	v_mfma_f32_16x16x32_bf16 v[190:193], v[162:165], v[86:89], v[190:193]
	v_add_u32_e32 v86, s23, v216
	v_add_u32_e32 v87, s23, v217
	v_cmp_gt_u32_e32 vcc, 8, v86
	v_mfma_f32_16x16x32_bf16 v[138:141], v[166:169], v[126:129], v[138:141]
	s_nop 0
	v_cndmask_b32_e32 v86, v214, v86, vcc
	v_cmp_gt_u32_e32 vcc, 8, v87
	v_mul_lo_u32 v86, v86, s58
	v_mfma_f32_16x16x32_bf16 v[130:133], v[162:165], v[126:129], v[130:133]
	v_cndmask_b32_e32 v87, v214, v87, vcc
	v_mul_lo_u32 v87, v87, s58
	v_add3_u32 v86, v0, v86, s30
	v_add3_u32 v126, v0, v87, s30
	ds_read_b128 v[86:89], v86
	ds_read_b128 v[126:129], v126
	v_mfma_f32_16x16x32_bf16 v[198:201], v[166:169], v[78:81], v[198:201]
	v_mfma_f32_16x16x32_bf16 v[182:185], v[162:165], v[78:81], v[182:185]
	v_mfma_f32_16x16x32_bf16 v[122:125], v[166:169], v[142:145], v[122:125]
	v_mfma_f32_16x16x32_bf16 v[118:121], v[162:165], v[142:145], v[118:121]
	v_mfma_f32_16x16x32_bf16 v[186:189], v[166:169], v[70:73], v[186:189]
	v_mfma_f32_16x16x32_bf16 v[174:177], v[162:165], v[70:73], v[174:177]
	v_mfma_f32_16x16x32_bf16 v[114:117], v[166:169], v[150:153], v[114:117]
	v_mfma_f32_16x16x32_bf16 v[106:109], v[162:165], v[150:153], v[106:109]
	v_mfma_f32_16x16x32_bf16 v[178:181], v[166:169], v[66:69], v[178:181]
	v_mfma_f32_16x16x32_bf16 v[170:173], v[162:165], v[66:69], v[170:173]
	v_mfma_f32_16x16x32_bf16 v[98:101], v[166:169], v[158:161], v[98:101]
	v_mfma_f32_16x16x32_bf16 v[94:97], v[162:165], v[158:161], v[94:97]
	v_mfma_f32_16x16x32_bf16 v[62:65], v[166:169], v[154:157], v[62:65]
	v_mfma_f32_16x16x32_bf16 v[54:57], v[162:165], v[154:157], v[54:57]
	v_mfma_f32_16x16x32_bf16 v[30:33], v[166:169], v[74:77], v[30:33]
	v_mfma_f32_16x16x32_bf16 v[26:29], v[162:165], v[74:77], v[26:29]
	v_mfma_f32_16x16x32_bf16 v[58:61], v[166:169], v[146:149], v[58:61]
	v_mfma_f32_16x16x32_bf16 v[46:49], v[162:165], v[146:149], v[46:49]
	v_mfma_f32_16x16x32_bf16 v[22:25], v[166:169], v[82:85], v[22:25]
	v_mfma_f32_16x16x32_bf16 v[18:21], v[162:165], v[82:85], v[18:21]
	v_mfma_f32_16x16x32_bf16 v[50:53], v[166:169], v[134:137], v[50:53]
	v_mfma_f32_16x16x32_bf16 v[38:41], v[162:165], v[134:137], v[38:41]
	v_mfma_f32_16x16x32_bf16 v[14:17], v[166:169], v[90:93], v[14:17]
	v_mfma_f32_16x16x32_bf16 v[10:13], v[162:165], v[90:93], v[10:13]
	s_waitcnt lgkmcnt(3)
	v_mfma_f32_16x16x32_bf16 v[42:45], v[166:169], v[110:113], v[42:45]
	v_mfma_f32_16x16x32_bf16 v[34:37], v[162:165], v[110:113], v[34:37]
	s_waitcnt lgkmcnt(2)
	v_mfma_f32_16x16x32_bf16 v[6:9], v[166:169], v[102:105], v[6:9]
	v_mfma_f32_16x16x32_bf16 v[2:5], v[162:165], v[102:105], v[2:5]

	v_add_u32_e32 v162, 0xa0, v218
	v_min_i32_e32 v162, 0x7f8, v162
	v_ashrrev_i32_e32 v163, 31, v162
	v_lshl_add_u64 v[162:163], v[162:163], 1, s[10:11]
	global_load_dwordx4 v[228:231], v[162:163], off
	global_load_dword v236, v[162:163], off offset:-4
	s_waitcnt vmcnt(4)
	v_perm_b32 v162, v210, v220, s67
	v_perm_b32 v163, v220, v221, s67
	v_perm_b32 v164, v221, v222, s67
	v_perm_b32 v165, v222, v223, s67

	s_add_i32 s23, s19, 21
	s_ashr_i32 s23, s23, 3
	v_mfma_f32_16x16x32_bf16 v[166:169], v[220:223], v[78:81], v[194:197]
	s_add_i32 s30, s22, 0x340
	s_and_b32 s30, s30, 0x1c0
	v_mfma_f32_16x16x32_bf16 v[190:193], v[162:165], v[78:81], v[190:193]
	v_add_u32_e32 v78, s23, v216
	v_add_u32_e32 v79, s23, v217
	v_cmp_gt_u32_e32 vcc, 8, v78
	v_mfma_f32_16x16x32_bf16 v[138:141], v[220:223], v[142:145], v[138:141]
	s_nop 0
	v_cndmask_b32_e32 v78, v214, v78, vcc
	v_cmp_gt_u32_e32 vcc, 8, v79
	v_mul_lo_u32 v78, v78, s58
	v_mfma_f32_16x16x32_bf16 v[130:133], v[162:165], v[142:145], v[130:133]
	v_cndmask_b32_e32 v79, v214, v79, vcc
	v_mul_lo_u32 v79, v79, s58
	v_add3_u32 v78, v0, v78, s30
	v_add3_u32 v142, v0, v79, s30
	ds_read_b128 v[78:81], v78
	ds_read_b128 v[142:145], v142
	v_mfma_f32_16x16x32_bf16 v[194:197], v[220:223], v[70:73], v[198:201]
	v_mfma_f32_16x16x32_bf16 v[182:185], v[162:165], v[70:73], v[182:185]
	v_mfma_f32_16x16x32_bf16 v[122:125], v[220:223], v[150:153], v[122:125]
	v_mfma_f32_16x16x32_bf16 v[118:121], v[162:165], v[150:153], v[118:121]
	v_mfma_f32_16x16x32_bf16 v[186:189], v[220:223], v[66:69], v[186:189]
	v_mfma_f32_16x16x32_bf16 v[174:177], v[162:165], v[66:69], v[174:177]
	v_mfma_f32_16x16x32_bf16 v[114:117], v[220:223], v[158:161], v[114:117]
	v_mfma_f32_16x16x32_bf16 v[106:109], v[162:165], v[158:161], v[106:109]
	v_mfma_f32_16x16x32_bf16 v[178:181], v[220:223], v[154:157], v[178:181]
	v_mfma_f32_16x16x32_bf16 v[170:173], v[162:165], v[154:157], v[170:173]
	v_mfma_f32_16x16x32_bf16 v[98:101], v[220:223], v[74:77], v[98:101]
	v_mfma_f32_16x16x32_bf16 v[94:97], v[162:165], v[74:77], v[94:97]
	v_mfma_f32_16x16x32_bf16 v[62:65], v[220:223], v[146:149], v[62:65]
	v_mfma_f32_16x16x32_bf16 v[54:57], v[162:165], v[146:149], v[54:57]
	v_mfma_f32_16x16x32_bf16 v[30:33], v[220:223], v[82:85], v[30:33]
	v_mfma_f32_16x16x32_bf16 v[26:29], v[162:165], v[82:85], v[26:29]
	v_mfma_f32_16x16x32_bf16 v[58:61], v[220:223], v[134:137], v[58:61]
	v_mfma_f32_16x16x32_bf16 v[46:49], v[162:165], v[134:137], v[46:49]
	v_mfma_f32_16x16x32_bf16 v[22:25], v[220:223], v[90:93], v[22:25]
	v_mfma_f32_16x16x32_bf16 v[18:21], v[162:165], v[90:93], v[18:21]
	v_mfma_f32_16x16x32_bf16 v[50:53], v[220:223], v[110:113], v[50:53]
	v_mfma_f32_16x16x32_bf16 v[38:41], v[162:165], v[110:113], v[38:41]
	v_mfma_f32_16x16x32_bf16 v[14:17], v[220:223], v[102:105], v[14:17]
	v_mfma_f32_16x16x32_bf16 v[10:13], v[162:165], v[102:105], v[10:13]
	s_waitcnt lgkmcnt(3)
	v_mfma_f32_16x16x32_bf16 v[42:45], v[220:223], v[86:89], v[42:45]
	v_mfma_f32_16x16x32_bf16 v[34:37], v[162:165], v[86:89], v[34:37]
	s_waitcnt lgkmcnt(2)
	v_mfma_f32_16x16x32_bf16 v[6:9], v[220:223], v[126:129], v[6:9]
	v_mfma_f32_16x16x32_bf16 v[2:5], v[162:165], v[126:129], v[2:5]

	v_add_u32_e32 v162, 0xc0, v218
	v_min_i32_e32 v162, 0x7f8, v162
	v_ashrrev_i32_e32 v163, 31, v162
	v_lshl_add_u64 v[198:199], v[162:163], 1, s[10:11]
	global_load_dwordx4 v[162:165], v[198:199], off
	global_load_dword v219, v[198:199], off offset:-4
	s_waitcnt vmcnt(4)
	v_perm_b32 v198, v211, v224, s67
	v_perm_b32 v199, v224, v225, s67
	v_perm_b32 v200, v225, v226, s67
	v_perm_b32 v201, v226, v227, s67

	s_add_i32 s23, s19, 22
	s_ashr_i32 s23, s23, 3
	v_mfma_f32_16x16x32_bf16 v[232:235], v[224:227], v[70:73], v[166:169]
	s_add_i32 s30, s22, 0x380
	s_and_b32 s30, s30, 0x1c0
	v_mfma_f32_16x16x32_bf16 v[190:193], v[198:201], v[70:73], v[190:193]
	v_add_u32_e32 v70, s23, v216
	v_add_u32_e32 v71, s23, v217
	v_cmp_gt_u32_e32 vcc, 8, v70
	v_mfma_f32_16x16x32_bf16 v[138:141], v[224:227], v[150:153], v[138:141]
	s_nop 0
	v_cndmask_b32_e32 v70, v214, v70, vcc
	v_cmp_gt_u32_e32 vcc, 8, v71
	v_mul_lo_u32 v70, v70, s58
	v_mfma_f32_16x16x32_bf16 v[130:133], v[198:201], v[150:153], v[130:133]
	v_cndmask_b32_e32 v71, v214, v71, vcc
	v_mul_lo_u32 v71, v71, s58
	v_add3_u32 v70, v0, v70, s30
	v_add3_u32 v150, v0, v71, s30
	ds_read_b128 v[70:73], v70
	ds_read_b128 v[150:153], v150
	v_mfma_f32_16x16x32_bf16 v[182:185], v[198:201], v[66:69], v[182:185]
	v_mfma_f32_16x16x32_bf16 v[122:125], v[224:227], v[158:161], v[122:125]
	v_mfma_f32_16x16x32_bf16 v[118:121], v[198:201], v[158:161], v[118:121]
	v_mfma_f32_16x16x32_bf16 v[186:189], v[224:227], v[154:157], v[186:189]
	v_mfma_f32_16x16x32_bf16 v[174:177], v[198:201], v[154:157], v[174:177]
	v_mfma_f32_16x16x32_bf16 v[114:117], v[224:227], v[74:77], v[114:117]
	v_mfma_f32_16x16x32_bf16 v[106:109], v[198:201], v[74:77], v[106:109]
	v_mfma_f32_16x16x32_bf16 v[178:181], v[224:227], v[146:149], v[178:181]
	v_mfma_f32_16x16x32_bf16 v[170:173], v[198:201], v[146:149], v[170:173]
	v_mfma_f32_16x16x32_bf16 v[98:101], v[224:227], v[82:85], v[98:101]
	v_mfma_f32_16x16x32_bf16 v[94:97], v[198:201], v[82:85], v[94:97]
	v_mfma_f32_16x16x32_bf16 v[62:65], v[224:227], v[134:137], v[62:65]
	v_mfma_f32_16x16x32_bf16 v[54:57], v[198:201], v[134:137], v[54:57]
	v_mfma_f32_16x16x32_bf16 v[30:33], v[224:227], v[90:93], v[30:33]
	v_mfma_f32_16x16x32_bf16 v[26:29], v[198:201], v[90:93], v[26:29]
	v_mfma_f32_16x16x32_bf16 v[58:61], v[224:227], v[110:113], v[58:61]
	v_mfma_f32_16x16x32_bf16 v[46:49], v[198:201], v[110:113], v[46:49]
	v_mfma_f32_16x16x32_bf16 v[22:25], v[224:227], v[102:105], v[22:25]
	v_mfma_f32_16x16x32_bf16 v[18:21], v[198:201], v[102:105], v[18:21]
	v_mfma_f32_16x16x32_bf16 v[50:53], v[224:227], v[86:89], v[50:53]
	v_mfma_f32_16x16x32_bf16 v[38:41], v[198:201], v[86:89], v[38:41]
	v_mfma_f32_16x16x32_bf16 v[14:17], v[224:227], v[126:129], v[14:17]
	v_mfma_f32_16x16x32_bf16 v[10:13], v[198:201], v[126:129], v[10:13]
	s_waitcnt lgkmcnt(3)
	v_mfma_f32_16x16x32_bf16 v[42:45], v[224:227], v[78:81], v[42:45]
	v_mfma_f32_16x16x32_bf16 v[34:37], v[198:201], v[78:81], v[34:37]
	s_waitcnt lgkmcnt(2)
	v_mfma_f32_16x16x32_bf16 v[6:9], v[224:227], v[142:145], v[6:9]
	v_mfma_f32_16x16x32_bf16 v[2:5], v[198:201], v[142:145], v[2:5]
	v_mfma_f32_16x16x32_bf16 v[242:245], v[224:227], v[66:69], v[194:197]

	v_add_u32_e32 v166, 0xe0, v218
	v_min_i32_e32 v166, 0x7f8, v166
	v_ashrrev_i32_e32 v167, 31, v166
	v_lshl_add_u64 v[194:195], v[166:167], 1, s[10:11]
	global_load_dwordx4 v[166:169], v[194:195], off
	global_load_dword v220, v[194:195], off offset:-4
	s_waitcnt vmcnt(4)
	v_perm_b32 v222, v236, v228, s67
	v_perm_b32 v223, v228, v229, s67
	v_perm_b32 v224, v229, v230, s67
	v_perm_b32 v225, v230, v231, s67

	s_add_i32 s23, s19, 23
	s_ashr_i32 s23, s23, 3
	v_mfma_f32_16x16x32_bf16 v[194:197], v[228:231], v[66:69], v[232:235]
	s_add_i32 s30, s22, 0x3c0
	s_and_b32 s30, s30, 0x1c0
	v_mfma_f32_16x16x32_bf16 v[190:193], v[222:225], v[66:69], v[190:193]
	v_add_u32_e32 v66, s23, v216
	v_add_u32_e32 v67, s23, v217
	v_cmp_gt_u32_e32 vcc, 8, v66
	v_mfma_f32_16x16x32_bf16 v[138:141], v[228:231], v[158:161], v[138:141]
	s_nop 0
	v_cndmask_b32_e32 v66, v214, v66, vcc
	v_cmp_gt_u32_e32 vcc, 8, v67
	v_mul_lo_u32 v66, v66, s58
	v_mfma_f32_16x16x32_bf16 v[130:133], v[222:225], v[158:161], v[130:133]
	v_cndmask_b32_e32 v67, v214, v67, vcc
	v_mul_lo_u32 v67, v67, s58
	v_add3_u32 v66, v0, v66, s30
	v_add3_u32 v158, v0, v67, s30
	ds_read_b128 v[66:69], v66
	ds_read_b128 v[158:161], v158
	v_mfma_f32_16x16x32_bf16 v[198:201], v[228:231], v[154:157], v[242:245]
	v_mfma_f32_16x16x32_bf16 v[182:185], v[222:225], v[154:157], v[182:185]
	v_mfma_f32_16x16x32_bf16 v[122:125], v[228:231], v[74:77], v[122:125]
	v_mfma_f32_16x16x32_bf16 v[118:121], v[222:225], v[74:77], v[118:121]
	v_mfma_f32_16x16x32_bf16 v[186:189], v[228:231], v[146:149], v[186:189]
	v_mfma_f32_16x16x32_bf16 v[174:177], v[222:225], v[146:149], v[174:177]
	v_mfma_f32_16x16x32_bf16 v[114:117], v[228:231], v[82:85], v[114:117]
	v_mfma_f32_16x16x32_bf16 v[106:109], v[222:225], v[82:85], v[106:109]
	v_mfma_f32_16x16x32_bf16 v[178:181], v[228:231], v[134:137], v[178:181]
	v_mfma_f32_16x16x32_bf16 v[170:173], v[222:225], v[134:137], v[170:173]
	v_mfma_f32_16x16x32_bf16 v[98:101], v[228:231], v[90:93], v[98:101]
	v_mfma_f32_16x16x32_bf16 v[94:97], v[222:225], v[90:93], v[94:97]
	v_mfma_f32_16x16x32_bf16 v[62:65], v[228:231], v[110:113], v[62:65]
	v_mfma_f32_16x16x32_bf16 v[54:57], v[222:225], v[110:113], v[54:57]
	v_mfma_f32_16x16x32_bf16 v[30:33], v[228:231], v[102:105], v[30:33]
	v_mfma_f32_16x16x32_bf16 v[26:29], v[222:225], v[102:105], v[26:29]
	v_mfma_f32_16x16x32_bf16 v[58:61], v[228:231], v[86:89], v[58:61]
	v_mfma_f32_16x16x32_bf16 v[46:49], v[222:225], v[86:89], v[46:49]
	v_mfma_f32_16x16x32_bf16 v[22:25], v[228:231], v[126:129], v[22:25]
	v_mfma_f32_16x16x32_bf16 v[18:21], v[222:225], v[126:129], v[18:21]
	v_mfma_f32_16x16x32_bf16 v[50:53], v[228:231], v[78:81], v[50:53]
	v_mfma_f32_16x16x32_bf16 v[38:41], v[222:225], v[78:81], v[38:41]
	v_mfma_f32_16x16x32_bf16 v[14:17], v[228:231], v[142:145], v[14:17]
	v_mfma_f32_16x16x32_bf16 v[10:13], v[222:225], v[142:145], v[10:13]
	s_waitcnt lgkmcnt(3)
	v_mfma_f32_16x16x32_bf16 v[42:45], v[228:231], v[70:73], v[42:45]
	v_mfma_f32_16x16x32_bf16 v[34:37], v[222:225], v[70:73], v[34:37]
	s_waitcnt lgkmcnt(2)
	v_mfma_f32_16x16x32_bf16 v[6:9], v[228:231], v[150:153], v[6:9]
	v_mfma_f32_16x16x32_bf16 v[2:5], v[222:225], v[150:153], v[2:5]

; #define CONV_BLOCK(DO0, DO1) do { CONV_STEP(0, DO0, DO1); CONV_STEP(1, DO0, DO1); CONV_STEP(2, DO0, DO1); CONV_STEP(3, DO0, DO1); CONV_STEP(4, DO0, DO1); CONV_STEP(5, DO0, DO1); CONV_STEP(6, DO0, DO1); CONV_STEP(7, DO0, DO1); } while (0)
; template <bool PROMPT, int HALF>
; __device__ __forceinline__ void conv_item(unsigned char* ws, KArgs ka, int ib, int oct, int g, LAS unsigned char* lds, int tid, int lane, int wave) {
;     ...
;     for (int e = E1; e < E2; e += 8) CONV_BLOCK(true, true);
;     for (int e = E2; e < E3; e += 8) CONV_BLOCK(true, false);
	s_add_i32 s19, s19, 8
	s_addk_i32 s22, 0x200
	s_cmp_lt_i32 s19, 25
	v_add_u32_e32 v218, 0x100, v218
	s_cbranch_scc1 .LBB0_732
	v_add_u32_e32 v90, 6, v216
	v_add_u32_e32 v91, 0x540, v215
	s_mov_b32 s19, 25
.LBB0_734:
	v_add_u32_e32 v74, 0xffffff20, v91
	v_min_i32_e32 v74, 0x7f8, v74
	v_ashrrev_i32_e32 v75, 31, v74
	v_lshl_add_u64 v[74:75], v[74:75], 1, s[10:11]
	global_load_dwordx4 v[102:105], v[74:75], off
	global_load_dword v210, v[74:75], off offset:-4
	s_waitcnt vmcnt(4)
	v_perm_b32 v82, v219, v162, s67
	v_perm_b32 v83, v162, v163, s67
	v_perm_b32 v84, v163, v164, s67
	v_perm_b32 v85, v164, v165, s67

	v_add_u32_e32 v74, -1, v90
	v_cmp_gt_u32_e32 vcc, 8, v74
	v_mfma_f32_16x16x32_bf16 v[174:177], v[82:85], v[134:137], v[174:177]
	s_nop 0
	v_cndmask_b32_e32 v74, v214, v74, vcc
	v_mad_u64_u32 v[92:93], s[22:23], v74, s58, v[0:1]
	v_mfma_f32_16x16x32_bf16 v[178:181], v[162:165], v[110:113], v[178:181]
	ds_read_b128 v[74:77], v92 offset:64
	v_mfma_f32_16x16x32_bf16 v[170:173], v[82:85], v[110:113], v[170:173]
	v_mfma_f32_16x16x32_bf16 v[62:65], v[162:165], v[86:89], v[62:65]
	v_mfma_f32_16x16x32_bf16 v[54:57], v[82:85], v[86:89], v[54:57]
	v_mfma_f32_16x16x32_bf16 v[58:61], v[162:165], v[78:81], v[58:61]
	v_mfma_f32_16x16x32_bf16 v[46:49], v[82:85], v[78:81], v[46:49]
	v_mfma_f32_16x16x32_bf16 v[50:53], v[162:165], v[70:73], v[50:53]
	v_mfma_f32_16x16x32_bf16 v[38:41], v[82:85], v[70:73], v[38:41]
	s_waitcnt lgkmcnt(2)
	v_mfma_f32_16x16x32_bf16 v[42:45], v[162:165], v[66:69], v[42:45]
	v_mfma_f32_16x16x32_bf16 v[34:37], v[82:85], v[66:69], v[34:37]
	v_mfma_f32_16x16x32_bf16 v[126:129], v[82:85], v[154:157], v[190:193]
	v_mfma_f32_16x16x32_bf16 v[142:145], v[162:165], v[146:149], v[198:201]
	v_mfma_f32_16x16x32_bf16 v[150:153], v[82:85], v[146:149], v[182:185]
	s_waitcnt lgkmcnt(1)
	v_mfma_f32_16x16x32_bf16 v[158:161], v[162:165], v[134:137], v[186:189]

	v_add_u32_e32 v82, 0xffffff40, v91
	v_min_i32_e32 v82, 0x7f8, v82
	v_ashrrev_i32_e32 v83, 31, v82
	v_lshl_add_u64 v[82:83], v[82:83], 1, s[10:11]
	global_load_dwordx4 v[182:185], v[82:83], off
	global_load_dword v93, v[82:83], off offset:-4
	s_waitcnt vmcnt(4)
	v_perm_b32 v82, v220, v166, s67
	v_perm_b32 v83, v166, v167, s67
	v_perm_b32 v84, v167, v168, s67
	v_perm_b32 v85, v168, v169, s67

	s_nop 0
	v_mfma_f32_16x16x32_bf16 v[126:129], v[82:85], v[146:149], v[126:129]
	v_mfma_f32_16x16x32_bf16 v[150:153], v[82:85], v[134:137], v[150:153]
	v_mfma_f32_16x16x32_bf16 v[174:177], v[82:85], v[110:113], v[174:177]
	v_mfma_f32_16x16x32_bf16 v[178:181], v[166:169], v[86:89], v[178:181]
	v_mfma_f32_16x16x32_bf16 v[170:173], v[82:85], v[86:89], v[170:173]
	v_mfma_f32_16x16x32_bf16 v[62:65], v[166:169], v[78:81], v[62:65]
	v_mfma_f32_16x16x32_bf16 v[54:57], v[82:85], v[78:81], v[54:57]
	v_mfma_f32_16x16x32_bf16 v[58:61], v[166:169], v[70:73], v[58:61]
	v_mfma_f32_16x16x32_bf16 v[46:49], v[82:85], v[70:73], v[46:49]
	v_mfma_f32_16x16x32_bf16 v[50:53], v[166:169], v[66:69], v[50:53]
	v_mfma_f32_16x16x32_bf16 v[38:41], v[82:85], v[66:69], v[38:41]
	s_waitcnt lgkmcnt(0)
	v_mfma_f32_16x16x32_bf16 v[42:45], v[166:169], v[74:77], v[42:45]
	v_mfma_f32_16x16x32_bf16 v[34:37], v[82:85], v[74:77], v[34:37]
	ds_read_b128 v[82:85], v92 offset:128
	v_mfma_f32_16x16x32_bf16 v[154:157], v[162:165], v[154:157], v[194:197]
	v_mfma_f32_16x16x32_bf16 v[142:145], v[166:169], v[134:137], v[142:145]
	v_mfma_f32_16x16x32_bf16 v[158:161], v[166:169], v[110:113], v[158:161]

	v_add_u32_e32 v162, 0xffffff60, v91
	v_min_i32_e32 v162, 0x7f8, v162
	v_ashrrev_i32_e32 v163, 31, v162
	v_lshl_add_u64 v[186:187], v[162:163], 1, s[10:11]
	global_load_dwordx4 v[162:165], v[186:187], off
	global_load_dword v190, v[186:187], off offset:-4
	s_waitcnt vmcnt(4)
	v_perm_b32 v186, v210, v102, s67
	v_perm_b32 v187, v102, v103, s67
	v_perm_b32 v188, v103, v104, s67
	v_perm_b32 v189, v104, v105, s67

	s_nop 0
	v_mfma_f32_16x16x32_bf16 v[174:177], v[186:189], v[86:89], v[174:177]
	ds_read_b128 v[222:225], v92 offset:192
	v_mfma_f32_16x16x32_bf16 v[178:181], v[102:105], v[78:81], v[178:181]
	v_mfma_f32_16x16x32_bf16 v[170:173], v[186:189], v[78:81], v[170:173]
	v_mfma_f32_16x16x32_bf16 v[62:65], v[102:105], v[70:73], v[62:65]
	v_mfma_f32_16x16x32_bf16 v[54:57], v[186:189], v[70:73], v[54:57]
	v_mfma_f32_16x16x32_bf16 v[58:61], v[102:105], v[66:69], v[58:61]
	v_mfma_f32_16x16x32_bf16 v[46:49], v[186:189], v[66:69], v[46:49]
	v_mfma_f32_16x16x32_bf16 v[50:53], v[102:105], v[74:77], v[50:53]
	v_mfma_f32_16x16x32_bf16 v[38:41], v[186:189], v[74:77], v[38:41]
	s_waitcnt lgkmcnt(1)
	v_mfma_f32_16x16x32_bf16 v[42:45], v[102:105], v[82:85], v[42:45]
	v_mfma_f32_16x16x32_bf16 v[34:37], v[186:189], v[82:85], v[34:37]
	v_mfma_f32_16x16x32_bf16 v[146:149], v[166:169], v[146:149], v[154:157]
	v_mfma_f32_16x16x32_bf16 v[126:129], v[186:189], v[134:137], v[126:129]
	v_mfma_f32_16x16x32_bf16 v[142:145], v[102:105], v[110:113], v[142:145]
	v_mfma_f32_16x16x32_bf16 v[150:153], v[186:189], v[110:113], v[150:153]
	v_mfma_f32_16x16x32_bf16 v[158:161], v[102:105], v[86:89], v[158:161]

	v_add_u32_e32 v154, 0xffffff80, v91
	v_min_i32_e32 v154, 0x7f8, v154
	v_ashrrev_i32_e32 v155, 31, v154
	v_lshl_add_u64 v[166:167], v[154:155], 1, s[10:11]
	global_load_dwordx4 v[154:157], v[166:167], off
	global_load_dword v186, v[166:167], off offset:-4
	s_waitcnt vmcnt(4)
	v_perm_b32 v166, v93, v182, s67
	v_perm_b32 v167, v182, v183, s67
	v_perm_b32 v168, v183, v184, s67
	v_perm_b32 v169, v184, v185, s67

	s_nop 0
	v_mfma_f32_16x16x32_bf16 v[174:177], v[166:169], v[78:81], v[174:177]
	ds_read_b128 v[226:229], v92 offset:256
	v_mfma_f32_16x16x32_bf16 v[178:181], v[182:185], v[70:73], v[178:181]
	v_mfma_f32_16x16x32_bf16 v[170:173], v[166:169], v[70:73], v[170:173]
	v_mfma_f32_16x16x32_bf16 v[62:65], v[182:185], v[66:69], v[62:65]
	v_mfma_f32_16x16x32_bf16 v[54:57], v[166:169], v[66:69], v[54:57]
	v_mfma_f32_16x16x32_bf16 v[58:61], v[182:185], v[74:77], v[58:61]
	v_mfma_f32_16x16x32_bf16 v[46:49], v[166:169], v[74:77], v[46:49]
	v_mfma_f32_16x16x32_bf16 v[50:53], v[182:185], v[82:85], v[50:53]
	v_mfma_f32_16x16x32_bf16 v[38:41], v[166:169], v[82:85], v[38:41]
	s_waitcnt lgkmcnt(1)
	v_mfma_f32_16x16x32_bf16 v[42:45], v[182:185], v[222:225], v[42:45]
	v_mfma_f32_16x16x32_bf16 v[34:37], v[166:169], v[222:225], v[34:37]
	v_mfma_f32_16x16x32_bf16 v[126:129], v[166:169], v[110:113], v[126:129]
	v_mfma_f32_16x16x32_bf16 v[142:145], v[182:185], v[86:89], v[142:145]
	v_mfma_f32_16x16x32_bf16 v[150:153], v[166:169], v[86:89], v[150:153]
	v_mfma_f32_16x16x32_bf16 v[158:161], v[182:185], v[78:81], v[158:161]
	v_mfma_f32_16x16x32_bf16 v[102:105], v[102:105], v[134:137], v[146:149]

	v_add_u32_e32 v93, 0xffffffa0, v91
	v_min_i32_e32 v134, 0x7f8, v93
	v_ashrrev_i32_e32 v135, 31, v134
	v_lshl_add_u64 v[146:147], v[134:135], 1, s[10:11]
	global_load_dwordx4 v[134:137], v[146:147], off
	global_load_dword v93, v[146:147], off offset:-4
	s_waitcnt vmcnt(4)
	v_perm_b32 v146, v190, v162, s67
	v_perm_b32 v147, v162, v163, s67
	v_perm_b32 v148, v163, v164, s67
	v_perm_b32 v149, v164, v165, s67

	s_nop 0
	v_mfma_f32_16x16x32_bf16 v[126:129], v[146:149], v[86:89], v[126:129]
	v_mfma_f32_16x16x32_bf16 v[150:153], v[146:149], v[78:81], v[150:153]
	v_mfma_f32_16x16x32_bf16 v[166:169], v[146:149], v[70:73], v[174:177]
	v_mfma_f32_16x16x32_bf16 v[170:173], v[146:149], v[66:69], v[170:173]
	v_mfma_f32_16x16x32_bf16 v[54:57], v[146:149], v[74:77], v[54:57]
	v_mfma_f32_16x16x32_bf16 v[46:49], v[146:149], v[82:85], v[46:49]
	v_mfma_f32_16x16x32_bf16 v[38:41], v[146:149], v[222:225], v[38:41]
	s_waitcnt lgkmcnt(0)
	v_mfma_f32_16x16x32_bf16 v[34:37], v[146:149], v[226:229], v[34:37]
	ds_read_b128 v[146:149], v92 offset:320
	v_mfma_f32_16x16x32_bf16 v[174:177], v[162:165], v[66:69], v[178:181]
	v_mfma_f32_16x16x32_bf16 v[62:65], v[162:165], v[74:77], v[62:65]
	v_mfma_f32_16x16x32_bf16 v[58:61], v[162:165], v[82:85], v[58:61]
	v_mfma_f32_16x16x32_bf16 v[50:53], v[162:165], v[222:225], v[50:53]
	v_mfma_f32_16x16x32_bf16 v[42:45], v[162:165], v[226:229], v[42:45]
	v_mfma_f32_16x16x32_bf16 v[142:145], v[162:165], v[78:81], v[142:145]
	v_mfma_f32_16x16x32_bf16 v[158:161], v[162:165], v[70:73], v[158:161]
	v_mfma_f32_16x16x32_bf16 v[102:105], v[182:185], v[110:113], v[102:105]

	v_subrev_u32_e32 v110, 64, v91
	v_min_i32_e32 v110, 0x7f8, v110
	v_ashrrev_i32_e32 v111, 31, v110
	v_lshl_add_u64 v[178:179], v[110:111], 1, s[10:11]
	global_load_dwordx4 v[110:113], v[178:179], off
	global_load_dword v182, v[178:179], off offset:-4
	s_waitcnt vmcnt(4)
	v_perm_b32 v178, v186, v154, s67
	v_perm_b32 v179, v154, v155, s67
	v_perm_b32 v180, v155, v156, s67
	v_perm_b32 v181, v156, v157, s67

	s_nop 0
	v_mfma_f32_16x16x32_bf16 v[166:169], v[178:181], v[66:69], v[166:169]
	ds_read_b128 v[230:233], v92 offset:384
	v_mfma_f32_16x16x32_bf16 v[174:177], v[154:157], v[74:77], v[174:177]
	v_mfma_f32_16x16x32_bf16 v[170:173], v[178:181], v[74:77], v[170:173]
	v_mfma_f32_16x16x32_bf16 v[62:65], v[154:157], v[82:85], v[62:65]
	v_mfma_f32_16x16x32_bf16 v[54:57], v[178:181], v[82:85], v[54:57]
	v_mfma_f32_16x16x32_bf16 v[58:61], v[154:157], v[222:225], v[58:61]
	v_mfma_f32_16x16x32_bf16 v[46:49], v[178:181], v[222:225], v[46:49]
	v_mfma_f32_16x16x32_bf16 v[50:53], v[154:157], v[226:229], v[50:53]
	v_mfma_f32_16x16x32_bf16 v[38:41], v[178:181], v[226:229], v[38:41]
	s_waitcnt lgkmcnt(1)
	v_mfma_f32_16x16x32_bf16 v[42:45], v[154:157], v[146:149], v[42:45]
	v_mfma_f32_16x16x32_bf16 v[34:37], v[178:181], v[146:149], v[34:37]
	v_mfma_f32_16x16x32_bf16 v[86:89], v[162:165], v[86:89], v[102:105]
	v_mfma_f32_16x16x32_bf16 v[126:129], v[178:181], v[78:81], v[126:129]
	v_mfma_f32_16x16x32_bf16 v[142:145], v[154:157], v[70:73], v[142:145]
	v_mfma_f32_16x16x32_bf16 v[150:153], v[178:181], v[70:73], v[150:153]
	v_mfma_f32_16x16x32_bf16 v[158:161], v[154:157], v[66:69], v[158:161]

	v_subrev_u32_e32 v102, 32, v91
	v_min_i32_e32 v102, 0x7f8, v102
	v_ashrrev_i32_e32 v103, 31, v102
	v_lshl_add_u64 v[102:103], v[102:103], 1, s[10:11]
	global_load_dwordx4 v[162:165], v[102:103], off
	global_load_dword v219, v[102:103], off offset:-4
	s_waitcnt vmcnt(4)
	v_perm_b32 v102, v93, v134, s67
	v_perm_b32 v103, v134, v135, s67
	v_perm_b32 v104, v135, v136, s67
	v_perm_b32 v105, v136, v137, s67

	s_nop 0
	v_mfma_f32_16x16x32_bf16 v[126:129], v[102:105], v[70:73], v[126:129]
	v_mfma_f32_16x16x32_bf16 v[150:153], v[102:105], v[66:69], v[150:153]
	v_mfma_f32_16x16x32_bf16 v[178:181], v[102:105], v[74:77], v[166:169]
	v_mfma_f32_16x16x32_bf16 v[194:197], v[134:137], v[82:85], v[174:177]
	v_mfma_f32_16x16x32_bf16 v[170:173], v[102:105], v[82:85], v[170:173]
	v_mfma_f32_16x16x32_bf16 v[62:65], v[134:137], v[222:225], v[62:65]
	v_mfma_f32_16x16x32_bf16 v[54:57], v[102:105], v[222:225], v[54:57]
	v_mfma_f32_16x16x32_bf16 v[58:61], v[134:137], v[226:229], v[58:61]
	v_mfma_f32_16x16x32_bf16 v[46:49], v[102:105], v[226:229], v[46:49]
	v_mfma_f32_16x16x32_bf16 v[50:53], v[134:137], v[146:149], v[50:53]
	v_mfma_f32_16x16x32_bf16 v[38:41], v[102:105], v[146:149], v[38:41]
	s_waitcnt lgkmcnt(0)
	v_mfma_f32_16x16x32_bf16 v[42:45], v[134:137], v[230:233], v[42:45]
	v_mfma_f32_16x16x32_bf16 v[34:37], v[102:105], v[230:233], v[34:37]
	ds_read_b128 v[102:105], v92 offset:448
	v_mfma_f32_16x16x32_bf16 v[78:81], v[154:157], v[78:81], v[86:89]
	v_mfma_f32_16x16x32_bf16 v[142:145], v[134:137], v[66:69], v[142:145]
	v_mfma_f32_16x16x32_bf16 v[158:161], v[134:137], v[74:77], v[158:161]

	v_min_i32_e32 v86, 0x7f8, v91
	v_ashrrev_i32_e32 v87, 31, v86
	v_lshl_add_u64 v[86:87], v[86:87], 1, s[10:11]
	global_load_dwordx4 v[166:169], v[86:87], off
	global_load_dword v220, v[86:87], off offset:-4
	s_waitcnt vmcnt(4)
	v_perm_b32 v86, v182, v110, s67
	v_perm_b32 v87, v110, v111, s67
	v_perm_b32 v88, v111, v112, s67
	v_perm_b32 v89, v112, v113, s67

	v_cmp_gt_u32_e32 vcc, 8, v90
	v_mfma_f32_16x16x32_bf16 v[70:73], v[134:137], v[70:73], v[78:81]
	v_mfma_f32_16x16x32_bf16 v[190:193], v[86:89], v[66:69], v[126:129]
	v_mfma_f32_16x16x32_bf16 v[182:185], v[86:89], v[74:77], v[150:153]
	v_mfma_f32_16x16x32_bf16 v[174:177], v[86:89], v[82:85], v[178:181]
	v_mfma_f32_16x16x32_bf16 v[170:173], v[86:89], v[222:225], v[170:173]
	v_mfma_f32_16x16x32_bf16 v[54:57], v[86:89], v[226:229], v[54:57]
	v_mfma_f32_16x16x32_bf16 v[46:49], v[86:89], v[146:149], v[46:49]
	v_mfma_f32_16x16x32_bf16 v[38:41], v[86:89], v[230:233], v[38:41]
	s_waitcnt lgkmcnt(0)
	v_mfma_f32_16x16x32_bf16 v[34:37], v[86:89], v[102:105], v[34:37]
	v_cndmask_b32_e32 v86, v214, v90, vcc
	v_mad_u64_u32 v[78:79], s[22:23], v86, s58, v[0:1]
	ds_read_b128 v[78:81], v78
	v_mfma_f32_16x16x32_bf16 v[198:201], v[110:113], v[74:77], v[142:145]
	v_mfma_f32_16x16x32_bf16 v[186:189], v[110:113], v[82:85], v[158:161]
	v_mfma_f32_16x16x32_bf16 v[178:181], v[110:113], v[222:225], v[194:197]
	v_mfma_f32_16x16x32_bf16 v[62:65], v[110:113], v[226:229], v[62:65]
	v_mfma_f32_16x16x32_bf16 v[58:61], v[110:113], v[146:149], v[58:61]
	v_mfma_f32_16x16x32_bf16 v[50:53], v[110:113], v[230:233], v[50:53]
	v_mfma_f32_16x16x32_bf16 v[42:45], v[110:113], v[102:105], v[42:45]
	v_mfma_f32_16x16x32_bf16 v[194:197], v[110:113], v[66:69], v[70:73]

; #define CONV_BLOCK(DO0, DO1) do { CONV_STEP(0, DO0, DO1); CONV_STEP(1, DO0, DO1); CONV_STEP(2, DO0, DO1); CONV_STEP(3, DO0, DO1); CONV_STEP(4, DO0, DO1); CONV_STEP(5, DO0, DO1); CONV_STEP(6, DO0, DO1); CONV_STEP(7, DO0, DO1); } while (0)
; template <bool PROMPT, int HALF>
; __device__ __forceinline__ void conv_item(unsigned char* ws, KArgs ka, int ib, int oct, int g, LAS unsigned char* lds, int tid, int lane, int wave) {
;     ...
;     for (int e = E2; e < E3; e += 8) CONV_BLOCK(true, false);
;     ...
;     __syncthreads();
;     int lane2; { unsigned ones_ = ~0u; asm volatile("" : "+s"(ones_)); lane2 = (int)__builtin_amdgcn_mbcnt_hi(ones_, __builtin_amdgcn_mbcnt_lo(ones_, 0u)); }
;     const int nn2 = lane2 & 15, kq2 = lane2 >> 4;
;     float nsum = 0.f;
;     { const float* kq_ = (const float*)(ws + WS_KPART) + ((size_t)ib * 320 + (PROMPT ? 0 : 256)) * 2048; constexpr int ntile = PROMPT ? 256 : 64;
;       for (int q = lane2; q < ntile; q += 64) nsum += kq_[(size_t)q * 2048 + c] + kq_[(size_t)q * 2048 + 1024 + c];
	s_waitcnt lgkmcnt(0)
	v_mov_b64_e32 v[66:67], v[78:79]
	v_mov_b64_e32 v[86:87], v[146:147]
	s_add_i32 s19, s19, 8
	v_mov_b64_e32 v[68:69], v[80:81]
	v_mov_b64_e32 v[70:71], v[102:103]
	v_mov_b64_e32 v[78:79], v[230:231]
	v_mov_b64_e32 v[88:89], v[148:149]
	v_mov_b64_e32 v[110:111], v[226:227]
	v_mov_b64_e32 v[134:135], v[222:223]
	v_mov_b64_e32 v[148:149], v[84:85]
	v_mov_b64_e32 v[156:157], v[76:77]
	v_add_u32_e32 v90, 1, v90
	v_add_u32_e32 v91, 0x100, v91
	s_cmp_gt_u32 s19, 56
	v_mov_b64_e32 v[72:73], v[104:105]
	v_mov_b64_e32 v[80:81], v[232:233]
	v_mov_b64_e32 v[112:113], v[228:229]
	v_mov_b64_e32 v[136:137], v[224:225]
	v_mov_b64_e32 v[146:147], v[82:83]
	v_mov_b64_e32 v[154:155], v[74:75]
	s_cbranch_scc0 .LBB0_734
	s_mov_b32 s10, -1
	s_barrier
	s_nop 0
	v_mbcnt_lo_u32_b32 v0, s10, 0
	v_mbcnt_hi_u32_b32 v74, s10, v0
	v_cmp_gt_i32_e32 vcc, 64, v74
	v_mov_b32_e32 v0, 0
	s_and_saveexec_b64 s[10:11], vcc
	s_cbranch_execz .LBB0_739
	s_lshl_b32 s19, s34, 2
	s_and_b32 s19, s19, -8
	v_readlane_b32 s22, v253, 4
	s_add_i32 s30, s22, s19
	s_lshl_b64 s[22:23], s[30:31], 2
	s_add_u32 s22, s49, s22
	v_lshlrev_b32_e32 v0, 13, v74
	s_addc_u32 s23, s50, s23
	v_subrev_u32_e32 v68, 64, v74
	v_lshl_add_u64 v[66:67], s[22:23], 0, v[0:1]
	v_mov_b32_e32 v0, 0
	s_mov_b64 s[22:23], 0

.LBB0_751:
	v_min_i32_e32 v68, 0x1ff8, v66
	v_ashrrev_i32_e32 v69, 31, v68
	v_lshl_add_u64 v[72:73], v[68:69], 1, s[22:23]
	global_load_dwordx4 v[68:71], v[72:73], off
	global_load_dword v67, v[72:73], off offset:-4
	s_waitcnt vmcnt(8)
	v_perm_b32 v72, v125, v2, s67
	v_perm_b32 v73, v2, v3, s67
	v_perm_b32 v74, v3, v4, s67
	v_perm_b32 v75, v4, v5, s67

	s_add_i32 s43, s11, 16
	s_ashr_i32 s43, s43, 3
	v_add_u32_e32 v76, s43, v124
	v_min_u32_e32 v76, 32, v76
	v_mad_u32_u24 v76, v76, s58, v0
	v_mfma_f32_16x16x32_bf16 v[38:41], v[72:75], v[62:65], v[38:41]
	ds_read_b128 v[76:79], v76 offset:64
	v_mfma_f32_16x16x32_bf16 v[42:45], v[2:5], v[58:61], v[42:45]
	v_mfma_f32_16x16x32_bf16 v[34:37], v[72:75], v[58:61], v[34:37]
	v_mfma_f32_16x16x32_bf16 v[30:33], v[2:5], v[54:57], v[30:33]
	v_mfma_f32_16x16x32_bf16 v[26:29], v[72:75], v[54:57], v[26:29]
	s_waitcnt lgkmcnt(1)
	v_mfma_f32_16x16x32_bf16 v[22:25], v[2:5], v[50:53], v[22:25]
	v_mfma_f32_16x16x32_bf16 v[18:21], v[72:75], v[50:53], v[18:21]

	v_add_u32_e32 v72, 32, v66
	v_min_i32_e32 v72, 0x1ff8, v72
	v_ashrrev_i32_e32 v73, 31, v72
	v_lshl_add_u64 v[80:81], v[72:73], 1, s[22:23]
	global_load_dwordx4 v[72:75], v[80:81], off
	global_load_dword v96, v[80:81], off offset:-4
	s_waitcnt vmcnt(8)
	v_perm_b32 v80, v126, v6, s67
	v_perm_b32 v81, v6, v7, s67
	v_perm_b32 v82, v7, v8, s67
	v_perm_b32 v83, v8, v9, s67

	s_add_i32 s43, s11, 17
	s_ashr_i32 s43, s43, 3
	v_add_u32_e32 v84, s43, v124
	v_mfma_f32_16x16x32_bf16 v[38:41], v[80:83], v[58:61], v[38:41]
	v_mfma_f32_16x16x32_bf16 v[34:37], v[80:83], v[54:57], v[34:37]
	v_mfma_f32_16x16x32_bf16 v[26:29], v[80:83], v[50:53], v[26:29]
	s_waitcnt lgkmcnt(0)
	v_mfma_f32_16x16x32_bf16 v[18:21], v[80:83], v[76:79], v[18:21]
	v_min_u32_e32 v80, 32, v84
	v_mad_u32_u24 v80, v80, s58, v0
	ds_read_b128 v[80:83], v80 offset:128
	v_mfma_f32_16x16x32_bf16 v[42:45], v[6:9], v[54:57], v[42:45]
	v_mfma_f32_16x16x32_bf16 v[30:33], v[6:9], v[50:53], v[30:33]
	v_mfma_f32_16x16x32_bf16 v[22:25], v[6:9], v[76:79], v[22:25]
	v_mfma_f32_16x16x32_bf16 v[2:5], v[2:5], v[62:65], v[46:49]

	s_nop 1
	v_add_u32_e32 v46, 64, v66
	v_min_i32_e32 v46, 0x1ff8, v46
	v_ashrrev_i32_e32 v47, 31, v46
	v_lshl_add_u64 v[62:63], v[46:47], 1, s[22:23]
	global_load_dwordx4 v[46:49], v[62:63], off
	global_load_dword v97, v[62:63], off offset:-4
	s_waitcnt vmcnt(8)
	v_perm_b32 v62, v127, v10, s67
	v_perm_b32 v63, v10, v11, s67
	v_perm_b32 v64, v11, v12, s67
	v_perm_b32 v65, v12, v13, s67

	s_add_i32 s43, s11, 18
	s_ashr_i32 s43, s43, 3
	v_add_u32_e32 v84, s43, v124
	v_mfma_f32_16x16x32_bf16 v[38:41], v[62:65], v[54:57], v[38:41]
	v_mfma_f32_16x16x32_bf16 v[34:37], v[62:65], v[50:53], v[34:37]
	v_mfma_f32_16x16x32_bf16 v[26:29], v[62:65], v[76:79], v[26:29]
	s_waitcnt lgkmcnt(0)
	v_mfma_f32_16x16x32_bf16 v[18:21], v[62:65], v[80:83], v[18:21]
	v_min_u32_e32 v62, 32, v84
	v_mad_u32_u24 v62, v62, s58, v0
	ds_read_b128 v[84:87], v62 offset:192
	v_mfma_f32_16x16x32_bf16 v[42:45], v[10:13], v[50:53], v[42:45]
	v_mfma_f32_16x16x32_bf16 v[30:33], v[10:13], v[76:79], v[30:33]
	v_mfma_f32_16x16x32_bf16 v[22:25], v[10:13], v[80:83], v[22:25]
	v_mfma_f32_16x16x32_bf16 v[2:5], v[6:9], v[58:61], v[2:5]

	v_add_u32_e32 v6, 0x60, v66
	v_min_i32_e32 v6, 0x1ff8, v6
	v_ashrrev_i32_e32 v7, 31, v6
	v_lshl_add_u64 v[6:7], v[6:7], 1, s[22:23]
	global_load_dwordx4 v[88:91], v[6:7], off
	global_load_dword v98, v[6:7], off offset:-4
	s_waitcnt vmcnt(8)
	v_perm_b32 v6, v128, v14, s67
	v_perm_b32 v7, v14, v15, s67
	v_perm_b32 v8, v15, v16, s67
	v_perm_b32 v9, v16, v17, s67

	s_add_i32 s43, s11, 19
	s_ashr_i32 s43, s43, 3
	v_add_u32_e32 v58, s43, v124
	v_mfma_f32_16x16x32_bf16 v[38:41], v[6:9], v[50:53], v[38:41]
	v_mfma_f32_16x16x32_bf16 v[34:37], v[6:9], v[76:79], v[34:37]
	v_mfma_f32_16x16x32_bf16 v[26:29], v[6:9], v[80:83], v[26:29]
	s_waitcnt lgkmcnt(0)
	v_mfma_f32_16x16x32_bf16 v[6:9], v[6:9], v[84:87], v[18:21]
	s_nop 2
	v_min_u32_e32 v18, 32, v58
	v_mad_u32_u24 v18, v18, s58, v0
	v_mfma_f32_16x16x32_bf16 v[42:45], v[14:17], v[76:79], v[42:45]
	ds_read_b128 v[92:95], v18 offset:256
	v_mfma_f32_16x16x32_bf16 v[30:33], v[14:17], v[80:83], v[30:33]
	v_mfma_f32_16x16x32_bf16 v[22:25], v[14:17], v[84:87], v[22:25]
	v_mfma_f32_16x16x32_bf16 v[10:13], v[10:13], v[54:57], v[2:5]

	s_nop 1
	v_add_u32_e32 v2, 0x80, v66
	v_min_i32_e32 v2, 0x1ff8, v2
	v_ashrrev_i32_e32 v3, 31, v2
	v_lshl_add_u64 v[18:19], v[2:3], 1, s[22:23]
	global_load_dwordx4 v[2:5], v[18:19], off
	global_load_dword v125, v[18:19], off offset:-4
	s_waitcnt vmcnt(8)
	v_perm_b32 v18, v67, v68, s67
	v_perm_b32 v19, v68, v69, s67
	v_perm_b32 v20, v69, v70, s67
	v_perm_b32 v21, v70, v71, s67

	s_add_i32 s43, s11, 20
	s_ashr_i32 s43, s43, 3
	v_add_u32_e32 v54, s43, v124
	v_mfma_f32_16x16x32_bf16 v[38:41], v[18:21], v[76:79], v[38:41]
	v_mfma_f32_16x16x32_bf16 v[34:37], v[18:21], v[80:83], v[34:37]
	v_mfma_f32_16x16x32_bf16 v[26:29], v[18:21], v[84:87], v[26:29]
	s_waitcnt lgkmcnt(0)
	v_mfma_f32_16x16x32_bf16 v[18:21], v[18:21], v[92:95], v[6:9]
	s_nop 2
	v_min_u32_e32 v6, 32, v54
	v_mad_u32_u24 v6, v6, s58, v0
	ds_read_b128 v[62:65], v6 offset:320
	v_mfma_f32_16x16x32_bf16 v[42:45], v[68:71], v[80:83], v[42:45]
	v_mfma_f32_16x16x32_bf16 v[30:33], v[68:71], v[84:87], v[30:33]
	v_mfma_f32_16x16x32_bf16 v[22:25], v[68:71], v[92:95], v[22:25]
	v_mfma_f32_16x16x32_bf16 v[10:13], v[14:17], v[50:53], v[10:13]

	v_add_u32_e32 v6, 0xa0, v66
	v_min_i32_e32 v6, 0x1ff8, v6
	v_ashrrev_i32_e32 v7, 31, v6
	v_lshl_add_u64 v[14:15], v[6:7], 1, s[22:23]
	global_load_dwordx4 v[6:9], v[14:15], off
	global_load_dword v126, v[14:15], off offset:-4
	s_waitcnt vmcnt(8)
	v_perm_b32 v14, v96, v72, s67
	v_perm_b32 v15, v72, v73, s67
	v_perm_b32 v16, v73, v74, s67
	v_perm_b32 v17, v74, v75, s67

	s_add_i32 s43, s11, 21
	s_ashr_i32 s43, s43, 3
	v_add_u32_e32 v50, s43, v124
	v_mfma_f32_16x16x32_bf16 v[38:41], v[14:17], v[80:83], v[38:41]
	v_mfma_f32_16x16x32_bf16 v[34:37], v[14:17], v[84:87], v[34:37]
	v_mfma_f32_16x16x32_bf16 v[26:29], v[14:17], v[92:95], v[26:29]
	s_waitcnt lgkmcnt(0)
	v_mfma_f32_16x16x32_bf16 v[14:17], v[14:17], v[62:65], v[18:21]
	s_nop 2
	v_min_u32_e32 v18, 32, v50
	v_mad_u32_u24 v18, v18, s58, v0
	ds_read_b128 v[58:61], v18 offset:384
	v_mfma_f32_16x16x32_bf16 v[42:45], v[72:75], v[84:87], v[42:45]
	v_mfma_f32_16x16x32_bf16 v[30:33], v[72:75], v[92:95], v[30:33]
	v_mfma_f32_16x16x32_bf16 v[22:25], v[72:75], v[62:65], v[22:25]
	v_mfma_f32_16x16x32_bf16 v[18:21], v[68:71], v[76:79], v[10:13]

	s_nop 1
	v_add_u32_e32 v10, 0xc0, v66
	v_min_i32_e32 v10, 0x1ff8, v10
	v_ashrrev_i32_e32 v11, 31, v10
	v_lshl_add_u64 v[50:51], v[10:11], 1, s[22:23]
	global_load_dwordx4 v[10:13], v[50:51], off
	global_load_dword v127, v[50:51], off offset:-4
	s_waitcnt vmcnt(8)
	v_perm_b32 v50, v97, v46, s67
	v_perm_b32 v51, v46, v47, s67
	v_perm_b32 v52, v47, v48, s67
	v_perm_b32 v53, v48, v49, s67

	s_add_i32 s43, s11, 22
	s_ashr_i32 s43, s43, 3
	v_add_u32_e32 v54, s43, v124
	v_mfma_f32_16x16x32_bf16 v[38:41], v[50:53], v[84:87], v[38:41]
	v_mfma_f32_16x16x32_bf16 v[34:37], v[50:53], v[92:95], v[34:37]
	v_mfma_f32_16x16x32_bf16 v[26:29], v[50:53], v[62:65], v[26:29]
	s_waitcnt lgkmcnt(0)
	v_mfma_f32_16x16x32_bf16 v[50:53], v[50:53], v[58:61], v[14:17]
	s_nop 2
	v_min_u32_e32 v14, 32, v54
	v_mad_u32_u24 v14, v14, s58, v0
	ds_read_b128 v[54:57], v14 offset:448
	v_mfma_f32_16x16x32_bf16 v[42:45], v[46:49], v[92:95], v[42:45]
	v_mfma_f32_16x16x32_bf16 v[30:33], v[46:49], v[62:65], v[30:33]
	v_mfma_f32_16x16x32_bf16 v[22:25], v[46:49], v[58:61], v[22:25]
	v_mfma_f32_16x16x32_bf16 v[68:71], v[72:75], v[80:83], v[18:21]

	v_add_u32_e32 v14, 0xe0, v66
	v_min_i32_e32 v14, 0x1ff8, v14
	v_ashrrev_i32_e32 v15, 31, v14
	v_lshl_add_u64 v[18:19], v[14:15], 1, s[22:23]
	global_load_dwordx4 v[14:17], v[18:19], off
	global_load_dword v128, v[18:19], off offset:-4
	s_waitcnt vmcnt(8)
	v_perm_b32 v18, v98, v88, s67
	v_perm_b32 v19, v88, v89, s67
	v_perm_b32 v20, v89, v90, s67
	v_perm_b32 v21, v90, v91, s67

	s_add_i32 s43, s11, 23
	s_ashr_i32 s43, s43, 3
	v_mfma_f32_16x16x32_bf16 v[38:41], v[18:21], v[92:95], v[38:41]
	v_mfma_f32_16x16x32_bf16 v[34:37], v[18:21], v[62:65], v[34:37]
	v_mfma_f32_16x16x32_bf16 v[26:29], v[18:21], v[58:61], v[26:29]
	s_waitcnt lgkmcnt(0)
	v_mfma_f32_16x16x32_bf16 v[18:21], v[18:21], v[54:57], v[50:53]
	s_nop 2
	v_add_u32_e32 v50, s43, v124
	v_mfma_f32_16x16x32_bf16 v[46:49], v[46:49], v[84:87], v[68:71]
	v_min_u32_e32 v50, 32, v50
	v_mad_u32_u24 v50, v50, s58, v0
	ds_read_b128 v[50:53], v50
	v_mfma_f32_16x16x32_bf16 v[42:45], v[88:91], v[62:65], v[42:45]
	v_mfma_f32_16x16x32_bf16 v[30:33], v[88:91], v[58:61], v[30:33]
	v_mfma_f32_16x16x32_bf16 v[22:25], v[88:91], v[54:57], v[22:25]
	v_mfma_f32_16x16x32_bf16 v[46:49], v[88:91], v[92:95], v[46:49]

; #define CONV_BLOCK(DO0, DO1) do { CONV_STEP(0, DO0, DO1); CONV_STEP(1, DO0, DO1); CONV_STEP(2, DO0, DO1); CONV_STEP(3, DO0, DO1); CONV_STEP(4, DO0, DO1); CONV_STEP(5, DO0, DO1); CONV_STEP(6, DO0, DO1); CONV_STEP(7, DO0, DO1); } while (0)
; template <bool PROMPT, int HALF>
; __device__ __forceinline__ void conv_item(unsigned char* ws, KArgs ka, int ib, int oct, int g, LAS unsigned char* lds, int tid, int lane, int wave) {
;     ...
;     for (int e = E0; e < E1; e += 8) CONV_BLOCK(false, true);
;     { unsigned zz_ = 0u; asm volatile("" : "+v"(zz_));
; #pragma unroll
;       for (int k = 0; k < W; ++k) F0[k] = (u32x4){zz_, zz_, zz_, zz_}; }
;     for (int e = E1; e < E2; e += 8) CONV_BLOCK(true, true);
	s_add_i32 s11, s11, 8
	s_cmp_gt_u32 s11, 0xffffff70
	v_add_u32_e32 v66, 0x100, v66
	s_cbranch_scc0 .LBB0_751
	v_mov_b32_e32 v66, v1
	v_mov_b32_e32 v70, 0
	v_add_u32_e32 v129, 0xffffefa0, v123
	s_movk_i32 s11, 0xff71
	s_movk_i32 s43, 0xde40
	v_mov_b32_e32 v71, v70
	v_mov_b32_e32 v72, v70
	v_mov_b32_e32 v73, v70
	v_mov_b32_e32 v78, v70
	v_mov_b32_e32 v79, v70
	v_mov_b32_e32 v80, v70
	v_mov_b32_e32 v81, v70
	v_mov_b32_e32 v94, v70
	v_mov_b32_e32 v95, v70
	v_mov_b32_e32 v96, v70
	v_mov_b32_e32 v97, v70
	v_mov_b32_e32 v106, v70
	v_mov_b32_e32 v107, v70
	v_mov_b32_e32 v108, v70
	v_mov_b32_e32 v109, v70
	v_mov_b32_e32 v82, v70
	v_mov_b32_e32 v83, v70
	v_mov_b32_e32 v84, v70
	v_mov_b32_e32 v85, v70
	v_mov_b32_e32 v98, v70
	v_mov_b32_e32 v99, v70
	v_mov_b32_e32 v100, v70
	v_mov_b32_e32 v101, v70
	v_mov_b32_e32 v110, v70
	v_mov_b32_e32 v111, v70
	v_mov_b32_e32 v112, v70
	v_mov_b32_e32 v113, v70
	v_mov_b32_e32 v102, v70
	v_mov_b32_e32 v103, v70
	v_mov_b32_e32 v104, v70
	v_mov_b32_e32 v105, v70
	v_mov_b32_e32 v67, v66
	v_mov_b32_e32 v68, v66
	v_mov_b32_e32 v69, v66
	v_mov_b32_e32 v74, v66
	v_mov_b32_e32 v75, v66
	v_mov_b32_e32 v76, v66
	v_mov_b32_e32 v77, v66
	v_mov_b32_e32 v86, v66
	v_mov_b32_e32 v87, v66
	v_mov_b32_e32 v88, v66
	v_mov_b32_e32 v89, v66
	v_mov_b32_e32 v90, v66
	v_mov_b32_e32 v91, v66
	v_mov_b32_e32 v92, v66
	v_mov_b32_e32 v93, v66
.LBB0_753:
	v_min_i32_e32 v114, 0x1ff8, v129
	v_ashrrev_i32_e32 v115, 31, v114
	v_lshl_add_u64 v[114:115], v[114:115], 1, s[22:23]
	global_load_dwordx4 v[118:121], v[114:115], off
	global_load_dword v138, v[114:115], off offset:-4
	s_waitcnt vmcnt(8)
	v_perm_b32 v114, v125, v2, s67
	v_perm_b32 v115, v2, v3, s67
	v_perm_b32 v116, v3, v4, s67
	v_perm_b32 v117, v4, v5, s67

	s_add_i32 s54, s11, 16
	s_ashr_i32 s54, s54, 3
	v_mfma_f32_16x16x32_bf16 v[102:105], v[2:5], v[90:93], v[102:105]
	s_and_b32 s55, s43, 0x1c0
	v_mfma_f32_16x16x32_bf16 v[90:93], v[114:117], v[90:93], v[106:109]
	s_nop 2
	v_add_u32_e32 v106, s54, v122
	v_min_u32_e32 v106, 32, v106
	v_add_u32_e32 v107, s54, v124
	v_mul_u32_u24_e32 v106, 0x210, v106
	v_min_u32_e32 v107, 32, v107
	v_add3_u32 v106, v0, v106, s55
	v_mul_u32_u24_e32 v107, 0x210, v107
	v_mfma_f32_16x16x32_bf16 v[46:49], v[2:5], v[62:65], v[46:49]
	v_mfma_f32_16x16x32_bf16 v[38:41], v[114:117], v[62:65], v[38:41]
	v_mfma_f32_16x16x32_bf16 v[62:65], v[2:5], v[86:89], v[110:113]
	v_mfma_f32_16x16x32_bf16 v[42:45], v[2:5], v[58:61], v[42:45]
	v_mfma_f32_16x16x32_bf16 v[98:101], v[2:5], v[74:77], v[98:101]
	v_mfma_f32_16x16x32_bf16 v[30:33], v[2:5], v[54:57], v[30:33]
	s_waitcnt lgkmcnt(1)
	v_mfma_f32_16x16x32_bf16 v[82:85], v[2:5], v[66:69], v[82:85]
	s_waitcnt lgkmcnt(0)
	v_mfma_f32_16x16x32_bf16 v[2:5], v[2:5], v[50:53], v[22:25]
	s_nop 2
	v_add3_u32 v22, v0, v107, s55
	ds_read_b128 v[106:109], v106
	ds_read_b128 v[110:113], v22
	v_mfma_f32_16x16x32_bf16 v[94:97], v[114:117], v[86:89], v[94:97]
	v_mfma_f32_16x16x32_bf16 v[34:37], v[114:117], v[58:61], v[34:37]
	v_mfma_f32_16x16x32_bf16 v[78:81], v[114:117], v[74:77], v[78:81]
	v_mfma_f32_16x16x32_bf16 v[26:29], v[114:117], v[54:57], v[26:29]
	v_mfma_f32_16x16x32_bf16 v[70:73], v[114:117], v[66:69], v[70:73]
	v_mfma_f32_16x16x32_bf16 v[22:25], v[114:117], v[50:53], v[18:21]

	s_nop 1
	v_add_u32_e32 v18, 32, v129
	v_min_i32_e32 v18, 0x1ff8, v18
	v_ashrrev_i32_e32 v19, 31, v18
	v_lshl_add_u64 v[114:115], v[18:19], 1, s[22:23]
	global_load_dwordx4 v[18:21], v[114:115], off
	global_load_dword v139, v[114:115], off offset:-4
	s_waitcnt vmcnt(8)
	v_perm_b32 v114, v126, v6, s67
	v_perm_b32 v115, v6, v7, s67
	v_perm_b32 v116, v7, v8, s67
	v_perm_b32 v117, v8, v9, s67

	s_add_i32 s54, s11, 17
	s_ashr_i32 s54, s54, 3
	v_mfma_f32_16x16x32_bf16 v[46:49], v[6:9], v[58:61], v[46:49]
	s_add_i32 s55, s43, 0x240
	s_and_b32 s55, s55, 0x1c0
	v_mfma_f32_16x16x32_bf16 v[38:41], v[114:117], v[58:61], v[38:41]
	v_mfma_f32_16x16x32_bf16 v[58:61], v[6:9], v[74:77], v[62:65]
	v_mfma_f32_16x16x32_bf16 v[62:65], v[114:117], v[74:77], v[94:97]
	s_nop 2
	v_add_u32_e32 v94, s54, v122
	v_min_u32_e32 v94, 32, v94
	v_add_u32_e32 v95, s54, v124
	v_mul_u32_u24_e32 v94, 0x210, v94
	v_min_u32_e32 v95, 32, v95
	v_add3_u32 v94, v0, v94, s55
	v_mul_u32_u24_e32 v95, 0x210, v95
	v_mfma_f32_16x16x32_bf16 v[102:105], v[6:9], v[86:89], v[102:105]
	v_mfma_f32_16x16x32_bf16 v[86:89], v[114:117], v[86:89], v[90:93]
	v_mfma_f32_16x16x32_bf16 v[42:45], v[6:9], v[54:57], v[42:45]
	v_mfma_f32_16x16x32_bf16 v[90:93], v[6:9], v[66:69], v[98:101]
	v_mfma_f32_16x16x32_bf16 v[30:33], v[6:9], v[50:53], v[30:33]
	s_waitcnt lgkmcnt(1)
	v_mfma_f32_16x16x32_bf16 v[82:85], v[6:9], v[106:109], v[82:85]
	s_waitcnt lgkmcnt(0)
	v_mfma_f32_16x16x32_bf16 v[2:5], v[6:9], v[110:113], v[2:5]
	v_add3_u32 v6, v0, v95, s55
	ds_read_b128 v[94:97], v94
	ds_read_b128 v[98:101], v6
	v_mfma_f32_16x16x32_bf16 v[34:37], v[114:117], v[54:57], v[34:37]
	v_mfma_f32_16x16x32_bf16 v[78:81], v[114:117], v[66:69], v[78:81]
	v_mfma_f32_16x16x32_bf16 v[26:29], v[114:117], v[50:53], v[26:29]
	v_mfma_f32_16x16x32_bf16 v[70:73], v[114:117], v[106:109], v[70:73]
	v_mfma_f32_16x16x32_bf16 v[6:9], v[114:117], v[110:113], v[22:25]

	s_nop 1
	v_add_u32_e32 v22, 64, v129
	v_min_i32_e32 v22, 0x1ff8, v22
	v_ashrrev_i32_e32 v23, 31, v22
	v_lshl_add_u64 v[114:115], v[22:23], 1, s[22:23]
	global_load_dwordx4 v[22:25], v[114:115], off
	global_load_dword v140, v[114:115], off offset:-4
	s_waitcnt vmcnt(8)
	v_perm_b32 v114, v127, v10, s67
	v_perm_b32 v115, v10, v11, s67
	v_perm_b32 v116, v11, v12, s67
	v_perm_b32 v117, v12, v13, s67

	s_add_i32 s54, s11, 18
	s_ashr_i32 s54, s54, 3
	v_mfma_f32_16x16x32_bf16 v[102:105], v[10:13], v[74:77], v[102:105]
	s_add_i32 s55, s43, 0x280
	s_and_b32 s55, s55, 0x1c0
	v_mfma_f32_16x16x32_bf16 v[74:77], v[114:117], v[74:77], v[86:89]
	s_nop 2
	v_add_u32_e32 v86, s54, v122
	v_min_u32_e32 v86, 32, v86
	v_add_u32_e32 v87, s54, v124
	v_mul_u32_u24_e32 v86, 0x210, v86
	v_min_u32_e32 v87, 32, v87
	v_add3_u32 v86, v0, v86, s55
	v_mul_u32_u24_e32 v87, 0x210, v87
	v_mfma_f32_16x16x32_bf16 v[46:49], v[10:13], v[54:57], v[46:49]
	v_mfma_f32_16x16x32_bf16 v[38:41], v[114:117], v[54:57], v[38:41]
	v_mfma_f32_16x16x32_bf16 v[54:57], v[10:13], v[66:69], v[58:61]
	v_mfma_f32_16x16x32_bf16 v[58:61], v[114:117], v[66:69], v[62:65]
	v_mfma_f32_16x16x32_bf16 v[42:45], v[10:13], v[50:53], v[42:45]
	v_mfma_f32_16x16x32_bf16 v[62:65], v[10:13], v[106:109], v[90:93]
	v_mfma_f32_16x16x32_bf16 v[30:33], v[10:13], v[110:113], v[30:33]
	s_waitcnt lgkmcnt(1)
	v_mfma_f32_16x16x32_bf16 v[82:85], v[10:13], v[94:97], v[82:85]
	s_waitcnt lgkmcnt(0)
	v_mfma_f32_16x16x32_bf16 v[2:5], v[10:13], v[98:101], v[2:5]
	v_add3_u32 v10, v0, v87, s55
	ds_read_b128 v[130:133], v86
	ds_read_b128 v[134:137], v10
	v_mfma_f32_16x16x32_bf16 v[34:37], v[114:117], v[50:53], v[34:37]
	v_mfma_f32_16x16x32_bf16 v[78:81], v[114:117], v[106:109], v[78:81]
	v_mfma_f32_16x16x32_bf16 v[26:29], v[114:117], v[110:113], v[26:29]
	v_mfma_f32_16x16x32_bf16 v[70:73], v[114:117], v[94:97], v[70:73]
	v_mfma_f32_16x16x32_bf16 v[6:9], v[114:117], v[98:101], v[6:9]

	v_add_u32_e32 v10, 0x60, v129
	v_min_i32_e32 v10, 0x1ff8, v10
	v_ashrrev_i32_e32 v11, 31, v10
	v_lshl_add_u64 v[10:11], v[10:11], 1, s[22:23]
	global_load_dwordx4 v[114:117], v[10:11], off
	global_load_dword v142, v[10:11], off offset:-4
	s_waitcnt vmcnt(8)
	v_perm_b32 v10, v128, v14, s67
	v_perm_b32 v11, v14, v15, s67
	v_perm_b32 v12, v15, v16, s67
	v_perm_b32 v13, v16, v17, s67

	s_add_i32 s54, s11, 19
	s_ashr_i32 s54, s54, 3
	v_mfma_f32_16x16x32_bf16 v[86:89], v[14:17], v[66:69], v[102:105]
	s_add_i32 s55, s43, 0x2c0
	s_and_b32 s55, s55, 0x1c0
	v_mfma_f32_16x16x32_bf16 v[66:69], v[10:13], v[66:69], v[74:77]
	s_nop 2
	v_add_u32_e32 v74, s54, v122
	v_mfma_f32_16x16x32_bf16 v[46:49], v[14:17], v[50:53], v[46:49]
	v_min_u32_e32 v74, 32, v74
	v_mfma_f32_16x16x32_bf16 v[38:41], v[10:13], v[50:53], v[38:41]
	v_mfma_f32_16x16x32_bf16 v[50:53], v[14:17], v[106:109], v[54:57]
	v_mfma_f32_16x16x32_bf16 v[54:57], v[10:13], v[106:109], v[58:61]
	v_mfma_f32_16x16x32_bf16 v[58:61], v[14:17], v[94:97], v[62:65]
	v_mfma_f32_16x16x32_bf16 v[62:65], v[10:13], v[94:97], v[78:81]
	s_nop 2
	v_add_u32_e32 v79, s54, v124
	v_mul_u32_u24_e32 v78, 0x210, v74
	v_min_u32_e32 v79, 32, v79
	v_add3_u32 v78, v0, v78, s55
	v_mul_u32_u24_e32 v79, 0x210, v79
	v_mfma_f32_16x16x32_bf16 v[42:45], v[14:17], v[110:113], v[42:45]
	v_mfma_f32_16x16x32_bf16 v[30:33], v[14:17], v[98:101], v[30:33]
	s_waitcnt lgkmcnt(1)
	v_mfma_f32_16x16x32_bf16 v[74:77], v[14:17], v[130:133], v[82:85]
	s_waitcnt lgkmcnt(0)
	v_mfma_f32_16x16x32_bf16 v[14:17], v[14:17], v[134:137], v[2:5]
	s_nop 2
	v_add3_u32 v2, v0, v79, s55
	ds_read_b128 v[78:81], v78
	ds_read_b128 v[82:85], v2
	v_mfma_f32_16x16x32_bf16 v[34:37], v[10:13], v[110:113], v[34:37]
	v_mfma_f32_16x16x32_bf16 v[26:29], v[10:13], v[98:101], v[26:29]
	v_mfma_f32_16x16x32_bf16 v[70:73], v[10:13], v[130:133], v[70:73]
	v_mfma_f32_16x16x32_bf16 v[6:9], v[10:13], v[134:137], v[6:9]

	v_add_u32_e32 v2, 0x80, v129
	v_min_i32_e32 v2, 0x1ff8, v2
	v_ashrrev_i32_e32 v3, 31, v2
	v_lshl_add_u64 v[10:11], v[2:3], 1, s[22:23]
	global_load_dwordx4 v[2:5], v[10:11], off
	global_load_dword v125, v[10:11], off offset:-4
	s_waitcnt vmcnt(8)
	v_perm_b32 v10, v138, v118, s67
	v_perm_b32 v11, v118, v119, s67
	v_perm_b32 v12, v119, v120, s67
	v_perm_b32 v13, v120, v121, s67

	s_add_i32 s54, s11, 20
	s_ashr_i32 s54, s54, 3
	v_mfma_f32_16x16x32_bf16 v[102:105], v[10:13], v[130:133], v[62:65]
	s_add_i32 s55, s43, 0x300
	s_and_b32 s55, s55, 0x1c0
	s_nop 0
	v_add_u32_e32 v62, s54, v122
	v_add_u32_e32 v63, s54, v124
	v_min_u32_e32 v62, 32, v62
	v_min_u32_e32 v63, 32, v63
	v_mul_u32_u24_e32 v62, 0x210, v62
	v_mul_u32_u24_e32 v63, 0x210, v63
	v_add3_u32 v62, v0, v62, s55
	v_add3_u32 v63, v0, v63, s55
	ds_read_b128 v[90:93], v62
	ds_read_b128 v[62:65], v63
	v_mfma_f32_16x16x32_bf16 v[86:89], v[118:121], v[106:109], v[86:89]
	v_mfma_f32_16x16x32_bf16 v[66:69], v[10:13], v[106:109], v[66:69]
	v_mfma_f32_16x16x32_bf16 v[46:49], v[118:121], v[110:113], v[46:49]
	v_mfma_f32_16x16x32_bf16 v[38:41], v[10:13], v[110:113], v[38:41]
	v_mfma_f32_16x16x32_bf16 v[50:53], v[118:121], v[94:97], v[50:53]
	v_mfma_f32_16x16x32_bf16 v[54:57], v[10:13], v[94:97], v[54:57]
	v_mfma_f32_16x16x32_bf16 v[42:45], v[118:121], v[98:101], v[42:45]
	v_mfma_f32_16x16x32_bf16 v[34:37], v[10:13], v[98:101], v[34:37]
	v_mfma_f32_16x16x32_bf16 v[58:61], v[118:121], v[130:133], v[58:61]
	v_mfma_f32_16x16x32_bf16 v[30:33], v[118:121], v[134:137], v[30:33]
	v_mfma_f32_16x16x32_bf16 v[26:29], v[10:13], v[134:137], v[26:29]
	s_waitcnt lgkmcnt(3)
	v_mfma_f32_16x16x32_bf16 v[74:77], v[118:121], v[78:81], v[74:77]
	v_mfma_f32_16x16x32_bf16 v[70:73], v[10:13], v[78:81], v[70:73]
	s_waitcnt lgkmcnt(2)
	v_mfma_f32_16x16x32_bf16 v[14:17], v[118:121], v[82:85], v[14:17]
	v_mfma_f32_16x16x32_bf16 v[10:13], v[10:13], v[82:85], v[6:9]

	s_nop 1
	v_add_u32_e32 v6, 0xa0, v129
	v_min_i32_e32 v6, 0x1ff8, v6
	v_ashrrev_i32_e32 v7, 31, v6
	v_lshl_add_u64 v[106:107], v[6:7], 1, s[22:23]
	global_load_dwordx4 v[6:9], v[106:107], off
	global_load_dword v126, v[106:107], off offset:-4
	s_waitcnt vmcnt(8)
	v_perm_b32 v106, v139, v18, s67
	v_perm_b32 v107, v18, v19, s67
	v_perm_b32 v108, v19, v20, s67
	v_perm_b32 v109, v20, v21, s67

	s_add_i32 s54, s11, 21
	s_ashr_i32 s54, s54, 3
	v_mfma_f32_16x16x32_bf16 v[110:113], v[18:21], v[94:97], v[86:89]
	s_add_i32 s55, s43, 0x340
	s_and_b32 s55, s55, 0x1c0
	v_mfma_f32_16x16x32_bf16 v[66:69], v[106:109], v[94:97], v[66:69]
	v_mfma_f32_16x16x32_bf16 v[94:97], v[18:21], v[78:81], v[58:61]
	s_nop 2
	v_add_u32_e32 v58, s54, v122
	v_min_u32_e32 v58, 32, v58
	v_add_u32_e32 v59, s54, v124
	v_mul_u32_u24_e32 v58, 0x210, v58
	v_min_u32_e32 v59, 32, v59
	v_add3_u32 v58, v0, v58, s55
	v_mul_u32_u24_e32 v59, 0x210, v59
	v_mfma_f32_16x16x32_bf16 v[46:49], v[18:21], v[98:101], v[46:49]
	v_mfma_f32_16x16x32_bf16 v[50:53], v[18:21], v[130:133], v[50:53]
	v_mfma_f32_16x16x32_bf16 v[42:45], v[18:21], v[134:137], v[42:45]
	v_mfma_f32_16x16x32_bf16 v[30:33], v[18:21], v[82:85], v[30:33]
	s_waitcnt lgkmcnt(1)
	v_mfma_f32_16x16x32_bf16 v[74:77], v[18:21], v[90:93], v[74:77]
	s_waitcnt lgkmcnt(0)
	v_mfma_f32_16x16x32_bf16 v[14:17], v[18:21], v[62:65], v[14:17]
	v_add3_u32 v18, v0, v59, s55
	ds_read_b128 v[86:89], v58
	ds_read_b128 v[58:61], v18
	v_mfma_f32_16x16x32_bf16 v[38:41], v[106:109], v[98:101], v[38:41]
	v_mfma_f32_16x16x32_bf16 v[54:57], v[106:109], v[130:133], v[54:57]
	v_mfma_f32_16x16x32_bf16 v[34:37], v[106:109], v[134:137], v[34:37]
	v_mfma_f32_16x16x32_bf16 v[98:101], v[106:109], v[78:81], v[102:105]
	v_mfma_f32_16x16x32_bf16 v[26:29], v[106:109], v[82:85], v[26:29]
	v_mfma_f32_16x16x32_bf16 v[70:73], v[106:109], v[90:93], v[70:73]
	v_mfma_f32_16x16x32_bf16 v[18:21], v[106:109], v[62:65], v[10:13]

	s_nop 1
	v_add_u32_e32 v10, 0xc0, v129
	v_min_i32_e32 v10, 0x1ff8, v10
	v_ashrrev_i32_e32 v11, 31, v10
	v_lshl_add_u64 v[102:103], v[10:11], 1, s[22:23]
	global_load_dwordx4 v[10:13], v[102:103], off
	global_load_dword v127, v[102:103], off offset:-4
	s_waitcnt vmcnt(8)
	v_perm_b32 v102, v140, v22, s67
	v_perm_b32 v103, v22, v23, s67
	v_perm_b32 v104, v23, v24, s67
	v_perm_b32 v105, v24, v25, s67

	s_add_i32 s54, s11, 22
	s_ashr_i32 s54, s54, 3
	v_mfma_f32_16x16x32_bf16 v[118:121], v[102:105], v[78:81], v[54:57]
	s_add_i32 s55, s43, 0x380
	s_and_b32 s55, s55, 0x1c0
	s_nop 0
	v_add_u32_e32 v54, s54, v122
	v_min_u32_e32 v54, 32, v54
	v_add_u32_e32 v55, s54, v124
	v_mul_u32_u24_e32 v54, 0x210, v54
	v_min_u32_e32 v55, 32, v55
	v_add3_u32 v54, v0, v54, s55
	v_mul_u32_u24_e32 v55, 0x210, v55
	v_mfma_f32_16x16x32_bf16 v[106:109], v[22:25], v[130:133], v[110:113]
	v_mfma_f32_16x16x32_bf16 v[66:69], v[102:105], v[130:133], v[66:69]
	v_mfma_f32_16x16x32_bf16 v[46:49], v[22:25], v[134:137], v[46:49]
	v_mfma_f32_16x16x32_bf16 v[50:53], v[22:25], v[78:81], v[50:53]
	v_mfma_f32_16x16x32_bf16 v[42:45], v[22:25], v[82:85], v[42:45]
	v_mfma_f32_16x16x32_bf16 v[130:133], v[22:25], v[90:93], v[94:97]
	v_mfma_f32_16x16x32_bf16 v[30:33], v[22:25], v[62:65], v[30:33]
	s_waitcnt lgkmcnt(1)
	v_mfma_f32_16x16x32_bf16 v[138:141], v[22:25], v[86:89], v[74:77]
	s_waitcnt lgkmcnt(0)
	v_mfma_f32_16x16x32_bf16 v[22:25], v[22:25], v[58:61], v[14:17]
	s_nop 2
	v_add3_u32 v14, v0, v55, s55
	ds_read_b128 v[74:77], v54
	ds_read_b128 v[54:57], v14
	v_mfma_f32_16x16x32_bf16 v[38:41], v[102:105], v[134:137], v[38:41]
	v_mfma_f32_16x16x32_bf16 v[34:37], v[102:105], v[82:85], v[34:37]
	v_mfma_f32_16x16x32_bf16 v[26:29], v[102:105], v[62:65], v[26:29]
	v_mfma_f32_16x16x32_bf16 v[70:73], v[102:105], v[86:89], v[70:73]
	v_mfma_f32_16x16x32_bf16 v[18:21], v[102:105], v[58:61], v[18:21]
	v_mfma_f32_16x16x32_bf16 v[134:137], v[102:105], v[90:93], v[98:101]

	v_add_u32_e32 v14, 0xe0, v129
	v_min_i32_e32 v14, 0x1ff8, v14
	v_ashrrev_i32_e32 v15, 31, v14
	v_lshl_add_u64 v[94:95], v[14:15], 1, s[22:23]
	global_load_dwordx4 v[14:17], v[94:95], off
	global_load_dword v128, v[94:95], off offset:-4
	s_waitcnt vmcnt(8)
	v_perm_b32 v142, v142, v114, s67
	v_perm_b32 v143, v114, v115, s67
	v_perm_b32 v144, v115, v116, s67
	v_perm_b32 v145, v116, v117, s67

	s_add_i32 s54, s11, 23
	s_ashr_i32 s54, s54, 3
	v_mfma_f32_16x16x32_bf16 v[110:113], v[114:117], v[90:93], v[50:53]
	s_add_i32 s55, s43, 0x3c0
	s_and_b32 s55, s55, 0x1c0
	s_nop 0
	v_add_u32_e32 v50, s54, v122
	v_add_u32_e32 v51, s54, v124
	v_min_u32_e32 v50, 32, v50
	v_min_u32_e32 v51, 32, v51
	v_mul_u32_u24_e32 v50, 0x210, v50
	v_mul_u32_u24_e32 v51, 0x210, v51
	v_add3_u32 v50, v0, v50, s55
	v_add3_u32 v51, v0, v51, s55
	v_mfma_f32_16x16x32_bf16 v[102:105], v[114:117], v[78:81], v[106:109]
	v_mfma_f32_16x16x32_bf16 v[106:109], v[142:145], v[78:81], v[66:69]
	s_nop 2
	ds_read_b128 v[66:69], v50
	ds_read_b128 v[50:53], v51
	v_mfma_f32_16x16x32_bf16 v[46:49], v[114:117], v[82:85], v[46:49]
	v_mfma_f32_16x16x32_bf16 v[38:41], v[142:145], v[82:85], v[38:41]
	v_mfma_f32_16x16x32_bf16 v[94:97], v[142:145], v[90:93], v[118:121]
	v_mfma_f32_16x16x32_bf16 v[42:45], v[114:117], v[62:65], v[42:45]
	v_mfma_f32_16x16x32_bf16 v[34:37], v[142:145], v[62:65], v[34:37]
	v_mfma_f32_16x16x32_bf16 v[98:101], v[114:117], v[86:89], v[130:133]
	v_mfma_f32_16x16x32_bf16 v[78:81], v[142:145], v[86:89], v[134:137]
	v_mfma_f32_16x16x32_bf16 v[30:33], v[114:117], v[58:61], v[30:33]
	v_mfma_f32_16x16x32_bf16 v[26:29], v[142:145], v[58:61], v[26:29]
	s_waitcnt lgkmcnt(3)
	v_mfma_f32_16x16x32_bf16 v[82:85], v[114:117], v[74:77], v[138:141]
	v_mfma_f32_16x16x32_bf16 v[70:73], v[142:145], v[74:77], v[70:73]
	s_waitcnt lgkmcnt(2)
	v_mfma_f32_16x16x32_bf16 v[22:25], v[114:117], v[54:57], v[22:25]
	v_mfma_f32_16x16x32_bf16 v[18:21], v[142:145], v[54:57], v[18:21]

; #define CONV_BLOCK(DO0, DO1) do { CONV_STEP(0, DO0, DO1); CONV_STEP(1, DO0, DO1); CONV_STEP(2, DO0, DO1); CONV_STEP(3, DO0, DO1); CONV_STEP(4, DO0, DO1); CONV_STEP(5, DO0, DO1); CONV_STEP(6, DO0, DO1); CONV_STEP(7, DO0, DO1); } while (0)
; template <bool PROMPT, int HALF>
; __device__ __forceinline__ void conv_item(unsigned char* ws, KArgs ka, int ib, int oct, int g, LAS unsigned char* lds, int tid, int lane, int wave) {
;     ...
;     for (int e = E1; e < E2; e += 8) CONV_BLOCK(true, true);
;     for (int e = E2; e < E3; e += 8) CONV_BLOCK(true, false);
	s_add_i32 s11, s11, 8
	s_addk_i32 s43, 0x200
	s_cmpk_lt_i32 s11, 0x79
	v_add_u32_e32 v129, 0x100, v129
	s_cbranch_scc1 .LBB0_753
	s_waitcnt lgkmcnt(0)
	v_add_u32_e32 v50, 18, v122
	v_add_u32_e32 v51, 0x1180, v123
	s_movk_i32 s11, 0x79
.LBB0_755:
	v_add_u32_e32 v52, 0xffffff20, v51
	v_min_i32_e32 v52, 0x1ff8, v52
	v_ashrrev_i32_e32 v53, 31, v52
	v_lshl_add_u64 v[56:57], v[52:53], 1, s[22:23]
	global_load_dwordx4 v[52:55], v[56:57], off
	global_load_dword v122, v[56:57], off offset:-4
	s_waitcnt vmcnt(8)
	v_perm_b32 v56, v125, v2, s67
	v_perm_b32 v57, v2, v3, s67
	v_perm_b32 v58, v3, v4, s67
	v_perm_b32 v59, v4, v5, s67

	v_add_u32_e32 v64, -1, v50
	v_min_u32_e32 v64, 32, v64
	v_mad_u32_u24 v123, v64, s58, v0
	v_mfma_f32_16x16x32_bf16 v[60:63], v[56:59], v[90:93], v[106:109]
	v_mfma_f32_16x16x32_bf16 v[106:109], v[2:5], v[86:89], v[110:113]
	s_nop 2
	ds_read_b128 v[110:113], v123 offset:64
	v_mfma_f32_16x16x32_bf16 v[94:97], v[56:59], v[86:89], v[94:97]
	v_mfma_f32_16x16x32_bf16 v[98:101], v[2:5], v[74:77], v[98:101]
	v_mfma_f32_16x16x32_bf16 v[78:81], v[56:59], v[74:77], v[78:81]
	s_waitcnt lgkmcnt(1)
	v_mfma_f32_16x16x32_bf16 v[82:85], v[2:5], v[66:69], v[82:85]
	v_mfma_f32_16x16x32_bf16 v[56:59], v[56:59], v[66:69], v[70:73]

	v_add_u32_e32 v64, 0xffffff40, v51
	v_min_i32_e32 v64, 0x1ff8, v64
	v_ashrrev_i32_e32 v65, 31, v64
	v_lshl_add_u64 v[64:65], v[64:65], 1, s[22:23]
	global_load_dwordx4 v[70:73], v[64:65], off
	global_load_dword v124, v[64:65], off offset:-4
	s_waitcnt vmcnt(8)
	v_perm_b32 v114, v126, v6, s67
	v_perm_b32 v115, v6, v7, s67
	v_perm_b32 v116, v7, v8, s67
	v_perm_b32 v117, v8, v9, s67

; #define CONV_BLOCK(DO0, DO1) do { CONV_STEP(0, DO0, DO1); CONV_STEP(1, DO0, DO1); CONV_STEP(2, DO0, DO1); CONV_STEP(3, DO0, DO1); CONV_STEP(4, DO0, DO1); CONV_STEP(5, DO0, DO1); CONV_STEP(6, DO0, DO1); CONV_STEP(7, DO0, DO1); } while (0)
; template <bool PROMPT, int HALF>
; __device__ __forceinline__ void conv_item(unsigned char* ws, KArgs ka, int ib, int oct, int g, LAS unsigned char* lds, int tid, int lane, int wave) {
;     ...
;     for (int e = E2; e < E3; e += 8) CONV_BLOCK(true, false);
	s_nop 0
	v_mfma_f32_16x16x32_bf16 v[60:63], v[114:117], v[86:89], v[60:63]
	v_mfma_f32_16x16x32_bf16 v[106:109], v[6:9], v[74:77], v[106:109]
	v_mfma_f32_16x16x32_bf16 v[94:97], v[114:117], v[74:77], v[94:97]
	v_mfma_f32_16x16x32_bf16 v[98:101], v[6:9], v[66:69], v[98:101]
	v_mfma_f32_16x16x32_bf16 v[78:81], v[114:117], v[66:69], v[78:81]
	s_waitcnt lgkmcnt(0)
	v_mfma_f32_16x16x32_bf16 v[82:85], v[6:9], v[110:113], v[82:85]
	v_mfma_f32_16x16x32_bf16 v[56:59], v[114:117], v[110:113], v[56:59]
	ds_read_b128 v[114:117], v123 offset:128
	v_mfma_f32_16x16x32_bf16 v[2:5], v[2:5], v[90:93], v[102:105]

	v_add_u32_e32 v64, 0xffffff60, v51
	v_min_i32_e32 v64, 0x1ff8, v64
	v_ashrrev_i32_e32 v65, 31, v64
	v_lshl_add_u64 v[64:65], v[64:65], 1, s[22:23]
	global_load_dwordx4 v[102:105], v[64:65], off
	global_load_dword v129, v[64:65], off offset:-4
	s_waitcnt vmcnt(8)
	v_perm_b32 v90, v127, v10, s67
	v_perm_b32 v91, v10, v11, s67
	v_perm_b32 v92, v11, v12, s67
	v_perm_b32 v93, v12, v13, s67

	v_mfma_f32_16x16x32_bf16 v[106:109], v[10:13], v[66:69], v[106:109]
	ds_read_b128 v[118:121], v123 offset:192
	v_mfma_f32_16x16x32_bf16 v[94:97], v[90:93], v[66:69], v[94:97]
	v_mfma_f32_16x16x32_bf16 v[98:101], v[10:13], v[110:113], v[98:101]
	v_mfma_f32_16x16x32_bf16 v[78:81], v[90:93], v[110:113], v[78:81]
	s_waitcnt lgkmcnt(1)
	v_mfma_f32_16x16x32_bf16 v[82:85], v[10:13], v[114:117], v[82:85]
	v_mfma_f32_16x16x32_bf16 v[2:5], v[6:9], v[86:89], v[2:5]
	v_mfma_f32_16x16x32_bf16 v[60:63], v[90:93], v[74:77], v[60:63]
	v_mfma_f32_16x16x32_bf16 v[56:59], v[90:93], v[114:117], v[56:59]

	v_add_u32_e32 v6, 0xffffff80, v51
	v_min_i32_e32 v6, 0x1ff8, v6
	v_ashrrev_i32_e32 v7, 31, v6
	v_lshl_add_u64 v[6:7], v[6:7], 1, s[22:23]
	global_load_dwordx4 v[130:133], v[6:7], off
	global_load_dword v142, v[6:7], off offset:-4
	s_waitcnt vmcnt(8)
	v_perm_b32 v6, v128, v14, s67
	v_perm_b32 v7, v14, v15, s67
	v_perm_b32 v8, v15, v16, s67
	v_perm_b32 v9, v16, v17, s67

	s_nop 0
	v_mfma_f32_16x16x32_bf16 v[60:63], v[6:9], v[66:69], v[60:63]
	v_mfma_f32_16x16x32_bf16 v[86:89], v[14:17], v[110:113], v[106:109]
	v_mfma_f32_16x16x32_bf16 v[90:93], v[6:9], v[110:113], v[94:97]
	v_mfma_f32_16x16x32_bf16 v[94:97], v[14:17], v[114:117], v[98:101]
	v_mfma_f32_16x16x32_bf16 v[78:81], v[6:9], v[114:117], v[78:81]
	s_waitcnt lgkmcnt(0)
	v_mfma_f32_16x16x32_bf16 v[82:85], v[14:17], v[118:121], v[82:85]
	v_mfma_f32_16x16x32_bf16 v[6:9], v[6:9], v[118:121], v[56:59]
	s_nop 2
	ds_read_b128 v[56:59], v123 offset:256
	v_mfma_f32_16x16x32_bf16 v[10:13], v[10:13], v[74:77], v[2:5]

	s_nop 1
	v_add_u32_e32 v2, 0xffffffa0, v51
	v_min_i32_e32 v2, 0x1ff8, v2
	v_ashrrev_i32_e32 v3, 31, v2
	v_lshl_add_u64 v[64:65], v[2:3], 1, s[22:23]
	global_load_dwordx4 v[2:5], v[64:65], off
	global_load_dword v125, v[64:65], off offset:-4
	s_waitcnt vmcnt(8)
	v_perm_b32 v74, v122, v52, s67
	v_perm_b32 v75, v52, v53, s67
	v_perm_b32 v76, v53, v54, s67
	v_perm_b32 v77, v54, v55, s67

	s_nop 0
	v_mfma_f32_16x16x32_bf16 v[98:101], v[74:77], v[114:117], v[90:93]
	s_nop 2
	ds_read_b128 v[90:93], v123 offset:320
	v_mfma_f32_16x16x32_bf16 v[60:63], v[74:77], v[110:113], v[60:63]
	v_mfma_f32_16x16x32_bf16 v[86:89], v[52:55], v[114:117], v[86:89]
	v_mfma_f32_16x16x32_bf16 v[94:97], v[52:55], v[118:121], v[94:97]
	v_mfma_f32_16x16x32_bf16 v[78:81], v[74:77], v[118:121], v[78:81]
	s_waitcnt lgkmcnt(1)
	v_mfma_f32_16x16x32_bf16 v[82:85], v[52:55], v[56:59], v[82:85]
	v_mfma_f32_16x16x32_bf16 v[74:77], v[74:77], v[56:59], v[6:9]
	v_mfma_f32_16x16x32_bf16 v[10:13], v[14:17], v[66:69], v[10:13]

	s_nop 0
	v_subrev_u32_e32 v6, 64, v51
	v_min_i32_e32 v6, 0x1ff8, v6
	v_ashrrev_i32_e32 v7, 31, v6
	v_lshl_add_u64 v[14:15], v[6:7], 1, s[22:23]
	global_load_dwordx4 v[6:9], v[14:15], off
	global_load_dword v126, v[14:15], off offset:-4
	s_waitcnt vmcnt(8)
	v_perm_b32 v14, v124, v70, s67
	v_perm_b32 v15, v70, v71, s67
	v_perm_b32 v16, v71, v72, s67
	v_perm_b32 v17, v72, v73, s67

	v_mfma_f32_16x16x32_bf16 v[64:67], v[70:73], v[118:121], v[86:89]
	s_nop 2
	ds_read_b128 v[86:89], v123 offset:384
	v_mfma_f32_16x16x32_bf16 v[60:63], v[14:17], v[114:117], v[60:63]
	v_mfma_f32_16x16x32_bf16 v[98:101], v[14:17], v[118:121], v[98:101]
	v_mfma_f32_16x16x32_bf16 v[94:97], v[70:73], v[56:59], v[94:97]
	v_mfma_f32_16x16x32_bf16 v[78:81], v[14:17], v[56:59], v[78:81]
	s_waitcnt lgkmcnt(1)
	v_mfma_f32_16x16x32_bf16 v[82:85], v[70:73], v[90:93], v[82:85]
	v_mfma_f32_16x16x32_bf16 v[14:17], v[14:17], v[90:93], v[74:77]
	v_mfma_f32_16x16x32_bf16 v[52:55], v[52:55], v[110:113], v[10:13]

	s_nop 1
	v_subrev_u32_e32 v10, 32, v51
	v_min_i32_e32 v10, 0x1ff8, v10
	v_ashrrev_i32_e32 v11, 31, v10
	v_lshl_add_u64 v[68:69], v[10:11], 1, s[22:23]
	global_load_dwordx4 v[10:13], v[68:69], off
	global_load_dword v127, v[68:69], off offset:-4
	s_waitcnt vmcnt(8)
	v_perm_b32 v74, v129, v102, s67
	v_perm_b32 v75, v102, v103, s67
	v_perm_b32 v76, v103, v104, s67
	v_perm_b32 v77, v104, v105, s67

	s_nop 0
	v_mfma_f32_16x16x32_bf16 v[60:63], v[74:77], v[118:121], v[60:63]
	v_mfma_f32_16x16x32_bf16 v[98:101], v[74:77], v[56:59], v[98:101]
	v_mfma_f32_16x16x32_bf16 v[78:81], v[74:77], v[90:93], v[78:81]
	s_waitcnt lgkmcnt(0)
	v_mfma_f32_16x16x32_bf16 v[138:141], v[74:77], v[86:89], v[14:17]
	ds_read_b128 v[74:77], v123 offset:448
	v_mfma_f32_16x16x32_bf16 v[64:67], v[102:105], v[56:59], v[64:67]
	v_mfma_f32_16x16x32_bf16 v[82:85], v[102:105], v[86:89], v[82:85]
	v_mfma_f32_16x16x32_bf16 v[134:137], v[102:105], v[90:93], v[94:97]
	v_mfma_f32_16x16x32_bf16 v[52:55], v[70:73], v[114:117], v[52:55]

	v_min_i32_e32 v14, 0x1ff8, v51
	v_ashrrev_i32_e32 v15, 31, v14
	v_lshl_add_u64 v[68:69], v[14:15], 1, s[22:23]
	global_load_dwordx4 v[14:17], v[68:69], off
	global_load_dword v128, v[68:69], off offset:-4
	s_waitcnt vmcnt(8)
	v_perm_b32 v68, v142, v130, s67
	v_perm_b32 v69, v130, v131, s67
	v_perm_b32 v70, v131, v132, s67
	v_perm_b32 v71, v132, v133, s67

	v_mfma_f32_16x16x32_bf16 v[52:55], v[102:105], v[118:121], v[52:55]
	v_mfma_f32_16x16x32_bf16 v[106:109], v[68:71], v[56:59], v[60:63]
	s_nop 2
	v_min_u32_e32 v60, 32, v50
	v_mad_u32_u24 v60, v60, s58, v0
	v_mfma_f32_16x16x32_bf16 v[110:113], v[130:133], v[90:93], v[64:67]
	v_mfma_f32_16x16x32_bf16 v[94:97], v[68:71], v[90:93], v[98:101]
	v_mfma_f32_16x16x32_bf16 v[78:81], v[68:71], v[86:89], v[78:81]
	s_waitcnt lgkmcnt(0)
	v_mfma_f32_16x16x32_bf16 v[70:73], v[68:71], v[74:77], v[138:141]
	ds_read_b128 v[66:69], v60
	v_mfma_f32_16x16x32_bf16 v[98:101], v[130:133], v[86:89], v[134:137]
	v_mfma_f32_16x16x32_bf16 v[82:85], v[130:133], v[74:77], v[82:85]
	v_mfma_f32_16x16x32_bf16 v[102:105], v[130:133], v[56:59], v[52:55]

; #define CONV_BLOCK(DO0, DO1) do { CONV_STEP(0, DO0, DO1); CONV_STEP(1, DO0, DO1); CONV_STEP(2, DO0, DO1); CONV_STEP(3, DO0, DO1); CONV_STEP(4, DO0, DO1); CONV_STEP(5, DO0, DO1); CONV_STEP(6, DO0, DO1); CONV_STEP(7, DO0, DO1); } while (0)
; template <bool PROMPT, int HALF>
; __device__ __forceinline__ void conv_item(unsigned char* ws, KArgs ka, int ib, int oct, int g, LAS unsigned char* lds, int tid, int lane, int wave) {
;     ...
;     for (int e = E2; e < E3; e += 8) CONV_BLOCK(true, false);
;     ...
;     __syncthreads();
;     int lane2; { unsigned ones_ = ~0u; asm volatile("" : "+s"(ones_)); lane2 = (int)__builtin_amdgcn_mbcnt_hi(ones_, __builtin_amdgcn_mbcnt_lo(ones_, 0u)); }
;     const int nn2 = lane2 & 15, kq2 = lane2 >> 4;
;     float nsum = 0.f;
;     { const float* kq_ = (const float*)(ws + WS_KPART) + ((size_t)ib * 320 + (PROMPT ? 0 : 256)) * 2048; constexpr int ntile = PROMPT ? 256 : 64;
;       for (int q = lane2; q < ntile; q += 64) nsum += kq_[(size_t)q * 2048 + c] + kq_[(size_t)q * 2048 + 1024 + c];
	s_add_i32 s11, s11, 8
	v_add_u32_e32 v50, 1, v50
	s_cmpk_gt_u32 s11, 0xf8
	v_add_u32_e32 v51, 0x100, v51
	s_cbranch_scc0 .LBB0_755
	s_mov_b32 s11, -1
	s_waitcnt lgkmcnt(0)
	s_barrier
	s_nop 0
	v_mbcnt_lo_u32_b32 v0, s11, 0
	s_waitcnt vmcnt(3)
	v_mbcnt_hi_u32_b32 v12, s11, v0
	s_movk_i32 s11, 0x100
	v_cmp_gt_i32_e32 vcc, s11, v12
	v_mov_b32_e32 v0, 0
	s_and_saveexec_b64 s[22:23], vcc
	s_cbranch_execz .LBB0_760
	s_lshl_b64 s[18:19], s[18:19], 2
	s_add_u32 s18, s51, s18
	v_lshlrev_b32_e32 v0, 13, v12
	s_addc_u32 s19, s52, s19
	v_subrev_u32_e32 v4, 64, v12
	v_lshl_add_u64 v[2:3], s[18:19], 0, v[0:1]
	v_mov_b32_e32 v0, 0
	s_mov_b64 s[18:19], 0

; #define CONV_BLOCK(DO0, DO1) do { CONV_STEP(0, DO0, DO1); CONV_STEP(1, DO0, DO1); CONV_STEP(2, DO0, DO1); CONV_STEP(3, DO0, DO1); CONV_STEP(4, DO0, DO1); CONV_STEP(5, DO0, DO1); CONV_STEP(6, DO0, DO1); CONV_STEP(7, DO0, DO1); } while (0)
; template <bool PROMPT, int HALF>
; __device__ __forceinline__ void conv_item(unsigned char* ws, KArgs ka, int ib, int oct, int g, LAS unsigned char* lds, int tid, int lane, int wave) {
;     ...
;     for (int e = E0; e < E1; e += 8) CONV_BLOCK(false, true);
.LBB0_769:
	v_min_i32_e32 v68, 0x1ff8, v66
	v_ashrrev_i32_e32 v69, 31, v68
	v_lshl_add_u64 v[72:73], v[68:69], 1, s[18:19]
	global_load_dwordx4 v[68:71], v[72:73], off
	global_load_dword v67, v[72:73], off offset:-4
	s_add_i32 s22, s11, 12
	s_waitcnt vmcnt(8)
	v_perm_b32 v72, v125, v2, s67
	v_perm_b32 v73, v2, v3, s67
	v_perm_b32 v74, v3, v4, s67
	v_perm_b32 v75, v4, v5, s67

	s_ashr_i32 s22, s22, 3
	v_add_u32_e32 v76, s22, v124
	v_min_u32_e32 v76, 32, v76
	v_mad_u32_u24 v76, v76, s58, v0
	v_mfma_f32_16x16x32_bf16 v[42:45], v[72:75], v[62:65], v[42:45]
	ds_read_b128 v[76:79], v76 offset:320
	v_mfma_f32_16x16x32_bf16 v[38:41], v[2:5], v[58:61], v[38:41]
	v_mfma_f32_16x16x32_bf16 v[34:37], v[72:75], v[58:61], v[34:37]
	v_mfma_f32_16x16x32_bf16 v[30:33], v[2:5], v[54:57], v[30:33]
	v_mfma_f32_16x16x32_bf16 v[26:29], v[72:75], v[54:57], v[26:29]
	s_waitcnt lgkmcnt(1)
	v_mfma_f32_16x16x32_bf16 v[22:25], v[2:5], v[50:53], v[22:25]
	v_mfma_f32_16x16x32_bf16 v[18:21], v[72:75], v[50:53], v[18:21]

	v_add_u32_e32 v72, 32, v66
	v_min_i32_e32 v72, 0x1ff8, v72
	v_ashrrev_i32_e32 v73, 31, v72
	v_lshl_add_u64 v[80:81], v[72:73], 1, s[18:19]
	global_load_dwordx4 v[72:75], v[80:81], off
	global_load_dword v96, v[80:81], off offset:-4
	s_add_i32 s22, s11, 13
	s_waitcnt vmcnt(8)
	v_perm_b32 v80, v126, v6, s67
	v_perm_b32 v81, v6, v7, s67
	v_perm_b32 v82, v7, v8, s67
	v_perm_b32 v83, v8, v9, s67

	s_ashr_i32 s22, s22, 3
	v_add_u32_e32 v84, s22, v124
	v_mfma_f32_16x16x32_bf16 v[42:45], v[80:83], v[58:61], v[42:45]
	v_mfma_f32_16x16x32_bf16 v[34:37], v[80:83], v[54:57], v[34:37]
	v_mfma_f32_16x16x32_bf16 v[26:29], v[80:83], v[50:53], v[26:29]
	s_waitcnt lgkmcnt(0)
	v_mfma_f32_16x16x32_bf16 v[18:21], v[80:83], v[76:79], v[18:21]
	v_min_u32_e32 v80, 32, v84
	v_mad_u32_u24 v80, v80, s58, v0
	ds_read_b128 v[80:83], v80 offset:384
	v_mfma_f32_16x16x32_bf16 v[38:41], v[6:9], v[54:57], v[38:41]
	v_mfma_f32_16x16x32_bf16 v[30:33], v[6:9], v[50:53], v[30:33]
	v_mfma_f32_16x16x32_bf16 v[22:25], v[6:9], v[76:79], v[22:25]
	v_mfma_f32_16x16x32_bf16 v[2:5], v[2:5], v[62:65], v[46:49]

	s_nop 1
	v_add_u32_e32 v46, 64, v66
	v_min_i32_e32 v46, 0x1ff8, v46
	v_ashrrev_i32_e32 v47, 31, v46
	v_lshl_add_u64 v[62:63], v[46:47], 1, s[18:19]
	global_load_dwordx4 v[46:49], v[62:63], off
	global_load_dword v97, v[62:63], off offset:-4
	s_waitcnt vmcnt(8)
	v_perm_b32 v62, v127, v10, s67
	v_perm_b32 v63, v10, v11, s67
	v_perm_b32 v64, v11, v12, s67
	v_perm_b32 v65, v12, v13, s67
	s_add_i32 s22, s11, 14

	s_ashr_i32 s22, s22, 3
	v_add_u32_e32 v84, s22, v124
	v_mfma_f32_16x16x32_bf16 v[42:45], v[62:65], v[54:57], v[42:45]
	v_mfma_f32_16x16x32_bf16 v[34:37], v[62:65], v[50:53], v[34:37]
	v_mfma_f32_16x16x32_bf16 v[26:29], v[62:65], v[76:79], v[26:29]
	s_waitcnt lgkmcnt(0)
	v_mfma_f32_16x16x32_bf16 v[18:21], v[62:65], v[80:83], v[18:21]
	v_min_u32_e32 v62, 32, v84
	v_mad_u32_u24 v62, v62, s58, v0
	ds_read_b128 v[84:87], v62 offset:448
	v_mfma_f32_16x16x32_bf16 v[38:41], v[10:13], v[50:53], v[38:41]
	v_mfma_f32_16x16x32_bf16 v[30:33], v[10:13], v[76:79], v[30:33]
	v_mfma_f32_16x16x32_bf16 v[22:25], v[10:13], v[80:83], v[22:25]
	v_mfma_f32_16x16x32_bf16 v[2:5], v[6:9], v[58:61], v[2:5]

	v_add_u32_e32 v6, 0x60, v66
	v_min_i32_e32 v6, 0x1ff8, v6
	v_ashrrev_i32_e32 v7, 31, v6
	v_lshl_add_u64 v[6:7], v[6:7], 1, s[18:19]
	global_load_dwordx4 v[88:91], v[6:7], off
	global_load_dword v98, v[6:7], off offset:-4
	s_waitcnt vmcnt(8)
	v_perm_b32 v6, v128, v14, s67
	v_perm_b32 v7, v14, v15, s67
	v_perm_b32 v8, v15, v16, s67
	v_perm_b32 v9, v16, v17, s67
	s_add_i32 s22, s11, 15

	s_ashr_i32 s22, s22, 3
	v_add_u32_e32 v58, s22, v124
	v_mfma_f32_16x16x32_bf16 v[42:45], v[6:9], v[50:53], v[42:45]
	v_mfma_f32_16x16x32_bf16 v[34:37], v[6:9], v[76:79], v[34:37]
	v_mfma_f32_16x16x32_bf16 v[26:29], v[6:9], v[80:83], v[26:29]
	s_waitcnt lgkmcnt(0)
	v_mfma_f32_16x16x32_bf16 v[6:9], v[6:9], v[84:87], v[18:21]
	s_nop 2
	v_min_u32_e32 v18, 32, v58
	v_mad_u32_u24 v18, v18, s58, v0
	v_mfma_f32_16x16x32_bf16 v[38:41], v[14:17], v[76:79], v[38:41]
	ds_read_b128 v[92:95], v18
	v_mfma_f32_16x16x32_bf16 v[30:33], v[14:17], v[80:83], v[30:33]
	v_mfma_f32_16x16x32_bf16 v[22:25], v[14:17], v[84:87], v[22:25]
	v_mfma_f32_16x16x32_bf16 v[10:13], v[10:13], v[54:57], v[2:5]

	s_nop 1
	v_add_u32_e32 v2, 0x80, v66
	v_min_i32_e32 v2, 0x1ff8, v2
	v_ashrrev_i32_e32 v3, 31, v2
	v_lshl_add_u64 v[18:19], v[2:3], 1, s[18:19]
	global_load_dwordx4 v[2:5], v[18:19], off
	global_load_dword v125, v[18:19], off offset:-4
	s_waitcnt vmcnt(8)
	v_perm_b32 v18, v67, v68, s67
	v_perm_b32 v19, v68, v69, s67
	v_perm_b32 v20, v69, v70, s67
	v_perm_b32 v21, v70, v71, s67
	s_add_i32 s22, s11, 16

	s_ashr_i32 s22, s22, 3
	v_add_u32_e32 v54, s22, v124
	v_mfma_f32_16x16x32_bf16 v[42:45], v[18:21], v[76:79], v[42:45]
	v_mfma_f32_16x16x32_bf16 v[34:37], v[18:21], v[80:83], v[34:37]
	v_mfma_f32_16x16x32_bf16 v[26:29], v[18:21], v[84:87], v[26:29]
	s_waitcnt lgkmcnt(0)
	v_mfma_f32_16x16x32_bf16 v[18:21], v[18:21], v[92:95], v[6:9]
	s_nop 2
	v_min_u32_e32 v6, 32, v54
	v_mad_u32_u24 v6, v6, s58, v0
	ds_read_b128 v[62:65], v6 offset:64
	v_mfma_f32_16x16x32_bf16 v[38:41], v[68:71], v[80:83], v[38:41]
	v_mfma_f32_16x16x32_bf16 v[30:33], v[68:71], v[84:87], v[30:33]
	v_mfma_f32_16x16x32_bf16 v[22:25], v[68:71], v[92:95], v[22:25]
	v_mfma_f32_16x16x32_bf16 v[10:13], v[14:17], v[50:53], v[10:13]

	v_add_u32_e32 v6, 0xa0, v66
	v_min_i32_e32 v6, 0x1ff8, v6
	v_ashrrev_i32_e32 v7, 31, v6
	v_lshl_add_u64 v[14:15], v[6:7], 1, s[18:19]
	global_load_dwordx4 v[6:9], v[14:15], off
	global_load_dword v126, v[14:15], off offset:-4
	s_waitcnt vmcnt(8)
	v_perm_b32 v14, v96, v72, s67
	v_perm_b32 v15, v72, v73, s67
	v_perm_b32 v16, v73, v74, s67
	v_perm_b32 v17, v74, v75, s67
	s_add_i32 s22, s11, 17

	s_ashr_i32 s22, s22, 3
	v_add_u32_e32 v50, s22, v124
	v_mfma_f32_16x16x32_bf16 v[42:45], v[14:17], v[80:83], v[42:45]
	v_mfma_f32_16x16x32_bf16 v[34:37], v[14:17], v[84:87], v[34:37]
	v_mfma_f32_16x16x32_bf16 v[26:29], v[14:17], v[92:95], v[26:29]
	s_waitcnt lgkmcnt(0)
	v_mfma_f32_16x16x32_bf16 v[14:17], v[14:17], v[62:65], v[18:21]
	s_nop 2
	v_min_u32_e32 v18, 32, v50
	v_mad_u32_u24 v18, v18, s58, v0
	ds_read_b128 v[58:61], v18 offset:128
	v_mfma_f32_16x16x32_bf16 v[38:41], v[72:75], v[84:87], v[38:41]
	v_mfma_f32_16x16x32_bf16 v[30:33], v[72:75], v[92:95], v[30:33]
	v_mfma_f32_16x16x32_bf16 v[22:25], v[72:75], v[62:65], v[22:25]
	v_mfma_f32_16x16x32_bf16 v[18:21], v[68:71], v[76:79], v[10:13]

	s_nop 1
	v_add_u32_e32 v10, 0xc0, v66
	v_min_i32_e32 v10, 0x1ff8, v10
	v_ashrrev_i32_e32 v11, 31, v10
	v_lshl_add_u64 v[50:51], v[10:11], 1, s[18:19]
	global_load_dwordx4 v[10:13], v[50:51], off
	global_load_dword v127, v[50:51], off offset:-4
	s_waitcnt vmcnt(8)
	v_perm_b32 v50, v97, v46, s67
	v_perm_b32 v51, v46, v47, s67
	v_perm_b32 v52, v47, v48, s67
	v_perm_b32 v53, v48, v49, s67
	s_add_i32 s22, s11, 18

	s_ashr_i32 s22, s22, 3
	v_add_u32_e32 v54, s22, v124
	v_mfma_f32_16x16x32_bf16 v[42:45], v[50:53], v[84:87], v[42:45]
	v_mfma_f32_16x16x32_bf16 v[34:37], v[50:53], v[92:95], v[34:37]
	v_mfma_f32_16x16x32_bf16 v[26:29], v[50:53], v[62:65], v[26:29]
	s_waitcnt lgkmcnt(0)
	v_mfma_f32_16x16x32_bf16 v[50:53], v[50:53], v[58:61], v[14:17]
	s_nop 2
	v_min_u32_e32 v14, 32, v54
	v_mad_u32_u24 v14, v14, s58, v0
	ds_read_b128 v[54:57], v14 offset:192
	v_mfma_f32_16x16x32_bf16 v[38:41], v[46:49], v[92:95], v[38:41]
	v_mfma_f32_16x16x32_bf16 v[30:33], v[46:49], v[62:65], v[30:33]
	v_mfma_f32_16x16x32_bf16 v[22:25], v[46:49], v[58:61], v[22:25]
	v_mfma_f32_16x16x32_bf16 v[68:71], v[72:75], v[80:83], v[18:21]

	v_add_u32_e32 v14, 0xe0, v66
	v_min_i32_e32 v14, 0x1ff8, v14
	v_ashrrev_i32_e32 v15, 31, v14
	v_lshl_add_u64 v[18:19], v[14:15], 1, s[18:19]
	global_load_dwordx4 v[14:17], v[18:19], off
	global_load_dword v128, v[18:19], off offset:-4
	s_waitcnt vmcnt(8)
	v_perm_b32 v18, v98, v88, s67
	v_perm_b32 v19, v88, v89, s67
	v_perm_b32 v20, v89, v90, s67
	v_perm_b32 v21, v90, v91, s67
	s_add_i32 s22, s11, 19

	s_ashr_i32 s22, s22, 3
	v_mfma_f32_16x16x32_bf16 v[42:45], v[18:21], v[92:95], v[42:45]
	v_mfma_f32_16x16x32_bf16 v[34:37], v[18:21], v[62:65], v[34:37]
	v_mfma_f32_16x16x32_bf16 v[26:29], v[18:21], v[58:61], v[26:29]
	s_waitcnt lgkmcnt(0)
	v_mfma_f32_16x16x32_bf16 v[18:21], v[18:21], v[54:57], v[50:53]
	s_nop 2
	v_add_u32_e32 v50, s22, v124
	v_mfma_f32_16x16x32_bf16 v[46:49], v[46:49], v[84:87], v[68:71]
	v_min_u32_e32 v50, 32, v50
	v_mad_u32_u24 v50, v50, s58, v0
	ds_read_b128 v[50:53], v50 offset:256
	v_mfma_f32_16x16x32_bf16 v[38:41], v[88:91], v[62:65], v[38:41]
	v_mfma_f32_16x16x32_bf16 v[30:33], v[88:91], v[58:61], v[30:33]
	v_mfma_f32_16x16x32_bf16 v[22:25], v[88:91], v[54:57], v[22:25]
	v_mfma_f32_16x16x32_bf16 v[46:49], v[88:91], v[92:95], v[46:49]

; #define CONV_BLOCK(DO0, DO1) do { CONV_STEP(0, DO0, DO1); CONV_STEP(1, DO0, DO1); CONV_STEP(2, DO0, DO1); CONV_STEP(3, DO0, DO1); CONV_STEP(4, DO0, DO1); CONV_STEP(5, DO0, DO1); CONV_STEP(6, DO0, DO1); CONV_STEP(7, DO0, DO1); } while (0)
; template <bool PROMPT, int HALF>
; __device__ __forceinline__ void conv_item(unsigned char* ws, KArgs ka, int ib, int oct, int g, LAS unsigned char* lds, int tid, int lane, int wave) {
;     ...
;     for (int e = E0; e < E1; e += 8) CONV_BLOCK(false, true);
;     { unsigned zz_ = 0u; asm volatile("" : "+v"(zz_));
; #pragma unroll
;       for (int k = 0; k < W; ++k) F0[k] = (u32x4){zz_, zz_, zz_, zz_}; }
;     for (int e = E1; e < E2; e += 8) CONV_BLOCK(true, true);
	s_add_i32 s11, s11, 8
	s_cmp_gt_u32 s11, 0xffffff70
	v_add_u32_e32 v66, 0x100, v66
	s_cbranch_scc0 .LBB0_769
	v_mov_b32_e32 v66, v1
	v_mov_b32_e32 v70, 0
	v_add_u32_e32 v129, 0xffffefa0, v123
	s_movk_i32 s11, 0xff71
	s_movk_i32 s22, 0xde40
	v_mov_b32_e32 v71, v70
	v_mov_b32_e32 v72, v70
	v_mov_b32_e32 v73, v70
	v_mov_b32_e32 v86, v70
	v_mov_b32_e32 v87, v70
	v_mov_b32_e32 v88, v70
	v_mov_b32_e32 v89, v70
	v_mov_b32_e32 v94, v70
	v_mov_b32_e32 v95, v70
	v_mov_b32_e32 v96, v70
	v_mov_b32_e32 v97, v70
	v_mov_b32_e32 v110, v70
	v_mov_b32_e32 v111, v70
	v_mov_b32_e32 v112, v70
	v_mov_b32_e32 v113, v70
	v_mov_b32_e32 v78, v70
	v_mov_b32_e32 v79, v70
	v_mov_b32_e32 v80, v70
	v_mov_b32_e32 v81, v70
	v_mov_b32_e32 v98, v70
	v_mov_b32_e32 v99, v70
	v_mov_b32_e32 v100, v70
	v_mov_b32_e32 v101, v70
	v_mov_b32_e32 v106, v70
	v_mov_b32_e32 v107, v70
	v_mov_b32_e32 v108, v70
	v_mov_b32_e32 v109, v70
	v_mov_b32_e32 v102, v70
	v_mov_b32_e32 v103, v70
	v_mov_b32_e32 v104, v70
	v_mov_b32_e32 v105, v70
	v_mov_b32_e32 v67, v66
	v_mov_b32_e32 v68, v66
	v_mov_b32_e32 v69, v66
	v_mov_b32_e32 v74, v66
	v_mov_b32_e32 v75, v66
	v_mov_b32_e32 v76, v66
	v_mov_b32_e32 v77, v66
	v_mov_b32_e32 v82, v66
	v_mov_b32_e32 v83, v66
	v_mov_b32_e32 v84, v66
	v_mov_b32_e32 v85, v66
	v_mov_b32_e32 v90, v66
	v_mov_b32_e32 v91, v66
	v_mov_b32_e32 v92, v66
	v_mov_b32_e32 v93, v66
.LBB0_771:
	v_min_i32_e32 v114, 0x1ff8, v129
	v_ashrrev_i32_e32 v115, 31, v114
	v_lshl_add_u64 v[118:119], v[114:115], 1, s[18:19]
	global_load_dwordx4 v[114:117], v[118:119], off
	global_load_dword v138, v[118:119], off offset:-4
	s_add_i32 s23, s11, 12
	s_waitcnt vmcnt(8)
	v_perm_b32 v118, v125, v2, s67
	v_perm_b32 v119, v2, v3, s67
	v_perm_b32 v120, v3, v4, s67
	v_perm_b32 v121, v4, v5, s67

	s_ashr_i32 s23, s23, 3
	v_mfma_f32_16x16x32_bf16 v[46:49], v[2:5], v[62:65], v[46:49]
	s_add_i32 s30, s22, 0x100
	s_and_b32 s30, s30, 0x1c0
	v_mfma_f32_16x16x32_bf16 v[42:45], v[118:121], v[62:65], v[42:45]
	v_mfma_f32_16x16x32_bf16 v[62:65], v[2:5], v[82:85], v[106:109]
	s_nop 2
	v_add_u32_e32 v106, s23, v122
	v_min_u32_e32 v106, 32, v106
	v_add_u32_e32 v107, s23, v124
	v_mul_u32_u24_e32 v106, 0x210, v106
	v_min_u32_e32 v107, 32, v107
	v_add3_u32 v106, v0, v106, s30
	v_mul_u32_u24_e32 v107, 0x210, v107
	v_mfma_f32_16x16x32_bf16 v[102:105], v[2:5], v[90:93], v[102:105]
	v_mfma_f32_16x16x32_bf16 v[90:93], v[118:121], v[90:93], v[110:113]
	v_mfma_f32_16x16x32_bf16 v[38:41], v[2:5], v[58:61], v[38:41]
	v_mfma_f32_16x16x32_bf16 v[98:101], v[2:5], v[74:77], v[98:101]
	v_mfma_f32_16x16x32_bf16 v[30:33], v[2:5], v[54:57], v[30:33]
	s_waitcnt lgkmcnt(1)
	v_mfma_f32_16x16x32_bf16 v[78:81], v[2:5], v[66:69], v[78:81]
	s_waitcnt lgkmcnt(0)
	v_mfma_f32_16x16x32_bf16 v[2:5], v[2:5], v[50:53], v[22:25]
	s_nop 2
	v_add3_u32 v22, v0, v107, s30
	ds_read_b128 v[106:109], v106
	ds_read_b128 v[110:113], v22
	v_mfma_f32_16x16x32_bf16 v[94:97], v[118:121], v[82:85], v[94:97]
	v_mfma_f32_16x16x32_bf16 v[34:37], v[118:121], v[58:61], v[34:37]
	v_mfma_f32_16x16x32_bf16 v[86:89], v[118:121], v[74:77], v[86:89]
	v_mfma_f32_16x16x32_bf16 v[26:29], v[118:121], v[54:57], v[26:29]
	v_mfma_f32_16x16x32_bf16 v[70:73], v[118:121], v[66:69], v[70:73]
	v_mfma_f32_16x16x32_bf16 v[22:25], v[118:121], v[50:53], v[18:21]

	s_nop 1
	v_add_u32_e32 v18, 32, v129
	v_min_i32_e32 v18, 0x1ff8, v18
	v_ashrrev_i32_e32 v19, 31, v18
	v_lshl_add_u64 v[118:119], v[18:19], 1, s[18:19]
	global_load_dwordx4 v[18:21], v[118:119], off
	global_load_dword v139, v[118:119], off offset:-4
	s_add_i32 s23, s11, 13
	s_waitcnt vmcnt(8)
	v_perm_b32 v118, v126, v6, s67
	v_perm_b32 v119, v6, v7, s67
	v_perm_b32 v120, v7, v8, s67
	v_perm_b32 v121, v8, v9, s67

	s_ashr_i32 s23, s23, 3
	v_mfma_f32_16x16x32_bf16 v[46:49], v[6:9], v[58:61], v[46:49]
	s_add_i32 s30, s22, 0x140
	s_and_b32 s30, s30, 0x1c0
	v_mfma_f32_16x16x32_bf16 v[42:45], v[118:121], v[58:61], v[42:45]
	v_mfma_f32_16x16x32_bf16 v[58:61], v[6:9], v[74:77], v[62:65]
	v_mfma_f32_16x16x32_bf16 v[62:65], v[118:121], v[74:77], v[94:97]
	s_nop 2
	v_add_u32_e32 v94, s23, v122
	v_min_u32_e32 v94, 32, v94
	v_add_u32_e32 v95, s23, v124
	v_mul_u32_u24_e32 v94, 0x210, v94
	v_min_u32_e32 v95, 32, v95
	v_add3_u32 v94, v0, v94, s30
	v_mul_u32_u24_e32 v95, 0x210, v95
	v_mfma_f32_16x16x32_bf16 v[102:105], v[6:9], v[82:85], v[102:105]
	v_mfma_f32_16x16x32_bf16 v[82:85], v[118:121], v[82:85], v[90:93]
	v_mfma_f32_16x16x32_bf16 v[38:41], v[6:9], v[54:57], v[38:41]
	v_mfma_f32_16x16x32_bf16 v[90:93], v[6:9], v[66:69], v[98:101]
	v_mfma_f32_16x16x32_bf16 v[30:33], v[6:9], v[50:53], v[30:33]
	s_waitcnt lgkmcnt(1)
	v_mfma_f32_16x16x32_bf16 v[78:81], v[6:9], v[106:109], v[78:81]
	s_waitcnt lgkmcnt(0)
	v_mfma_f32_16x16x32_bf16 v[2:5], v[6:9], v[110:113], v[2:5]
	v_add3_u32 v6, v0, v95, s30
	ds_read_b128 v[94:97], v94
	ds_read_b128 v[98:101], v6
	v_mfma_f32_16x16x32_bf16 v[34:37], v[118:121], v[54:57], v[34:37]
	v_mfma_f32_16x16x32_bf16 v[86:89], v[118:121], v[66:69], v[86:89]
	v_mfma_f32_16x16x32_bf16 v[26:29], v[118:121], v[50:53], v[26:29]
	v_mfma_f32_16x16x32_bf16 v[70:73], v[118:121], v[106:109], v[70:73]
	v_mfma_f32_16x16x32_bf16 v[6:9], v[118:121], v[110:113], v[22:25]

	s_nop 1
	v_add_u32_e32 v22, 64, v129
	v_min_i32_e32 v22, 0x1ff8, v22
	v_ashrrev_i32_e32 v23, 31, v22
	v_lshl_add_u64 v[118:119], v[22:23], 1, s[18:19]
	global_load_dwordx4 v[22:25], v[118:119], off
	global_load_dword v140, v[118:119], off offset:-4
	s_add_i32 s23, s11, 14
	s_waitcnt vmcnt(8)
	v_perm_b32 v118, v127, v10, s67
	v_perm_b32 v119, v10, v11, s67
	v_perm_b32 v120, v11, v12, s67
	v_perm_b32 v121, v12, v13, s67

	s_ashr_i32 s23, s23, 3
	v_mfma_f32_16x16x32_bf16 v[102:105], v[10:13], v[74:77], v[102:105]
	s_add_i32 s30, s22, 0x180
	s_and_b32 s30, s30, 0x1c0
	v_mfma_f32_16x16x32_bf16 v[74:77], v[118:121], v[74:77], v[82:85]
	v_mfma_f32_16x16x32_bf16 v[82:85], v[118:121], v[106:109], v[86:89]
	s_nop 2
	v_add_u32_e32 v86, s23, v122
	v_min_u32_e32 v86, 32, v86
	v_add_u32_e32 v87, s23, v124
	v_mul_u32_u24_e32 v86, 0x210, v86
	v_min_u32_e32 v87, 32, v87
	v_add3_u32 v86, v0, v86, s30
	v_mul_u32_u24_e32 v87, 0x210, v87
	v_mfma_f32_16x16x32_bf16 v[46:49], v[10:13], v[54:57], v[46:49]
	v_mfma_f32_16x16x32_bf16 v[42:45], v[118:121], v[54:57], v[42:45]
	v_mfma_f32_16x16x32_bf16 v[54:57], v[10:13], v[66:69], v[58:61]
	v_mfma_f32_16x16x32_bf16 v[58:61], v[118:121], v[66:69], v[62:65]
	v_mfma_f32_16x16x32_bf16 v[38:41], v[10:13], v[50:53], v[38:41]
	v_mfma_f32_16x16x32_bf16 v[62:65], v[10:13], v[106:109], v[90:93]
	v_mfma_f32_16x16x32_bf16 v[30:33], v[10:13], v[110:113], v[30:33]
	s_waitcnt lgkmcnt(1)
	v_mfma_f32_16x16x32_bf16 v[78:81], v[10:13], v[94:97], v[78:81]
	s_waitcnt lgkmcnt(0)
	v_mfma_f32_16x16x32_bf16 v[2:5], v[10:13], v[98:101], v[2:5]
	v_add3_u32 v10, v0, v87, s30
	ds_read_b128 v[86:89], v86
	ds_read_b128 v[130:133], v10
	v_mfma_f32_16x16x32_bf16 v[34:37], v[118:121], v[50:53], v[34:37]
	v_mfma_f32_16x16x32_bf16 v[26:29], v[118:121], v[110:113], v[26:29]
	v_mfma_f32_16x16x32_bf16 v[70:73], v[118:121], v[94:97], v[70:73]
	v_mfma_f32_16x16x32_bf16 v[6:9], v[118:121], v[98:101], v[6:9]

	v_add_u32_e32 v10, 0x60, v129
	v_min_i32_e32 v10, 0x1ff8, v10
	v_ashrrev_i32_e32 v11, 31, v10
	v_lshl_add_u64 v[10:11], v[10:11], 1, s[18:19]
	global_load_dwordx4 v[118:121], v[10:11], off
	global_load_dword v142, v[10:11], off offset:-4
	s_waitcnt vmcnt(8)
	v_perm_b32 v10, v128, v14, s67
	v_perm_b32 v11, v14, v15, s67
	v_perm_b32 v12, v15, v16, s67
	v_perm_b32 v13, v16, v17, s67
	s_add_i32 s23, s11, 15

	s_ashr_i32 s23, s23, 3
	v_mfma_f32_16x16x32_bf16 v[90:93], v[14:17], v[66:69], v[102:105]
	s_add_i32 s30, s22, 0x1c0
	s_and_b32 s30, s30, 0x1c0
	v_mfma_f32_16x16x32_bf16 v[66:69], v[10:13], v[66:69], v[74:77]
	s_nop 2
	v_add_u32_e32 v74, s23, v122
	v_min_u32_e32 v74, 32, v74
	v_mfma_f32_16x16x32_bf16 v[46:49], v[14:17], v[50:53], v[46:49]
	v_mfma_f32_16x16x32_bf16 v[42:45], v[10:13], v[50:53], v[42:45]
	v_mfma_f32_16x16x32_bf16 v[50:53], v[14:17], v[106:109], v[54:57]
	v_mfma_f32_16x16x32_bf16 v[54:57], v[10:13], v[106:109], v[58:61]
	v_mfma_f32_16x16x32_bf16 v[58:61], v[14:17], v[94:97], v[62:65]
	v_mfma_f32_16x16x32_bf16 v[62:65], v[10:13], v[94:97], v[82:85]
	s_nop 2
	v_mul_u32_u24_e32 v82, 0x210, v74
	s_waitcnt lgkmcnt(1)
	v_mfma_f32_16x16x32_bf16 v[74:77], v[14:17], v[86:89], v[78:81]
	s_nop 2
	v_add_u32_e32 v79, s23, v124
	v_min_u32_e32 v79, 32, v79
	v_add3_u32 v78, v0, v82, s30
	v_mul_u32_u24_e32 v79, 0x210, v79
	v_mfma_f32_16x16x32_bf16 v[38:41], v[14:17], v[110:113], v[38:41]
	v_mfma_f32_16x16x32_bf16 v[30:33], v[14:17], v[98:101], v[30:33]
	s_waitcnt lgkmcnt(0)
	v_mfma_f32_16x16x32_bf16 v[14:17], v[14:17], v[130:133], v[2:5]
	s_nop 2
	v_add3_u32 v2, v0, v79, s30
	ds_read_b128 v[78:81], v78
	ds_read_b128 v[134:137], v2
	v_mfma_f32_16x16x32_bf16 v[34:37], v[10:13], v[110:113], v[34:37]
	v_mfma_f32_16x16x32_bf16 v[26:29], v[10:13], v[98:101], v[26:29]
	v_mfma_f32_16x16x32_bf16 v[70:73], v[10:13], v[86:89], v[70:73]
	v_mfma_f32_16x16x32_bf16 v[6:9], v[10:13], v[130:133], v[6:9]

	v_add_u32_e32 v2, 0x80, v129
	v_min_i32_e32 v2, 0x1ff8, v2
	v_ashrrev_i32_e32 v3, 31, v2
	v_lshl_add_u64 v[10:11], v[2:3], 1, s[18:19]
	global_load_dwordx4 v[2:5], v[10:11], off
	global_load_dword v125, v[10:11], off offset:-4
	s_waitcnt vmcnt(8)
	v_perm_b32 v10, v138, v114, s67
	v_perm_b32 v11, v114, v115, s67
	v_perm_b32 v12, v115, v116, s67
	v_perm_b32 v13, v116, v117, s67
	s_add_i32 s23, s11, 16

	s_ashr_i32 s23, s23, 3
	v_mfma_f32_16x16x32_bf16 v[102:105], v[10:13], v[86:89], v[62:65]
	s_and_b32 s30, s22, 0x1c0
	s_nop 1
	v_add_u32_e32 v62, s23, v122
	v_add_u32_e32 v63, s23, v124
	v_min_u32_e32 v62, 32, v62
	v_min_u32_e32 v63, 32, v63
	v_mul_u32_u24_e32 v62, 0x210, v62
	v_mul_u32_u24_e32 v63, 0x210, v63
	v_add3_u32 v62, v0, v62, s30
	v_add3_u32 v63, v0, v63, s30
	v_mfma_f32_16x16x32_bf16 v[82:85], v[114:117], v[106:109], v[90:93]
	s_nop 2
	ds_read_b128 v[90:93], v62
	ds_read_b128 v[62:65], v63
	v_mfma_f32_16x16x32_bf16 v[66:69], v[10:13], v[106:109], v[66:69]
	v_mfma_f32_16x16x32_bf16 v[46:49], v[114:117], v[110:113], v[46:49]
	v_mfma_f32_16x16x32_bf16 v[42:45], v[10:13], v[110:113], v[42:45]
	v_mfma_f32_16x16x32_bf16 v[50:53], v[114:117], v[94:97], v[50:53]
	v_mfma_f32_16x16x32_bf16 v[54:57], v[10:13], v[94:97], v[54:57]
	v_mfma_f32_16x16x32_bf16 v[38:41], v[114:117], v[98:101], v[38:41]
	v_mfma_f32_16x16x32_bf16 v[34:37], v[10:13], v[98:101], v[34:37]
	v_mfma_f32_16x16x32_bf16 v[58:61], v[114:117], v[86:89], v[58:61]
	v_mfma_f32_16x16x32_bf16 v[30:33], v[114:117], v[130:133], v[30:33]
	v_mfma_f32_16x16x32_bf16 v[26:29], v[10:13], v[130:133], v[26:29]
	s_waitcnt lgkmcnt(3)
	v_mfma_f32_16x16x32_bf16 v[74:77], v[114:117], v[78:81], v[74:77]
	v_mfma_f32_16x16x32_bf16 v[70:73], v[10:13], v[78:81], v[70:73]
	s_waitcnt lgkmcnt(2)
	v_mfma_f32_16x16x32_bf16 v[14:17], v[114:117], v[134:137], v[14:17]
	v_mfma_f32_16x16x32_bf16 v[10:13], v[10:13], v[134:137], v[6:9]

	s_nop 1
	v_add_u32_e32 v6, 0xa0, v129
	v_min_i32_e32 v6, 0x1ff8, v6
	v_ashrrev_i32_e32 v7, 31, v6
	v_lshl_add_u64 v[106:107], v[6:7], 1, s[18:19]
	global_load_dwordx4 v[6:9], v[106:107], off
	global_load_dword v126, v[106:107], off offset:-4
	s_waitcnt vmcnt(8)
	v_perm_b32 v106, v139, v18, s67
	v_perm_b32 v107, v18, v19, s67
	v_perm_b32 v108, v19, v20, s67
	v_perm_b32 v109, v20, v21, s67
	s_add_i32 s23, s11, 17

	s_ashr_i32 s23, s23, 3
	v_mfma_f32_16x16x32_bf16 v[110:113], v[18:21], v[94:97], v[82:85]
	s_add_i32 s30, s22, 0x240
	s_and_b32 s30, s30, 0x1c0
	v_mfma_f32_16x16x32_bf16 v[66:69], v[106:109], v[94:97], v[66:69]
	v_mfma_f32_16x16x32_bf16 v[94:97], v[18:21], v[78:81], v[58:61]
	s_nop 2
	v_add_u32_e32 v58, s23, v122
	v_min_u32_e32 v58, 32, v58
	v_add_u32_e32 v59, s23, v124
	v_mul_u32_u24_e32 v58, 0x210, v58
	v_min_u32_e32 v59, 32, v59
	v_add3_u32 v58, v0, v58, s30
	v_mul_u32_u24_e32 v59, 0x210, v59
	v_mfma_f32_16x16x32_bf16 v[46:49], v[18:21], v[98:101], v[46:49]
	v_mfma_f32_16x16x32_bf16 v[50:53], v[18:21], v[86:89], v[50:53]
	v_mfma_f32_16x16x32_bf16 v[38:41], v[18:21], v[130:133], v[38:41]
	v_mfma_f32_16x16x32_bf16 v[30:33], v[18:21], v[134:137], v[30:33]
	s_waitcnt lgkmcnt(1)
	v_mfma_f32_16x16x32_bf16 v[74:77], v[18:21], v[90:93], v[74:77]
	s_waitcnt lgkmcnt(0)
	v_mfma_f32_16x16x32_bf16 v[14:17], v[18:21], v[62:65], v[14:17]
	v_add3_u32 v18, v0, v59, s30
	ds_read_b128 v[82:85], v58
	ds_read_b128 v[58:61], v18
	v_mfma_f32_16x16x32_bf16 v[42:45], v[106:109], v[98:101], v[42:45]
	v_mfma_f32_16x16x32_bf16 v[54:57], v[106:109], v[86:89], v[54:57]
	v_mfma_f32_16x16x32_bf16 v[34:37], v[106:109], v[130:133], v[34:37]
	v_mfma_f32_16x16x32_bf16 v[98:101], v[106:109], v[78:81], v[102:105]
	v_mfma_f32_16x16x32_bf16 v[26:29], v[106:109], v[134:137], v[26:29]
	v_mfma_f32_16x16x32_bf16 v[70:73], v[106:109], v[90:93], v[70:73]
	v_mfma_f32_16x16x32_bf16 v[18:21], v[106:109], v[62:65], v[10:13]

	s_nop 1
	v_add_u32_e32 v10, 0xc0, v129
	v_min_i32_e32 v10, 0x1ff8, v10
	v_ashrrev_i32_e32 v11, 31, v10
	v_lshl_add_u64 v[102:103], v[10:11], 1, s[18:19]
	global_load_dwordx4 v[10:13], v[102:103], off
	global_load_dword v127, v[102:103], off offset:-4
	s_waitcnt vmcnt(8)
	v_perm_b32 v102, v140, v22, s67
	v_perm_b32 v103, v22, v23, s67
	v_perm_b32 v104, v23, v24, s67
	v_perm_b32 v105, v24, v25, s67
	s_add_i32 s23, s11, 18

	s_ashr_i32 s23, s23, 3
	v_mfma_f32_16x16x32_bf16 v[106:109], v[22:25], v[86:89], v[110:113]
	s_add_i32 s30, s22, 0x280
	s_and_b32 s30, s30, 0x1c0
	v_mfma_f32_16x16x32_bf16 v[66:69], v[102:105], v[86:89], v[66:69]
	v_mfma_f32_16x16x32_bf16 v[86:89], v[102:105], v[78:81], v[54:57]
	s_nop 2
	v_add_u32_e32 v54, s23, v122
	v_min_u32_e32 v54, 32, v54
	v_add_u32_e32 v55, s23, v124
	v_mul_u32_u24_e32 v54, 0x210, v54
	v_min_u32_e32 v55, 32, v55
	v_add3_u32 v54, v0, v54, s30
	v_mul_u32_u24_e32 v55, 0x210, v55
	v_mfma_f32_16x16x32_bf16 v[46:49], v[22:25], v[130:133], v[46:49]
	v_mfma_f32_16x16x32_bf16 v[50:53], v[22:25], v[78:81], v[50:53]
	v_mfma_f32_16x16x32_bf16 v[38:41], v[22:25], v[134:137], v[38:41]
	v_mfma_f32_16x16x32_bf16 v[114:117], v[22:25], v[90:93], v[94:97]
	v_mfma_f32_16x16x32_bf16 v[30:33], v[22:25], v[62:65], v[30:33]
	s_waitcnt lgkmcnt(1)
	v_mfma_f32_16x16x32_bf16 v[138:141], v[22:25], v[82:85], v[74:77]
	s_waitcnt lgkmcnt(0)
	v_mfma_f32_16x16x32_bf16 v[22:25], v[22:25], v[58:61], v[14:17]
	s_nop 2
	v_add3_u32 v14, v0, v55, s30
	ds_read_b128 v[74:77], v54
	ds_read_b128 v[54:57], v14
	v_mfma_f32_16x16x32_bf16 v[42:45], v[102:105], v[130:133], v[42:45]
	v_mfma_f32_16x16x32_bf16 v[34:37], v[102:105], v[134:137], v[34:37]
	v_mfma_f32_16x16x32_bf16 v[26:29], v[102:105], v[62:65], v[26:29]
	v_mfma_f32_16x16x32_bf16 v[70:73], v[102:105], v[82:85], v[70:73]
	v_mfma_f32_16x16x32_bf16 v[18:21], v[102:105], v[58:61], v[18:21]
	v_mfma_f32_16x16x32_bf16 v[130:133], v[102:105], v[90:93], v[98:101]

	v_add_u32_e32 v14, 0xe0, v129
	v_min_i32_e32 v14, 0x1ff8, v14
	v_ashrrev_i32_e32 v15, 31, v14
	v_lshl_add_u64 v[94:95], v[14:15], 1, s[18:19]
	global_load_dwordx4 v[14:17], v[94:95], off
	global_load_dword v128, v[94:95], off offset:-4
	s_add_i32 s23, s11, 19
	s_waitcnt vmcnt(8)
	v_perm_b32 v142, v142, v118, s67
	v_perm_b32 v143, v118, v119, s67
	v_perm_b32 v144, v119, v120, s67
	v_perm_b32 v145, v120, v121, s67

	s_ashr_i32 s23, s23, 3
	v_mfma_f32_16x16x32_bf16 v[102:105], v[118:121], v[78:81], v[106:109]
	s_add_i32 s30, s22, 0x2c0
	s_and_b32 s30, s30, 0x1c0
	v_mfma_f32_16x16x32_bf16 v[106:109], v[118:121], v[90:93], v[50:53]
	s_nop 2
	v_add_u32_e32 v50, s23, v122
	v_add_u32_e32 v51, s23, v124
	v_min_u32_e32 v50, 32, v50
	v_min_u32_e32 v51, 32, v51
	v_mul_u32_u24_e32 v50, 0x210, v50
	v_mul_u32_u24_e32 v51, 0x210, v51
	v_add3_u32 v50, v0, v50, s30
	v_add3_u32 v51, v0, v51, s30
	v_mfma_f32_16x16x32_bf16 v[110:113], v[142:145], v[78:81], v[66:69]
	s_nop 2
	ds_read_b128 v[66:69], v50
	ds_read_b128 v[50:53], v51
	v_mfma_f32_16x16x32_bf16 v[46:49], v[118:121], v[134:137], v[46:49]
	v_mfma_f32_16x16x32_bf16 v[42:45], v[142:145], v[134:137], v[42:45]
	v_mfma_f32_16x16x32_bf16 v[94:97], v[142:145], v[90:93], v[86:89]
	v_mfma_f32_16x16x32_bf16 v[38:41], v[118:121], v[62:65], v[38:41]
	v_mfma_f32_16x16x32_bf16 v[34:37], v[142:145], v[62:65], v[34:37]
	v_mfma_f32_16x16x32_bf16 v[98:101], v[118:121], v[82:85], v[114:117]
	v_mfma_f32_16x16x32_bf16 v[86:89], v[142:145], v[82:85], v[130:133]
	v_mfma_f32_16x16x32_bf16 v[30:33], v[118:121], v[58:61], v[30:33]
	v_mfma_f32_16x16x32_bf16 v[26:29], v[142:145], v[58:61], v[26:29]
	s_waitcnt lgkmcnt(3)
	v_mfma_f32_16x16x32_bf16 v[78:81], v[118:121], v[74:77], v[138:141]
	v_mfma_f32_16x16x32_bf16 v[70:73], v[142:145], v[74:77], v[70:73]
	s_waitcnt lgkmcnt(2)
	v_mfma_f32_16x16x32_bf16 v[22:25], v[118:121], v[54:57], v[22:25]
	v_mfma_f32_16x16x32_bf16 v[18:21], v[142:145], v[54:57], v[18:21]

; #define CONV_BLOCK(DO0, DO1) do { CONV_STEP(0, DO0, DO1); CONV_STEP(1, DO0, DO1); CONV_STEP(2, DO0, DO1); CONV_STEP(3, DO0, DO1); CONV_STEP(4, DO0, DO1); CONV_STEP(5, DO0, DO1); CONV_STEP(6, DO0, DO1); CONV_STEP(7, DO0, DO1); } while (0)
; template <bool PROMPT, int HALF>
; __device__ __forceinline__ void conv_item(unsigned char* ws, KArgs ka, int ib, int oct, int g, LAS unsigned char* lds, int tid, int lane, int wave) {
;     ...
;     for (int e = E1; e < E2; e += 8) CONV_BLOCK(true, true);
;     for (int e = E2; e < E3; e += 8) CONV_BLOCK(true, false);
	s_add_i32 s11, s11, 8
	s_addk_i32 s22, 0x200
	s_cmpk_gt_i32 s11, 0x78
	v_add_u32_e32 v129, 0x100, v129
	s_cbranch_scc0 .LBB0_771
	s_waitcnt lgkmcnt(0)
	v_add_u32_e32 v50, 0x1180, v123
	v_add_u32_e32 v51, 17, v122
	s_movk_i32 s11, 0x79
.LBB0_773:
	v_add_u32_e32 v52, 0xffffff20, v50
	v_min_i32_e32 v52, 0x1ff8, v52
	v_ashrrev_i32_e32 v53, 31, v52
	v_lshl_add_u64 v[56:57], v[52:53], 1, s[18:19]
	global_load_dwordx4 v[52:55], v[56:57], off
	global_load_dword v122, v[56:57], off offset:-4
	s_waitcnt vmcnt(8)
	v_perm_b32 v56, v125, v2, s67
	v_perm_b32 v57, v2, v3, s67
	v_perm_b32 v58, v3, v4, s67
	v_perm_b32 v59, v4, v5, s67

	v_add_u32_e32 v64, -1, v51
	v_min_u32_e32 v64, 32, v64
	v_mad_u32_u24 v118, v64, s58, v0
	v_mfma_f32_16x16x32_bf16 v[60:63], v[56:59], v[90:93], v[110:113]
	s_nop 2
	ds_read_b128 v[110:113], v118 offset:320
	v_mfma_f32_16x16x32_bf16 v[106:109], v[2:5], v[82:85], v[106:109]
	v_mfma_f32_16x16x32_bf16 v[94:97], v[56:59], v[82:85], v[94:97]
	v_mfma_f32_16x16x32_bf16 v[98:101], v[2:5], v[74:77], v[98:101]
	v_mfma_f32_16x16x32_bf16 v[86:89], v[56:59], v[74:77], v[86:89]
	s_waitcnt lgkmcnt(1)
	v_mfma_f32_16x16x32_bf16 v[78:81], v[2:5], v[66:69], v[78:81]
	v_mfma_f32_16x16x32_bf16 v[56:59], v[56:59], v[66:69], v[70:73]

	v_add_u32_e32 v64, 0xffffff40, v50
	v_min_i32_e32 v64, 0x1ff8, v64
	v_ashrrev_i32_e32 v65, 31, v64
	v_lshl_add_u64 v[64:65], v[64:65], 1, s[18:19]
	global_load_dwordx4 v[70:73], v[64:65], off
	global_load_dword v123, v[64:65], off offset:-4
	s_waitcnt vmcnt(8)
	v_perm_b32 v114, v126, v6, s67
	v_perm_b32 v115, v6, v7, s67
	v_perm_b32 v116, v7, v8, s67
	v_perm_b32 v117, v8, v9, s67

	s_nop 0
	v_mfma_f32_16x16x32_bf16 v[60:63], v[114:117], v[82:85], v[60:63]
	v_mfma_f32_16x16x32_bf16 v[106:109], v[6:9], v[74:77], v[106:109]
	v_mfma_f32_16x16x32_bf16 v[94:97], v[114:117], v[74:77], v[94:97]
	v_mfma_f32_16x16x32_bf16 v[98:101], v[6:9], v[66:69], v[98:101]
	v_mfma_f32_16x16x32_bf16 v[86:89], v[114:117], v[66:69], v[86:89]
	s_waitcnt lgkmcnt(0)
	v_mfma_f32_16x16x32_bf16 v[78:81], v[6:9], v[110:113], v[78:81]
	v_mfma_f32_16x16x32_bf16 v[56:59], v[114:117], v[110:113], v[56:59]
	ds_read_b128 v[114:117], v118 offset:384
	v_mfma_f32_16x16x32_bf16 v[2:5], v[2:5], v[90:93], v[102:105]

	v_add_u32_e32 v64, 0xffffff60, v50
	v_min_i32_e32 v64, 0x1ff8, v64
	v_ashrrev_i32_e32 v65, 31, v64
	v_lshl_add_u64 v[64:65], v[64:65], 1, s[18:19]
	global_load_dwordx4 v[102:105], v[64:65], off
	global_load_dword v124, v[64:65], off offset:-4
	s_waitcnt vmcnt(8)
	v_perm_b32 v90, v127, v10, s67
	v_perm_b32 v91, v10, v11, s67
	v_perm_b32 v92, v11, v12, s67
	v_perm_b32 v93, v12, v13, s67

	v_mfma_f32_16x16x32_bf16 v[106:109], v[10:13], v[66:69], v[106:109]
	ds_read_b128 v[118:121], v118 offset:448
	v_mfma_f32_16x16x32_bf16 v[94:97], v[90:93], v[66:69], v[94:97]
	v_mfma_f32_16x16x32_bf16 v[98:101], v[10:13], v[110:113], v[98:101]
	v_mfma_f32_16x16x32_bf16 v[86:89], v[90:93], v[110:113], v[86:89]
	s_waitcnt lgkmcnt(1)
	v_mfma_f32_16x16x32_bf16 v[78:81], v[10:13], v[114:117], v[78:81]
	v_mfma_f32_16x16x32_bf16 v[2:5], v[6:9], v[82:85], v[2:5]
	v_mfma_f32_16x16x32_bf16 v[60:63], v[90:93], v[74:77], v[60:63]
	v_mfma_f32_16x16x32_bf16 v[56:59], v[90:93], v[114:117], v[56:59]

	v_add_u32_e32 v6, 0xffffff80, v50
	v_min_i32_e32 v6, 0x1ff8, v6
	v_ashrrev_i32_e32 v7, 31, v6
	v_lshl_add_u64 v[6:7], v[6:7], 1, s[18:19]
	global_load_dwordx4 v[130:133], v[6:7], off
	global_load_dword v129, v[6:7], off offset:-4
	s_waitcnt vmcnt(8)
	v_perm_b32 v6, v128, v14, s67
	v_perm_b32 v7, v14, v15, s67
	v_perm_b32 v8, v15, v16, s67
	v_perm_b32 v9, v16, v17, s67

	s_nop 0
	v_mfma_f32_16x16x32_bf16 v[60:63], v[6:9], v[66:69], v[60:63]
	v_mfma_f32_16x16x32_bf16 v[90:93], v[6:9], v[110:113], v[94:97]
	v_mfma_f32_16x16x32_bf16 v[86:89], v[6:9], v[114:117], v[86:89]
	s_waitcnt lgkmcnt(0)
	v_mfma_f32_16x16x32_bf16 v[6:9], v[6:9], v[118:121], v[56:59]
	s_nop 2
	v_min_u32_e32 v56, 32, v51
	v_mad_u32_u24 v142, v56, s58, v0
	v_mfma_f32_16x16x32_bf16 v[82:85], v[14:17], v[110:113], v[106:109]
	ds_read_b128 v[56:59], v142
	v_mfma_f32_16x16x32_bf16 v[94:97], v[14:17], v[114:117], v[98:101]
	v_mfma_f32_16x16x32_bf16 v[78:81], v[14:17], v[118:121], v[78:81]
	v_mfma_f32_16x16x32_bf16 v[10:13], v[10:13], v[74:77], v[2:5]

	s_nop 1
	v_add_u32_e32 v2, 0xffffffa0, v50
	v_min_i32_e32 v2, 0x1ff8, v2
	v_ashrrev_i32_e32 v3, 31, v2
	v_lshl_add_u64 v[64:65], v[2:3], 1, s[18:19]
	global_load_dwordx4 v[2:5], v[64:65], off
	global_load_dword v125, v[64:65], off offset:-4
	s_waitcnt vmcnt(8)
	v_perm_b32 v74, v122, v52, s67
	v_perm_b32 v75, v52, v53, s67
	v_perm_b32 v76, v53, v54, s67
	v_perm_b32 v77, v54, v55, s67

	s_nop 0
	v_mfma_f32_16x16x32_bf16 v[98:101], v[74:77], v[114:117], v[90:93]
	s_nop 2
	ds_read_b128 v[90:93], v142 offset:64
	v_mfma_f32_16x16x32_bf16 v[60:63], v[74:77], v[110:113], v[60:63]
	v_mfma_f32_16x16x32_bf16 v[82:85], v[52:55], v[114:117], v[82:85]
	v_mfma_f32_16x16x32_bf16 v[94:97], v[52:55], v[118:121], v[94:97]
	v_mfma_f32_16x16x32_bf16 v[86:89], v[74:77], v[118:121], v[86:89]
	s_waitcnt lgkmcnt(1)
	v_mfma_f32_16x16x32_bf16 v[78:81], v[52:55], v[56:59], v[78:81]
	v_mfma_f32_16x16x32_bf16 v[74:77], v[74:77], v[56:59], v[6:9]
	v_mfma_f32_16x16x32_bf16 v[10:13], v[14:17], v[66:69], v[10:13]

	s_nop 0
	v_subrev_u32_e32 v6, 64, v50
	v_min_i32_e32 v6, 0x1ff8, v6
	v_ashrrev_i32_e32 v7, 31, v6
	v_lshl_add_u64 v[14:15], v[6:7], 1, s[18:19]
	global_load_dwordx4 v[6:9], v[14:15], off
	global_load_dword v126, v[14:15], off offset:-4
	s_waitcnt vmcnt(8)
	v_perm_b32 v14, v123, v70, s67
	v_perm_b32 v15, v70, v71, s67
	v_perm_b32 v16, v71, v72, s67
	v_perm_b32 v17, v72, v73, s67

	v_mfma_f32_16x16x32_bf16 v[64:67], v[70:73], v[118:121], v[82:85]
	s_nop 2
	ds_read_b128 v[82:85], v142 offset:128
	v_mfma_f32_16x16x32_bf16 v[60:63], v[14:17], v[114:117], v[60:63]
	v_mfma_f32_16x16x32_bf16 v[98:101], v[14:17], v[118:121], v[98:101]
	v_mfma_f32_16x16x32_bf16 v[94:97], v[70:73], v[56:59], v[94:97]
	v_mfma_f32_16x16x32_bf16 v[86:89], v[14:17], v[56:59], v[86:89]
	s_waitcnt lgkmcnt(1)
	v_mfma_f32_16x16x32_bf16 v[78:81], v[70:73], v[90:93], v[78:81]
	v_mfma_f32_16x16x32_bf16 v[14:17], v[14:17], v[90:93], v[74:77]
	v_mfma_f32_16x16x32_bf16 v[52:55], v[52:55], v[110:113], v[10:13]

	s_nop 1
	v_subrev_u32_e32 v10, 32, v50
	v_min_i32_e32 v10, 0x1ff8, v10
	v_ashrrev_i32_e32 v11, 31, v10
	v_lshl_add_u64 v[68:69], v[10:11], 1, s[18:19]
	global_load_dwordx4 v[10:13], v[68:69], off
	global_load_dword v127, v[68:69], off offset:-4
	s_waitcnt vmcnt(8)
	v_perm_b32 v74, v124, v102, s67
	v_perm_b32 v75, v102, v103, s67
	v_perm_b32 v76, v103, v104, s67
	v_perm_b32 v77, v104, v105, s67

	s_nop 0
	v_mfma_f32_16x16x32_bf16 v[60:63], v[74:77], v[118:121], v[60:63]
	v_mfma_f32_16x16x32_bf16 v[98:101], v[74:77], v[56:59], v[98:101]
	v_mfma_f32_16x16x32_bf16 v[86:89], v[74:77], v[90:93], v[86:89]
	s_waitcnt lgkmcnt(0)
	v_mfma_f32_16x16x32_bf16 v[138:141], v[74:77], v[82:85], v[14:17]
	ds_read_b128 v[74:77], v142 offset:192
	v_mfma_f32_16x16x32_bf16 v[64:67], v[102:105], v[56:59], v[64:67]
	v_mfma_f32_16x16x32_bf16 v[78:81], v[102:105], v[82:85], v[78:81]
	v_mfma_f32_16x16x32_bf16 v[134:137], v[102:105], v[90:93], v[94:97]
	v_mfma_f32_16x16x32_bf16 v[52:55], v[70:73], v[114:117], v[52:55]

	v_min_i32_e32 v14, 0x1ff8, v50
	v_ashrrev_i32_e32 v15, 31, v14
	v_lshl_add_u64 v[68:69], v[14:15], 1, s[18:19]
	global_load_dwordx4 v[14:17], v[68:69], off
	global_load_dword v128, v[68:69], off offset:-4
	s_waitcnt vmcnt(8)
	v_perm_b32 v68, v129, v130, s67
	v_perm_b32 v69, v130, v131, s67
	v_perm_b32 v70, v131, v132, s67
	v_perm_b32 v71, v132, v133, s67

	v_mfma_f32_16x16x32_bf16 v[52:55], v[102:105], v[118:121], v[52:55]
	v_mfma_f32_16x16x32_bf16 v[110:113], v[68:71], v[56:59], v[60:63]
	v_mfma_f32_16x16x32_bf16 v[106:109], v[130:133], v[90:93], v[64:67]
	v_mfma_f32_16x16x32_bf16 v[94:97], v[68:71], v[90:93], v[98:101]
	v_mfma_f32_16x16x32_bf16 v[86:89], v[68:71], v[82:85], v[86:89]
	s_waitcnt lgkmcnt(0)
	v_mfma_f32_16x16x32_bf16 v[70:73], v[68:71], v[74:77], v[138:141]
	ds_read_b128 v[66:69], v142 offset:256
	v_mfma_f32_16x16x32_bf16 v[98:101], v[130:133], v[82:85], v[134:137]
	v_mfma_f32_16x16x32_bf16 v[78:81], v[130:133], v[74:77], v[78:81]
	v_mfma_f32_16x16x32_bf16 v[102:105], v[130:133], v[56:59], v[52:55]

; #define CONV_BLOCK(DO0, DO1) do { CONV_STEP(0, DO0, DO1); CONV_STEP(1, DO0, DO1); CONV_STEP(2, DO0, DO1); CONV_STEP(3, DO0, DO1); CONV_STEP(4, DO0, DO1); CONV_STEP(5, DO0, DO1); CONV_STEP(6, DO0, DO1); CONV_STEP(7, DO0, DO1); } while (0)
; template <bool PROMPT, int HALF>
; __device__ __forceinline__ void conv_item(unsigned char* ws, KArgs ka, int ib, int oct, int g, LAS unsigned char* lds, int tid, int lane, int wave) {
;     ...
;     for (int e = E0; e < E1; e += 8) CONV_BLOCK(false, true);
;     { unsigned zz_ = 0u; asm volatile("" : "+v"(zz_));
; #pragma unroll
;       for (int k = 0; k < W; ++k) F0[k] = (u32x4){zz_, zz_, zz_, zz_}; }
;     for (int e = E1; e < E2; e += 8) CONV_BLOCK(true, true);
;     for (int e = E2; e < E3; e += 8) CONV_BLOCK(true, false);
;     ...
;     __syncthreads();
;     int lane2; { unsigned ones_ = ~0u; asm volatile("" : "+s"(ones_)); lane2 = (int)__builtin_amdgcn_mbcnt_hi(ones_, __builtin_amdgcn_mbcnt_lo(ones_, 0u)); }
;     const int nn2 = lane2 & 15, kq2 = lane2 >> 4;
;     float nsum = 0.f;
;     { const float* kq_ = (const float*)(ws + WS_KPART) + ((size_t)ib * 320 + (PROMPT ? 0 : 256)) * 2048; constexpr int ntile = PROMPT ? 256 : 64;
;       for (int q = lane2; q < ntile; q += 64) nsum += kq_[(size_t)q * 2048 + c] + kq_[(size_t)q * 2048 + 1024 + c];
	s_add_i32 s11, s11, 8
	v_add_u32_e32 v50, 0x100, v50
	s_cmpk_gt_u32 s11, 0xf8
	v_add_u32_e32 v51, 1, v51
	s_cbranch_scc0 .LBB0_773
	s_mov_b32 s11, -1
	s_waitcnt lgkmcnt(0)
	s_barrier
	s_nop 0
	v_mbcnt_lo_u32_b32 v0, s11, 0
	s_waitcnt vmcnt(3)
	v_mbcnt_hi_u32_b32 v12, s11, v0
	s_movk_i32 s11, 0x100
	v_cmp_gt_i32_e32 vcc, s11, v12
	v_mov_b32_e32 v0, 0
	s_and_saveexec_b64 s[18:19], vcc
	s_cbranch_execz .LBB0_778
	s_ashr_i32 s43, s42, 31
	s_lshl_b64 s[22:23], s[42:43], 2
	s_add_u32 s22, s51, s22
	v_lshlrev_b32_e32 v0, 13, v12
	s_addc_u32 s23, s52, s23
	v_subrev_u32_e32 v4, 64, v12
	v_lshl_add_u64 v[2:3], s[22:23], 0, v[0:1]
	v_mov_b32_e32 v0, 0
	s_mov_b64 s[22:23], 0

; #define PG8_STAGE(bufoff, gbase, voff) do { _Pragma("unroll") for (int _i = 0; _i < 2; ++_i) \
;         __builtin_amdgcn_global_load_lds((const unsigned*)((const char*)(gbase) + (voff)[_i]), (LAS unsigned*)(lds + (bufoff) + ldsw + _i * 8192), 16, 0, 0); } while (0)
; #define PG8_LDA(dst, b, h) do { _Pragma("unroll") for (int m = 0; m < 4; ++m) _Pragma("unroll") for (int k = 0; k < 2; ++k) dst[m][k] = *(const LAS bf16x8*)(lds + PG8_SA(b, h) + aoff + m * 2048 + k * 1024); } while (0)
; #define PG8_LDB(dst, b, h) do { _Pragma("unroll") for (int n = 0; n < 2; ++n) _Pragma("unroll") for (int k = 0; k < 2; ++k) dst[n][k] = *(const LAS bf16x8*)(lds + PG8_SB(b, h) + boff + n * 2048 + k * 1024); } while (0)
; #define PG8_MMA(ai, bj, At, Bt) do { __builtin_amdgcn_s_setprio(1); _Pragma("unroll") for (int m = 0; m < 4; ++m) _Pragma("unroll") for (int n = 0; n < 2; ++n) _Pragma("unroll") for (int k = 0; k < 2; ++k) \
;         acc[ai][bj][m][n] = __builtin_amdgcn_mfma_f32_16x16x32_bf16(Bt[n][k], At[m][k], acc[ai][bj][m][n], 0, 0, 0); __builtin_amdgcn_s_setprio(0); } while (0)
; #define PG8_WAIT_V(n) asm volatile("s_waitcnt vmcnt(" #n ")" ::: "memory")
; #define PG8_WAIT_L(n) asm volatile("s_waitcnt lgkmcnt(" #n ")" ::: "memory")
; #define PG8_BAR __builtin_amdgcn_s_barrier()
; #define PG8_SCHED __builtin_amdgcn_sched_barrier(0)
; template <class Epi, bool ALIGN_EPI>
; __device__ __forceinline__ void gemm_phase(LAS unsigned char* lds, const Gemm g, const StaticOrder& S, const Epi& E, const int tid) {
;     ...
;         for (int t = 0; t < nt; t += 2) {
;             const bool last = (t == nt - 2);
;             const char* a1 = cA + (size_t)(t + 1) * kstepA;
;             const char* a2 = last ? nA : cA + (size_t)(t + 2) * kstepA; const char* b2 = last ? nB : cB + (size_t)(t + 2) * kstepB;
;             const char* a3 = a2 + kstepA; const char* b3 = b2 + kstepB;
;             PG8_LDB(B0, 0, 0); PG8_LDB(B1, 0, 1); PG8_SCHED; PG8_LDA(At, 0, 0); PG8_STAGE(PG8_SA(1, 1), a1 + hstepA, voffA);
;             PG8_WAIT_V(8); PG8_WAIT_L(0); PG8_BAR; PG8_MMA(0, 0, At, B0); PG8_MMA(0, 1, At, B1); PG8_BAR; PG8_SCHED;
.LBB0_847:
	s_add_u32 s22, s10, 0xfff80080
	s_addc_u32 s23, s11, -1
	s_add_i32 s87, 0, 0x10000
	s_cmp_eq_u32 s86, 28
	s_cselect_b32 s35, s49, s23
	s_cselect_b32 s34, s82, s22
	v_add_u32_e32 v0, s87, v154
	s_cselect_b32 s23, s47, s85
	s_cselect_b32 s22, s83, s84
	s_add_i32 s90, 0, 0x14000
	s_waitcnt lgkmcnt(0)
	ds_read_b128 v[132:135], v0
	ds_read_b128 v[148:151], v0 offset:1024
	ds_read_b128 v[156:159], v0 offset:2048
	ds_read_b128 v[160:163], v0 offset:3072
	v_add_u32_e32 v0, s90, v154
	ds_read_b128 v[164:167], v0
	ds_read_b128 v[168:171], v0 offset:1024
	ds_read_b128 v[172:175], v0 offset:2048
	ds_read_b128 v[176:179], v0 offset:3072
	s_add_i32 m0, s70, 0xc000
	ds_read_b128 v[180:183], v155
	ds_read_b128 v[184:187], v155 offset:1024
	ds_read_b128 v[188:191], v155 offset:2048
	ds_read_b128 v[192:195], v155 offset:3072
	ds_read_b128 v[196:199], v155 offset:4096
	ds_read_b128 v[214:217], v155 offset:5120
	ds_read_b128 v[218:221], v155 offset:6144
	ds_read_b128 v[222:225], v155 offset:7168
	global_load_lds_dwordx4 v144, s[10:11]
	s_add_i32 m0, s70, 0xe000
	s_nop 0
	global_load_lds_dwordx4 v146, s[10:11]
	s_waitcnt vmcnt(8)
	s_waitcnt lgkmcnt(0)
	s_barrier


; #define PG8_MMA(ai, bj, At, Bt) do { __builtin_amdgcn_s_setprio(1); _Pragma("unroll") for (int m = 0; m < 4; ++m) _Pragma("unroll") for (int n = 0; n < 2; ++n) _Pragma("unroll") for (int k = 0; k < 2; ++k) \
;         acc[ai][bj][m][n] = __builtin_amdgcn_mfma_f32_16x16x32_bf16(Bt[n][k], At[m][k], acc[ai][bj][m][n], 0, 0, 0); __builtin_amdgcn_s_setprio(0); } while (0)
; #define PG8_WAIT_V(n) asm volatile("s_waitcnt vmcnt(" #n ")" ::: "memory")
; #define PG8_WAIT_L(n) asm volatile("s_waitcnt lgkmcnt(" #n ")" ::: "memory")
; #define PG8_BAR __builtin_amdgcn_s_barrier()
; #define PG8_SCHED __builtin_amdgcn_sched_barrier(0)
; template <class Epi, bool ALIGN_EPI>
; __device__ __forceinline__ void gemm_phase(LAS unsigned char* lds, const Gemm g, const StaticOrder& S, const Epi& E, const int tid) {
;     ...
;             PG8_WAIT_V(8); PG8_WAIT_L(0); PG8_BAR; PG8_MMA(0, 0, At, B0); PG8_MMA(0, 1, At, B1); PG8_BAR; PG8_SCHED;
	v_mfma_f32_16x16x32_bf16 v[8:11], v[132:135], v[180:183], v[8:11]
	v_mfma_f32_16x16x32_bf16 v[56:59], v[156:159], v[180:183], v[56:59]
	v_mfma_f32_16x16x32_bf16 v[52:55], v[132:135], v[188:191], v[52:55]
	v_mfma_f32_16x16x32_bf16 v[48:51], v[156:159], v[188:191], v[48:51]
	v_mfma_f32_16x16x32_bf16 v[44:47], v[132:135], v[196:199], v[44:47]
	v_mfma_f32_16x16x32_bf16 v[40:43], v[156:159], v[196:199], v[40:43]
	v_mfma_f32_16x16x32_bf16 v[36:39], v[132:135], v[218:221], v[36:39]
	v_mfma_f32_16x16x32_bf16 v[32:35], v[156:159], v[218:221], v[32:35]
	v_mfma_f32_16x16x32_bf16 v[8:11], v[148:151], v[184:187], v[8:11]
	v_mfma_f32_16x16x32_bf16 v[56:59], v[160:163], v[184:187], v[56:59]
	v_mfma_f32_16x16x32_bf16 v[52:55], v[148:151], v[192:195], v[52:55]
	v_mfma_f32_16x16x32_bf16 v[48:51], v[160:163], v[192:195], v[48:51]
	v_mfma_f32_16x16x32_bf16 v[44:47], v[148:151], v[214:217], v[44:47]
	v_mfma_f32_16x16x32_bf16 v[40:43], v[160:163], v[214:217], v[40:43]
	v_mfma_f32_16x16x32_bf16 v[36:39], v[148:151], v[222:225], v[36:39]
	v_mfma_f32_16x16x32_bf16 v[32:35], v[160:163], v[222:225], v[32:35]


; #define PG8_MMA(ai, bj, At, Bt) do { __builtin_amdgcn_s_setprio(1); _Pragma("unroll") for (int m = 0; m < 4; ++m) _Pragma("unroll") for (int n = 0; n < 2; ++n) _Pragma("unroll") for (int k = 0; k < 2; ++k) \
;         acc[ai][bj][m][n] = __builtin_amdgcn_mfma_f32_16x16x32_bf16(Bt[n][k], At[m][k], acc[ai][bj][m][n], 0, 0, 0); __builtin_amdgcn_s_setprio(0); } while (0)
; #define PG8_WAIT_V(n) asm volatile("s_waitcnt vmcnt(" #n ")" ::: "memory")
; #define PG8_WAIT_L(n) asm volatile("s_waitcnt lgkmcnt(" #n ")" ::: "memory")
; #define PG8_BAR __builtin_amdgcn_s_barrier()
; #define PG8_SCHED __builtin_amdgcn_sched_barrier(0)
; template <class Epi, bool ALIGN_EPI>
; __device__ __forceinline__ void gemm_phase(LAS unsigned char* lds, const Gemm g, const StaticOrder& S, const Epi& E, const int tid) {
;     ...
;             PG8_WAIT_V(8); PG8_WAIT_L(0); PG8_BAR; PG8_MMA(0, 0, At, B0); PG8_MMA(0, 1, At, B1); PG8_BAR; PG8_SCHED;
	v_mfma_f32_16x16x32_bf16 v[2:5], v[164:167], v[180:183], v[4:7]
	v_mfma_f32_16x16x32_bf16 v[28:31], v[172:175], v[180:183], v[28:31]
	v_mfma_f32_16x16x32_bf16 v[96:99], v[164:167], v[188:191], v[96:99]
	v_mfma_f32_16x16x32_bf16 v[92:95], v[172:175], v[188:191], v[92:95]
	v_mfma_f32_16x16x32_bf16 v[88:91], v[164:167], v[196:199], v[88:91]
	v_mfma_f32_16x16x32_bf16 v[84:87], v[172:175], v[196:199], v[84:87]
	v_mfma_f32_16x16x32_bf16 v[80:83], v[164:167], v[218:221], v[80:83]
	v_mfma_f32_16x16x32_bf16 v[76:79], v[172:175], v[218:221], v[76:79]
	v_mfma_f32_16x16x32_bf16 v[2:5], v[168:171], v[184:187], v[2:5]
	v_mfma_f32_16x16x32_bf16 v[28:31], v[176:179], v[184:187], v[28:31]
	v_mfma_f32_16x16x32_bf16 v[96:99], v[168:171], v[192:195], v[96:99]
	v_mfma_f32_16x16x32_bf16 v[92:95], v[176:179], v[192:195], v[92:95]
	v_mfma_f32_16x16x32_bf16 v[88:91], v[168:171], v[214:217], v[88:91]
	v_mfma_f32_16x16x32_bf16 v[84:87], v[176:179], v[214:217], v[84:87]
	v_mfma_f32_16x16x32_bf16 v[80:83], v[168:171], v[222:225], v[80:83]
	v_mfma_f32_16x16x32_bf16 v[76:79], v[176:179], v[222:225], v[76:79]

; #define PG8_STAGE(bufoff, gbase, voff) do { _Pragma("unroll") for (int _i = 0; _i < 2; ++_i) \
;         __builtin_amdgcn_global_load_lds((const unsigned*)((const char*)(gbase) + (voff)[_i]), (LAS unsigned*)(lds + (bufoff) + ldsw + _i * 8192), 16, 0, 0); } while (0)
; #define PG8_LDA(dst, b, h) do { _Pragma("unroll") for (int m = 0; m < 4; ++m) _Pragma("unroll") for (int k = 0; k < 2; ++k) dst[m][k] = *(const LAS bf16x8*)(lds + PG8_SA(b, h) + aoff + m * 2048 + k * 1024); } while (0)
; #define PG8_MMA(ai, bj, At, Bt) do { __builtin_amdgcn_s_setprio(1); _Pragma("unroll") for (int m = 0; m < 4; ++m) _Pragma("unroll") for (int n = 0; n < 2; ++n) _Pragma("unroll") for (int k = 0; k < 2; ++k) \
;         acc[ai][bj][m][n] = __builtin_amdgcn_mfma_f32_16x16x32_bf16(Bt[n][k], At[m][k], acc[ai][bj][m][n], 0, 0, 0); __builtin_amdgcn_s_setprio(0); } while (0)
; #define PG8_WAIT_V(n) asm volatile("s_waitcnt vmcnt(" #n ")" ::: "memory")
; #define PG8_WAIT_L(n) asm volatile("s_waitcnt lgkmcnt(" #n ")" ::: "memory")
; #define PG8_BAR __builtin_amdgcn_s_barrier()
; #define PG8_SCHED __builtin_amdgcn_sched_barrier(0)
; template <class Epi, bool ALIGN_EPI>
; __device__ __forceinline__ void gemm_phase(LAS unsigned char* lds, const Gemm g, const StaticOrder& S, const Epi& E, const int tid) {
;     ...
;             PG8_WAIT_V(8); PG8_WAIT_L(0); PG8_BAR; PG8_MMA(0, 0, At, B0); PG8_MMA(0, 1, At, B1); PG8_BAR; PG8_SCHED;
;             PG8_LDA(At, 0, 1); PG8_STAGE(PG8_SB(0, 0), b2, voffB); PG8_STAGE(PG8_SB(0, 1), b2 + hstepB, voffB); PG8_STAGE(PG8_SA(0, 0), a2, voffA);
;             PG8_WAIT_V(8); PG8_WAIT_L(0); PG8_BAR; PG8_MMA(1, 0, At, B0); PG8_MMA(1, 1, At, B1); PG8_BAR; PG8_SCHED;
	s_barrier
	s_add_i32 s87, s87, s61
	s_mov_b32 m0, s87
	ds_read_b128 v[180:183], v155 offset:16384
	ds_read_b128 v[184:187], v155 offset:17408
	ds_read_b128 v[188:191], v155 offset:18432
	ds_read_b128 v[192:195], v155 offset:19456
	ds_read_b128 v[196:199], v155 offset:20480
	ds_read_b128 v[214:217], v155 offset:21504
	ds_read_b128 v[218:221], v155 offset:22528
	ds_read_b128 v[222:225], v155 offset:23552
	global_load_lds_dwordx4 v140, s[22:23]
	s_add_i32 m0, s87, 0x2000
	s_add_u32 s88, s22, 0x4000
	s_addc_u32 s89, s23, 0
	s_add_i32 s87, s90, s61
	global_load_lds_dwordx4 v136, s[22:23]
	s_mov_b32 m0, s87
	v_lshl_add_u64 v[152:153], s[34:35], 0, v[142:143]
	global_load_lds_dwordx4 v140, s[88:89]
	s_add_i32 m0, s87, 0x2000
	v_lshl_add_u64 v[200:201], s[34:35], 0, v[138:139]
	global_load_lds_dwordx4 v136, s[88:89]
	s_mov_b32 m0, s70
	s_nop 0
	global_load_lds_dwordx4 v[152:153], off
	s_mov_b32 m0, s71
	s_nop 0
	global_load_lds_dwordx4 v[200:201], off
	s_waitcnt vmcnt(8)
	s_waitcnt lgkmcnt(0)
	s_barrier


; #define PG8_MMA(ai, bj, At, Bt) do { __builtin_amdgcn_s_setprio(1); _Pragma("unroll") for (int m = 0; m < 4; ++m) _Pragma("unroll") for (int n = 0; n < 2; ++n) _Pragma("unroll") for (int k = 0; k < 2; ++k) \
;         acc[ai][bj][m][n] = __builtin_amdgcn_mfma_f32_16x16x32_bf16(Bt[n][k], At[m][k], acc[ai][bj][m][n], 0, 0, 0); __builtin_amdgcn_s_setprio(0); } while (0)
; #define PG8_WAIT_V(n) asm volatile("s_waitcnt vmcnt(" #n ")" ::: "memory")
; #define PG8_WAIT_L(n) asm volatile("s_waitcnt lgkmcnt(" #n ")" ::: "memory")
; #define PG8_BAR __builtin_amdgcn_s_barrier()
; #define PG8_SCHED __builtin_amdgcn_sched_barrier(0)
; template <class Epi, bool ALIGN_EPI>
; __device__ __forceinline__ void gemm_phase(LAS unsigned char* lds, const Gemm g, const StaticOrder& S, const Epi& E, const int tid) {
;     ...
;             PG8_WAIT_V(8); PG8_WAIT_L(0); PG8_BAR; PG8_MMA(1, 0, At, B0); PG8_MMA(1, 1, At, B1); PG8_BAR; PG8_SCHED;
	v_mfma_f32_16x16x32_bf16 v[24:27], v[132:135], v[180:183], v[24:27]
	v_mfma_f32_16x16x32_bf16 v[20:23], v[156:159], v[180:183], v[20:23]
	v_mfma_f32_16x16x32_bf16 v[64:67], v[132:135], v[188:191], v[64:67]
	v_mfma_f32_16x16x32_bf16 v[72:75], v[156:159], v[188:191], v[72:75]
	v_mfma_f32_16x16x32_bf16 v[16:19], v[132:135], v[196:199], v[16:19]
	v_mfma_f32_16x16x32_bf16 v[12:15], v[156:159], v[196:199], v[12:15]
	v_mfma_f32_16x16x32_bf16 v[60:63], v[132:135], v[218:221], v[60:63]
	v_mfma_f32_16x16x32_bf16 v[68:71], v[156:159], v[218:221], v[68:71]
	v_mfma_f32_16x16x32_bf16 v[24:27], v[148:151], v[184:187], v[24:27]
	v_mfma_f32_16x16x32_bf16 v[20:23], v[160:163], v[184:187], v[20:23]
	v_mfma_f32_16x16x32_bf16 v[64:67], v[148:151], v[192:195], v[64:67]
	v_mfma_f32_16x16x32_bf16 v[72:75], v[160:163], v[192:195], v[72:75]
	v_mfma_f32_16x16x32_bf16 v[16:19], v[148:151], v[214:217], v[16:19]
	v_mfma_f32_16x16x32_bf16 v[12:15], v[160:163], v[214:217], v[12:15]
	v_mfma_f32_16x16x32_bf16 v[60:63], v[148:151], v[222:225], v[60:63]
	v_mfma_f32_16x16x32_bf16 v[68:71], v[160:163], v[222:225], v[68:71]


; #define PG8_MMA(ai, bj, At, Bt) do { __builtin_amdgcn_s_setprio(1); _Pragma("unroll") for (int m = 0; m < 4; ++m) _Pragma("unroll") for (int n = 0; n < 2; ++n) _Pragma("unroll") for (int k = 0; k < 2; ++k) \
;         acc[ai][bj][m][n] = __builtin_amdgcn_mfma_f32_16x16x32_bf16(Bt[n][k], At[m][k], acc[ai][bj][m][n], 0, 0, 0); __builtin_amdgcn_s_setprio(0); } while (0)
; #define PG8_WAIT_V(n) asm volatile("s_waitcnt vmcnt(" #n ")" ::: "memory")
; #define PG8_WAIT_L(n) asm volatile("s_waitcnt lgkmcnt(" #n ")" ::: "memory")
; #define PG8_BAR __builtin_amdgcn_s_barrier()
; #define PG8_SCHED __builtin_amdgcn_sched_barrier(0)
; template <class Epi, bool ALIGN_EPI>
; __device__ __forceinline__ void gemm_phase(LAS unsigned char* lds, const Gemm g, const StaticOrder& S, const Epi& E, const int tid) {
;     ...
;             PG8_WAIT_V(8); PG8_WAIT_L(0); PG8_BAR; PG8_MMA(1, 0, At, B0); PG8_MMA(1, 1, At, B1); PG8_BAR; PG8_SCHED;
	v_mfma_f32_16x16x32_bf16 v[128:131], v[164:167], v[180:183], v[128:131]
	v_mfma_f32_16x16x32_bf16 v[124:127], v[172:175], v[180:183], v[124:127]
	v_mfma_f32_16x16x32_bf16 v[120:123], v[164:167], v[188:191], v[120:123]
	v_mfma_f32_16x16x32_bf16 v[116:119], v[172:175], v[188:191], v[116:119]
	v_mfma_f32_16x16x32_bf16 v[112:115], v[164:167], v[196:199], v[112:115]
	v_mfma_f32_16x16x32_bf16 v[108:111], v[172:175], v[196:199], v[108:111]
	v_mfma_f32_16x16x32_bf16 v[104:107], v[164:167], v[218:221], v[104:107]
	v_mfma_f32_16x16x32_bf16 v[100:103], v[172:175], v[218:221], v[100:103]
	v_mfma_f32_16x16x32_bf16 v[128:131], v[168:171], v[184:187], v[128:131]
	v_mfma_f32_16x16x32_bf16 v[124:127], v[176:179], v[184:187], v[124:127]
	v_mfma_f32_16x16x32_bf16 v[120:123], v[168:171], v[192:195], v[120:123]
	v_mfma_f32_16x16x32_bf16 v[116:119], v[176:179], v[192:195], v[116:119]
	v_mfma_f32_16x16x32_bf16 v[112:115], v[168:171], v[214:217], v[112:115]
	v_mfma_f32_16x16x32_bf16 v[108:111], v[176:179], v[214:217], v[108:111]
	v_mfma_f32_16x16x32_bf16 v[104:107], v[168:171], v[222:225], v[104:107]
	v_mfma_f32_16x16x32_bf16 v[100:103], v[176:179], v[222:225], v[100:103]

; #define PG8_STAGE(bufoff, gbase, voff) do { _Pragma("unroll") for (int _i = 0; _i < 2; ++_i) \
;         __builtin_amdgcn_global_load_lds((const unsigned*)((const char*)(gbase) + (voff)[_i]), (LAS unsigned*)(lds + (bufoff) + ldsw + _i * 8192), 16, 0, 0); } while (0)
; #define PG8_LDA(dst, b, h) do { _Pragma("unroll") for (int m = 0; m < 4; ++m) _Pragma("unroll") for (int k = 0; k < 2; ++k) dst[m][k] = *(const LAS bf16x8*)(lds + PG8_SA(b, h) + aoff + m * 2048 + k * 1024); } while (0)
; #define PG8_LDB(dst, b, h) do { _Pragma("unroll") for (int n = 0; n < 2; ++n) _Pragma("unroll") for (int k = 0; k < 2; ++k) dst[n][k] = *(const LAS bf16x8*)(lds + PG8_SB(b, h) + boff + n * 2048 + k * 1024); } while (0)
; #define PG8_MMA(ai, bj, At, Bt) do { __builtin_amdgcn_s_setprio(1); _Pragma("unroll") for (int m = 0; m < 4; ++m) _Pragma("unroll") for (int n = 0; n < 2; ++n) _Pragma("unroll") for (int k = 0; k < 2; ++k) \
;         acc[ai][bj][m][n] = __builtin_amdgcn_mfma_f32_16x16x32_bf16(Bt[n][k], At[m][k], acc[ai][bj][m][n], 0, 0, 0); __builtin_amdgcn_s_setprio(0); } while (0)
; #define PG8_WAIT_V(n) asm volatile("s_waitcnt vmcnt(" #n ")" ::: "memory")
; #define PG8_WAIT_L(n) asm volatile("s_waitcnt lgkmcnt(" #n ")" ::: "memory")
; #define PG8_BAR __builtin_amdgcn_s_barrier()
; #define PG8_SCHED __builtin_amdgcn_sched_barrier(0)
; template <class Epi, bool ALIGN_EPI>
; __device__ __forceinline__ void gemm_phase(LAS unsigned char* lds, const Gemm g, const StaticOrder& S, const Epi& E, const int tid) {
;     ...
;             PG8_LDB(B0, 1, 0); PG8_LDB(B1, 1, 1); PG8_SCHED; PG8_LDA(At, 1, 0); PG8_STAGE(PG8_SA(0, 1), a2 + hstepA, voffA);
;             PG8_WAIT_V(8); PG8_WAIT_L(0); PG8_BAR; PG8_MMA(0, 0, At, B0); PG8_MMA(0, 1, At, B1); PG8_BAR; PG8_SCHED;
	s_barrier
	s_add_i32 s87, 0, 0x18000
	v_add_u32_e32 v0, s87, v154
	s_add_i32 s88, 0, 0x1c000
	ds_read_b128 v[132:135], v0
	ds_read_b128 v[148:151], v0 offset:1024
	ds_read_b128 v[156:159], v0 offset:2048
	ds_read_b128 v[160:163], v0 offset:3072
	v_add_u32_e32 v0, s88, v154
	ds_read_b128 v[164:167], v0
	ds_read_b128 v[168:171], v0 offset:1024
	ds_read_b128 v[172:175], v0 offset:2048
	ds_read_b128 v[176:179], v0 offset:3072
	s_add_u32 s34, s34, 0x80000
	s_addc_u32 s35, s35, 0
	s_mov_b32 m0, s72
	ds_read_b128 v[180:183], v155 offset:32768
	ds_read_b128 v[184:187], v155 offset:33792
	ds_read_b128 v[188:191], v155 offset:34816
	ds_read_b128 v[192:195], v155 offset:35840
	ds_read_b128 v[196:199], v155 offset:36864
	ds_read_b128 v[214:217], v155 offset:37888
	ds_read_b128 v[218:221], v155 offset:38912
	ds_read_b128 v[222:225], v155 offset:39936
	global_load_lds_dwordx4 v142, s[34:35]
	s_mov_b32 m0, s73
	s_nop 0
	global_load_lds_dwordx4 v138, s[34:35]
	s_waitcnt vmcnt(8)
	s_waitcnt lgkmcnt(0)
	s_barrier


; #define PG8_MMA(ai, bj, At, Bt) do { __builtin_amdgcn_s_setprio(1); _Pragma("unroll") for (int m = 0; m < 4; ++m) _Pragma("unroll") for (int n = 0; n < 2; ++n) _Pragma("unroll") for (int k = 0; k < 2; ++k) \
;         acc[ai][bj][m][n] = __builtin_amdgcn_mfma_f32_16x16x32_bf16(Bt[n][k], At[m][k], acc[ai][bj][m][n], 0, 0, 0); __builtin_amdgcn_s_setprio(0); } while (0)
; #define PG8_WAIT_V(n) asm volatile("s_waitcnt vmcnt(" #n ")" ::: "memory")
; #define PG8_WAIT_L(n) asm volatile("s_waitcnt lgkmcnt(" #n ")" ::: "memory")
; #define PG8_BAR __builtin_amdgcn_s_barrier()
; #define PG8_SCHED __builtin_amdgcn_sched_barrier(0)
; template <class Epi, bool ALIGN_EPI>
; __device__ __forceinline__ void gemm_phase(LAS unsigned char* lds, const Gemm g, const StaticOrder& S, const Epi& E, const int tid) {
;     ...
;             PG8_WAIT_V(8); PG8_WAIT_L(0); PG8_BAR; PG8_MMA(0, 0, At, B0); PG8_MMA(0, 1, At, B1); PG8_BAR; PG8_SCHED;
	v_mfma_f32_16x16x32_bf16 v[6:9], v[132:135], v[180:183], v[8:11]
	v_mfma_f32_16x16x32_bf16 v[56:59], v[156:159], v[180:183], v[56:59]
	v_mfma_f32_16x16x32_bf16 v[52:55], v[132:135], v[188:191], v[52:55]
	v_mfma_f32_16x16x32_bf16 v[48:51], v[156:159], v[188:191], v[48:51]
	v_mfma_f32_16x16x32_bf16 v[44:47], v[132:135], v[196:199], v[44:47]
	v_mfma_f32_16x16x32_bf16 v[40:43], v[156:159], v[196:199], v[40:43]
	v_mfma_f32_16x16x32_bf16 v[36:39], v[132:135], v[218:221], v[36:39]
	v_mfma_f32_16x16x32_bf16 v[32:35], v[156:159], v[218:221], v[32:35]
	v_mfma_f32_16x16x32_bf16 v[8:11], v[148:151], v[184:187], v[6:9]
	v_mfma_f32_16x16x32_bf16 v[56:59], v[160:163], v[184:187], v[56:59]
	v_mfma_f32_16x16x32_bf16 v[52:55], v[148:151], v[192:195], v[52:55]
	v_mfma_f32_16x16x32_bf16 v[48:51], v[160:163], v[192:195], v[48:51]
	v_mfma_f32_16x16x32_bf16 v[44:47], v[148:151], v[214:217], v[44:47]
	v_mfma_f32_16x16x32_bf16 v[40:43], v[160:163], v[214:217], v[40:43]
	v_mfma_f32_16x16x32_bf16 v[36:39], v[148:151], v[222:225], v[36:39]
	v_mfma_f32_16x16x32_bf16 v[32:35], v[160:163], v[222:225], v[32:35]


; #define PG8_MMA(ai, bj, At, Bt) do { __builtin_amdgcn_s_setprio(1); _Pragma("unroll") for (int m = 0; m < 4; ++m) _Pragma("unroll") for (int n = 0; n < 2; ++n) _Pragma("unroll") for (int k = 0; k < 2; ++k) \
;         acc[ai][bj][m][n] = __builtin_amdgcn_mfma_f32_16x16x32_bf16(Bt[n][k], At[m][k], acc[ai][bj][m][n], 0, 0, 0); __builtin_amdgcn_s_setprio(0); } while (0)
; #define PG8_WAIT_V(n) asm volatile("s_waitcnt vmcnt(" #n ")" ::: "memory")
; #define PG8_WAIT_L(n) asm volatile("s_waitcnt lgkmcnt(" #n ")" ::: "memory")
; #define PG8_BAR __builtin_amdgcn_s_barrier()
; #define PG8_SCHED __builtin_amdgcn_sched_barrier(0)
; template <class Epi, bool ALIGN_EPI>
; __device__ __forceinline__ void gemm_phase(LAS unsigned char* lds, const Gemm g, const StaticOrder& S, const Epi& E, const int tid) {
;     ...
;             PG8_WAIT_V(8); PG8_WAIT_L(0); PG8_BAR; PG8_MMA(0, 0, At, B0); PG8_MMA(0, 1, At, B1); PG8_BAR; PG8_SCHED;
	v_mfma_f32_16x16x32_bf16 v[2:5], v[164:167], v[180:183], v[2:5]
	v_mfma_f32_16x16x32_bf16 v[28:31], v[172:175], v[180:183], v[28:31]
	v_mfma_f32_16x16x32_bf16 v[96:99], v[164:167], v[188:191], v[96:99]
	v_mfma_f32_16x16x32_bf16 v[92:95], v[172:175], v[188:191], v[92:95]
	v_mfma_f32_16x16x32_bf16 v[88:91], v[164:167], v[196:199], v[88:91]
	v_mfma_f32_16x16x32_bf16 v[84:87], v[172:175], v[196:199], v[84:87]
	v_mfma_f32_16x16x32_bf16 v[80:83], v[164:167], v[218:221], v[80:83]
	v_mfma_f32_16x16x32_bf16 v[76:79], v[172:175], v[218:221], v[76:79]
	v_mfma_f32_16x16x32_bf16 v[4:7], v[168:171], v[184:187], v[2:5]
	v_mfma_f32_16x16x32_bf16 v[28:31], v[176:179], v[184:187], v[28:31]
	v_mfma_f32_16x16x32_bf16 v[96:99], v[168:171], v[192:195], v[96:99]
	v_mfma_f32_16x16x32_bf16 v[92:95], v[176:179], v[192:195], v[92:95]
	v_mfma_f32_16x16x32_bf16 v[88:91], v[168:171], v[214:217], v[88:91]
	v_mfma_f32_16x16x32_bf16 v[84:87], v[176:179], v[214:217], v[84:87]
	v_mfma_f32_16x16x32_bf16 v[80:83], v[168:171], v[222:225], v[80:83]
	v_mfma_f32_16x16x32_bf16 v[76:79], v[176:179], v[222:225], v[76:79]

; #define PG8_STAGE(bufoff, gbase, voff) do { _Pragma("unroll") for (int _i = 0; _i < 2; ++_i) \
;         __builtin_amdgcn_global_load_lds((const unsigned*)((const char*)(gbase) + (voff)[_i]), (LAS unsigned*)(lds + (bufoff) + ldsw + _i * 8192), 16, 0, 0); } while (0)
; #define PG8_LDA(dst, b, h) do { _Pragma("unroll") for (int m = 0; m < 4; ++m) _Pragma("unroll") for (int k = 0; k < 2; ++k) dst[m][k] = *(const LAS bf16x8*)(lds + PG8_SA(b, h) + aoff + m * 2048 + k * 1024); } while (0)
; #define PG8_MMA(ai, bj, At, Bt) do { __builtin_amdgcn_s_setprio(1); _Pragma("unroll") for (int m = 0; m < 4; ++m) _Pragma("unroll") for (int n = 0; n < 2; ++n) _Pragma("unroll") for (int k = 0; k < 2; ++k) \
;         acc[ai][bj][m][n] = __builtin_amdgcn_mfma_f32_16x16x32_bf16(Bt[n][k], At[m][k], acc[ai][bj][m][n], 0, 0, 0); __builtin_amdgcn_s_setprio(0); } while (0)
; #define PG8_WAIT_V(n) asm volatile("s_waitcnt vmcnt(" #n ")" ::: "memory")
; #define PG8_WAIT_L(n) asm volatile("s_waitcnt lgkmcnt(" #n ")" ::: "memory")
; #define PG8_BAR __builtin_amdgcn_s_barrier()
; #define PG8_SCHED __builtin_amdgcn_sched_barrier(0)
; template <class Epi, bool ALIGN_EPI>
; __device__ __forceinline__ void gemm_phase(LAS unsigned char* lds, const Gemm g, const StaticOrder& S, const Epi& E, const int tid) {
;     ...
;             PG8_LDA(At, 1, 1); PG8_STAGE(PG8_SB(1, 0), b3, voffB); PG8_STAGE(PG8_SB(1, 1), b3 + hstepB, voffB); PG8_STAGE(PG8_SA(1, 0), a3, voffA);
;             PG8_WAIT_V(8); PG8_WAIT_L(0); PG8_BAR; PG8_MMA(1, 0, At, B0); PG8_MMA(1, 1, At, B1); PG8_BAR; PG8_SCHED;
	s_barrier
	s_add_u32 s34, s22, 0x8000
	s_addc_u32 s35, s23, 0
	s_add_i32 s87, s87, s61
	s_mov_b32 m0, s87
	ds_read_b128 v[180:183], v155 offset:49152
	ds_read_b128 v[184:187], v155 offset:50176
	ds_read_b128 v[188:191], v155 offset:51200
	ds_read_b128 v[192:195], v155 offset:52224
	ds_read_b128 v[196:199], v155 offset:53248
	ds_read_b128 v[214:217], v155 offset:54272
	ds_read_b128 v[218:221], v155 offset:55296
	ds_read_b128 v[222:225], v155 offset:56320
	global_load_lds_dwordx4 v140, s[34:35]
	s_add_i32 m0, s87, 0x2000
	s_add_u32 s22, s22, 0xc000
	s_addc_u32 s23, s23, 0
	global_load_lds_dwordx4 v136, s[34:35]
	s_add_i32 s34, s88, s61
	s_mov_b32 m0, s34
	s_nop 0
	global_load_lds_dwordx4 v140, s[22:23]
	s_add_i32 m0, s34, 0x2000
	s_nop 0
	global_load_lds_dwordx4 v136, s[22:23]
	v_lshl_add_u64 v[2:3], v[152:153], 0, s[6:7]
	s_mov_b32 m0, s78
	s_nop 0
	global_load_lds_dwordx4 v[2:3], off
	v_lshl_add_u64 v[2:3], v[200:201], 0, s[6:7]
	s_mov_b32 m0, s79
	s_nop 0
	global_load_lds_dwordx4 v[2:3], off
	s_waitcnt vmcnt(8)
	s_waitcnt lgkmcnt(0)
	s_barrier


; #define PG8_MMA(ai, bj, At, Bt) do { __builtin_amdgcn_s_setprio(1); _Pragma("unroll") for (int m = 0; m < 4; ++m) _Pragma("unroll") for (int n = 0; n < 2; ++n) _Pragma("unroll") for (int k = 0; k < 2; ++k) \
;         acc[ai][bj][m][n] = __builtin_amdgcn_mfma_f32_16x16x32_bf16(Bt[n][k], At[m][k], acc[ai][bj][m][n], 0, 0, 0); __builtin_amdgcn_s_setprio(0); } while (0)
; #define PG8_WAIT_V(n) asm volatile("s_waitcnt vmcnt(" #n ")" ::: "memory")
; #define PG8_WAIT_L(n) asm volatile("s_waitcnt lgkmcnt(" #n ")" ::: "memory")
; #define PG8_BAR __builtin_amdgcn_s_barrier()
; #define PG8_SCHED __builtin_amdgcn_sched_barrier(0)
; template <class Epi, bool ALIGN_EPI>
; __device__ __forceinline__ void gemm_phase(LAS unsigned char* lds, const Gemm g, const StaticOrder& S, const Epi& E, const int tid) {
;     ...
;             PG8_WAIT_V(8); PG8_WAIT_L(0); PG8_BAR; PG8_MMA(1, 0, At, B0); PG8_MMA(1, 1, At, B1); PG8_BAR; PG8_SCHED;
	v_mfma_f32_16x16x32_bf16 v[24:27], v[132:135], v[180:183], v[24:27]
	v_mfma_f32_16x16x32_bf16 v[20:23], v[156:159], v[180:183], v[20:23]
	v_mfma_f32_16x16x32_bf16 v[64:67], v[132:135], v[188:191], v[64:67]
	v_mfma_f32_16x16x32_bf16 v[72:75], v[156:159], v[188:191], v[72:75]
	v_mfma_f32_16x16x32_bf16 v[16:19], v[132:135], v[196:199], v[16:19]
	v_mfma_f32_16x16x32_bf16 v[12:15], v[156:159], v[196:199], v[12:15]
	v_mfma_f32_16x16x32_bf16 v[60:63], v[132:135], v[218:221], v[60:63]
	v_mfma_f32_16x16x32_bf16 v[68:71], v[156:159], v[218:221], v[68:71]
	v_mfma_f32_16x16x32_bf16 v[24:27], v[148:151], v[184:187], v[24:27]
	v_mfma_f32_16x16x32_bf16 v[20:23], v[160:163], v[184:187], v[20:23]
	v_mfma_f32_16x16x32_bf16 v[64:67], v[148:151], v[192:195], v[64:67]
	v_mfma_f32_16x16x32_bf16 v[72:75], v[160:163], v[192:195], v[72:75]
	v_mfma_f32_16x16x32_bf16 v[16:19], v[148:151], v[214:217], v[16:19]
	v_mfma_f32_16x16x32_bf16 v[12:15], v[160:163], v[214:217], v[12:15]
	v_mfma_f32_16x16x32_bf16 v[60:63], v[148:151], v[222:225], v[60:63]
	v_mfma_f32_16x16x32_bf16 v[68:71], v[160:163], v[222:225], v[68:71]


; #define PG8_MMA(ai, bj, At, Bt) do { __builtin_amdgcn_s_setprio(1); _Pragma("unroll") for (int m = 0; m < 4; ++m) _Pragma("unroll") for (int n = 0; n < 2; ++n) _Pragma("unroll") for (int k = 0; k < 2; ++k) \
;         acc[ai][bj][m][n] = __builtin_amdgcn_mfma_f32_16x16x32_bf16(Bt[n][k], At[m][k], acc[ai][bj][m][n], 0, 0, 0); __builtin_amdgcn_s_setprio(0); } while (0)
; #define PG8_WAIT_V(n) asm volatile("s_waitcnt vmcnt(" #n ")" ::: "memory")
; #define PG8_WAIT_L(n) asm volatile("s_waitcnt lgkmcnt(" #n ")" ::: "memory")
; #define PG8_BAR __builtin_amdgcn_s_barrier()
; #define PG8_SCHED __builtin_amdgcn_sched_barrier(0)
; template <class Epi, bool ALIGN_EPI>
; __device__ __forceinline__ void gemm_phase(LAS unsigned char* lds, const Gemm g, const StaticOrder& S, const Epi& E, const int tid) {
;     ...
;             PG8_WAIT_V(8); PG8_WAIT_L(0); PG8_BAR; PG8_MMA(1, 0, At, B0); PG8_MMA(1, 1, At, B1); PG8_BAR; PG8_SCHED;
	v_mfma_f32_16x16x32_bf16 v[128:131], v[164:167], v[180:183], v[128:131]
	v_mfma_f32_16x16x32_bf16 v[124:127], v[172:175], v[180:183], v[124:127]
	v_mfma_f32_16x16x32_bf16 v[120:123], v[164:167], v[188:191], v[120:123]
	v_mfma_f32_16x16x32_bf16 v[116:119], v[172:175], v[188:191], v[116:119]
	v_mfma_f32_16x16x32_bf16 v[112:115], v[164:167], v[196:199], v[112:115]
	v_mfma_f32_16x16x32_bf16 v[108:111], v[172:175], v[196:199], v[108:111]
	v_mfma_f32_16x16x32_bf16 v[104:107], v[164:167], v[218:221], v[104:107]
	v_mfma_f32_16x16x32_bf16 v[100:103], v[172:175], v[218:221], v[100:103]
	v_mfma_f32_16x16x32_bf16 v[128:131], v[168:171], v[184:187], v[128:131]
	v_mfma_f32_16x16x32_bf16 v[124:127], v[176:179], v[184:187], v[124:127]
	v_mfma_f32_16x16x32_bf16 v[120:123], v[168:171], v[192:195], v[120:123]
	v_mfma_f32_16x16x32_bf16 v[116:119], v[176:179], v[192:195], v[116:119]
	v_mfma_f32_16x16x32_bf16 v[112:115], v[168:171], v[214:217], v[112:115]
	v_mfma_f32_16x16x32_bf16 v[108:111], v[176:179], v[214:217], v[108:111]
	v_mfma_f32_16x16x32_bf16 v[104:107], v[168:171], v[222:225], v[104:107]
	v_mfma_f32_16x16x32_bf16 v[100:103], v[176:179], v[222:225], v[100:103]

; #define PG8_STAGE(bufoff, gbase, voff) do { _Pragma("unroll") for (int _i = 0; _i < 2; ++_i) \
;         __builtin_amdgcn_global_load_lds((const unsigned*)((const char*)(gbase) + (voff)[_i]), (LAS unsigned*)(lds + (bufoff) + ldsw + _i * 8192), 16, 0, 0); } while (0)
; #define PG8_LDA(dst, b, h) do { _Pragma("unroll") for (int m = 0; m < 4; ++m) _Pragma("unroll") for (int k = 0; k < 2; ++k) dst[m][k] = *(const LAS bf16x8*)(lds + PG8_SA(b, h) + aoff + m * 2048 + k * 1024); } while (0)
; #define PG8_LDB(dst, b, h) do { _Pragma("unroll") for (int n = 0; n < 2; ++n) _Pragma("unroll") for (int k = 0; k < 2; ++k) dst[n][k] = *(const LAS bf16x8*)(lds + PG8_SB(b, h) + boff + n * 2048 + k * 1024); } while (0)
; #define PG8_BAR __builtin_amdgcn_s_barrier()
; template <class Epi, bool ALIGN_EPI>
; __device__ __forceinline__ void gemm_phase(LAS unsigned char* lds, const Gemm g, const StaticOrder& S, const Epi& E, const int tid) {
;     ...
;         for (int t = 0; t < nt; t += 2) {
;             const bool last = (t == nt - 2);
;             const char* a1 = cA + (size_t)(t + 1) * kstepA;
;             const char* a2 = last ? nA : cA + (size_t)(t + 2) * kstepA; const char* b2 = last ? nB : cB + (size_t)(t + 2) * kstepB;
;             const char* a3 = a2 + kstepA; const char* b3 = b2 + kstepB;
;             PG8_LDB(B0, 0, 0); PG8_LDB(B1, 0, 1); PG8_SCHED; PG8_LDA(At, 0, 0); PG8_STAGE(PG8_SA(1, 1), a1 + hstepA, voffA);
;             PG8_WAIT_V(8); PG8_WAIT_L(0); PG8_BAR; PG8_MMA(0, 0, At, B0); PG8_MMA(0, 1, At, B1); PG8_BAR; PG8_SCHED;
;             PG8_LDA(At, 0, 1); PG8_STAGE(PG8_SB(0, 0), b2, voffB); PG8_STAGE(PG8_SB(0, 1), b2 + hstepB, voffB); PG8_STAGE(PG8_SA(0, 0), a2, voffA);
;             PG8_WAIT_V(8); PG8_WAIT_L(0); PG8_BAR; PG8_MMA(1, 0, At, B0); PG8_MMA(1, 1, At, B1); PG8_BAR; PG8_SCHED;
;             PG8_LDB(B0, 1, 0); PG8_LDB(B1, 1, 1); PG8_SCHED; PG8_LDA(At, 1, 0); PG8_STAGE(PG8_SA(0, 1), a2 + hstepA, voffA);
;             PG8_WAIT_V(8); PG8_WAIT_L(0); PG8_BAR; PG8_MMA(0, 0, At, B0); PG8_MMA(0, 1, At, B1); PG8_BAR; PG8_SCHED;
;             PG8_LDA(At, 1, 1); PG8_STAGE(PG8_SB(1, 0), b3, voffB); PG8_STAGE(PG8_SB(1, 1), b3 + hstepB, voffB); PG8_STAGE(PG8_SA(1, 0), a3, voffA);
;             PG8_WAIT_V(8); PG8_WAIT_L(0); PG8_BAR; PG8_MMA(1, 0, At, B0); PG8_MMA(1, 1, At, B1); PG8_BAR; PG8_SCHED;
;         }
;         if constexpr (ALIGN_EPI) { if (wr == 0) PG8_BAR; }
	s_barrier
	s_add_i32 s86, s86, 2
	s_add_u32 s10, s10, 0x100
	s_addc_u32 s11, s11, 0
	s_add_u32 s84, s84, 0x10000
	s_addc_u32 s85, s85, 0
	s_cmp_gt_u32 s86, 29
	s_cbranch_scc0 .LBB0_847
	s_and_b64 vcc, exec, s[44:45]
	s_cbranch_vccz .LBB0_850
	s_barrier
